# speedup vs baseline: 1.0018x; 1.0018x over previous
; __device__ __forceinline__ unsigned pack2(float a, float b) { return (unsigned)f2bf(a) | ((unsigned)f2bf(b) << 16); }
; template <int EPI, bool HS = false>
; __device__ __forceinline__ void gemm_phase(const Params& p, const GemmCfg& g, char* shm, const int wave_s) {
;     ...
;             for (int bj = 0; bj < 2; ++bj) {
;               float2 xn;
;               xn.x = xv[j][bj].x + gt[bj][0] * acc[ai][bj][m][0][j];
;               xn.y = xv[j][bj].y + gt[bj][1] * acc[ai][bj][m][1][j];
;               const unsigned o = tb + (unsigned)((ai * 128 + m * 16 + j) * 1024 + bj * 128);
;               *(float2*)(xout_t + o) = xn;
;               if (g.has_next) *(unsigned*)(xg_t + o) = pack2(xn.x * gn[bj][0], xn.y * gn[bj][1]);
;               ss += xn.x * xn.x + xn.y * xn.y;
;             }
;             if (g.has_next) {
;               ss = dpp_row_sum16(ss);
;               if (fr == 0) rss_t[(wr * 64 + fq * 4 + ai * 128 + m * 16 + j) * 16] = ss;
;             }
.LBB0_107:
	s_or_b64 exec, exec, s[68:69]
	v_or_b32_e32 v144, 0x400, v0
	v_mov_b32_e32 v126, v123
	v_mov_b32_e32 v145, v1
	s_waitcnt lgkmcnt(2)
	v_pk_fma_f32 v[156:157], v[150:151], v[126:127], v[138:139]
	v_lshl_add_u64 v[144:145], v[144:145], 2, s[2:3]
	global_store_dwordx2 v[144:145], v[156:157], off
	v_pk_mul_f32 v[144:145], v[148:149], v[156:157]
	v_or_b32_e32 v158, 0x480, v0
	s_nop 0
	s_nop 0
	v_cvt_pk_bf16_f32 v118, v144, v144
	v_cvt_pk_bf16_f32 v114, v145, v145
	v_lshrrev_b32_e32 v118, 16, v118
	v_and_or_b32 v114, v114, s28, v118
	v_mov_b32_e32 v118, v115
	v_mov_b32_e32 v159, v1
	v_pk_fma_f32 v[144:145], v[146:147], v[118:119], v[140:141]
	v_lshl_add_u64 v[158:159], v[158:159], 2, s[2:3]
	global_store_dword v[154:155], v114, off offset:2048
	global_store_dwordx2 v[158:159], v[144:145], off
	v_pk_mul_f32 v[158:159], v[152:153], v[144:145]
	v_pk_mul_f32 v[156:157], v[156:157], v[156:157]
	s_nop 0
	v_cvt_pk_bf16_f32 v118, v158, v158
	v_cvt_pk_bf16_f32 v114, v159, v159
	v_lshrrev_b32_e32 v118, 16, v118
	v_and_or_b32 v114, v114, s28, v118
	v_pk_mul_f32 v[144:145], v[144:145], v[144:145]
	global_store_dword v[154:155], v114, off offset:2304
	v_add_f32_e32 v114, v144, v145
	v_add_f32_e32 v118, v156, v157
	v_add_f32_e32 v114, v118, v114
	s_nop 1
	v_add_f32_dpp v114, v114, v114 quad_perm:[1,0,3,2] row_mask:0xf bank_mask:0xf bound_ctrl:1
	s_nop 1
	v_add_f32_dpp v114, v114, v114 quad_perm:[2,3,0,1] row_mask:0xf bank_mask:0xf bound_ctrl:1
	s_nop 1
	v_add_f32_dpp v114, v114, v114 row_half_mirror row_mask:0xf bank_mask:0xf bound_ctrl:1
	s_nop 1
	v_mov_b32_dpp v118, v114 row_mirror row_mask:0xf bank_mask:0xf bound_ctrl:1
	s_and_saveexec_b64 s[68:69], s[4:5]
	s_cbranch_execz .LBB0_109
	v_lshlrev_b32_e32 v144, 4, v160
	v_ashrrev_i32_e32 v145, 31, v144
	v_add_f32_e32 v114, v114, v118
	v_lshl_add_u64 v[144:145], v[144:145], 2, v[142:143]
	global_store_dword v[144:145], v114, off offset:64

; #define SCHED __builtin_amdgcn_sched_barrier(0)
; template <int EPI, bool HS = false>
; __device__ __forceinline__ void gemm_phase(const Params& p, const GemmCfg& g, char* shm, const int wave_s) {
;     ...
;         u16* ot = g.o16 + (size_t)TOK * 1024 + (size_t)orow0 * 1024 + (pn - 4) * 128;
;         const unsigned tb = (unsigned)((wr * 64 + fq * 4) * 1024 + wc * 16 + fr);
; #pragma unroll
;         for (int ai = 0; ai < 2; ++ai)
; #pragma unroll
;           for (int m = 0; m < 4; ++m) {
;             const f32x4 r4 = *(const f32x4*)(rsw + ai * 128 + m * 16);
; #pragma unroll
;             for (int j = 0; j < 4; ++j)
; #pragma unroll
;               for (int bj = 0; bj < 2; ++bj)
;                 ot[tb + (ai * 128 + m * 16 + j) * 1024 + bj * 64] =
;                     f2bf((r4[j] * acc[ai][bj][m][0][j] + swv[bj][0]) * (r4[j] * acc[ai][bj][m][1][j] + swv[bj][1]));
;             SCHED;
;           }
.LBB0_325:
	ds_read_b128 v[138:141], v130
	s_add_u32 s3, s8, s2
	s_addc_u32 s7, s9, 0
	s_add_u32 s6, s3, 0x7fffc00
	v_lshlrev_b32_e32 v0, 4, v131
	s_waitcnt lgkmcnt(0)
	v_fma_f32 v142, v118, v138, v137
	v_fma_f32 v143, v114, v138, v136
	v_mul_f32_e32 v142, v142, v143
	s_addc_u32 s7, s7, 0
	v_or3_b32 v0, v133, v0, v132
	s_nop 0
	v_cvt_pk_bf16_f32 v144, v142, v142
	v_lshl_add_u64 v[142:143], v[0:1], 1, s[6:7]
	global_store_short_d16_hi v[142:143], v144, off
	v_fma_f32 v142, v126, v138, v135
	v_fma_f32 v138, v122, v138, v134
	v_mul_f32_e32 v138, v142, v138
	s_nop 0
	v_cvt_pk_bf16_f32 v138, v138, v138
	v_or_b32_e32 v142, 64, v0
	v_mov_b32_e32 v143, v1
	v_lshl_add_u64 v[142:143], v[142:143], 1, s[6:7]
	global_store_short_d16_hi v[142:143], v138, off
	v_fma_f32 v138, v119, v139, v137
	v_fma_f32 v143, v115, v139, v136
	v_mul_f32_e32 v138, v138, v143
	s_nop 0
	v_or_b32_e32 v142, 0x400, v0
	v_cvt_pk_bf16_f32 v138, v138, v138
	v_mov_b32_e32 v143, v1
	v_lshl_add_u64 v[142:143], v[142:143], 1, s[6:7]
	global_store_short_d16_hi v[142:143], v138, off
	v_fma_f32 v138, v127, v139, v135
	v_fma_f32 v139, v123, v139, v134
	v_mul_f32_e32 v138, v138, v139
	s_nop 0
	v_cvt_pk_bf16_f32 v142, v138, v138
	v_or_b32_e32 v138, 0x440, v0
	v_mov_b32_e32 v139, v1
	v_lshl_add_u64 v[138:139], v[138:139], 1, s[6:7]
	global_store_short_d16_hi v[138:139], v142, off
	v_fma_f32 v139, v120, v140, v137
	v_fma_f32 v142, v116, v140, v136
	v_mul_f32_e32 v139, v139, v142
	s_nop 0
	v_or_b32_e32 v138, 0x800, v0
	v_cvt_pk_bf16_f32 v142, v139, v139
	v_mov_b32_e32 v139, v1
	v_lshl_add_u64 v[138:139], v[138:139], 1, s[6:7]
	global_store_short_d16_hi v[138:139], v142, off
	v_fma_f32 v138, v128, v140, v135
	v_fma_f32 v139, v124, v140, v134
	v_mul_f32_e32 v138, v138, v139
	s_nop 0
	v_cvt_pk_bf16_f32 v140, v138, v138
	v_or_b32_e32 v138, 0x840, v0
	v_mov_b32_e32 v139, v1
	v_lshl_add_u64 v[138:139], v[138:139], 1, s[6:7]
	global_store_short_d16_hi v[138:139], v140, off
	v_fma_f32 v139, v121, v141, v137
	v_fma_f32 v140, v117, v141, v136
	v_mul_f32_e32 v139, v139, v140
	s_nop 0
	v_or_b32_e32 v138, 0xc00, v0
	v_cvt_pk_bf16_f32 v140, v139, v139
	v_mov_b32_e32 v139, v1
	v_lshl_add_u64 v[138:139], v[138:139], 1, s[6:7]
	global_store_short_d16_hi v[138:139], v140, off
	v_fma_f32 v138, v129, v141, v135
	v_fma_f32 v139, v125, v141, v134
	v_mul_f32_e32 v138, v138, v139
	s_nop 0
	v_cvt_pk_bf16_f32 v140, v138, v138
	v_or_b32_e32 v138, 0xc40, v0
	v_mov_b32_e32 v139, v1
	v_lshl_add_u64 v[138:139], v[138:139], 1, s[6:7]
	global_store_short_d16_hi v[138:139], v140, off
	ds_read_b128 v[138:141], v130 offset:64
	v_or_b32_e32 v142, 0x4000, v0
	v_mov_b32_e32 v143, v1
	v_lshl_add_u64 v[142:143], v[142:143], 1, s[6:7]
	s_waitcnt lgkmcnt(0)
	v_fma_f32 v144, v102, v138, v137
	v_fma_f32 v145, v98, v138, v136
	v_mul_f32_e32 v144, v144, v145
	s_nop 0
	v_cvt_pk_bf16_f32 v144, v144, v144
	global_store_short_d16_hi v[142:143], v144, off
	v_fma_f32 v142, v110, v138, v135
	v_fma_f32 v138, v106, v138, v134
	v_mul_f32_e32 v138, v142, v138
	v_cvt_pk_bf16_f32 v138, v138, v138
	v_or_b32_e32 v142, 0x4040, v0
	v_mov_b32_e32 v143, v1
	v_lshl_add_u64 v[142:143], v[142:143], 1, s[6:7]
	global_store_short_d16_hi v[142:143], v138, off
	v_fma_f32 v138, v103, v139, v137
	v_fma_f32 v143, v99, v139, v136
	v_mul_f32_e32 v138, v138, v143
	s_nop 0
	v_or_b32_e32 v142, 0x4400, v0
	v_cvt_pk_bf16_f32 v138, v138, v138
	v_mov_b32_e32 v143, v1
	v_lshl_add_u64 v[142:143], v[142:143], 1, s[6:7]
	global_store_short_d16_hi v[142:143], v138, off
	v_fma_f32 v138, v111, v139, v135
	v_fma_f32 v139, v107, v139, v134
	v_mul_f32_e32 v138, v138, v139
	s_nop 0
	v_cvt_pk_bf16_f32 v142, v138, v138
	v_or_b32_e32 v138, 0x4440, v0
	v_mov_b32_e32 v139, v1
	v_lshl_add_u64 v[138:139], v[138:139], 1, s[6:7]
	global_store_short_d16_hi v[138:139], v142, off
	v_fma_f32 v139, v104, v140, v137
	v_fma_f32 v142, v100, v140, v136
	v_mul_f32_e32 v139, v139, v142
	s_nop 0
	v_or_b32_e32 v138, 0x4800, v0
	v_cvt_pk_bf16_f32 v142, v139, v139
	v_mov_b32_e32 v139, v1
	v_lshl_add_u64 v[138:139], v[138:139], 1, s[6:7]
	global_store_short_d16_hi v[138:139], v142, off
	v_fma_f32 v138, v112, v140, v135
	v_fma_f32 v139, v108, v140, v134
	v_mul_f32_e32 v138, v138, v139
	s_nop 0
	v_cvt_pk_bf16_f32 v140, v138, v138
	v_or_b32_e32 v138, 0x4840, v0
	v_mov_b32_e32 v139, v1
	v_lshl_add_u64 v[138:139], v[138:139], 1, s[6:7]
	global_store_short_d16_hi v[138:139], v140, off
	v_fma_f32 v139, v105, v141, v137
	v_fma_f32 v140, v101, v141, v136
	v_mul_f32_e32 v139, v139, v140
	s_nop 0
	v_or_b32_e32 v138, 0x4c00, v0
	v_cvt_pk_bf16_f32 v140, v139, v139
	v_mov_b32_e32 v139, v1
	v_lshl_add_u64 v[138:139], v[138:139], 1, s[6:7]
	global_store_short_d16_hi v[138:139], v140, off
	v_fma_f32 v138, v113, v141, v135
	v_fma_f32 v139, v109, v141, v134
	v_mul_f32_e32 v138, v138, v139
	s_nop 0
	v_cvt_pk_bf16_f32 v140, v138, v138
	v_or_b32_e32 v138, 0x4c40, v0
	v_mov_b32_e32 v139, v1
	v_lshl_add_u64 v[138:139], v[138:139], 1, s[6:7]
	global_store_short_d16_hi v[138:139], v140, off
	ds_read_b128 v[138:141], v130 offset:128
	v_or_b32_e32 v142, 0x8000, v0
	v_mov_b32_e32 v143, v1
	v_lshl_add_u64 v[142:143], v[142:143], 1, s[6:7]
	s_waitcnt lgkmcnt(0)
; #define SCHED __builtin_amdgcn_sched_barrier(0)
; template <int EPI, bool HS = false>
; __device__ __forceinline__ void gemm_phase(const Params& p, const GemmCfg& g, char* shm, const int wave_s) {
;     ...
;         u16* ot = g.o16 + (size_t)TOK * 1024 + (size_t)orow0 * 1024 + (pn - 4) * 128;
;         const unsigned tb = (unsigned)((wr * 64 + fq * 4) * 1024 + wc * 16 + fr);
; #pragma unroll
;         for (int ai = 0; ai < 2; ++ai)
; #pragma unroll
;           for (int m = 0; m < 4; ++m) {
;             const f32x4 r4 = *(const f32x4*)(rsw + ai * 128 + m * 16);
; #pragma unroll
;             for (int j = 0; j < 4; ++j)
; #pragma unroll
;               for (int bj = 0; bj < 2; ++bj)
;                 ot[tb + (ai * 128 + m * 16 + j) * 1024 + bj * 64] =
;                     f2bf((r4[j] * acc[ai][bj][m][0][j] + swv[bj][0]) * (r4[j] * acc[ai][bj][m][1][j] + swv[bj][1]));
;             SCHED;
;           }
	v_fma_f32 v144, v86, v138, v137
	v_fma_f32 v145, v82, v138, v136
	v_mul_f32_e32 v144, v144, v145
	s_nop 0
	v_cvt_pk_bf16_f32 v144, v144, v144
	global_store_short_d16_hi v[142:143], v144, off
	v_fma_f32 v142, v94, v138, v135
	v_fma_f32 v138, v90, v138, v134
	v_mul_f32_e32 v138, v142, v138
	v_cvt_pk_bf16_f32 v138, v138, v138
	v_or_b32_e32 v142, 0x8040, v0
	v_mov_b32_e32 v143, v1
	v_lshl_add_u64 v[142:143], v[142:143], 1, s[6:7]
	global_store_short_d16_hi v[142:143], v138, off
	v_fma_f32 v138, v87, v139, v137
	v_fma_f32 v143, v83, v139, v136
	v_mul_f32_e32 v138, v138, v143
	s_nop 0
	v_or_b32_e32 v142, 0x8400, v0
	v_cvt_pk_bf16_f32 v138, v138, v138
	v_mov_b32_e32 v143, v1
	v_lshl_add_u64 v[142:143], v[142:143], 1, s[6:7]
	global_store_short_d16_hi v[142:143], v138, off
	v_fma_f32 v138, v95, v139, v135
	v_fma_f32 v139, v91, v139, v134
	v_mul_f32_e32 v138, v138, v139
	s_nop 0
	v_cvt_pk_bf16_f32 v142, v138, v138
	v_or_b32_e32 v138, 0x8440, v0
	v_mov_b32_e32 v139, v1
	v_lshl_add_u64 v[138:139], v[138:139], 1, s[6:7]
	global_store_short_d16_hi v[138:139], v142, off
	v_fma_f32 v139, v88, v140, v137
	v_fma_f32 v142, v84, v140, v136
	v_mul_f32_e32 v139, v139, v142
	s_nop 0
	v_or_b32_e32 v138, 0x8800, v0
	v_cvt_pk_bf16_f32 v142, v139, v139
	v_mov_b32_e32 v139, v1
	v_lshl_add_u64 v[138:139], v[138:139], 1, s[6:7]
	global_store_short_d16_hi v[138:139], v142, off
	v_fma_f32 v138, v96, v140, v135
	v_fma_f32 v139, v92, v140, v134
	v_mul_f32_e32 v138, v138, v139
	s_nop 0
	v_cvt_pk_bf16_f32 v140, v138, v138
	v_or_b32_e32 v138, 0x8840, v0
	v_mov_b32_e32 v139, v1
	v_lshl_add_u64 v[138:139], v[138:139], 1, s[6:7]
	global_store_short_d16_hi v[138:139], v140, off
	v_fma_f32 v139, v89, v141, v137
	v_fma_f32 v140, v85, v141, v136
	v_mul_f32_e32 v139, v139, v140
	s_nop 0
	v_or_b32_e32 v138, 0x8c00, v0
	v_cvt_pk_bf16_f32 v140, v139, v139
	v_mov_b32_e32 v139, v1
	v_lshl_add_u64 v[138:139], v[138:139], 1, s[6:7]
	global_store_short_d16_hi v[138:139], v140, off
	v_fma_f32 v138, v97, v141, v135
	v_fma_f32 v139, v93, v141, v134
	v_mul_f32_e32 v138, v138, v139
	s_nop 0
	v_cvt_pk_bf16_f32 v140, v138, v138
	v_or_b32_e32 v138, 0x8c40, v0
	v_mov_b32_e32 v139, v1
	v_lshl_add_u64 v[138:139], v[138:139], 1, s[6:7]
	global_store_short_d16_hi v[138:139], v140, off
	ds_read_b128 v[138:141], v130 offset:192
	v_or_b32_e32 v142, 0xc000, v0
	v_mov_b32_e32 v143, v1
	v_lshl_add_u64 v[142:143], v[142:143], 1, s[6:7]
	s_waitcnt lgkmcnt(0)
	v_fma_f32 v144, v70, v138, v137
	v_fma_f32 v145, v66, v138, v136
	v_mul_f32_e32 v144, v144, v145
	s_nop 0
	v_cvt_pk_bf16_f32 v144, v144, v144
	global_store_short_d16_hi v[142:143], v144, off
	v_fma_f32 v142, v78, v138, v135
	v_fma_f32 v138, v74, v138, v134
	v_mul_f32_e32 v138, v142, v138
	v_cvt_pk_bf16_f32 v138, v138, v138
	v_or_b32_e32 v142, 0xc040, v0
	v_mov_b32_e32 v143, v1
	v_lshl_add_u64 v[142:143], v[142:143], 1, s[6:7]
	global_store_short_d16_hi v[142:143], v138, off
	v_fma_f32 v138, v71, v139, v137
	v_fma_f32 v143, v67, v139, v136
	v_mul_f32_e32 v138, v138, v143
	s_nop 0
	v_or_b32_e32 v142, 0xc400, v0
	v_cvt_pk_bf16_f32 v138, v138, v138
	v_mov_b32_e32 v143, v1
	v_lshl_add_u64 v[142:143], v[142:143], 1, s[6:7]
	global_store_short_d16_hi v[142:143], v138, off
	v_fma_f32 v138, v79, v139, v135
	v_fma_f32 v139, v75, v139, v134
	v_mul_f32_e32 v138, v138, v139
	s_nop 0
	v_cvt_pk_bf16_f32 v142, v138, v138
	v_or_b32_e32 v138, 0xc440, v0
	v_mov_b32_e32 v139, v1
	v_lshl_add_u64 v[138:139], v[138:139], 1, s[6:7]
	global_store_short_d16_hi v[138:139], v142, off
	v_fma_f32 v139, v72, v140, v137
	v_fma_f32 v142, v68, v140, v136
	v_mul_f32_e32 v139, v139, v142
	s_nop 0
	v_or_b32_e32 v138, 0xc800, v0
	v_cvt_pk_bf16_f32 v142, v139, v139
	v_mov_b32_e32 v139, v1
	v_lshl_add_u64 v[138:139], v[138:139], 1, s[6:7]
	global_store_short_d16_hi v[138:139], v142, off
	v_fma_f32 v138, v80, v140, v135
	v_fma_f32 v139, v76, v140, v134
	v_mul_f32_e32 v138, v138, v139
	s_nop 0
	v_cvt_pk_bf16_f32 v140, v138, v138
	v_or_b32_e32 v138, 0xc840, v0
	v_mov_b32_e32 v139, v1
	v_lshl_add_u64 v[138:139], v[138:139], 1, s[6:7]
	global_store_short_d16_hi v[138:139], v140, off
	v_fma_f32 v139, v73, v141, v137
	v_fma_f32 v140, v69, v141, v136
	v_mul_f32_e32 v139, v139, v140
	s_nop 0
	v_or_b32_e32 v138, 0xcc00, v0
	v_cvt_pk_bf16_f32 v140, v139, v139
	v_mov_b32_e32 v139, v1
	v_lshl_add_u64 v[138:139], v[138:139], 1, s[6:7]
	global_store_short_d16_hi v[138:139], v140, off
	v_fma_f32 v138, v81, v141, v135
	v_fma_f32 v139, v77, v141, v134
	v_mul_f32_e32 v138, v138, v139
	s_nop 0
	v_cvt_pk_bf16_f32 v140, v138, v138
	v_or_b32_e32 v138, 0xcc40, v0
	v_mov_b32_e32 v139, v1
	v_lshl_add_u64 v[138:139], v[138:139], 1, s[6:7]
	global_store_short_d16_hi v[138:139], v140, off
	ds_read_b128 v[138:141], v130 offset:512
	v_add_u32_e32 v142, 0x20000, v0
	v_mov_b32_e32 v143, v1
	v_lshl_add_u64 v[142:143], v[142:143], 1, s[6:7]
	s_waitcnt lgkmcnt(0)
; #define SCHED __builtin_amdgcn_sched_barrier(0)
; template <int EPI, bool HS = false>
; __device__ __forceinline__ void gemm_phase(const Params& p, const GemmCfg& g, char* shm, const int wave_s) {
;     ...
;         u16* ot = g.o16 + (size_t)TOK * 1024 + (size_t)orow0 * 1024 + (pn - 4) * 128;
;         const unsigned tb = (unsigned)((wr * 64 + fq * 4) * 1024 + wc * 16 + fr);
; #pragma unroll
;         for (int ai = 0; ai < 2; ++ai)
; #pragma unroll
;           for (int m = 0; m < 4; ++m) {
;             const f32x4 r4 = *(const f32x4*)(rsw + ai * 128 + m * 16);
; #pragma unroll
;             for (int j = 0; j < 4; ++j)
; #pragma unroll
;               for (int bj = 0; bj < 2; ++bj)
;                 ot[tb + (ai * 128 + m * 16 + j) * 1024 + bj * 64] =
;                     f2bf((r4[j] * acc[ai][bj][m][0][j] + swv[bj][0]) * (r4[j] * acc[ai][bj][m][1][j] + swv[bj][1]));
;             SCHED;
;           }
	v_fma_f32 v144, v58, v138, v137
	v_fma_f32 v145, v50, v138, v136
	v_mul_f32_e32 v144, v144, v145
	s_nop 0
	v_cvt_pk_bf16_f32 v144, v144, v144
	global_store_short_d16_hi v[142:143], v144, off
	v_fma_f32 v142, v62, v138, v135
	v_fma_f32 v138, v54, v138, v134
	v_mul_f32_e32 v138, v142, v138
	v_cvt_pk_bf16_f32 v138, v138, v138
	v_add_u32_e32 v142, 0x20040, v0
	v_mov_b32_e32 v143, v1
	v_lshl_add_u64 v[142:143], v[142:143], 1, s[6:7]
	global_store_short_d16_hi v[142:143], v138, off
	v_fma_f32 v138, v59, v139, v137
	v_fma_f32 v143, v51, v139, v136
	v_mul_f32_e32 v138, v138, v143
	s_nop 0
	v_add_u32_e32 v142, 0x20400, v0
	v_cvt_pk_bf16_f32 v138, v138, v138
	v_mov_b32_e32 v143, v1
	v_lshl_add_u64 v[142:143], v[142:143], 1, s[6:7]
	global_store_short_d16_hi v[142:143], v138, off
	v_fma_f32 v138, v63, v139, v135
	v_fma_f32 v139, v55, v139, v134
	v_mul_f32_e32 v138, v138, v139
	s_nop 0
	v_cvt_pk_bf16_f32 v142, v138, v138
	v_add_u32_e32 v138, 0x20440, v0
	v_mov_b32_e32 v139, v1
	v_lshl_add_u64 v[138:139], v[138:139], 1, s[6:7]
	global_store_short_d16_hi v[138:139], v142, off
	v_fma_f32 v139, v60, v140, v137
	v_fma_f32 v142, v52, v140, v136
	v_mul_f32_e32 v139, v139, v142
	s_nop 0
	v_add_u32_e32 v138, 0x20800, v0
	v_cvt_pk_bf16_f32 v142, v139, v139
	v_mov_b32_e32 v139, v1
	v_lshl_add_u64 v[138:139], v[138:139], 1, s[6:7]
	global_store_short_d16_hi v[138:139], v142, off
	v_fma_f32 v138, v64, v140, v135
	v_fma_f32 v139, v56, v140, v134
	v_mul_f32_e32 v138, v138, v139
	s_nop 0
	v_cvt_pk_bf16_f32 v140, v138, v138
	v_add_u32_e32 v138, 0x20840, v0
	v_mov_b32_e32 v139, v1
	v_lshl_add_u64 v[138:139], v[138:139], 1, s[6:7]
	global_store_short_d16_hi v[138:139], v140, off
	v_fma_f32 v139, v61, v141, v137
	v_fma_f32 v140, v53, v141, v136
	v_mul_f32_e32 v139, v139, v140
	s_nop 0
	v_add_u32_e32 v138, 0x20c00, v0
	v_cvt_pk_bf16_f32 v140, v139, v139
	v_mov_b32_e32 v139, v1
	v_lshl_add_u64 v[138:139], v[138:139], 1, s[6:7]
	global_store_short_d16_hi v[138:139], v140, off
	v_fma_f32 v138, v65, v141, v135
	v_fma_f32 v139, v57, v141, v134
	v_mul_f32_e32 v138, v138, v139
	s_nop 0
	v_cvt_pk_bf16_f32 v140, v138, v138
	v_add_u32_e32 v138, 0x20c40, v0
	v_mov_b32_e32 v139, v1
	v_lshl_add_u64 v[138:139], v[138:139], 1, s[6:7]
	global_store_short_d16_hi v[138:139], v140, off
	ds_read_b128 v[138:141], v130 offset:576
	v_add_u32_e32 v142, 0x24000, v0
	v_mov_b32_e32 v143, v1
	v_lshl_add_u64 v[142:143], v[142:143], 1, s[6:7]
	s_waitcnt lgkmcnt(0)
	v_fma_f32 v144, v42, v138, v137
	v_fma_f32 v145, v34, v138, v136
	v_mul_f32_e32 v144, v144, v145
	s_nop 0
	v_cvt_pk_bf16_f32 v144, v144, v144
	global_store_short_d16_hi v[142:143], v144, off
	v_fma_f32 v142, v46, v138, v135
	v_fma_f32 v138, v38, v138, v134
	v_mul_f32_e32 v138, v142, v138
	v_cvt_pk_bf16_f32 v138, v138, v138
	v_add_u32_e32 v142, 0x24040, v0
	v_mov_b32_e32 v143, v1
	v_lshl_add_u64 v[142:143], v[142:143], 1, s[6:7]
	global_store_short_d16_hi v[142:143], v138, off
	v_fma_f32 v138, v43, v139, v137
	v_fma_f32 v143, v35, v139, v136
	v_mul_f32_e32 v138, v138, v143
	s_nop 0
	v_add_u32_e32 v142, 0x24400, v0
	v_cvt_pk_bf16_f32 v138, v138, v138
	v_mov_b32_e32 v143, v1
	v_lshl_add_u64 v[142:143], v[142:143], 1, s[6:7]
	global_store_short_d16_hi v[142:143], v138, off
	v_fma_f32 v138, v47, v139, v135
	v_fma_f32 v139, v39, v139, v134
	v_mul_f32_e32 v138, v138, v139
	s_nop 0
	v_cvt_pk_bf16_f32 v142, v138, v138
	v_add_u32_e32 v138, 0x24440, v0
	v_mov_b32_e32 v139, v1
	v_lshl_add_u64 v[138:139], v[138:139], 1, s[6:7]
	global_store_short_d16_hi v[138:139], v142, off
	v_fma_f32 v139, v44, v140, v137
	v_fma_f32 v142, v36, v140, v136
	v_mul_f32_e32 v139, v139, v142
	s_nop 0
	v_add_u32_e32 v138, 0x24800, v0
	v_cvt_pk_bf16_f32 v142, v139, v139
	v_mov_b32_e32 v139, v1
	v_lshl_add_u64 v[138:139], v[138:139], 1, s[6:7]
	global_store_short_d16_hi v[138:139], v142, off
	v_fma_f32 v138, v48, v140, v135
	v_fma_f32 v139, v40, v140, v134
	v_mul_f32_e32 v138, v138, v139
	s_nop 0
	v_cvt_pk_bf16_f32 v140, v138, v138
	v_add_u32_e32 v138, 0x24840, v0
	v_mov_b32_e32 v139, v1
	v_lshl_add_u64 v[138:139], v[138:139], 1, s[6:7]
	global_store_short_d16_hi v[138:139], v140, off
	v_fma_f32 v139, v45, v141, v137
	v_fma_f32 v140, v37, v141, v136
	v_mul_f32_e32 v139, v139, v140
	s_nop 0
	v_add_u32_e32 v138, 0x24c00, v0
	v_cvt_pk_bf16_f32 v140, v139, v139
	v_mov_b32_e32 v139, v1
	v_lshl_add_u64 v[138:139], v[138:139], 1, s[6:7]
	global_store_short_d16_hi v[138:139], v140, off
	v_fma_f32 v138, v49, v141, v135
	v_fma_f32 v139, v41, v141, v134
	v_mul_f32_e32 v138, v138, v139
	s_nop 0
	v_cvt_pk_bf16_f32 v140, v138, v138
	v_add_u32_e32 v138, 0x24c40, v0
	v_mov_b32_e32 v139, v1
	v_lshl_add_u64 v[138:139], v[138:139], 1, s[6:7]
	global_store_short_d16_hi v[138:139], v140, off
	ds_read_b128 v[138:141], v130 offset:640
	v_add_u32_e32 v142, 0x28000, v0
	v_mov_b32_e32 v143, v1
	v_lshl_add_u64 v[142:143], v[142:143], 1, s[6:7]
	s_waitcnt lgkmcnt(0)
; #define SCHED __builtin_amdgcn_sched_barrier(0)
; template <int EPI, bool HS = false>
; __device__ __forceinline__ void gemm_phase(const Params& p, const GemmCfg& g, char* shm, const int wave_s) {
;     ...
;         u16* ot = g.o16 + (size_t)TOK * 1024 + (size_t)orow0 * 1024 + (pn - 4) * 128;
;         const unsigned tb = (unsigned)((wr * 64 + fq * 4) * 1024 + wc * 16 + fr);
; #pragma unroll
;         for (int ai = 0; ai < 2; ++ai)
; #pragma unroll
;           for (int m = 0; m < 4; ++m) {
;             const f32x4 r4 = *(const f32x4*)(rsw + ai * 128 + m * 16);
; #pragma unroll
;             for (int j = 0; j < 4; ++j)
; #pragma unroll
;               for (int bj = 0; bj < 2; ++bj)
;                 ot[tb + (ai * 128 + m * 16 + j) * 1024 + bj * 64] =
;                     f2bf((r4[j] * acc[ai][bj][m][0][j] + swv[bj][0]) * (r4[j] * acc[ai][bj][m][1][j] + swv[bj][1]));
;             SCHED;
;           }
	v_fma_f32 v144, v26, v138, v137
	v_fma_f32 v145, v18, v138, v136
	v_mul_f32_e32 v144, v144, v145
	s_nop 0
	v_cvt_pk_bf16_f32 v144, v144, v144
	global_store_short_d16_hi v[142:143], v144, off
	v_fma_f32 v142, v30, v138, v135
	v_fma_f32 v138, v22, v138, v134
	v_mul_f32_e32 v138, v142, v138
	v_cvt_pk_bf16_f32 v138, v138, v138
	v_add_u32_e32 v142, 0x28040, v0
	v_mov_b32_e32 v143, v1
	v_lshl_add_u64 v[142:143], v[142:143], 1, s[6:7]
	global_store_short_d16_hi v[142:143], v138, off
	v_fma_f32 v138, v27, v139, v137
	v_fma_f32 v143, v19, v139, v136
	v_mul_f32_e32 v138, v138, v143
	s_nop 0
	v_add_u32_e32 v142, 0x28400, v0
	v_cvt_pk_bf16_f32 v138, v138, v138
	v_mov_b32_e32 v143, v1
	v_lshl_add_u64 v[142:143], v[142:143], 1, s[6:7]
	global_store_short_d16_hi v[142:143], v138, off
	v_fma_f32 v138, v31, v139, v135
	v_fma_f32 v139, v23, v139, v134
	v_mul_f32_e32 v138, v138, v139
	s_nop 0
	v_cvt_pk_bf16_f32 v142, v138, v138
	v_add_u32_e32 v138, 0x28440, v0
	v_mov_b32_e32 v139, v1
	v_lshl_add_u64 v[138:139], v[138:139], 1, s[6:7]
	global_store_short_d16_hi v[138:139], v142, off
	v_fma_f32 v139, v28, v140, v137
	v_fma_f32 v142, v20, v140, v136
	v_mul_f32_e32 v139, v139, v142
	s_nop 0
	v_add_u32_e32 v138, 0x28800, v0
	v_cvt_pk_bf16_f32 v142, v139, v139
	v_mov_b32_e32 v139, v1
	v_lshl_add_u64 v[138:139], v[138:139], 1, s[6:7]
	global_store_short_d16_hi v[138:139], v142, off
	v_fma_f32 v138, v32, v140, v135
	v_fma_f32 v139, v24, v140, v134
	v_mul_f32_e32 v138, v138, v139
	s_nop 0
	v_cvt_pk_bf16_f32 v140, v138, v138
	v_add_u32_e32 v138, 0x28840, v0
	v_mov_b32_e32 v139, v1
	v_lshl_add_u64 v[138:139], v[138:139], 1, s[6:7]
	global_store_short_d16_hi v[138:139], v140, off
	v_fma_f32 v139, v29, v141, v137
	v_fma_f32 v140, v21, v141, v136
	v_mul_f32_e32 v139, v139, v140
	s_nop 0
	v_add_u32_e32 v138, 0x28c00, v0
	v_cvt_pk_bf16_f32 v140, v139, v139
	v_mov_b32_e32 v139, v1
	v_lshl_add_u64 v[138:139], v[138:139], 1, s[6:7]
	global_store_short_d16_hi v[138:139], v140, off
	v_fma_f32 v138, v33, v141, v135
	v_fma_f32 v139, v25, v141, v134
	v_mul_f32_e32 v138, v138, v139
	s_nop 0
	v_cvt_pk_bf16_f32 v140, v138, v138
	v_add_u32_e32 v138, 0x28c40, v0
	v_mov_b32_e32 v139, v1
	v_lshl_add_u64 v[138:139], v[138:139], 1, s[6:7]
	global_store_short_d16_hi v[138:139], v140, off
	ds_read_b128 v[138:141], v130 offset:704
	v_add_u32_e32 v142, 0x2c000, v0
	v_mov_b32_e32 v143, v1
	v_lshl_add_u64 v[142:143], v[142:143], 1, s[6:7]
	s_waitcnt lgkmcnt(0)
	v_fma_f32 v144, v10, v138, v137
	v_fma_f32 v145, v2, v138, v136
	v_mul_f32_e32 v144, v144, v145
	v_bfe_u32 v145, v144, 16, 1
	v_add3_u32 v144, v144, v145, s81
	global_store_short_d16_hi v[142:143], v144, off
	v_fma_f32 v142, v14, v138, v135
	v_fma_f32 v138, v6, v138, v134
	v_mul_f32_e32 v138, v142, v138
	v_cvt_pk_bf16_f32 v138, v138, v138
	v_add_u32_e32 v142, 0x2c040, v0
	v_mov_b32_e32 v143, v1
	v_lshl_add_u64 v[142:143], v[142:143], 1, s[6:7]
	global_store_short_d16_hi v[142:143], v138, off
	v_fma_f32 v138, v11, v139, v137
	v_fma_f32 v143, v3, v139, v136
	v_mul_f32_e32 v138, v138, v143
	s_nop 0
	v_add_u32_e32 v142, 0x2c400, v0
	v_cvt_pk_bf16_f32 v138, v138, v138
	v_mov_b32_e32 v143, v1
	v_lshl_add_u64 v[142:143], v[142:143], 1, s[6:7]
	global_store_short_d16_hi v[142:143], v138, off
	v_fma_f32 v138, v15, v139, v135
	v_fma_f32 v139, v7, v139, v134
	v_mul_f32_e32 v138, v138, v139
	s_nop 0
	v_cvt_pk_bf16_f32 v142, v138, v138
	v_add_u32_e32 v138, 0x2c440, v0
	v_mov_b32_e32 v139, v1
	v_lshl_add_u64 v[138:139], v[138:139], 1, s[6:7]
	global_store_short_d16_hi v[138:139], v142, off
	v_fma_f32 v139, v12, v140, v137
	v_fma_f32 v142, v4, v140, v136
	v_mul_f32_e32 v139, v139, v142
	v_bfe_u32 v142, v139, 16, 1
	v_add_u32_e32 v138, 0x2c800, v0
	v_add3_u32 v142, v139, v142, s81
	v_mov_b32_e32 v139, v1
	v_lshl_add_u64 v[138:139], v[138:139], 1, s[6:7]
	global_store_short_d16_hi v[138:139], v142, off
	v_fma_f32 v138, v16, v140, v135
	v_fma_f32 v139, v8, v140, v134
	v_mul_f32_e32 v138, v138, v139
	s_nop 0
	v_cvt_pk_bf16_f32 v140, v138, v138
	v_add_u32_e32 v138, 0x2c840, v0
	v_mov_b32_e32 v139, v1
	v_lshl_add_u64 v[138:139], v[138:139], 1, s[6:7]
	global_store_short_d16_hi v[138:139], v140, off
	v_fma_f32 v139, v13, v141, v137
	v_fma_f32 v140, v5, v141, v136
	v_mul_f32_e32 v139, v139, v140
	s_nop 0
	v_add_u32_e32 v138, 0x2cc00, v0
	v_cvt_pk_bf16_f32 v140, v139, v139
	v_mov_b32_e32 v139, v1
	v_lshl_add_u64 v[138:139], v[138:139], 1, s[6:7]
	global_store_short_d16_hi v[138:139], v140, off
	v_fma_f32 v138, v17, v141, v135
	v_fma_f32 v139, v9, v141, v134
	v_mul_f32_e32 v138, v138, v139
	v_bfe_u32 v139, v138, 16, 1
	v_add_u32_e32 v0, 0x2cc40, v0
	v_add3_u32 v140, v138, v139, s81
	v_lshl_add_u64 v[138:139], v[0:1], 1, s[6:7]
	global_store_short_d16_hi v[138:139], v140, off
	s_cbranch_execnz .LBB0_312
; #define SCHED __builtin_amdgcn_sched_barrier(0)
; template <int EPI, bool HS = false>
; __device__ __forceinline__ void gemm_phase(const Params& p, const GemmCfg& g, char* shm, const int wave_s) {
;     ...
;       if (pn < 4) {
;         u16* ot = g.o16 + (size_t)orow0 * 1024 + pn * 256;
;         const unsigned tb = (unsigned)((wr * 64 + fq * 4) * 1024 + wc * 32 + fr);
; #pragma unroll
;         for (int ai = 0; ai < 2; ++ai)
; #pragma unroll
;           for (int m = 0; m < 4; ++m) {
;             const f32x4 r4 = *(const f32x4*)(rsw + ai * 128 + m * 16);
; #pragma unroll
;             for (int j = 0; j < 4; ++j)
; #pragma unroll
;               for (int bj = 0; bj < 2; ++bj)
; #pragma unroll
;                 for (int n = 0; n < 2; ++n)
;                   ot[tb + (ai * 128 + m * 16 + j) * 1024 + bj * 128 + n * 16] = f2bf(r4[j] * acc[ai][bj][m][n][j] + swv[bj][n]);
;             SCHED;
;           }
.LBB0_326:
	ds_read_b128 v[138:141], v130
	s_ashr_i32 s3, s2, 31
	s_lshl_b64 s[2:3], s[2:3], 1
	s_add_u32 s2, s8, s2
	v_lshlrev_b32_e32 v0, 5, v131
	s_waitcnt lgkmcnt(0)
	v_fma_f32 v118, v118, v138, v137
	s_addc_u32 s3, s9, s3
	v_or3_b32 v0, v133, v0, v132
	v_bfe_u32 v131, v118, 16, 1
	v_add3_u32 v118, v118, v131, s81
	v_lshl_add_u64 v[132:133], v[0:1], 1, s[2:3]
	v_fma_f32 v114, v114, v138, v136
	global_store_short_d16_hi v[132:133], v118, off
	s_nop 0
	v_cvt_pk_bf16_f32 v114, v114, v114
	global_store_short_d16_hi v[132:133], v114, off offset:32
	v_fma_f32 v114, v126, v138, v135
	v_cvt_pk_bf16_f32 v114, v114, v114
	global_store_short_d16_hi v[132:133], v114, off offset:256
	v_fma_f32 v114, v122, v138, v134
	v_cvt_pk_bf16_f32 v114, v114, v114
	global_store_short_d16_hi v[132:133], v114, off offset:288
	v_fma_f32 v114, v119, v139, v137
	v_cvt_pk_bf16_f32 v114, v114, v114
	global_store_short_d16_hi v[132:133], v114, off offset:2048
	v_fma_f32 v114, v115, v139, v136
	v_cvt_pk_bf16_f32 v114, v114, v114
	global_store_short_d16_hi v[132:133], v114, off offset:2080
	v_fma_f32 v114, v127, v139, v135
	v_cvt_pk_bf16_f32 v114, v114, v114
	global_store_short_d16_hi v[132:133], v114, off offset:2304
	v_fma_f32 v114, v123, v139, v134
	v_cvt_pk_bf16_f32 v114, v114, v114
	v_fma_f32 v115, v120, v140, v137
	global_store_short_d16_hi v[132:133], v114, off offset:2336
	v_or_b32_e32 v114, 0x800, v0
	v_cvt_pk_bf16_f32 v118, v115, v115
	v_mov_b32_e32 v115, v1
	v_lshl_add_u64 v[114:115], v[114:115], 1, s[2:3]
	global_store_short_d16_hi v[114:115], v118, off
	v_fma_f32 v114, v116, v140, v136
	s_nop 0
	v_cvt_pk_bf16_f32 v116, v114, v114
	v_or_b32_e32 v114, 0x810, v0
	v_mov_b32_e32 v115, v1
	v_lshl_add_u64 v[114:115], v[114:115], 1, s[2:3]
	global_store_short_d16_hi v[114:115], v116, off
	v_fma_f32 v115, v128, v140, v135
	s_nop 0
	v_or_b32_e32 v114, 0x880, v0
	v_cvt_pk_bf16_f32 v116, v115, v115
	v_mov_b32_e32 v115, v1
	v_lshl_add_u64 v[114:115], v[114:115], 1, s[2:3]
	global_store_short_d16_hi v[114:115], v116, off
	v_fma_f32 v114, v124, v140, v134
	s_nop 0
	v_cvt_pk_bf16_f32 v116, v114, v114
	v_or_b32_e32 v114, 0x890, v0
	v_mov_b32_e32 v115, v1
	v_lshl_add_u64 v[114:115], v[114:115], 1, s[2:3]
	global_store_short_d16_hi v[114:115], v116, off
	v_fma_f32 v115, v121, v141, v137
	s_nop 0
	v_or_b32_e32 v114, 0xc00, v0
	v_cvt_pk_bf16_f32 v116, v115, v115
	v_mov_b32_e32 v115, v1
	v_lshl_add_u64 v[114:115], v[114:115], 1, s[2:3]
	global_store_short_d16_hi v[114:115], v116, off
	v_fma_f32 v114, v117, v141, v136
	s_nop 0
	v_cvt_pk_bf16_f32 v116, v114, v114
	v_or_b32_e32 v114, 0xc10, v0
	v_mov_b32_e32 v115, v1
	v_lshl_add_u64 v[114:115], v[114:115], 1, s[2:3]
	global_store_short_d16_hi v[114:115], v116, off
	v_fma_f32 v115, v129, v141, v135
	s_nop 0
	v_or_b32_e32 v114, 0xc80, v0
	v_cvt_pk_bf16_f32 v116, v115, v115
	v_mov_b32_e32 v115, v1
	v_lshl_add_u64 v[114:115], v[114:115], 1, s[2:3]
	global_store_short_d16_hi v[114:115], v116, off
	v_fma_f32 v114, v125, v141, v134
	s_nop 0
	v_cvt_pk_bf16_f32 v116, v114, v114
	v_or_b32_e32 v114, 0xc90, v0
	v_mov_b32_e32 v115, v1
	v_lshl_add_u64 v[114:115], v[114:115], 1, s[2:3]
	global_store_short_d16_hi v[114:115], v116, off
	ds_read_b128 v[114:117], v130 offset:64
	v_or_b32_e32 v118, 0x4000, v0
	v_mov_b32_e32 v119, v1
	v_lshl_add_u64 v[118:119], v[118:119], 1, s[2:3]
	s_waitcnt lgkmcnt(0)
	v_fma_f32 v102, v102, v114, v137
	v_bfe_u32 v120, v102, 16, 1
	v_fma_f32 v98, v98, v114, v136
	v_add3_u32 v102, v102, v120, s81
	global_store_short_d16_hi v[118:119], v102, off
	v_or_b32_e32 v118, 0x4010, v0
	v_mov_b32_e32 v119, v1
	v_cvt_pk_bf16_f32 v98, v98, v98
	v_lshl_add_u64 v[118:119], v[118:119], 1, s[2:3]
	global_store_short_d16_hi v[118:119], v98, off
	v_fma_f32 v98, v110, v114, v135
	v_or_b32_e32 v118, 0x4080, v0
	s_nop 0
	v_mov_b32_e32 v119, v1
	v_cvt_pk_bf16_f32 v98, v98, v98
	v_lshl_add_u64 v[118:119], v[118:119], 1, s[2:3]
	global_store_short_d16_hi v[118:119], v98, off
	v_fma_f32 v98, v106, v114, v134
	s_nop 0
	v_or_b32_e32 v118, 0x4090, v0
	v_mov_b32_e32 v119, v1
	v_cvt_pk_bf16_f32 v98, v98, v98
	v_lshl_add_u64 v[118:119], v[118:119], 1, s[2:3]
	global_store_short_d16_hi v[118:119], v98, off
	v_fma_f32 v98, v103, v115, v137
	s_nop 0
	v_or_b32_e32 v102, 0x4400, v0
	v_cvt_pk_bf16_f32 v98, v98, v98
	v_mov_b32_e32 v103, v1
	v_lshl_add_u64 v[102:103], v[102:103], 1, s[2:3]
	global_store_short_d16_hi v[102:103], v98, off
	v_fma_f32 v98, v99, v115, v136
	s_nop 0
	v_cvt_pk_bf16_f32 v102, v98, v98
	v_or_b32_e32 v98, 0x4410, v0
	v_mov_b32_e32 v99, v1
	v_lshl_add_u64 v[98:99], v[98:99], 1, s[2:3]
	global_store_short_d16_hi v[98:99], v102, off
	v_fma_f32 v99, v111, v115, v135
	s_nop 0
	v_or_b32_e32 v98, 0x4480, v0
	v_cvt_pk_bf16_f32 v102, v99, v99
	v_mov_b32_e32 v99, v1
	v_lshl_add_u64 v[98:99], v[98:99], 1, s[2:3]
	global_store_short_d16_hi v[98:99], v102, off
	v_fma_f32 v98, v107, v115, v134
	s_nop 0
	v_cvt_pk_bf16_f32 v102, v98, v98
	v_or_b32_e32 v98, 0x4490, v0
	v_mov_b32_e32 v99, v1
	v_lshl_add_u64 v[98:99], v[98:99], 1, s[2:3]
	global_store_short_d16_hi v[98:99], v102, off
	v_fma_f32 v99, v104, v116, v137
	s_nop 0
	v_or_b32_e32 v98, 0x4800, v0
	v_cvt_pk_bf16_f32 v102, v99, v99
	v_mov_b32_e32 v99, v1
	v_lshl_add_u64 v[98:99], v[98:99], 1, s[2:3]
	global_store_short_d16_hi v[98:99], v102, off
	v_fma_f32 v98, v100, v116, v136
	s_nop 0
	v_cvt_pk_bf16_f32 v100, v98, v98
	v_or_b32_e32 v98, 0x4810, v0
	v_mov_b32_e32 v99, v1
	v_lshl_add_u64 v[98:99], v[98:99], 1, s[2:3]
	global_store_short_d16_hi v[98:99], v100, off
	v_fma_f32 v99, v112, v116, v135
	s_nop 0
	v_or_b32_e32 v98, 0x4880, v0
	v_cvt_pk_bf16_f32 v100, v99, v99
	v_mov_b32_e32 v99, v1
	v_lshl_add_u64 v[98:99], v[98:99], 1, s[2:3]
	global_store_short_d16_hi v[98:99], v100, off
	v_fma_f32 v98, v108, v116, v134
	s_nop 0
	v_cvt_pk_bf16_f32 v100, v98, v98
	v_or_b32_e32 v98, 0x4890, v0
	v_mov_b32_e32 v99, v1
	v_lshl_add_u64 v[98:99], v[98:99], 1, s[2:3]
	global_store_short_d16_hi v[98:99], v100, off
	v_fma_f32 v99, v105, v117, v137
	s_nop 0
	v_or_b32_e32 v98, 0x4c00, v0
	v_cvt_pk_bf16_f32 v100, v99, v99
	v_mov_b32_e32 v99, v1
	v_lshl_add_u64 v[98:99], v[98:99], 1, s[2:3]
	global_store_short_d16_hi v[98:99], v100, off
	v_fma_f32 v98, v101, v117, v136
	s_nop 0
	v_cvt_pk_bf16_f32 v100, v98, v98
	v_or_b32_e32 v98, 0x4c10, v0
	v_mov_b32_e32 v99, v1
	v_lshl_add_u64 v[98:99], v[98:99], 1, s[2:3]
	global_store_short_d16_hi v[98:99], v100, off
	v_fma_f32 v99, v113, v117, v135
	s_nop 0
	v_or_b32_e32 v98, 0x4c80, v0
	v_cvt_pk_bf16_f32 v100, v99, v99
	v_mov_b32_e32 v99, v1
	v_lshl_add_u64 v[98:99], v[98:99], 1, s[2:3]
	global_store_short_d16_hi v[98:99], v100, off
	v_fma_f32 v98, v109, v117, v134
	s_nop 0
	v_cvt_pk_bf16_f32 v100, v98, v98
	v_or_b32_e32 v98, 0x4c90, v0
	v_mov_b32_e32 v99, v1
	v_lshl_add_u64 v[98:99], v[98:99], 1, s[2:3]
	global_store_short_d16_hi v[98:99], v100, off
	ds_read_b128 v[98:101], v130 offset:128
	v_or_b32_e32 v102, 0x8000, v0
	v_mov_b32_e32 v103, v1
	v_lshl_add_u64 v[102:103], v[102:103], 1, s[2:3]
	s_waitcnt lgkmcnt(0)
; #define SCHED __builtin_amdgcn_sched_barrier(0)
; template <int EPI, bool HS = false>
; __device__ __forceinline__ void gemm_phase(const Params& p, const GemmCfg& g, char* shm, const int wave_s) {
;     ...
;       if (pn < 4) {
;         u16* ot = g.o16 + (size_t)orow0 * 1024 + pn * 256;
;         const unsigned tb = (unsigned)((wr * 64 + fq * 4) * 1024 + wc * 32 + fr);
; #pragma unroll
;         for (int ai = 0; ai < 2; ++ai)
; #pragma unroll
;           for (int m = 0; m < 4; ++m) {
;             const f32x4 r4 = *(const f32x4*)(rsw + ai * 128 + m * 16);
; #pragma unroll
;             for (int j = 0; j < 4; ++j)
; #pragma unroll
;               for (int bj = 0; bj < 2; ++bj)
; #pragma unroll
;                 for (int n = 0; n < 2; ++n)
;                   ot[tb + (ai * 128 + m * 16 + j) * 1024 + bj * 128 + n * 16] = f2bf(r4[j] * acc[ai][bj][m][n][j] + swv[bj][n]);
;             SCHED;
;           }
	v_fma_f32 v86, v86, v98, v137
	v_bfe_u32 v104, v86, 16, 1
	v_fma_f32 v82, v82, v98, v136
	v_add3_u32 v86, v86, v104, s81
	global_store_short_d16_hi v[102:103], v86, off
	v_or_b32_e32 v102, 0x8010, v0
	v_mov_b32_e32 v103, v1
	v_cvt_pk_bf16_f32 v82, v82, v82
	v_lshl_add_u64 v[102:103], v[102:103], 1, s[2:3]
	global_store_short_d16_hi v[102:103], v82, off
	v_fma_f32 v82, v94, v98, v135
	v_or_b32_e32 v102, 0x8080, v0
	s_nop 0
	v_mov_b32_e32 v103, v1
	v_cvt_pk_bf16_f32 v82, v82, v82
	v_lshl_add_u64 v[102:103], v[102:103], 1, s[2:3]
	global_store_short_d16_hi v[102:103], v82, off
	v_fma_f32 v82, v90, v98, v134
	s_nop 0
	v_or_b32_e32 v102, 0x8090, v0
	v_mov_b32_e32 v103, v1
	v_cvt_pk_bf16_f32 v82, v82, v82
	v_lshl_add_u64 v[102:103], v[102:103], 1, s[2:3]
	global_store_short_d16_hi v[102:103], v82, off
	v_fma_f32 v82, v87, v99, v137
	s_nop 0
	v_or_b32_e32 v86, 0x8400, v0
	v_cvt_pk_bf16_f32 v82, v82, v82
	v_mov_b32_e32 v87, v1
	v_lshl_add_u64 v[86:87], v[86:87], 1, s[2:3]
	global_store_short_d16_hi v[86:87], v82, off
	v_fma_f32 v82, v83, v99, v136
	s_nop 0
	v_cvt_pk_bf16_f32 v86, v82, v82
	v_or_b32_e32 v82, 0x8410, v0
	v_mov_b32_e32 v83, v1
	v_lshl_add_u64 v[82:83], v[82:83], 1, s[2:3]
	global_store_short_d16_hi v[82:83], v86, off
	v_fma_f32 v83, v95, v99, v135
	s_nop 0
	v_or_b32_e32 v82, 0x8480, v0
	v_cvt_pk_bf16_f32 v86, v83, v83
	v_mov_b32_e32 v83, v1
	v_lshl_add_u64 v[82:83], v[82:83], 1, s[2:3]
	global_store_short_d16_hi v[82:83], v86, off
	v_fma_f32 v82, v91, v99, v134
	s_nop 0
	v_cvt_pk_bf16_f32 v86, v82, v82
	v_or_b32_e32 v82, 0x8490, v0
	v_mov_b32_e32 v83, v1
	v_lshl_add_u64 v[82:83], v[82:83], 1, s[2:3]
	global_store_short_d16_hi v[82:83], v86, off
	v_fma_f32 v83, v88, v100, v137
	s_nop 0
	v_or_b32_e32 v82, 0x8800, v0
	v_cvt_pk_bf16_f32 v86, v83, v83
	v_mov_b32_e32 v83, v1
	v_lshl_add_u64 v[82:83], v[82:83], 1, s[2:3]
	global_store_short_d16_hi v[82:83], v86, off
	v_fma_f32 v82, v84, v100, v136
	s_nop 0
	v_cvt_pk_bf16_f32 v84, v82, v82
	v_or_b32_e32 v82, 0x8810, v0
	v_mov_b32_e32 v83, v1
	v_lshl_add_u64 v[82:83], v[82:83], 1, s[2:3]
	global_store_short_d16_hi v[82:83], v84, off
	v_fma_f32 v83, v96, v100, v135
	s_nop 0
	v_or_b32_e32 v82, 0x8880, v0
	v_cvt_pk_bf16_f32 v84, v83, v83
	v_mov_b32_e32 v83, v1
	v_lshl_add_u64 v[82:83], v[82:83], 1, s[2:3]
	global_store_short_d16_hi v[82:83], v84, off
	v_fma_f32 v82, v92, v100, v134
	s_nop 0
	v_cvt_pk_bf16_f32 v84, v82, v82
	v_or_b32_e32 v82, 0x8890, v0
	v_mov_b32_e32 v83, v1
	v_lshl_add_u64 v[82:83], v[82:83], 1, s[2:3]
	global_store_short_d16_hi v[82:83], v84, off
	v_fma_f32 v83, v89, v101, v137
	s_nop 0
	v_or_b32_e32 v82, 0x8c00, v0
	v_cvt_pk_bf16_f32 v84, v83, v83
	v_mov_b32_e32 v83, v1
	v_lshl_add_u64 v[82:83], v[82:83], 1, s[2:3]
	global_store_short_d16_hi v[82:83], v84, off
	v_fma_f32 v82, v85, v101, v136
	s_nop 0
	v_cvt_pk_bf16_f32 v84, v82, v82
	v_or_b32_e32 v82, 0x8c10, v0
	v_mov_b32_e32 v83, v1
	v_lshl_add_u64 v[82:83], v[82:83], 1, s[2:3]
	global_store_short_d16_hi v[82:83], v84, off
	v_fma_f32 v83, v97, v101, v135
	s_nop 0
	v_or_b32_e32 v82, 0x8c80, v0
	v_cvt_pk_bf16_f32 v84, v83, v83
	v_mov_b32_e32 v83, v1
	v_lshl_add_u64 v[82:83], v[82:83], 1, s[2:3]
	global_store_short_d16_hi v[82:83], v84, off
	v_fma_f32 v82, v93, v101, v134
	s_nop 0
	v_cvt_pk_bf16_f32 v84, v82, v82
	v_or_b32_e32 v82, 0x8c90, v0
	v_mov_b32_e32 v83, v1
	v_lshl_add_u64 v[82:83], v[82:83], 1, s[2:3]
	global_store_short_d16_hi v[82:83], v84, off
	ds_read_b128 v[82:85], v130 offset:192
	v_or_b32_e32 v86, 0xc000, v0
	v_mov_b32_e32 v87, v1
	v_lshl_add_u64 v[86:87], v[86:87], 1, s[2:3]
	s_waitcnt lgkmcnt(0)
	v_fma_f32 v70, v70, v82, v137
	v_bfe_u32 v88, v70, 16, 1
	v_fma_f32 v66, v66, v82, v136
	v_add3_u32 v70, v70, v88, s81
	global_store_short_d16_hi v[86:87], v70, off
	v_or_b32_e32 v86, 0xc010, v0
	v_mov_b32_e32 v87, v1
	v_cvt_pk_bf16_f32 v66, v66, v66
	v_lshl_add_u64 v[86:87], v[86:87], 1, s[2:3]
	global_store_short_d16_hi v[86:87], v66, off
	v_fma_f32 v66, v78, v82, v135
	v_or_b32_e32 v86, 0xc080, v0
	s_nop 0
	v_mov_b32_e32 v87, v1
	v_cvt_pk_bf16_f32 v66, v66, v66
	v_lshl_add_u64 v[86:87], v[86:87], 1, s[2:3]
	global_store_short_d16_hi v[86:87], v66, off
	v_fma_f32 v66, v74, v82, v134
	s_nop 0
	v_or_b32_e32 v86, 0xc090, v0
	v_mov_b32_e32 v87, v1
	v_cvt_pk_bf16_f32 v66, v66, v66
	v_lshl_add_u64 v[86:87], v[86:87], 1, s[2:3]
	global_store_short_d16_hi v[86:87], v66, off
	v_fma_f32 v66, v71, v83, v137
	s_nop 0
	v_or_b32_e32 v70, 0xc400, v0
	v_cvt_pk_bf16_f32 v66, v66, v66
	v_mov_b32_e32 v71, v1
	v_lshl_add_u64 v[70:71], v[70:71], 1, s[2:3]
	global_store_short_d16_hi v[70:71], v66, off
	v_fma_f32 v66, v67, v83, v136
	s_nop 0
	v_cvt_pk_bf16_f32 v70, v66, v66
	v_or_b32_e32 v66, 0xc410, v0
	v_mov_b32_e32 v67, v1
	v_lshl_add_u64 v[66:67], v[66:67], 1, s[2:3]
	global_store_short_d16_hi v[66:67], v70, off
	v_fma_f32 v67, v79, v83, v135
	s_nop 0
	v_or_b32_e32 v66, 0xc480, v0
	v_cvt_pk_bf16_f32 v70, v67, v67
	v_mov_b32_e32 v67, v1
	v_lshl_add_u64 v[66:67], v[66:67], 1, s[2:3]
	global_store_short_d16_hi v[66:67], v70, off
	v_fma_f32 v66, v75, v83, v134
	s_nop 0
	v_cvt_pk_bf16_f32 v70, v66, v66
	v_or_b32_e32 v66, 0xc490, v0
	v_mov_b32_e32 v67, v1
	v_lshl_add_u64 v[66:67], v[66:67], 1, s[2:3]
	global_store_short_d16_hi v[66:67], v70, off
	v_fma_f32 v67, v72, v84, v137
	s_nop 0
	v_or_b32_e32 v66, 0xc800, v0
	v_cvt_pk_bf16_f32 v70, v67, v67
	v_mov_b32_e32 v67, v1
	v_lshl_add_u64 v[66:67], v[66:67], 1, s[2:3]
	global_store_short_d16_hi v[66:67], v70, off
	v_fma_f32 v66, v68, v84, v136
	s_nop 0
	v_cvt_pk_bf16_f32 v68, v66, v66
	v_or_b32_e32 v66, 0xc810, v0
	v_mov_b32_e32 v67, v1
	v_lshl_add_u64 v[66:67], v[66:67], 1, s[2:3]
; #define SCHED __builtin_amdgcn_sched_barrier(0)
; template <int EPI, bool HS = false>
; __device__ __forceinline__ void gemm_phase(const Params& p, const GemmCfg& g, char* shm, const int wave_s) {
;     ...
;       if (pn < 4) {
;         u16* ot = g.o16 + (size_t)orow0 * 1024 + pn * 256;
;         const unsigned tb = (unsigned)((wr * 64 + fq * 4) * 1024 + wc * 32 + fr);
; #pragma unroll
;         for (int ai = 0; ai < 2; ++ai)
; #pragma unroll
;           for (int m = 0; m < 4; ++m) {
;             const f32x4 r4 = *(const f32x4*)(rsw + ai * 128 + m * 16);
; #pragma unroll
;             for (int j = 0; j < 4; ++j)
; #pragma unroll
;               for (int bj = 0; bj < 2; ++bj)
; #pragma unroll
;                 for (int n = 0; n < 2; ++n)
;                   ot[tb + (ai * 128 + m * 16 + j) * 1024 + bj * 128 + n * 16] = f2bf(r4[j] * acc[ai][bj][m][n][j] + swv[bj][n]);
;             SCHED;
;           }
	global_store_short_d16_hi v[66:67], v68, off
	v_fma_f32 v67, v80, v84, v135
	s_nop 0
	v_or_b32_e32 v66, 0xc880, v0
	v_cvt_pk_bf16_f32 v68, v67, v67
	v_mov_b32_e32 v67, v1
	v_lshl_add_u64 v[66:67], v[66:67], 1, s[2:3]
	global_store_short_d16_hi v[66:67], v68, off
	v_fma_f32 v66, v76, v84, v134
	s_nop 0
	v_cvt_pk_bf16_f32 v68, v66, v66
	v_or_b32_e32 v66, 0xc890, v0
	v_mov_b32_e32 v67, v1
	v_lshl_add_u64 v[66:67], v[66:67], 1, s[2:3]
	global_store_short_d16_hi v[66:67], v68, off
	v_fma_f32 v67, v73, v85, v137
	s_nop 0
	v_or_b32_e32 v66, 0xcc00, v0
	v_cvt_pk_bf16_f32 v68, v67, v67
	v_mov_b32_e32 v67, v1
	v_lshl_add_u64 v[66:67], v[66:67], 1, s[2:3]
	global_store_short_d16_hi v[66:67], v68, off
	v_fma_f32 v66, v69, v85, v136
	s_nop 0
	v_cvt_pk_bf16_f32 v68, v66, v66
	v_or_b32_e32 v66, 0xcc10, v0
	v_mov_b32_e32 v67, v1
	v_lshl_add_u64 v[66:67], v[66:67], 1, s[2:3]
	global_store_short_d16_hi v[66:67], v68, off
	v_fma_f32 v67, v81, v85, v135
	s_nop 0
	v_or_b32_e32 v66, 0xcc80, v0
	v_cvt_pk_bf16_f32 v68, v67, v67
	v_mov_b32_e32 v67, v1
	v_lshl_add_u64 v[66:67], v[66:67], 1, s[2:3]
	global_store_short_d16_hi v[66:67], v68, off
	v_fma_f32 v66, v77, v85, v134
	s_nop 0
	v_cvt_pk_bf16_f32 v68, v66, v66
	v_or_b32_e32 v66, 0xcc90, v0
	v_mov_b32_e32 v67, v1
	v_lshl_add_u64 v[66:67], v[66:67], 1, s[2:3]
	global_store_short_d16_hi v[66:67], v68, off
	ds_read_b128 v[66:69], v130 offset:512
	v_add_u32_e32 v70, 0x20000, v0
	v_mov_b32_e32 v71, v1
	v_lshl_add_u64 v[70:71], v[70:71], 1, s[2:3]
	s_waitcnt lgkmcnt(0)
	v_fma_f32 v58, v58, v66, v137
	v_bfe_u32 v72, v58, 16, 1
	v_fma_f32 v50, v50, v66, v136
	v_add3_u32 v58, v58, v72, s81
	global_store_short_d16_hi v[70:71], v58, off
	v_add_u32_e32 v70, 0x20010, v0
	v_mov_b32_e32 v71, v1
	v_cvt_pk_bf16_f32 v50, v50, v50
	v_lshl_add_u64 v[70:71], v[70:71], 1, s[2:3]
	global_store_short_d16_hi v[70:71], v50, off
	v_fma_f32 v50, v62, v66, v135
	v_add_u32_e32 v70, 0x20080, v0
	s_nop 0
	v_mov_b32_e32 v71, v1
	v_cvt_pk_bf16_f32 v50, v50, v50
	v_lshl_add_u64 v[70:71], v[70:71], 1, s[2:3]
	global_store_short_d16_hi v[70:71], v50, off
	v_fma_f32 v50, v54, v66, v134
	s_nop 0
	v_add_u32_e32 v70, 0x20090, v0
	v_mov_b32_e32 v71, v1
	v_cvt_pk_bf16_f32 v50, v50, v50
	v_lshl_add_u64 v[70:71], v[70:71], 1, s[2:3]
	global_store_short_d16_hi v[70:71], v50, off
	v_fma_f32 v50, v59, v67, v137
	v_add_u32_e32 v58, 0x20400, v0
	s_nop 0
	v_mov_b32_e32 v59, v1
	v_cvt_pk_bf16_f32 v50, v50, v50
	v_lshl_add_u64 v[58:59], v[58:59], 1, s[2:3]
	global_store_short_d16_hi v[58:59], v50, off
	v_fma_f32 v50, v51, v67, v136
	s_nop 0
	v_cvt_pk_bf16_f32 v54, v50, v50
	v_add_u32_e32 v50, 0x20410, v0
	v_mov_b32_e32 v51, v1
	v_lshl_add_u64 v[50:51], v[50:51], 1, s[2:3]
	global_store_short_d16_hi v[50:51], v54, off
	v_fma_f32 v51, v63, v67, v135
	s_nop 0
	v_add_u32_e32 v50, 0x20480, v0
	v_cvt_pk_bf16_f32 v54, v51, v51
	v_mov_b32_e32 v51, v1
	v_lshl_add_u64 v[50:51], v[50:51], 1, s[2:3]
	global_store_short_d16_hi v[50:51], v54, off
	v_fma_f32 v50, v55, v67, v134
	s_nop 0
	v_cvt_pk_bf16_f32 v54, v50, v50
	v_add_u32_e32 v50, 0x20490, v0
	v_mov_b32_e32 v51, v1
	v_lshl_add_u64 v[50:51], v[50:51], 1, s[2:3]
	global_store_short_d16_hi v[50:51], v54, off
	v_fma_f32 v51, v60, v68, v137
	s_nop 0
	v_add_u32_e32 v50, 0x20800, v0
	v_cvt_pk_bf16_f32 v54, v51, v51
	v_mov_b32_e32 v51, v1
	v_lshl_add_u64 v[50:51], v[50:51], 1, s[2:3]
	global_store_short_d16_hi v[50:51], v54, off
	v_fma_f32 v50, v52, v68, v136
	s_nop 0
	v_cvt_pk_bf16_f32 v52, v50, v50
	v_add_u32_e32 v50, 0x20810, v0
	v_mov_b32_e32 v51, v1
	v_lshl_add_u64 v[50:51], v[50:51], 1, s[2:3]
	global_store_short_d16_hi v[50:51], v52, off
	v_fma_f32 v51, v64, v68, v135
	s_nop 0
	v_add_u32_e32 v50, 0x20880, v0
	v_cvt_pk_bf16_f32 v52, v51, v51
	v_mov_b32_e32 v51, v1
	v_lshl_add_u64 v[50:51], v[50:51], 1, s[2:3]
	global_store_short_d16_hi v[50:51], v52, off
	v_fma_f32 v50, v56, v68, v134
	s_nop 0
	v_cvt_pk_bf16_f32 v52, v50, v50
	v_add_u32_e32 v50, 0x20890, v0
	v_mov_b32_e32 v51, v1
	v_lshl_add_u64 v[50:51], v[50:51], 1, s[2:3]
	global_store_short_d16_hi v[50:51], v52, off
	v_fma_f32 v51, v61, v69, v137
	s_nop 0
	v_add_u32_e32 v50, 0x20c00, v0
	v_cvt_pk_bf16_f32 v52, v51, v51
	v_mov_b32_e32 v51, v1
	v_lshl_add_u64 v[50:51], v[50:51], 1, s[2:3]
	global_store_short_d16_hi v[50:51], v52, off
	v_fma_f32 v50, v53, v69, v136
	s_nop 0
	v_cvt_pk_bf16_f32 v52, v50, v50
	v_add_u32_e32 v50, 0x20c10, v0
	v_mov_b32_e32 v51, v1
	v_lshl_add_u64 v[50:51], v[50:51], 1, s[2:3]
	global_store_short_d16_hi v[50:51], v52, off
	v_fma_f32 v51, v65, v69, v135
	s_nop 0
	v_add_u32_e32 v50, 0x20c80, v0
	v_cvt_pk_bf16_f32 v52, v51, v51
	v_mov_b32_e32 v51, v1
	v_lshl_add_u64 v[50:51], v[50:51], 1, s[2:3]
	global_store_short_d16_hi v[50:51], v52, off
	v_fma_f32 v50, v57, v69, v134
	s_nop 0
	v_cvt_pk_bf16_f32 v52, v50, v50
	v_add_u32_e32 v50, 0x20c90, v0
	v_mov_b32_e32 v51, v1
	v_lshl_add_u64 v[50:51], v[50:51], 1, s[2:3]
	global_store_short_d16_hi v[50:51], v52, off
	ds_read_b128 v[50:53], v130 offset:576
	v_add_u32_e32 v54, 0x24000, v0
	v_mov_b32_e32 v55, v1
	v_lshl_add_u64 v[54:55], v[54:55], 1, s[2:3]
	s_waitcnt lgkmcnt(0)
; #define SCHED __builtin_amdgcn_sched_barrier(0)
; template <int EPI, bool HS = false>
; __device__ __forceinline__ void gemm_phase(const Params& p, const GemmCfg& g, char* shm, const int wave_s) {
;     ...
;       if (pn < 4) {
;         u16* ot = g.o16 + (size_t)orow0 * 1024 + pn * 256;
;         const unsigned tb = (unsigned)((wr * 64 + fq * 4) * 1024 + wc * 32 + fr);
; #pragma unroll
;         for (int ai = 0; ai < 2; ++ai)
; #pragma unroll
;           for (int m = 0; m < 4; ++m) {
;             const f32x4 r4 = *(const f32x4*)(rsw + ai * 128 + m * 16);
; #pragma unroll
;             for (int j = 0; j < 4; ++j)
; #pragma unroll
;               for (int bj = 0; bj < 2; ++bj)
; #pragma unroll
;                 for (int n = 0; n < 2; ++n)
;                   ot[tb + (ai * 128 + m * 16 + j) * 1024 + bj * 128 + n * 16] = f2bf(r4[j] * acc[ai][bj][m][n][j] + swv[bj][n]);
;             SCHED;
;           }
	v_fma_f32 v42, v42, v50, v137
	v_bfe_u32 v56, v42, 16, 1
	v_fma_f32 v34, v34, v50, v136
	v_add3_u32 v42, v42, v56, s81
	global_store_short_d16_hi v[54:55], v42, off
	v_add_u32_e32 v54, 0x24010, v0
	v_mov_b32_e32 v55, v1
	v_cvt_pk_bf16_f32 v34, v34, v34
	v_lshl_add_u64 v[54:55], v[54:55], 1, s[2:3]
	global_store_short_d16_hi v[54:55], v34, off
	v_fma_f32 v34, v46, v50, v135
	v_add_u32_e32 v54, 0x24080, v0
	s_nop 0
	v_mov_b32_e32 v55, v1
	v_cvt_pk_bf16_f32 v34, v34, v34
	v_lshl_add_u64 v[54:55], v[54:55], 1, s[2:3]
	global_store_short_d16_hi v[54:55], v34, off
	v_fma_f32 v34, v38, v50, v134
	s_nop 0
	v_add_u32_e32 v54, 0x24090, v0
	v_mov_b32_e32 v55, v1
	v_cvt_pk_bf16_f32 v34, v34, v34
	v_lshl_add_u64 v[54:55], v[54:55], 1, s[2:3]
	global_store_short_d16_hi v[54:55], v34, off
	v_fma_f32 v34, v43, v51, v137
	v_add_u32_e32 v42, 0x24400, v0
	s_nop 0
	v_mov_b32_e32 v43, v1
	v_cvt_pk_bf16_f32 v34, v34, v34
	v_lshl_add_u64 v[42:43], v[42:43], 1, s[2:3]
	global_store_short_d16_hi v[42:43], v34, off
	v_fma_f32 v34, v35, v51, v136
	s_nop 0
	v_cvt_pk_bf16_f32 v38, v34, v34
	v_add_u32_e32 v34, 0x24410, v0
	v_mov_b32_e32 v35, v1
	v_lshl_add_u64 v[34:35], v[34:35], 1, s[2:3]
	global_store_short_d16_hi v[34:35], v38, off
	v_fma_f32 v35, v47, v51, v135
	s_nop 0
	v_add_u32_e32 v34, 0x24480, v0
	v_cvt_pk_bf16_f32 v38, v35, v35
	v_mov_b32_e32 v35, v1
	v_lshl_add_u64 v[34:35], v[34:35], 1, s[2:3]
	global_store_short_d16_hi v[34:35], v38, off
	v_fma_f32 v34, v39, v51, v134
	s_nop 0
	v_cvt_pk_bf16_f32 v38, v34, v34
	v_add_u32_e32 v34, 0x24490, v0
	v_mov_b32_e32 v35, v1
	v_lshl_add_u64 v[34:35], v[34:35], 1, s[2:3]
	global_store_short_d16_hi v[34:35], v38, off
	v_fma_f32 v35, v44, v52, v137
	s_nop 0
	v_add_u32_e32 v34, 0x24800, v0
	v_cvt_pk_bf16_f32 v38, v35, v35
	v_mov_b32_e32 v35, v1
	v_lshl_add_u64 v[34:35], v[34:35], 1, s[2:3]
	global_store_short_d16_hi v[34:35], v38, off
	v_fma_f32 v34, v36, v52, v136
	s_nop 0
	v_cvt_pk_bf16_f32 v36, v34, v34
	v_add_u32_e32 v34, 0x24810, v0
	v_mov_b32_e32 v35, v1
	v_lshl_add_u64 v[34:35], v[34:35], 1, s[2:3]
	global_store_short_d16_hi v[34:35], v36, off
	v_fma_f32 v35, v48, v52, v135
	s_nop 0
	v_add_u32_e32 v34, 0x24880, v0
	v_cvt_pk_bf16_f32 v36, v35, v35
	v_mov_b32_e32 v35, v1
	v_lshl_add_u64 v[34:35], v[34:35], 1, s[2:3]
	global_store_short_d16_hi v[34:35], v36, off
	v_fma_f32 v34, v40, v52, v134
	s_nop 0
	v_cvt_pk_bf16_f32 v36, v34, v34
	v_add_u32_e32 v34, 0x24890, v0
	v_mov_b32_e32 v35, v1
	v_lshl_add_u64 v[34:35], v[34:35], 1, s[2:3]
	global_store_short_d16_hi v[34:35], v36, off
	v_fma_f32 v35, v45, v53, v137
	s_nop 0
	v_add_u32_e32 v34, 0x24c00, v0
	v_cvt_pk_bf16_f32 v36, v35, v35
	v_mov_b32_e32 v35, v1
	v_lshl_add_u64 v[34:35], v[34:35], 1, s[2:3]
	global_store_short_d16_hi v[34:35], v36, off
	v_fma_f32 v34, v37, v53, v136
	s_nop 0
	v_cvt_pk_bf16_f32 v36, v34, v34
	v_add_u32_e32 v34, 0x24c10, v0
	v_mov_b32_e32 v35, v1
	v_lshl_add_u64 v[34:35], v[34:35], 1, s[2:3]
	global_store_short_d16_hi v[34:35], v36, off
	v_fma_f32 v35, v49, v53, v135
	s_nop 0
	v_add_u32_e32 v34, 0x24c80, v0
	v_cvt_pk_bf16_f32 v36, v35, v35
	v_mov_b32_e32 v35, v1
	v_lshl_add_u64 v[34:35], v[34:35], 1, s[2:3]
	global_store_short_d16_hi v[34:35], v36, off
	v_fma_f32 v34, v41, v53, v134
	s_nop 0
	v_cvt_pk_bf16_f32 v36, v34, v34
	v_add_u32_e32 v34, 0x24c90, v0
	v_mov_b32_e32 v35, v1
	v_lshl_add_u64 v[34:35], v[34:35], 1, s[2:3]
	global_store_short_d16_hi v[34:35], v36, off
	ds_read_b128 v[34:37], v130 offset:640
	v_add_u32_e32 v38, 0x28000, v0
	v_mov_b32_e32 v39, v1
	v_lshl_add_u64 v[38:39], v[38:39], 1, s[2:3]
	s_waitcnt lgkmcnt(0)
; #define SCHED __builtin_amdgcn_sched_barrier(0)
; template <int EPI, bool HS = false>
; __device__ __forceinline__ void gemm_phase(const Params& p, const GemmCfg& g, char* shm, const int wave_s) {
;     ...
;       if (pn < 4) {
;         u16* ot = g.o16 + (size_t)orow0 * 1024 + pn * 256;
;         const unsigned tb = (unsigned)((wr * 64 + fq * 4) * 1024 + wc * 32 + fr);
; #pragma unroll
;         for (int ai = 0; ai < 2; ++ai)
; #pragma unroll
;           for (int m = 0; m < 4; ++m) {
;             const f32x4 r4 = *(const f32x4*)(rsw + ai * 128 + m * 16);
; #pragma unroll
;             for (int j = 0; j < 4; ++j)
; #pragma unroll
;               for (int bj = 0; bj < 2; ++bj)
; #pragma unroll
;                 for (int n = 0; n < 2; ++n)
;                   ot[tb + (ai * 128 + m * 16 + j) * 1024 + bj * 128 + n * 16] = f2bf(r4[j] * acc[ai][bj][m][n][j] + swv[bj][n]);
;             SCHED;
;           }
	v_fma_f32 v26, v26, v34, v137
	v_bfe_u32 v40, v26, 16, 1
	v_fma_f32 v18, v18, v34, v136
	v_add3_u32 v26, v26, v40, s81
	global_store_short_d16_hi v[38:39], v26, off
	v_add_u32_e32 v38, 0x28010, v0
	v_mov_b32_e32 v39, v1
	v_cvt_pk_bf16_f32 v18, v18, v18
	v_lshl_add_u64 v[38:39], v[38:39], 1, s[2:3]
	global_store_short_d16_hi v[38:39], v18, off
	v_fma_f32 v18, v30, v34, v135
	v_add_u32_e32 v38, 0x28080, v0
	s_nop 0
	v_mov_b32_e32 v39, v1
	v_cvt_pk_bf16_f32 v18, v18, v18
	v_lshl_add_u64 v[38:39], v[38:39], 1, s[2:3]
	global_store_short_d16_hi v[38:39], v18, off
	v_fma_f32 v18, v22, v34, v134
	s_nop 0
	v_add_u32_e32 v38, 0x28090, v0
	v_mov_b32_e32 v39, v1
	v_cvt_pk_bf16_f32 v18, v18, v18
	v_lshl_add_u64 v[38:39], v[38:39], 1, s[2:3]
	global_store_short_d16_hi v[38:39], v18, off
	v_fma_f32 v18, v27, v35, v137
	v_add_u32_e32 v26, 0x28400, v0
	s_nop 0
	v_mov_b32_e32 v27, v1
	v_cvt_pk_bf16_f32 v18, v18, v18
	v_lshl_add_u64 v[26:27], v[26:27], 1, s[2:3]
	global_store_short_d16_hi v[26:27], v18, off
	v_fma_f32 v18, v19, v35, v136
	s_nop 0
	v_cvt_pk_bf16_f32 v22, v18, v18
	v_add_u32_e32 v18, 0x28410, v0
	v_mov_b32_e32 v19, v1
	v_lshl_add_u64 v[18:19], v[18:19], 1, s[2:3]
	global_store_short_d16_hi v[18:19], v22, off
	v_fma_f32 v19, v31, v35, v135
	s_nop 0
	v_add_u32_e32 v18, 0x28480, v0
	v_cvt_pk_bf16_f32 v22, v19, v19
	v_mov_b32_e32 v19, v1
	v_lshl_add_u64 v[18:19], v[18:19], 1, s[2:3]
	global_store_short_d16_hi v[18:19], v22, off
	v_fma_f32 v18, v23, v35, v134
	s_nop 0
	v_cvt_pk_bf16_f32 v22, v18, v18
	v_add_u32_e32 v18, 0x28490, v0
	v_mov_b32_e32 v19, v1
	v_lshl_add_u64 v[18:19], v[18:19], 1, s[2:3]
	global_store_short_d16_hi v[18:19], v22, off
	v_fma_f32 v19, v28, v36, v137
	s_nop 0
	v_add_u32_e32 v18, 0x28800, v0
	v_cvt_pk_bf16_f32 v22, v19, v19
	v_mov_b32_e32 v19, v1
	v_lshl_add_u64 v[18:19], v[18:19], 1, s[2:3]
	global_store_short_d16_hi v[18:19], v22, off
	v_fma_f32 v18, v20, v36, v136
	s_nop 0
	v_cvt_pk_bf16_f32 v20, v18, v18
	v_add_u32_e32 v18, 0x28810, v0
	v_mov_b32_e32 v19, v1
	v_lshl_add_u64 v[18:19], v[18:19], 1, s[2:3]
	global_store_short_d16_hi v[18:19], v20, off
	v_fma_f32 v19, v32, v36, v135
	s_nop 0
	v_add_u32_e32 v18, 0x28880, v0
	v_cvt_pk_bf16_f32 v20, v19, v19
	v_mov_b32_e32 v19, v1
	v_lshl_add_u64 v[18:19], v[18:19], 1, s[2:3]
	global_store_short_d16_hi v[18:19], v20, off
	v_fma_f32 v18, v24, v36, v134
	s_nop 0
	v_cvt_pk_bf16_f32 v20, v18, v18
	v_add_u32_e32 v18, 0x28890, v0
	v_mov_b32_e32 v19, v1
	v_lshl_add_u64 v[18:19], v[18:19], 1, s[2:3]
	global_store_short_d16_hi v[18:19], v20, off
	v_fma_f32 v19, v29, v37, v137
	s_nop 0
	v_add_u32_e32 v18, 0x28c00, v0
	v_cvt_pk_bf16_f32 v20, v19, v19
	v_mov_b32_e32 v19, v1
	v_lshl_add_u64 v[18:19], v[18:19], 1, s[2:3]
	global_store_short_d16_hi v[18:19], v20, off
	v_fma_f32 v18, v21, v37, v136
	s_nop 0
	v_cvt_pk_bf16_f32 v20, v18, v18
	v_add_u32_e32 v18, 0x28c10, v0
	v_mov_b32_e32 v19, v1
	v_lshl_add_u64 v[18:19], v[18:19], 1, s[2:3]
	global_store_short_d16_hi v[18:19], v20, off
	v_fma_f32 v19, v33, v37, v135
	s_nop 0
	v_add_u32_e32 v18, 0x28c80, v0
	v_cvt_pk_bf16_f32 v20, v19, v19
	v_mov_b32_e32 v19, v1
	v_lshl_add_u64 v[18:19], v[18:19], 1, s[2:3]
	global_store_short_d16_hi v[18:19], v20, off
	v_fma_f32 v18, v25, v37, v134
	s_nop 0
	v_cvt_pk_bf16_f32 v20, v18, v18
	v_add_u32_e32 v18, 0x28c90, v0
	v_mov_b32_e32 v19, v1
	v_lshl_add_u64 v[18:19], v[18:19], 1, s[2:3]
	global_store_short_d16_hi v[18:19], v20, off
	ds_read_b128 v[18:21], v130 offset:704
	v_add_u32_e32 v22, 0x2c000, v0
	v_mov_b32_e32 v23, v1
	v_lshl_add_u64 v[22:23], v[22:23], 1, s[2:3]
	s_waitcnt lgkmcnt(0)
	v_fma_f32 v10, v10, v18, v137
	v_bfe_u32 v24, v10, 16, 1
	v_fma_f32 v2, v2, v18, v136
	v_add3_u32 v10, v10, v24, s81
	global_store_short_d16_hi v[22:23], v10, off
	v_add_u32_e32 v22, 0x2c010, v0
	v_mov_b32_e32 v23, v1
	v_cvt_pk_bf16_f32 v2, v2, v2
	v_lshl_add_u64 v[22:23], v[22:23], 1, s[2:3]
	global_store_short_d16_hi v[22:23], v2, off
	v_fma_f32 v2, v14, v18, v135
	v_add_u32_e32 v22, 0x2c080, v0
	s_nop 0
	v_mov_b32_e32 v23, v1
	v_cvt_pk_bf16_f32 v2, v2, v2
	v_lshl_add_u64 v[22:23], v[22:23], 1, s[2:3]
	global_store_short_d16_hi v[22:23], v2, off
	v_fma_f32 v2, v6, v18, v134
	s_nop 0
	v_add_u32_e32 v22, 0x2c090, v0
	v_mov_b32_e32 v23, v1
	v_cvt_pk_bf16_f32 v2, v2, v2
	v_lshl_add_u64 v[22:23], v[22:23], 1, s[2:3]
	global_store_short_d16_hi v[22:23], v2, off
	v_fma_f32 v2, v11, v19, v137
	v_add_u32_e32 v10, 0x2c400, v0
	s_nop 0
	v_mov_b32_e32 v11, v1
	v_cvt_pk_bf16_f32 v2, v2, v2
	v_lshl_add_u64 v[10:11], v[10:11], 1, s[2:3]
	global_store_short_d16_hi v[10:11], v2, off
	v_fma_f32 v2, v3, v19, v136
	s_nop 0
	v_cvt_pk_bf16_f32 v6, v2, v2
	v_add_u32_e32 v2, 0x2c410, v0
	v_mov_b32_e32 v3, v1
	v_lshl_add_u64 v[2:3], v[2:3], 1, s[2:3]
	global_store_short_d16_hi v[2:3], v6, off
	v_fma_f32 v3, v15, v19, v135
	s_nop 0
	v_add_u32_e32 v2, 0x2c480, v0
	v_cvt_pk_bf16_f32 v6, v3, v3
	v_mov_b32_e32 v3, v1
	v_lshl_add_u64 v[2:3], v[2:3], 1, s[2:3]
	global_store_short_d16_hi v[2:3], v6, off
	v_fma_f32 v2, v7, v19, v134
	s_nop 0
	v_cvt_pk_bf16_f32 v6, v2, v2
	v_add_u32_e32 v2, 0x2c490, v0
	v_mov_b32_e32 v3, v1
	v_lshl_add_u64 v[2:3], v[2:3], 1, s[2:3]
	global_store_short_d16_hi v[2:3], v6, off
	v_fma_f32 v3, v12, v20, v137
	v_bfe_u32 v6, v3, 16, 1
	v_add_u32_e32 v2, 0x2c800, v0
	v_add3_u32 v6, v3, v6, s81
	v_mov_b32_e32 v3, v1
	v_lshl_add_u64 v[2:3], v[2:3], 1, s[2:3]
	global_store_short_d16_hi v[2:3], v6, off
	v_fma_f32 v2, v4, v20, v136
	s_nop 0
	v_cvt_pk_bf16_f32 v4, v2, v2
	v_add_u32_e32 v2, 0x2c810, v0
	v_mov_b32_e32 v3, v1
	v_lshl_add_u64 v[2:3], v[2:3], 1, s[2:3]
	global_store_short_d16_hi v[2:3], v4, off
	v_fma_f32 v3, v16, v20, v135
	s_nop 0
	v_add_u32_e32 v2, 0x2c880, v0
	v_cvt_pk_bf16_f32 v4, v3, v3
	v_mov_b32_e32 v3, v1
	v_lshl_add_u64 v[2:3], v[2:3], 1, s[2:3]
	global_store_short_d16_hi v[2:3], v4, off
	v_fma_f32 v2, v8, v20, v134
	s_nop 0
	v_cvt_pk_bf16_f32 v4, v2, v2
	v_add_u32_e32 v2, 0x2c890, v0
	v_mov_b32_e32 v3, v1
	v_lshl_add_u64 v[2:3], v[2:3], 1, s[2:3]
	v_fmac_f32_e32 v137, v13, v21
	global_store_short_d16_hi v[2:3], v4, off
	s_nop 0
	v_add_u32_e32 v2, 0x2cc00, v0
	v_cvt_pk_bf16_f32 v4, v137, v137
	v_mov_b32_e32 v3, v1
	v_lshl_add_u64 v[2:3], v[2:3], 1, s[2:3]
	v_fmac_f32_e32 v136, v5, v21
	global_store_short_d16_hi v[2:3], v4, off
	s_nop 0
	v_cvt_pk_bf16_f32 v4, v136, v136
	v_add_u32_e32 v2, 0x2cc10, v0
	v_mov_b32_e32 v3, v1
	v_lshl_add_u64 v[2:3], v[2:3], 1, s[2:3]
	v_fmac_f32_e32 v135, v17, v21
	global_store_short_d16_hi v[2:3], v4, off
	s_nop 0
	v_add_u32_e32 v2, 0x2cc80, v0
	v_cvt_pk_bf16_f32 v4, v135, v135
	v_mov_b32_e32 v3, v1
	v_lshl_add_u64 v[2:3], v[2:3], 1, s[2:3]
	v_fmac_f32_e32 v134, v9, v21
	global_store_short_d16_hi v[2:3], v4, off
	v_bfe_u32 v2, v134, 16, 1
	v_add_u32_e32 v0, 0x2cc90, v0
	v_add3_u32 v4, v134, v2, s81
	v_lshl_add_u64 v[2:3], v[0:1], 1, s[2:3]
	global_store_short_d16_hi v[2:3], v4, off
	s_branch .LBB0_312

; __device__ __forceinline__ unsigned pack2(float a, float b) { return (unsigned)f2bf(a) | ((unsigned)f2bf(b) << 16); }
; __device__ __forceinline__ void ret_core_phase(const Params& p, const PD& d, char* shm, const int wave_s) {
;     ...
; #pragma unroll
;       for (int df = 0; df < 4; ++df)
; #pragma unroll
;         for (int vf = 0; vf < 4; ++vf)
; #pragma unroll
;           for (int r = 0; r < 4; ++r) S[df][vf][r] = st[((df * 4 + vf) * 4 + r) * 512 + tid];
;     }
;     __syncthreads();
; #pragma unroll
;     for (int df = 0; df < 4; ++df)
; #pragma unroll
;       for (int vf = 0; vf < 4; ++vf) {
;         uint2 pk; pk.x = pack2(S[df][vf][0], S[df][vf][1]); pk.y = pack2(S[df][vf][2], S[df][vf][3]);
;         *(uint2*)(R2 + (64 * wj + 16 * vf + fr) * 528 + (64 * wi + 16 * df + 4 * fq) * 2) = pk;
;       }
.LBB0_561:
	v_bfe_u32 v164, v68, 6, 1
	v_and_b32_e32 v70, 15, v68
	v_lshlrev_b32_e32 v241, 6, v164
	v_lshrrev_b32_e32 v3, 1, v68
	v_or_b32_e32 v0, v241, v70
	v_and_b32_e32 v2, 0xffffff80, v68
	v_and_b32_e32 v71, 24, v3
	s_add_i32 s73, 0, 0x11000
	s_waitcnt vmcnt(62)
	s_nop 0
	v_add_u32_e32 v2, s73, v2
	v_mul_u32_u24_e32 v0, 0x210, v0
	v_cvt_pk_bf16_f32 v72, v4, v4
	s_waitcnt vmcnt(60)
	v_add3_u32 v0, v2, v71, v0
	v_cvt_pk_bf16_f32 v3, v7, v7
	v_cvt_pk_bf16_f32 v73, v5, v5
	v_cvt_pk_bf16_f32 v2, v6, v6
	v_and_b32_e32 v3, 0xffff0000, v3
	v_and_b32_e32 v73, 0xffff0000, v73
	v_or_b32_sdwa v3, v3, v2 dst_sel:DWORD dst_unused:UNUSED_PAD src0_sel:DWORD src1_sel:WORD_1
	v_or_b32_sdwa v2, v73, v72 dst_sel:DWORD dst_unused:UNUSED_PAD src0_sel:DWORD src1_sel:WORD_1
	s_waitcnt vmcnt(59)
	v_cvt_pk_bf16_f32 v74, v8, v8
	s_waitcnt vmcnt(56)
	v_cvt_pk_bf16_f32 v73, v11, v11
	v_cvt_pk_bf16_f32 v75, v9, v9
	v_cvt_pk_bf16_f32 v72, v10, v10
	v_and_b32_e32 v73, 0xffff0000, v73
	v_and_b32_e32 v75, 0xffff0000, v75
	v_or_b32_sdwa v73, v73, v72 dst_sel:DWORD dst_unused:UNUSED_PAD src0_sel:DWORD src1_sel:WORD_1
	v_or_b32_sdwa v72, v75, v74 dst_sel:DWORD dst_unused:UNUSED_PAD src0_sel:DWORD src1_sel:WORD_1
	s_waitcnt vmcnt(55)
	v_cvt_pk_bf16_f32 v76, v12, v12
	s_waitcnt vmcnt(52)
	v_cvt_pk_bf16_f32 v75, v15, v15
	v_cvt_pk_bf16_f32 v83, v13, v13
	v_cvt_pk_bf16_f32 v74, v14, v14
	v_and_b32_e32 v75, 0xffff0000, v75
	v_and_b32_e32 v83, 0xffff0000, v83
	s_waitcnt vmcnt(48)
	v_or_b32_sdwa v75, v75, v74 dst_sel:DWORD dst_unused:UNUSED_PAD src0_sel:DWORD src1_sel:WORD_1
	v_or_b32_sdwa v74, v83, v76 dst_sel:DWORD dst_unused:UNUSED_PAD src0_sel:DWORD src1_sel:WORD_1
	v_cvt_pk_bf16_f32 v84, v19, v19
	v_cvt_pk_bf16_f32 v85, v17, v17
	v_cvt_pk_bf16_f32 v83, v16, v16
	v_cvt_pk_bf16_f32 v76, v18, v18
	v_and_b32_e32 v84, 0xffff0000, v84
	v_and_b32_e32 v86, 0xffff0000, v85
	v_or_b32_sdwa v85, v84, v76 dst_sel:DWORD dst_unused:UNUSED_PAD src0_sel:DWORD src1_sel:WORD_1
	v_or_b32_sdwa v84, v86, v83 dst_sel:DWORD dst_unused:UNUSED_PAD src0_sel:DWORD src1_sel:WORD_1
	s_waitcnt vmcnt(44)
	v_cvt_pk_bf16_f32 v86, v23, v23
	v_cvt_pk_bf16_f32 v87, v21, v21
	v_cvt_pk_bf16_f32 v83, v20, v20
	v_cvt_pk_bf16_f32 v76, v22, v22
	v_and_b32_e32 v86, 0xffff0000, v86
	v_and_b32_e32 v88, 0xffff0000, v87
	v_or_b32_sdwa v87, v86, v76 dst_sel:DWORD dst_unused:UNUSED_PAD src0_sel:DWORD src1_sel:WORD_1
	v_or_b32_sdwa v86, v88, v83 dst_sel:DWORD dst_unused:UNUSED_PAD src0_sel:DWORD src1_sel:WORD_1
	s_barrier
	ds_write2_b64 v0, v[2:3], v[86:87] offset1:4
	s_waitcnt vmcnt(43)
	s_nop 0
	v_cvt_pk_bf16_f32 v76, v24, v24
	s_waitcnt vmcnt(40)
	v_cvt_pk_bf16_f32 v3, v27, v27
	v_cvt_pk_bf16_f32 v83, v25, v25
	v_cvt_pk_bf16_f32 v2, v26, v26
	v_and_b32_e32 v3, 0xffff0000, v3
	v_and_b32_e32 v83, 0xffff0000, v83
	v_or_b32_sdwa v3, v3, v2 dst_sel:DWORD dst_unused:UNUSED_PAD src0_sel:DWORD src1_sel:WORD_1
	v_or_b32_sdwa v2, v83, v76 dst_sel:DWORD dst_unused:UNUSED_PAD src0_sel:DWORD src1_sel:WORD_1
	v_add_u32_e32 v76, 0x2000, v0
	ds_write2_b64 v76, v[72:73], v[2:3] offset0:32 offset1:36
	s_waitcnt vmcnt(39)
	v_cvt_pk_bf16_f32 v72, v28, v28
	s_waitcnt vmcnt(36)
	s_waitcnt lgkmcnt(2)
	v_cvt_pk_bf16_f32 v3, v31, v31
	v_cvt_pk_bf16_f32 v73, v29, v29
	v_cvt_pk_bf16_f32 v2, v30, v30
	v_and_b32_e32 v3, 0xffff0000, v3
	v_and_b32_e32 v73, 0xffff0000, v73
	v_or_b32_sdwa v3, v3, v2 dst_sel:DWORD dst_unused:UNUSED_PAD src0_sel:DWORD src1_sel:WORD_1
	v_or_b32_sdwa v2, v73, v72 dst_sel:DWORD dst_unused:UNUSED_PAD src0_sel:DWORD src1_sel:WORD_1
	v_add_u32_e32 v83, 0x4000, v0
	ds_write2_b64 v83, v[74:75], v[2:3] offset0:64 offset1:68
	s_waitcnt vmcnt(35)
	v_cvt_pk_bf16_f32 v72, v32, v32
	s_waitcnt vmcnt(32)
	v_cvt_pk_bf16_f32 v3, v35, v35
	v_cvt_pk_bf16_f32 v73, v33, v33
	v_cvt_pk_bf16_f32 v2, v34, v34
	v_and_b32_e32 v3, 0xffff0000, v3
	v_and_b32_e32 v73, 0xffff0000, v73
	v_or_b32_sdwa v3, v3, v2 dst_sel:DWORD dst_unused:UNUSED_PAD src0_sel:DWORD src1_sel:WORD_1
	v_or_b32_sdwa v2, v73, v72 dst_sel:DWORD dst_unused:UNUSED_PAD src0_sel:DWORD src1_sel:WORD_1
	v_add_u32_e32 v88, 0x6000, v0
	ds_write2_b64 v88, v[84:85], v[2:3] offset0:96 offset1:100
	s_waitcnt vmcnt(31)
	v_cvt_pk_bf16_f32 v72, v36, v36
	s_waitcnt vmcnt(28)
	v_cvt_pk_bf16_f32 v3, v39, v39
	v_cvt_pk_bf16_f32 v73, v37, v37
	v_cvt_pk_bf16_f32 v2, v38, v38
	v_and_b32_e32 v3, 0xffff0000, v3
	v_and_b32_e32 v73, 0xffff0000, v73
	v_or_b32_sdwa v3, v3, v2 dst_sel:DWORD dst_unused:UNUSED_PAD src0_sel:DWORD src1_sel:WORD_1
	v_or_b32_sdwa v2, v73, v72 dst_sel:DWORD dst_unused:UNUSED_PAD src0_sel:DWORD src1_sel:WORD_1
	s_waitcnt vmcnt(27)
	v_cvt_pk_bf16_f32 v74, v40, v40
	s_waitcnt vmcnt(24)
	v_cvt_pk_bf16_f32 v73, v43, v43
	v_cvt_pk_bf16_f32 v75, v41, v41
	v_cvt_pk_bf16_f32 v72, v42, v42
	v_and_b32_e32 v73, 0xffff0000, v73
	v_and_b32_e32 v75, 0xffff0000, v75
	v_or_b32_sdwa v73, v73, v72 dst_sel:DWORD dst_unused:UNUSED_PAD src0_sel:DWORD src1_sel:WORD_1
	v_or_b32_sdwa v72, v75, v74 dst_sel:DWORD dst_unused:UNUSED_PAD src0_sel:DWORD src1_sel:WORD_1
	s_waitcnt vmcnt(23)
	v_cvt_pk_bf16_f32 v84, v44, v44
	s_waitcnt vmcnt(20)
	v_cvt_pk_bf16_f32 v75, v47, v47
	v_cvt_pk_bf16_f32 v85, v45, v45
	v_cvt_pk_bf16_f32 v74, v46, v46
	v_and_b32_e32 v75, 0xffff0000, v75
	v_and_b32_e32 v85, 0xffff0000, v85
	v_or_b32_sdwa v75, v75, v74 dst_sel:DWORD dst_unused:UNUSED_PAD src0_sel:DWORD src1_sel:WORD_1
	v_or_b32_sdwa v74, v85, v84 dst_sel:DWORD dst_unused:UNUSED_PAD src0_sel:DWORD src1_sel:WORD_1
	s_waitcnt vmcnt(19)
	v_cvt_pk_bf16_f32 v86, v48, v48
	s_waitcnt vmcnt(16)
; __device__ __forceinline__ unsigned pack2(float a, float b) { return (unsigned)f2bf(a) | ((unsigned)f2bf(b) << 16); }
; __device__ __forceinline__ void ret_core_phase(const Params& p, const PD& d, char* shm, const int wave_s) {
;     ...
;     for (int df = 0; df < 4; ++df)
; #pragma unroll
;       for (int vf = 0; vf < 4; ++vf) {
;         uint2 pk; pk.x = pack2(S[df][vf][0], S[df][vf][1]); pk.y = pack2(S[df][vf][2], S[df][vf][3]);
;         *(uint2*)(R2 + (64 * wj + 16 * vf + fr) * 528 + (64 * wi + 16 * df + 4 * fq) * 2) = pk;
;       }
;     bf16x8 kpre[8];
;     bf16x8 Qf[2][8];
;     {
;       const size_t lt0 = (size_t)b * 2048;
; #pragma unroll
;       for (int i = 0; i < 8; ++i) {
;         int c = i * 512 + tid, row = c >> 5, cc = c & 31;
;         kpre[i] = *(const bf16x8*)(Kb + (lt0 + row) * 1024 + hh * 256 + cc * 8);
;       }
;       const u16* Qw = Qb + (lt0 + 32 * wi + fr) * 1024 + hh * 256 + fq * 8;
; #pragma unroll
;       for (int f = 0; f < 2; ++f)
; #pragma unroll
;         for (int ks = 0; ks < 8; ++ks) Qf[f][ks] = *(const bf16x8*)(Qw + f * 16 * 1024 + ks * 32);
;     }
	v_cvt_pk_bf16_f32 v85, v51, v51
	v_cvt_pk_bf16_f32 v87, v49, v49
	v_cvt_pk_bf16_f32 v84, v50, v50
	v_and_b32_e32 v85, 0xffff0000, v85
	v_and_b32_e32 v87, 0xffff0000, v87
	v_or_b32_sdwa v85, v85, v84 dst_sel:DWORD dst_unused:UNUSED_PAD src0_sel:DWORD src1_sel:WORD_1
	v_or_b32_sdwa v84, v87, v86 dst_sel:DWORD dst_unused:UNUSED_PAD src0_sel:DWORD src1_sel:WORD_1
	s_waitcnt vmcnt(15)
	v_cvt_pk_bf16_f32 v89, v52, v52
	s_waitcnt vmcnt(12)
	v_cvt_pk_bf16_f32 v87, v55, v55
	v_cvt_pk_bf16_f32 v90, v53, v53
	v_cvt_pk_bf16_f32 v86, v54, v54
	v_and_b32_e32 v87, 0xffff0000, v87
	v_and_b32_e32 v90, 0xffff0000, v90
	v_or_b32_sdwa v87, v87, v86 dst_sel:DWORD dst_unused:UNUSED_PAD src0_sel:DWORD src1_sel:WORD_1
	v_or_b32_sdwa v86, v90, v89 dst_sel:DWORD dst_unused:UNUSED_PAD src0_sel:DWORD src1_sel:WORD_1
	ds_write2_b64 v0, v[2:3], v[86:87] offset0:8 offset1:12
	s_waitcnt vmcnt(8)
	v_cvt_pk_bf16_f32 v3, v59, v59
	v_cvt_pk_bf16_f32 v86, v57, v57
	v_cvt_pk_bf16_f32 v2, v56, v56
	v_cvt_pk_bf16_f32 v0, v58, v58
	v_and_b32_e32 v3, 0xffff0000, v3
	v_and_b32_e32 v86, 0xffff0000, v86
	v_or_b32_sdwa v3, v3, v0 dst_sel:DWORD dst_unused:UNUSED_PAD src0_sel:DWORD src1_sel:WORD_1
	v_or_b32_sdwa v2, v86, v2 dst_sel:DWORD dst_unused:UNUSED_PAD src0_sel:DWORD src1_sel:WORD_1
	s_lshl_b32 s2, s72, 4
	ds_write2_b64 v76, v[72:73], v[2:3] offset0:40 offset1:44
	s_waitcnt vmcnt(4)
	s_nop 0
	s_nop 0
	s_and_b32 s7, s2, 0x380
	s_lshl_b32 s2, s90, 3
	s_nop 0
	s_nop 0
	v_cvt_pk_bf16_f32 v3, v63, v63
	v_cvt_pk_bf16_f32 v72, v61, v61
	s_and_b32 s2, s2, 56
	v_cvt_pk_bf16_f32 v2, v60, v60
	v_cvt_pk_bf16_f32 v0, v62, v62
	v_and_b32_e32 v3, 0xffff0000, v3
	v_and_b32_e32 v72, 0xffff0000, v72
	s_add_i32 s2, s2, s4
	v_or_b32_sdwa v3, v3, v0 dst_sel:DWORD dst_unused:UNUSED_PAD src0_sel:DWORD src1_sel:WORD_1
	v_or_b32_sdwa v2, v72, v2 dst_sel:DWORD dst_unused:UNUSED_PAD src0_sel:DWORD src1_sel:WORD_1
	s_waitcnt vmcnt(2)
	s_nop 0
	s_ashr_i32 s2, s2, 2
	ds_write2_b64 v83, v[74:75], v[2:3] offset0:72 offset1:76
	s_nop 0
	s_waitcnt vmcnt(0)
	s_nop 0
	v_cvt_pk_bf16_f32 v72, v65, v65
	v_cvt_pk_bf16_f32 v2, v64, v64
	v_cvt_pk_bf16_f32 v3, v67, v67
	v_and_b32_e32 v72, 0xffff0000, v72
	s_ashr_i32 s3, s2, 31
	v_readlane_b32 s12, v253, 53
	s_bfe_u32 s8, s90, 0x20003
	v_cvt_pk_bf16_f32 v0, v66, v66
	v_and_b32_e32 v3, 0xffff0000, v3
	v_or_b32_sdwa v2, v72, v2 dst_sel:DWORD dst_unused:UNUSED_PAD src0_sel:DWORD src1_sel:WORD_1
	s_lshl_b64 s[92:93], s[2:3], 11
	s_lshl_b32 s12, s5, 9
	v_readlane_b32 s2, v252, 59
	v_ashrrev_i32_e32 v72, 5, v68
	v_or_b32_sdwa v3, v3, v0 dst_sel:DWORD dst_unused:UNUSED_PAD src0_sel:DWORD src1_sel:WORD_1
	s_add_u32 s88, s2, s12
	v_readlane_b32 s2, v252, 60
	v_lshlrev_b32_e32 v0, 4, v68
	v_ashrrev_i32_e32 v73, 31, v72
	s_addc_u32 s89, s2, 0
	v_and_b32_e32 v0, 0x1f0, v0
	v_lshl_add_u64 v[72:73], s[92:93], 0, v[72:73]
	ds_write2_b64 v88, v[84:85], v[2:3] offset0:104 offset1:108
	v_lshl_add_u64 v[2:3], s[88:89], 0, v[0:1]
	v_lshlrev_b64 v[72:73], 11, v[72:73]
	v_lshl_add_u64 v[72:73], v[2:3], 0, v[72:73]
	global_load_dwordx4 v[100:103], v[72:73], off
	v_ashrrev_i32_e32 v72, 5, v82
	v_ashrrev_i32_e32 v73, 31, v72
	v_lshl_add_u64 v[72:73], s[92:93], 0, v[72:73]
	v_lshlrev_b64 v[72:73], 11, v[72:73]
	v_lshl_add_u64 v[72:73], v[2:3], 0, v[72:73]
	global_load_dwordx4 v[104:107], v[72:73], off
	v_ashrrev_i32_e32 v72, 5, v81
	v_ashrrev_i32_e32 v73, 31, v72
	v_lshl_add_u64 v[72:73], s[92:93], 0, v[72:73]
	v_lshlrev_b64 v[72:73], 11, v[72:73]
	v_lshl_add_u64 v[72:73], v[2:3], 0, v[72:73]
	global_load_dwordx4 v[108:111], v[72:73], off
	v_ashrrev_i32_e32 v72, 5, v80
	v_ashrrev_i32_e32 v73, 31, v72
	v_lshl_add_u64 v[72:73], s[92:93], 0, v[72:73]
	v_lshlrev_b64 v[72:73], 11, v[72:73]
	v_lshl_add_u64 v[72:73], v[2:3], 0, v[72:73]
	global_load_dwordx4 v[116:119], v[72:73], off
	v_ashrrev_i32_e32 v72, 5, v79
	v_ashrrev_i32_e32 v73, 31, v72
	v_lshl_add_u64 v[72:73], s[92:93], 0, v[72:73]
	v_lshlrev_b64 v[72:73], 11, v[72:73]
	v_lshl_add_u64 v[72:73], v[2:3], 0, v[72:73]
	global_load_dwordx4 v[124:127], v[72:73], off
	v_ashrrev_i32_e32 v72, 5, v78
	v_ashrrev_i32_e32 v73, 31, v72
	v_lshl_add_u64 v[72:73], s[92:93], 0, v[72:73]
	v_lshlrev_b64 v[72:73], 11, v[72:73]
	v_lshl_add_u64 v[72:73], v[2:3], 0, v[72:73]
	v_ashrrev_i32_e32 v165, 7, v68
	global_load_dwordx4 v[128:131], v[72:73], off
	v_ashrrev_i32_e32 v72, 5, v77
	v_ashrrev_i32_e32 v68, 5, v69
	v_ashrrev_i32_e32 v73, 31, v72
	v_ashrrev_i32_e32 v69, 31, v68
	v_lshl_add_u64 v[72:73], s[92:93], 0, v[72:73]
	v_lshl_add_u64 v[68:69], s[92:93], 0, v[68:69]
	v_lshlrev_b64 v[72:73], 11, v[72:73]
	v_lshlrev_b64 v[68:69], 11, v[68:69]
	v_lshl_add_u64 v[72:73], v[2:3], 0, v[72:73]
	v_lshl_add_u64 v[2:3], v[2:3], 0, v[68:69]
	global_load_dwordx4 v[132:135], v[72:73], off
	global_load_dwordx4 v[136:139], v[2:3], off
	v_lshlrev_b32_e32 v2, 5, v165
	v_ashrrev_i32_e32 v3, 31, v2
	v_lshl_add_u64 v[176:177], s[92:93], 0, v[2:3]
	v_or_b32_e32 v68, v176, v70
	v_mov_b32_e32 v69, v177
	v_readlane_b32 s16, v254, 47
	v_lshlrev_b64 v[68:69], 11, v[68:69]
	v_readlane_b32 s18, v254, 49
	v_readlane_b32 s19, v254, 50
	v_readlane_b32 s13, v253, 54
	v_lshlrev_b32_e32 v0, 1, v71
	v_lshl_add_u64 v[68:69], s[18:19], 0, v[68:69]
	v_lshl_add_u64 v[68:69], v[68:69], 0, s[12:13]
	v_lshl_add_u64 v[72:73], v[68:69], 0, v[0:1]
	global_load_dwordx4 v[156:159], v[72:73], off
	global_load_dwordx4 v[144:147], v[72:73], off offset:64
	global_load_dwordx4 v[140:143], v[72:73], off offset:128
	global_load_dwordx4 v[96:99], v[72:73], off offset:192
	global_load_dwordx4 v[92:95], v[72:73], off offset:256
	global_load_dwordx4 v[80:83], v[72:73], off offset:320
	global_load_dwordx4 v[76:79], v[72:73], off offset:384
; __device__ __forceinline__ unsigned pack2(float a, float b) { return (unsigned)f2bf(a) | ((unsigned)f2bf(b) << 16); }
; __device__ __forceinline__ void ret_core_phase(const Params& p, const PD& d, char* shm, const int wave_s) {
;     ...
;       for (int f = 0; f < 2; ++f)
; #pragma unroll
;         for (int ks = 0; ks < 8; ++ks) Qf[f][ks] = *(const bf16x8*)(Qw + f * 16 * 1024 + ks * 32);
;     ...
;           for (int vf = 0; vf < 4; ++vf) {
;             uint2 gq = gpre[vf][f];
;             float g0 = __uint_as_float(gq.x << 16), g1 = __uint_as_float(gq.x & 0xffff0000u);
;             float g2 = __uint_as_float(gq.y << 16), g3 = __uint_as_float(gq.y & 0xffff0000u);
;             uint2 o;
;             o.x = pack2(silu_f(g0) * OT[vf][f][0], silu_f(g1) * OT[vf][f][1]);
;             o.y = pack2(silu_f(g2) * OT[vf][f][2], silu_f(g3) * OT[vf][f][3]);
;             *(uint2*)(got + f * 16 * 2048 + vf * 16) = o;
;           }
	global_load_dwordx4 v[68:71], v[72:73], off offset:448
	v_add_co_u32_e32 v72, vcc, s20, v72
	v_writelane_b32 v253, s12, 53
	s_nop 0
	v_addc_co_u32_e32 v73, vcc, 0, v73, vcc
	global_load_dwordx4 v[160:163], v[72:73], off
	global_load_dwordx4 v[152:155], v[72:73], off offset:64
	global_load_dwordx4 v[148:151], v[72:73], off offset:128
	global_load_dwordx4 v[120:123], v[72:73], off offset:192
	global_load_dwordx4 v[112:115], v[72:73], off offset:256
	global_load_dwordx4 v[88:91], v[72:73], off offset:320
	global_load_dwordx4 v[84:87], v[72:73], off offset:384
	s_nop 0
	global_load_dwordx4 v[72:75], v[72:73], off offset:448
	s_add_u32 s84, s18, s12
	s_addc_u32 s85, s19, 0
	s_lshl_b32 s9, s8, 7
	s_lshl_b32 s2, s5, 10
	v_readlane_b32 s3, v254, 9
	s_add_u32 s2, s3, s2
	v_readlane_b32 s3, v254, 10
	s_addc_u32 s3, s3, 0
	s_lshl_b32 s11, s8, 8
	s_add_u32 s2, s2, s11
	v_readlane_b32 s17, v254, 48
	v_lshlrev_b32_e32 v0, 7, v164
	s_addc_u32 s3, s3, 0
	v_writelane_b32 v253, s13, 54
	v_lshl_add_u64 v[180:181], s[2:3], 0, v[0:1]
	s_lshl_b32 s2, s5, 5
	v_readlane_b32 s12, v252, 0
	v_readlane_b32 s13, v252, 1
	s_add_u32 s2, s12, s2
	s_addc_u32 s3, s13, 0
	s_lshl_b32 s5, s8, 3
	s_add_u32 s2, s2, s5
	v_add_u32_e32 v242, 0, v0
	s_addc_u32 s3, s3, 0
	v_lshlrev_b32_e32 v0, 2, v164
	v_lshl_add_u64 v[184:185], s[2:3], 0, v[0:1]
	s_lshl_b32 s2, s4, 4
	s_add_i32 s2, s7, s2
	v_lshlrev_b32_e32 v182, 6, v165
	s_ashr_i32 s3, s2, 31
	v_ashrrev_i32_e32 v183, 31, v182
	s_lshl_b64 s[4:5], s[2:3], 8
	s_lshl_b64 s[2:3], s[2:3], 9
	s_mov_b32 s11, s10
	s_mov_b32 s76, s10
	s_mov_b32 s77, s10
	v_lshl_add_u64 v[186:187], s[4:5], 0, v[182:183]
	s_or_b32 s2, s2, s9
	s_mov_b64 s[8:9], 0
	v_mov_b32_e32 v183, s6
	s_mov_b64 s[68:69], 0
	v_readlane_b32 s14, v252, 2
	v_readlane_b32 s15, v252, 3
	v_readlane_b32 s16, v252, 4
	v_readlane_b32 s17, v252, 5
	v_readlane_b32 s18, v252, 6
	v_readlane_b32 s19, v252, 7
	s_branch .LBB0_563
.LBB0_562:
	s_or_b64 exec, exec, s[4:5]
	s_waitcnt vmcnt(15)
	v_lshlrev_b32_e32 v126, 16, v146
	v_mul_f32_e32 v125, 0xbfb8aa3b, v126
	v_exp_f32_e32 v125, v125
	v_and_b32_e32 v128, 0xffff0000, v146
	v_lshlrev_b32_e32 v127, 16, v147
	v_and_b32_e32 v129, 0xffff0000, v147
	v_add_f32_e32 v125, 1.0, v125
	v_rcp_f32_e32 v130, v125
	v_mul_f32_e32 v125, 0xbfb8aa3b, v128
	v_exp_f32_e32 v125, v125
	s_mov_b64 s[4:5], 0x10000
	v_lshl_add_u64 v[122:123], v[148:149], 0, s[4:5]
	s_mov_b64 s[4:5], 0x10020
	v_add_f32_e32 v125, 1.0, v125
	v_rcp_f32_e32 v146, v125
	v_mul_f32_e32 v125, 0xbfb8aa3b, v127
	v_exp_f32_e32 v125, v125
	v_lshl_add_u64 v[120:121], v[148:149], 0, s[4:5]
	s_mov_b64 s[4:5], 0x10040
	v_lshl_add_u64 v[118:119], v[148:149], 0, s[4:5]
	v_add_f32_e32 v125, 1.0, v125
	v_rcp_f32_e32 v131, v125
	s_add_u32 s8, s8, 0x80
	s_addc_u32 s9, s9, 0
	s_mov_b64 s[4:5], 0x10060
	v_pk_mul_f32 v[126:127], v[130:131], v[126:127]
	v_mov_b32_e32 v130, v112
	v_mul_f32_e32 v112, 0xbfb8aa3b, v129
	v_exp_f32_e32 v112, v112
	v_mov_b32_e32 v131, v114
	v_pk_mul_f32 v[126:127], v[126:127], v[130:131]
	v_mov_b32_e32 v114, v113
	v_add_f32_e32 v112, 1.0, v112
	v_rcp_f32_e32 v147, v112
	s_cmpk_lg_i32 s68, 0x1e00
	s_waitcnt lgkmcnt(0)
	v_lshl_add_u64 v[116:117], v[148:149], 0, s[4:5]
	s_cselect_b32 s4, s8, 0x780
	v_pk_mul_f32 v[128:129], v[146:147], v[128:129]
	v_lshlrev_b32_e32 v124, 3, v191
	v_pk_mul_f32 v[112:113], v[128:129], v[114:115]
	s_nop 0
	v_cvt_pk_bf16_f32 v115, v126, v126
	v_cvt_pk_bf16_f32 v113, v113, v113
	v_cvt_pk_bf16_f32 v112, v112, v112
	v_cvt_pk_bf16_f32 v114, v127, v127
	v_and_b32_e32 v113, 0xffff0000, v113
	v_and_b32_e32 v112, 0xffff0000, v112
	v_or_b32_sdwa v113, v113, v114 dst_sel:DWORD dst_unused:UNUSED_PAD src0_sel:DWORD src1_sel:WORD_1
	v_or_b32_sdwa v112, v112, v115 dst_sel:DWORD dst_unused:UNUSED_PAD src0_sel:DWORD src1_sel:WORD_1
	s_waitcnt vmcnt(14)
	v_and_b32_e32 v114, 0xffff0000, v144
	global_store_dwordx2 v[122:123], v[112:113], off
	v_mul_f32_e32 v123, 0xbfb8aa3b, v114
	v_exp_f32_e32 v123, v123
	v_lshlrev_b32_e32 v113, 16, v145
	v_lshlrev_b32_e32 v112, 16, v144
	v_mul_f32_e32 v122, 0xbfb8aa3b, v112
	v_add_f32_e32 v123, 1.0, v123
	v_rcp_f32_e32 v126, v123
	v_mul_f32_e32 v123, 0xbfb8aa3b, v113
	v_exp_f32_e32 v122, v122
	v_exp_f32_e32 v123, v123
	v_and_b32_e32 v115, 0xffff0000, v145
	s_add_u32 s4, s92, s4
	v_add_f32_e32 v122, 1.0, v122
	v_add_f32_e32 v123, 1.0, v123
	v_rcp_f32_e32 v122, v122
	v_rcp_f32_e32 v123, v123
	v_mul_u32_u24_e32 v164, 0x210, v193
	v_lshlrev_b32_e32 v165, 2, v195
	v_mul_u32_u24_e32 v166, 0x110, v193
	v_pk_mul_f32 v[112:113], v[122:123], v[112:113]
	v_mov_b32_e32 v122, v108
	v_mul_f32_e32 v108, 0xbfb8aa3b, v115
	v_exp_f32_e32 v108, v108
	v_mov_b32_e32 v123, v110
	v_pk_mul_f32 v[112:113], v[112:113], v[122:123]
	v_mov_b32_e32 v110, v109
	v_add_f32_e32 v108, 1.0, v108
	v_rcp_f32_e32 v127, v108
	s_addc_u32 s5, s93, 0
	v_pk_mul_f32 v[114:115], v[126:127], v[114:115]
	s_nop 0
	v_pk_mul_f32 v[108:109], v[114:115], v[110:111]
	s_nop 0
	v_cvt_pk_bf16_f32 v111, v112, v112
	v_cvt_pk_bf16_f32 v109, v109, v109
	v_cvt_pk_bf16_f32 v110, v113, v113
	v_and_b32_e32 v109, 0xffff0000, v109
	v_or_b32_sdwa v109, v109, v110 dst_sel:DWORD dst_unused:UNUSED_PAD src0_sel:DWORD src1_sel:WORD_1
	s_waitcnt vmcnt(14)
; __device__ __forceinline__ unsigned pack2(float a, float b) { return (unsigned)f2bf(a) | ((unsigned)f2bf(b) << 16); }
; #define SCHED __builtin_amdgcn_sched_barrier(0)
; __device__ __forceinline__ void ret_core_phase(const Params& p, const PD& d, char* shm, const int wave_s) {
;     ...
;           for (int vf = 0; vf < 4; ++vf) {
;             uint2 gq = gpre[vf][f];
;             float g0 = __uint_as_float(gq.x << 16), g1 = __uint_as_float(gq.x & 0xffff0000u);
;             float g2 = __uint_as_float(gq.y << 16), g3 = __uint_as_float(gq.y & 0xffff0000u);
;             uint2 o;
;             o.x = pack2(silu_f(g0) * OT[vf][f][0], silu_f(g1) * OT[vf][f][1]);
;             o.y = pack2(silu_f(g2) * OT[vf][f][2], silu_f(g3) * OT[vf][f][3]);
;             *(uint2*)(got + f * 16 * 2048 + vf * 16) = o;
;           }
;         }
;       }
;       SCHED;
; #pragma unroll
;       for (int ks = 2; ks < 4; ++ks)
; #pragma unroll
;         for (int df = 0; df < 4; ++df) ktf[ks][df] = *(const bf16x8*)(KTw + df * 16 * 128 + ks * 32);
; #pragma unroll
;       for (int i = 0; i < 8; ++i) {
;         int c = i * 512 + tidv, row = c >> 5, cc = c & 31;
;         kpre[i] = *(const bf16x8*)(Kb + (lt1 + row) * 1024 + hh * 256 + cc * 8);
;       }
	v_and_b32_e32 v110, 0xffff0000, v142
	v_cvt_pk_bf16_f32 v108, v108, v108
	v_mul_f32_e32 v113, 0xbfb8aa3b, v110
	v_exp_f32_e32 v113, v113
	v_and_b32_e32 v108, 0xffff0000, v108
	v_or_b32_sdwa v108, v108, v111 dst_sel:DWORD dst_unused:UNUSED_PAD src0_sel:DWORD src1_sel:WORD_1
	global_store_dwordx2 v[120:121], v[108:109], off
	v_lshlrev_b32_e32 v109, 16, v143
	v_lshlrev_b32_e32 v108, 16, v142
	v_add_f32_e32 v113, 1.0, v113
	v_mul_f32_e32 v112, 0xbfb8aa3b, v108
	v_rcp_f32_e32 v114, v113
	v_mul_f32_e32 v113, 0xbfb8aa3b, v109
	v_exp_f32_e32 v112, v112
	v_exp_f32_e32 v113, v113
	v_and_b32_e32 v111, 0xffff0000, v143
	v_add_f32_e32 v112, 1.0, v112
	v_add_f32_e32 v113, 1.0, v113
	v_rcp_f32_e32 v112, v112
	v_rcp_f32_e32 v113, v113
	s_nop 0
	v_pk_mul_f32 v[108:109], v[112:113], v[108:109]
	v_mov_b32_e32 v112, v104
	v_mul_f32_e32 v104, 0xbfb8aa3b, v111
	v_exp_f32_e32 v104, v104
	v_mov_b32_e32 v113, v106
	v_pk_mul_f32 v[108:109], v[108:109], v[112:113]
	v_mov_b32_e32 v106, v105
	v_add_f32_e32 v104, 1.0, v104
	v_rcp_f32_e32 v115, v104
	s_nop 0
	v_pk_mul_f32 v[110:111], v[114:115], v[110:111]
	s_nop 0
	v_pk_mul_f32 v[104:105], v[110:111], v[106:107]
	s_nop 0
	v_cvt_pk_bf16_f32 v107, v108, v108
	v_cvt_pk_bf16_f32 v105, v105, v105
	v_cvt_pk_bf16_f32 v106, v109, v109
	v_and_b32_e32 v105, 0xffff0000, v105
	v_or_b32_sdwa v105, v105, v106 dst_sel:DWORD dst_unused:UNUSED_PAD src0_sel:DWORD src1_sel:WORD_1
	s_waitcnt vmcnt(14)
	v_and_b32_e32 v106, 0xffff0000, v140
	v_cvt_pk_bf16_f32 v104, v104, v104
	v_mul_f32_e32 v109, 0xbfb8aa3b, v106
	v_exp_f32_e32 v109, v109
	v_and_b32_e32 v104, 0xffff0000, v104
	v_or_b32_sdwa v104, v104, v107 dst_sel:DWORD dst_unused:UNUSED_PAD src0_sel:DWORD src1_sel:WORD_1
	global_store_dwordx2 v[118:119], v[104:105], off
	v_lshlrev_b32_e32 v105, 16, v141
	v_lshlrev_b32_e32 v104, 16, v140
	v_add_f32_e32 v109, 1.0, v109
	v_mul_f32_e32 v108, 0xbfb8aa3b, v104
	v_rcp_f32_e32 v110, v109
	v_mul_f32_e32 v109, 0xbfb8aa3b, v105
	v_exp_f32_e32 v108, v108
	v_exp_f32_e32 v109, v109
	v_and_b32_e32 v107, 0xffff0000, v141
	v_add_f32_e32 v108, 1.0, v108
	v_add_f32_e32 v109, 1.0, v109
	v_rcp_f32_e32 v108, v108
	v_rcp_f32_e32 v109, v109
	s_nop 0
	v_pk_mul_f32 v[104:105], v[108:109], v[104:105]
	v_mov_b32_e32 v108, v100
	v_mul_f32_e32 v100, 0xbfb8aa3b, v107
	v_exp_f32_e32 v100, v100
	v_mov_b32_e32 v109, v102
	v_pk_mul_f32 v[104:105], v[104:105], v[108:109]
	v_mov_b32_e32 v102, v101
	v_add_f32_e32 v100, 1.0, v100
	v_rcp_f32_e32 v111, v100
	s_nop 0
	v_pk_mul_f32 v[106:107], v[110:111], v[106:107]
	s_nop 0
	v_pk_mul_f32 v[100:101], v[106:107], v[102:103]
	s_nop 0
	v_cvt_pk_bf16_f32 v103, v104, v104
	v_cvt_pk_bf16_f32 v102, v105, v105
	v_cvt_pk_bf16_f32 v101, v101, v101
	v_cvt_pk_bf16_f32 v100, v100, v100
	v_and_b32_e32 v101, 0xffff0000, v101
	v_and_b32_e32 v100, 0xffff0000, v100
	v_or_b32_sdwa v101, v101, v102 dst_sel:DWORD dst_unused:UNUSED_PAD src0_sel:DWORD src1_sel:WORD_1
	v_or_b32_sdwa v100, v100, v103 dst_sel:DWORD dst_unused:UNUSED_PAD src0_sel:DWORD src1_sel:WORD_1
	global_store_dwordx2 v[116:117], v[100:101], off
	global_load_dwordx4 v[148:151], v[132:133], off offset:128
	global_load_dwordx4 v[144:147], v[132:133], off offset:192
	global_load_dwordx4 v[160:163], v[134:135], off offset:128
	global_load_dwordx4 v[140:143], v[134:135], off offset:192
	global_load_dwordx4 v[156:159], v[136:137], off offset:128
	global_load_dwordx4 v[120:123], v[136:137], off offset:192
	global_load_dwordx4 v[152:155], v[138:139], off offset:128
	global_load_dwordx4 v[112:115], v[138:139], off offset:192
	v_and_b32_e32 v100, 0xf8, v124
	v_lshlrev_b32_e32 v100, 1, v100
	v_mov_b32_e32 v101, v1
	v_ashrrev_i32_e32 v205, 31, v204
	v_ashrrev_i32_e32 v203, 31, v202
	v_ashrrev_i32_e32 v201, 31, v200
	v_ashrrev_i32_e32 v199, 31, v198
	v_ashrrev_i32_e32 v197, 31, v196
	v_ashrrev_i32_e32 v195, 31, v194
	v_ashrrev_i32_e32 v193, 31, v192
	v_ashrrev_i32_e32 v191, 31, v190
	v_lshl_add_u64 v[132:133], s[88:89], 0, v[100:101]
	v_lshl_add_u64 v[100:101], s[4:5], 0, v[204:205]
	v_lshl_add_u64 v[102:103], s[4:5], 0, v[202:203]
	v_lshl_add_u64 v[108:109], s[4:5], 0, v[200:201]
	v_lshl_add_u64 v[110:111], s[4:5], 0, v[198:199]
	v_lshl_add_u64 v[124:125], s[4:5], 0, v[196:197]
	v_lshl_add_u64 v[126:127], s[4:5], 0, v[194:195]
	v_lshl_add_u64 v[134:135], s[4:5], 0, v[192:193]
	v_lshl_add_u64 v[136:137], s[4:5], 0, v[190:191]
	v_lshlrev_b64 v[100:101], 11, v[100:101]
	v_lshlrev_b64 v[102:103], 11, v[102:103]
	v_lshlrev_b64 v[108:109], 11, v[108:109]
	v_lshlrev_b64 v[110:111], 11, v[110:111]
	v_lshlrev_b64 v[124:125], 11, v[124:125]
	v_lshlrev_b64 v[126:127], 11, v[126:127]
	v_lshlrev_b64 v[134:135], 11, v[134:135]
	v_lshlrev_b64 v[136:137], 11, v[136:137]
	v_lshl_add_u64 v[100:101], v[132:133], 0, v[100:101]
	v_lshl_add_u64 v[104:105], v[132:133], 0, v[102:103]
	v_lshl_add_u64 v[108:109], v[132:133], 0, v[108:109]
	v_lshl_add_u64 v[116:117], v[132:133], 0, v[110:111]
	v_lshl_add_u64 v[124:125], v[132:133], 0, v[124:125]
	v_lshl_add_u64 v[128:129], v[132:133], 0, v[126:127]
	v_lshl_add_u64 v[134:135], v[132:133], 0, v[134:135]
	v_lshl_add_u64 v[136:137], v[132:133], 0, v[136:137]
	global_load_dwordx4 v[100:103], v[100:101], off
	s_nop 0
	global_load_dwordx4 v[104:107], v[104:105], off
	s_nop 0
	global_load_dwordx4 v[108:111], v[108:109], off
	s_nop 0
	global_load_dwordx4 v[116:119], v[116:117], off
	s_nop 0
	global_load_dwordx4 v[124:127], v[124:125], off
	s_nop 0
	global_load_dwordx4 v[128:131], v[128:129], off
	s_nop 0
	global_load_dwordx4 v[132:135], v[134:135], off
	s_nop 0
	global_load_dwordx4 v[136:139], v[136:137], off
	v_add_u32_e32 v174, v209, v166
	ds_read_b128 v[166:169], v174 offset:34816
; __device__ __forceinline__ void ret_core_phase(const Params& p, const PD& d, char* shm, const int wave_s) {
;     ...
; #pragma unroll
;       for (int df = 0; df < 4; ++df)
; #pragma unroll
;         for (int vf = 0; vf < 4; ++vf) S[df][vf] *= cdec;
; #pragma unroll
;       for (int ks = 0; ks < 4; ++ks) {
;         bf16x8 Vf[4];
; #pragma unroll
;         for (int vf = 0; vf < 4; ++vf) Vf[vf] = *(const bf16x8*)(Vl + (64 * wj + 16 * vf + frv) * 272 + (ks * 32 + fqv * 8) * 2);
; #pragma unroll
;         for (int df = 0; df < 4; ++df)
; #pragma unroll
;           for (int vf = 0; vf < 4; ++vf) S[df][vf] = __builtin_amdgcn_mfma_f32_16x16x32_bf16(ktf[ks][df], Vf[vf], S[df][vf], 0, 0, 0);
;       }
	ds_read_b128 v[170:173], v174 offset:39168
	ds_read_b128 v[190:193], v174 offset:43520
	ds_read_b128 v[194:197], v174 offset:47872
	v_pk_mul_f32 v[6:7], s[76:77], v[6:7]
	v_pk_mul_f32 v[4:5], s[10:11], v[4:5]
	v_pk_mul_f32 v[10:11], s[76:77], v[10:11]
	v_pk_mul_f32 v[8:9], s[10:11], v[8:9]
	v_pk_mul_f32 v[14:15], s[76:77], v[14:15]
	v_pk_mul_f32 v[12:13], s[10:11], v[12:13]
	v_pk_mul_f32 v[18:19], s[76:77], v[18:19]
	v_pk_mul_f32 v[16:17], s[10:11], v[16:17]
	v_pk_mul_f32 v[22:23], s[76:77], v[22:23]
	v_pk_mul_f32 v[20:21], s[10:11], v[20:21]
	v_pk_mul_f32 v[26:27], s[76:77], v[26:27]
	v_pk_mul_f32 v[24:25], s[10:11], v[24:25]
	v_pk_mul_f32 v[30:31], s[76:77], v[30:31]
	v_pk_mul_f32 v[28:29], s[10:11], v[28:29]
	v_pk_mul_f32 v[34:35], s[76:77], v[34:35]
	v_pk_mul_f32 v[32:33], s[10:11], v[32:33]
	v_pk_mul_f32 v[38:39], s[76:77], v[38:39]
	v_pk_mul_f32 v[36:37], s[10:11], v[36:37]
	v_pk_mul_f32 v[42:43], s[76:77], v[42:43]
	v_pk_mul_f32 v[40:41], s[10:11], v[40:41]
	v_pk_mul_f32 v[46:47], s[76:77], v[46:47]
	v_pk_mul_f32 v[44:45], s[10:11], v[44:45]
	v_pk_mul_f32 v[50:51], s[76:77], v[50:51]
	v_pk_mul_f32 v[48:49], s[10:11], v[48:49]
	v_pk_mul_f32 v[54:55], s[76:77], v[54:55]
	v_pk_mul_f32 v[52:53], s[10:11], v[52:53]
	v_pk_mul_f32 v[58:59], s[76:77], v[58:59]
	v_pk_mul_f32 v[56:57], s[10:11], v[56:57]
	v_pk_mul_f32 v[62:63], s[76:77], v[62:63]
	v_pk_mul_f32 v[60:61], s[10:11], v[60:61]
	v_pk_mul_f32 v[66:67], s[76:77], v[66:67]
	v_pk_mul_f32 v[64:65], s[10:11], v[64:65]
	s_waitcnt vmcnt(31) lgkmcnt(3)
	v_mfma_f32_16x16x32_bf16 v[4:7], v[92:95], v[166:169], v[4:7]
	v_readlane_b32 s6, v254, 41
	s_waitcnt lgkmcnt(2)
	v_mfma_f32_16x16x32_bf16 v[8:11], v[92:95], v[170:173], v[8:11]
	s_waitcnt lgkmcnt(1)
	v_mfma_f32_16x16x32_bf16 v[12:15], v[92:95], v[190:193], v[12:15]
	s_waitcnt lgkmcnt(0)
	v_mfma_f32_16x16x32_bf16 v[16:19], v[92:95], v[194:197], v[16:19]
	s_waitcnt vmcnt(29)
	v_mfma_f32_16x16x32_bf16 v[20:23], v[96:99], v[166:169], v[20:23]
	v_mfma_f32_16x16x32_bf16 v[24:27], v[96:99], v[170:173], v[24:27]
	v_mfma_f32_16x16x32_bf16 v[28:31], v[96:99], v[190:193], v[28:31]
	v_mfma_f32_16x16x32_bf16 v[32:35], v[96:99], v[194:197], v[32:35]
	s_waitcnt vmcnt(27)
	v_mfma_f32_16x16x32_bf16 v[36:39], v[88:91], v[166:169], v[36:39]
	v_mfma_f32_16x16x32_bf16 v[40:43], v[88:91], v[170:173], v[40:43]
	v_mfma_f32_16x16x32_bf16 v[44:47], v[88:91], v[190:193], v[44:47]
	v_mfma_f32_16x16x32_bf16 v[48:51], v[88:91], v[194:197], v[48:51]
	s_waitcnt vmcnt(25)
	v_mfma_f32_16x16x32_bf16 v[52:55], v[84:87], v[166:169], v[52:55]
	v_mfma_f32_16x16x32_bf16 v[56:59], v[84:87], v[170:173], v[56:59]
	v_mfma_f32_16x16x32_bf16 v[60:63], v[84:87], v[190:193], v[60:63]
	v_mfma_f32_16x16x32_bf16 v[64:67], v[84:87], v[194:197], v[64:67]
	ds_read_b128 v[84:87], v174 offset:34880
	ds_read_b128 v[88:91], v174 offset:39232
	ds_read_b128 v[92:95], v174 offset:43584
	ds_read_b128 v[96:99], v174 offset:47936
	s_waitcnt lgkmcnt(3)
	v_mfma_f32_16x16x32_bf16 v[4:7], v[80:83], v[84:87], v[4:7]
	s_waitcnt lgkmcnt(2)
	v_mfma_f32_16x16x32_bf16 v[8:11], v[80:83], v[88:91], v[8:11]
	s_waitcnt lgkmcnt(1)
	v_mfma_f32_16x16x32_bf16 v[12:15], v[80:83], v[92:95], v[12:15]
	s_waitcnt lgkmcnt(0)
	v_mfma_f32_16x16x32_bf16 v[16:19], v[80:83], v[96:99], v[16:19]
	v_mfma_f32_16x16x32_bf16 v[20:23], v[76:79], v[84:87], v[20:23]
	v_mfma_f32_16x16x32_bf16 v[24:27], v[76:79], v[88:91], v[24:27]
	v_mfma_f32_16x16x32_bf16 v[28:31], v[76:79], v[92:95], v[28:31]
	v_mfma_f32_16x16x32_bf16 v[32:35], v[76:79], v[96:99], v[32:35]
	v_mfma_f32_16x16x32_bf16 v[36:39], v[72:75], v[84:87], v[36:39]
	v_mfma_f32_16x16x32_bf16 v[40:43], v[72:75], v[88:91], v[40:43]
	v_mfma_f32_16x16x32_bf16 v[44:47], v[72:75], v[92:95], v[44:47]
	v_mfma_f32_16x16x32_bf16 v[48:51], v[72:75], v[96:99], v[48:51]
	s_waitcnt vmcnt(24)
	v_mfma_f32_16x16x32_bf16 v[52:55], v[68:71], v[84:87], v[52:55]
	v_mfma_f32_16x16x32_bf16 v[56:59], v[68:71], v[88:91], v[56:59]
	v_mfma_f32_16x16x32_bf16 v[60:63], v[68:71], v[92:95], v[60:63]
	v_mfma_f32_16x16x32_bf16 v[64:67], v[68:71], v[96:99], v[64:67]
	ds_read_b128 v[68:71], v174 offset:34944
	ds_read_b128 v[72:75], v174 offset:39296
	ds_read_b128 v[76:79], v174 offset:43648
	ds_read_b128 v[80:83], v174 offset:48000
	s_waitcnt vmcnt(15) lgkmcnt(3)
	v_mfma_f32_16x16x32_bf16 v[4:7], v[148:151], v[68:71], v[4:7]
	s_waitcnt lgkmcnt(2)
	v_mfma_f32_16x16x32_bf16 v[8:11], v[148:151], v[72:75], v[8:11]
	s_waitcnt lgkmcnt(1)
	v_mfma_f32_16x16x32_bf16 v[12:15], v[148:151], v[76:79], v[12:15]
	s_waitcnt lgkmcnt(0)
	v_mfma_f32_16x16x32_bf16 v[16:19], v[148:151], v[80:83], v[16:19]
	s_waitcnt vmcnt(13)
	v_mfma_f32_16x16x32_bf16 v[20:23], v[160:163], v[68:71], v[20:23]
	v_mfma_f32_16x16x32_bf16 v[24:27], v[160:163], v[72:75], v[24:27]
	v_mfma_f32_16x16x32_bf16 v[28:31], v[160:163], v[76:79], v[28:31]
	v_mfma_f32_16x16x32_bf16 v[32:35], v[160:163], v[80:83], v[32:35]
	s_waitcnt vmcnt(11)
	v_mfma_f32_16x16x32_bf16 v[36:39], v[156:159], v[68:71], v[36:39]
	v_mfma_f32_16x16x32_bf16 v[40:43], v[156:159], v[72:75], v[40:43]
	v_mfma_f32_16x16x32_bf16 v[44:47], v[156:159], v[76:79], v[44:47]
	v_mfma_f32_16x16x32_bf16 v[48:51], v[156:159], v[80:83], v[48:51]
	s_waitcnt vmcnt(9)
	v_mfma_f32_16x16x32_bf16 v[52:55], v[152:155], v[68:71], v[52:55]
	v_mfma_f32_16x16x32_bf16 v[56:59], v[152:155], v[72:75], v[56:59]
	v_mfma_f32_16x16x32_bf16 v[60:63], v[152:155], v[76:79], v[60:63]
	v_mfma_f32_16x16x32_bf16 v[64:67], v[152:155], v[80:83], v[64:67]
	ds_read_b128 v[68:71], v174 offset:35008
	ds_read_b128 v[72:75], v174 offset:39360
	ds_read_b128 v[76:79], v174 offset:43712
	ds_read_b128 v[80:83], v174 offset:48064
	s_waitcnt lgkmcnt(3)
; __device__ __forceinline__ unsigned pack2(float a, float b) { return (unsigned)f2bf(a) | ((unsigned)f2bf(b) << 16); }
; __device__ __forceinline__ void ret_core_phase(const Params& p, const PD& d, char* shm, const int wave_s) {
;     ...
;           for (int vf = 0; vf < 4; ++vf) S[df][vf] = __builtin_amdgcn_mfma_f32_16x16x32_bf16(ktf[ks][df], Vf[vf], S[df][vf], 0, 0, 0);
;       }
; #pragma unroll
;       for (int df = 0; df < 4; ++df)
; #pragma unroll
;         for (int vf = 0; vf < 4; ++vf) {
;           uint2 pk; pk.x = pack2(S[df][vf][0], S[df][vf][1]); pk.y = pack2(S[df][vf][2], S[df][vf][3]);
;           *(uint2*)(R2 + (64 * wj + 16 * vf + frv) * 528 + (64 * wi + 16 * df + 4 * fqv) * 2) = pk;
;         }
	v_mfma_f32_16x16x32_bf16 v[4:7], v[144:147], v[68:71], v[4:7]
	v_mfma_f32_16x16x32_bf16 v[20:23], v[140:143], v[68:71], v[20:23]
	v_mfma_f32_16x16x32_bf16 v[36:39], v[120:123], v[68:71], v[36:39]
	s_waitcnt vmcnt(8)
	v_mfma_f32_16x16x32_bf16 v[52:55], v[112:115], v[68:71], v[52:55]
	s_nop 3
	s_nop 0
	v_or_b32_e32 v68, v165, v182
	v_lshlrev_b32_e32 v70, 1, v68
	s_waitcnt lgkmcnt(2)
	v_mfma_f32_16x16x32_bf16 v[8:11], v[144:147], v[72:75], v[8:11]
	s_nop 0
	v_cvt_pk_bf16_f32 v68, v6, v6
	v_add3_u32 v71, s73, v70, v164
	v_mfma_f32_16x16x32_bf16 v[24:27], v[140:143], v[72:75], v[24:27]
	v_mfma_f32_16x16x32_bf16 v[40:43], v[120:123], v[72:75], v[40:43]
	v_mfma_f32_16x16x32_bf16 v[56:59], v[112:115], v[72:75], v[56:59]
	v_cvt_pk_bf16_f32 v72, v4, v4
	s_nop 0
	s_nop 0
	v_cvt_pk_bf16_f32 v69, v7, v7
	v_cvt_pk_bf16_f32 v73, v5, v5
	v_and_b32_e32 v69, 0xffff0000, v69
	v_and_b32_e32 v73, 0xffff0000, v73
	v_or_b32_sdwa v69, v69, v68 dst_sel:DWORD dst_unused:UNUSED_PAD src0_sel:DWORD src1_sel:WORD_1
	v_or_b32_sdwa v68, v73, v72 dst_sel:DWORD dst_unused:UNUSED_PAD src0_sel:DWORD src1_sel:WORD_1
	ds_write_b64 v71, v[68:69]
	s_nop 0
	s_waitcnt lgkmcnt(2)
	v_mfma_f32_16x16x32_bf16 v[12:15], v[144:147], v[76:79], v[12:15]
	v_cvt_pk_bf16_f32 v72, v8, v8
	s_nop 0
	s_nop 0
	s_nop 0
	v_cvt_pk_bf16_f32 v69, v11, v11
	v_cvt_pk_bf16_f32 v73, v9, v9
	v_cvt_pk_bf16_f32 v68, v10, v10
	v_and_b32_e32 v69, 0xffff0000, v69
	v_and_b32_e32 v73, 0xffff0000, v73
	v_or_b32_sdwa v69, v69, v68 dst_sel:DWORD dst_unused:UNUSED_PAD src0_sel:DWORD src1_sel:WORD_1
	v_or_b32_sdwa v68, v73, v72 dst_sel:DWORD dst_unused:UNUSED_PAD src0_sel:DWORD src1_sel:WORD_1
	ds_write_b64 v71, v[68:69] offset:8448
	s_nop 0
	s_waitcnt lgkmcnt(2)
	v_mfma_f32_16x16x32_bf16 v[16:19], v[144:147], v[80:83], v[16:19]
	v_cvt_pk_bf16_f32 v72, v12, v12
	s_nop 0
	s_nop 0
	s_nop 0
	v_cvt_pk_bf16_f32 v69, v15, v15
	v_cvt_pk_bf16_f32 v73, v13, v13
	v_cvt_pk_bf16_f32 v68, v14, v14
	v_and_b32_e32 v69, 0xffff0000, v69
	v_and_b32_e32 v73, 0xffff0000, v73
	v_or_b32_sdwa v69, v69, v68 dst_sel:DWORD dst_unused:UNUSED_PAD src0_sel:DWORD src1_sel:WORD_1
	v_or_b32_sdwa v68, v73, v72 dst_sel:DWORD dst_unused:UNUSED_PAD src0_sel:DWORD src1_sel:WORD_1
	ds_write_b64 v71, v[68:69] offset:16896
	v_cvt_pk_bf16_f32 v72, v16, v16
	v_cvt_pk_bf16_f32 v69, v19, v19
	v_cvt_pk_bf16_f32 v73, v17, v17
	v_cvt_pk_bf16_f32 v68, v18, v18
	v_and_b32_e32 v69, 0xffff0000, v69
	v_and_b32_e32 v73, 0xffff0000, v73
	v_or_b32_sdwa v69, v69, v68 dst_sel:DWORD dst_unused:UNUSED_PAD src0_sel:DWORD src1_sel:WORD_1
	v_or_b32_sdwa v68, v73, v72 dst_sel:DWORD dst_unused:UNUSED_PAD src0_sel:DWORD src1_sel:WORD_1
	ds_write_b64 v71, v[68:69] offset:25344
	v_cvt_pk_bf16_f32 v72, v20, v20
	v_cvt_pk_bf16_f32 v69, v23, v23
	v_cvt_pk_bf16_f32 v73, v21, v21
	v_cvt_pk_bf16_f32 v68, v22, v22
	v_and_b32_e32 v69, 0xffff0000, v69
	v_and_b32_e32 v73, 0xffff0000, v73
	v_add3_u32 v71, s6, v70, v164
	v_or_b32_sdwa v69, v69, v68 dst_sel:DWORD dst_unused:UNUSED_PAD src0_sel:DWORD src1_sel:WORD_1
	v_or_b32_sdwa v68, v73, v72 dst_sel:DWORD dst_unused:UNUSED_PAD src0_sel:DWORD src1_sel:WORD_1
	ds_write_b64 v71, v[68:69]
	s_nop 0
	v_mfma_f32_16x16x32_bf16 v[28:31], v[140:143], v[76:79], v[28:31]
	v_cvt_pk_bf16_f32 v72, v24, v24
	s_nop 0
	s_nop 0
	s_nop 0
	v_cvt_pk_bf16_f32 v69, v27, v27
	v_cvt_pk_bf16_f32 v73, v25, v25
	v_cvt_pk_bf16_f32 v68, v26, v26
	v_and_b32_e32 v69, 0xffff0000, v69
	v_and_b32_e32 v73, 0xffff0000, v73
	v_or_b32_sdwa v69, v69, v68 dst_sel:DWORD dst_unused:UNUSED_PAD src0_sel:DWORD src1_sel:WORD_1
	v_or_b32_sdwa v68, v73, v72 dst_sel:DWORD dst_unused:UNUSED_PAD src0_sel:DWORD src1_sel:WORD_1
	ds_write_b64 v71, v[68:69] offset:8448
	s_nop 0
	v_mfma_f32_16x16x32_bf16 v[32:35], v[140:143], v[80:83], v[32:35]
	v_cvt_pk_bf16_f32 v72, v28, v28
	s_nop 0
	s_nop 0
	s_nop 0
	v_cvt_pk_bf16_f32 v69, v31, v31
	v_cvt_pk_bf16_f32 v73, v29, v29
	v_cvt_pk_bf16_f32 v68, v30, v30
	v_and_b32_e32 v69, 0xffff0000, v69
	v_and_b32_e32 v73, 0xffff0000, v73
	v_or_b32_sdwa v69, v69, v68 dst_sel:DWORD dst_unused:UNUSED_PAD src0_sel:DWORD src1_sel:WORD_1
	v_or_b32_sdwa v68, v73, v72 dst_sel:DWORD dst_unused:UNUSED_PAD src0_sel:DWORD src1_sel:WORD_1
	ds_write_b64 v71, v[68:69] offset:16896
	v_cvt_pk_bf16_f32 v72, v32, v32
	v_cvt_pk_bf16_f32 v69, v35, v35
	v_cvt_pk_bf16_f32 v73, v33, v33
	v_cvt_pk_bf16_f32 v68, v34, v34
	v_and_b32_e32 v69, 0xffff0000, v69
	v_and_b32_e32 v73, 0xffff0000, v73
	v_or_b32_sdwa v69, v69, v68 dst_sel:DWORD dst_unused:UNUSED_PAD src0_sel:DWORD src1_sel:WORD_1
	v_or_b32_sdwa v68, v73, v72 dst_sel:DWORD dst_unused:UNUSED_PAD src0_sel:DWORD src1_sel:WORD_1
	ds_write_b64 v71, v[68:69] offset:25344
	v_cvt_pk_bf16_f32 v72, v36, v36
	s_nop 0
	v_cvt_pk_bf16_f32 v69, v39, v39
	v_cvt_pk_bf16_f32 v73, v37, v37
	v_readlane_b32 s6, v254, 42
	v_cvt_pk_bf16_f32 v68, v38, v38
	v_and_b32_e32 v69, 0xffff0000, v69
	v_and_b32_e32 v73, 0xffff0000, v73
	v_add3_u32 v71, s6, v70, v164
	v_or_b32_sdwa v69, v69, v68 dst_sel:DWORD dst_unused:UNUSED_PAD src0_sel:DWORD src1_sel:WORD_1
	v_or_b32_sdwa v68, v73, v72 dst_sel:DWORD dst_unused:UNUSED_PAD src0_sel:DWORD src1_sel:WORD_1
	ds_write_b64 v71, v[68:69]
	s_nop 0
	v_mfma_f32_16x16x32_bf16 v[44:47], v[120:123], v[76:79], v[44:47]
	v_cvt_pk_bf16_f32 v72, v40, v40
	s_nop 0
	s_nop 0
	s_nop 0
	v_cvt_pk_bf16_f32 v69, v43, v43
	v_cvt_pk_bf16_f32 v73, v41, v41
	v_cvt_pk_bf16_f32 v68, v42, v42
	v_and_b32_e32 v69, 0xffff0000, v69
	v_and_b32_e32 v73, 0xffff0000, v73
	v_or_b32_sdwa v69, v69, v68 dst_sel:DWORD dst_unused:UNUSED_PAD src0_sel:DWORD src1_sel:WORD_1
	v_or_b32_sdwa v68, v73, v72 dst_sel:DWORD dst_unused:UNUSED_PAD src0_sel:DWORD src1_sel:WORD_1
; __device__ __forceinline__ unsigned pack2(float a, float b) { return (unsigned)f2bf(a) | ((unsigned)f2bf(b) << 16); }
; #define SCHED __builtin_amdgcn_sched_barrier(0)
; __device__ __forceinline__ void ret_core_phase(const Params& p, const PD& d, char* shm, const int wave_s) {
;     ...
; #pragma unroll
;       for (int df = 0; df < 4; ++df)
; #pragma unroll
;         for (int vf = 0; vf < 4; ++vf) {
;           uint2 pk; pk.x = pack2(S[df][vf][0], S[df][vf][1]); pk.y = pack2(S[df][vf][2], S[df][vf][3]);
;           *(uint2*)(R2 + (64 * wj + 16 * vf + frv) * 528 + (64 * wi + 16 * df + 4 * fqv) * 2) = pk;
;         }
;       SCHED;
;       {
;         const u16* Qw = Qb + (lt1 + 32 * wi + frv) * 1024 + hh * 256 + fqv * 8;
; #pragma unroll
;         for (int f = 0; f < 2; ++f)
; #pragma unroll
;           for (int ks = 0; ks < 8; ++ks) Qf[f][ks] = *(const bf16x8*)(Qw + f * 16 * 1024 + ks * 32);
;       }
;       __syncthreads();
	ds_write_b64 v71, v[68:69] offset:8448
	s_nop 0
	v_mfma_f32_16x16x32_bf16 v[48:51], v[120:123], v[80:83], v[48:51]
	v_cvt_pk_bf16_f32 v72, v44, v44
	s_nop 0
	s_nop 0
	s_nop 0
	v_cvt_pk_bf16_f32 v69, v47, v47
	v_cvt_pk_bf16_f32 v73, v45, v45
	v_cvt_pk_bf16_f32 v68, v46, v46
	v_and_b32_e32 v69, 0xffff0000, v69
	v_and_b32_e32 v73, 0xffff0000, v73
	v_or_b32_sdwa v69, v69, v68 dst_sel:DWORD dst_unused:UNUSED_PAD src0_sel:DWORD src1_sel:WORD_1
	v_or_b32_sdwa v68, v73, v72 dst_sel:DWORD dst_unused:UNUSED_PAD src0_sel:DWORD src1_sel:WORD_1
	ds_write_b64 v71, v[68:69] offset:16896
	v_cvt_pk_bf16_f32 v72, v48, v48
	v_cvt_pk_bf16_f32 v69, v51, v51
	v_cvt_pk_bf16_f32 v73, v49, v49
	v_cvt_pk_bf16_f32 v68, v50, v50
	v_and_b32_e32 v69, 0xffff0000, v69
	v_and_b32_e32 v73, 0xffff0000, v73
	v_or_b32_sdwa v69, v69, v68 dst_sel:DWORD dst_unused:UNUSED_PAD src0_sel:DWORD src1_sel:WORD_1
	v_or_b32_sdwa v68, v73, v72 dst_sel:DWORD dst_unused:UNUSED_PAD src0_sel:DWORD src1_sel:WORD_1
	ds_write_b64 v71, v[68:69] offset:25344
	v_cvt_pk_bf16_f32 v71, v52, v52
	s_nop 0
	v_cvt_pk_bf16_f32 v69, v55, v55
	v_cvt_pk_bf16_f32 v72, v53, v53
	v_readlane_b32 s6, v254, 43
	v_cvt_pk_bf16_f32 v68, v54, v54
	v_and_b32_e32 v69, 0xffff0000, v69
	v_and_b32_e32 v72, 0xffff0000, v72
	v_add3_u32 v70, s6, v70, v164
	v_or_b32_sdwa v69, v69, v68 dst_sel:DWORD dst_unused:UNUSED_PAD src0_sel:DWORD src1_sel:WORD_1
	v_or_b32_sdwa v68, v72, v71 dst_sel:DWORD dst_unused:UNUSED_PAD src0_sel:DWORD src1_sel:WORD_1
	ds_write_b64 v70, v[68:69]
	s_nop 0
	v_mfma_f32_16x16x32_bf16 v[60:63], v[112:115], v[76:79], v[60:63]
	v_cvt_pk_bf16_f32 v71, v56, v56
	s_nop 0
	s_nop 0
	s_nop 0
	v_cvt_pk_bf16_f32 v69, v59, v59
	v_cvt_pk_bf16_f32 v72, v57, v57
	v_cvt_pk_bf16_f32 v68, v58, v58
	v_and_b32_e32 v69, 0xffff0000, v69
	v_and_b32_e32 v72, 0xffff0000, v72
	v_or_b32_sdwa v69, v69, v68 dst_sel:DWORD dst_unused:UNUSED_PAD src0_sel:DWORD src1_sel:WORD_1
	v_or_b32_sdwa v68, v72, v71 dst_sel:DWORD dst_unused:UNUSED_PAD src0_sel:DWORD src1_sel:WORD_1
	ds_write_b64 v70, v[68:69] offset:8448
	s_nop 0
	v_mfma_f32_16x16x32_bf16 v[64:67], v[112:115], v[80:83], v[64:67]
	v_cvt_pk_bf16_f32 v71, v60, v60
	s_nop 0
	s_nop 0
	s_nop 0
	v_cvt_pk_bf16_f32 v69, v63, v63
	v_cvt_pk_bf16_f32 v72, v61, v61
	v_cvt_pk_bf16_f32 v68, v62, v62
	v_and_b32_e32 v69, 0xffff0000, v69
	v_and_b32_e32 v72, 0xffff0000, v72
	v_or_b32_sdwa v69, v69, v68 dst_sel:DWORD dst_unused:UNUSED_PAD src0_sel:DWORD src1_sel:WORD_1
	v_or_b32_sdwa v68, v72, v71 dst_sel:DWORD dst_unused:UNUSED_PAD src0_sel:DWORD src1_sel:WORD_1
	ds_write_b64 v70, v[68:69] offset:16896
	v_cvt_pk_bf16_f32 v71, v64, v64
	v_cvt_pk_bf16_f32 v69, v67, v67
	v_cvt_pk_bf16_f32 v72, v65, v65
	v_cvt_pk_bf16_f32 v68, v66, v66
	v_and_b32_e32 v69, 0xffff0000, v69
	v_and_b32_e32 v72, 0xffff0000, v72
	v_or_b32_sdwa v69, v69, v68 dst_sel:DWORD dst_unused:UNUSED_PAD src0_sel:DWORD src1_sel:WORD_1
	v_or_b32_sdwa v68, v72, v71 dst_sel:DWORD dst_unused:UNUSED_PAD src0_sel:DWORD src1_sel:WORD_1
	ds_write_b64 v70, v[68:69] offset:25344
	v_lshl_add_u64 v[68:69], s[4:5], 0, v[2:3]
	v_or_b32_e32 v68, v68, v0
	v_lshlrev_b64 v[68:69], 11, v[68:69]
	v_lshl_add_u64 v[68:69], s[84:85], 0, v[68:69]
	v_lshlrev_b32_e32 v0, 1, v188
	v_lshl_add_u64 v[72:73], v[68:69], 0, v[0:1]
	global_load_dwordx4 v[156:159], v[72:73], off
	global_load_dwordx4 v[144:147], v[72:73], off offset:64
	global_load_dwordx4 v[140:143], v[72:73], off offset:128
	global_load_dwordx4 v[96:99], v[72:73], off offset:192
	global_load_dwordx4 v[92:95], v[72:73], off offset:256
	global_load_dwordx4 v[80:83], v[72:73], off offset:320
	global_load_dwordx4 v[76:79], v[72:73], off offset:384
	global_load_dwordx4 v[68:71], v[72:73], off offset:448
	v_add_co_u32_e32 v72, vcc, s20, v72
	s_add_u32 s68, s68, 0x200
	s_nop 0
	v_addc_co_u32_e32 v73, vcc, 0, v73, vcc
	global_load_dwordx4 v[160:163], v[72:73], off
	global_load_dwordx4 v[152:155], v[72:73], off offset:64
	global_load_dwordx4 v[148:151], v[72:73], off offset:128
	global_load_dwordx4 v[120:123], v[72:73], off offset:192
	global_load_dwordx4 v[112:115], v[72:73], off offset:256
	global_load_dwordx4 v[88:91], v[72:73], off offset:320
	global_load_dwordx4 v[84:87], v[72:73], off offset:384
	s_nop 0
	global_load_dwordx4 v[72:75], v[72:73], off offset:448
	s_addc_u32 s69, s69, 0
	s_cmpk_eq_i32 s68, 0x2000
	v_lshl_add_u64 v[186:187], v[186:187], 0, s[78:79]
	s_waitcnt lgkmcnt(0)
	s_barrier
	s_cbranch_scc1 .LBB0_555
; __device__ __forceinline__ void ret_core_phase(const Params& p, const PD& d, char* shm, const int wave_s) {
;     ...
;       const int tidv = fresh_tid(wave_s);
;       const int frv = tidv & 15, fqv = (tidv >> 4) & 3;
;       float lg2v = lg2;
;       asm volatile("" : "+v"(lg2v));
; #pragma unroll
;       for (int i = 0; i < 8; ++i) {
;         int c = i * 512 + tidv, row = c >> 5, cc = c & 31;
;         *(bf16x8*)(R1 + row * 528 + cc * 16) = kpre[i];
;       }
;       bf16x8 vpre[4];
; #pragma unroll
;       for (int i = 0; i < 4; ++i) {
;         int c = i * 512 + tidv, row = c >> 4, cc = c & 15;
;         vpre[i] = *(const bf16x8*)(VTb + ((size_t)(bh * 16 + lc) * 512 + vs * 128 + row) * 128 + cc * 8);
;       }
;       __syncthreads();
;       f32x4 PT[4][2];
; #pragma unroll
;       for (int a = 0; a < 4; ++a)
; #pragma unroll
;         for (int c = 0; c < 2; ++c) PT[a][c] = f32x4{0.f, 0.f, 0.f, 0.f};
; #pragma unroll
;       for (int ks = 0; ks < 8; ++ks) {
; #pragma unroll
;         for (int jf = 0; jf < 4; ++jf) {
;           bf16x8 Kf = *(const bf16x8*)(R1 + (64 * wj + 16 * jf + frv) * 528 + (ks * 32 + fqv * 8) * 2);
; #pragma unroll
;           for (int f = 0; f < 2; ++f) PT[jf][f] = __builtin_amdgcn_mfma_f32_16x16x32_bf16(Kf, Qf[f][ks], PT[jf][f], 0, 0, 0);
;         }
;       }
.LBB0_563:
	s_mov_b32 s4, s82
	s_mov_b32 s5, -1
	v_mov_b32_e32 v197, v183
	v_mbcnt_lo_u32_b32 v0, s5, 0
	v_mbcnt_hi_u32_b32 v0, s5, v0
	v_lshl_add_u32 v191, s4, 6, v0
	s_nop 0
	v_lshlrev_b32_e32 v166, 4, v191
	v_and_b32_e32 v0, 0x1f0, v166
	v_add_u32_e32 v0, 0, v0
	v_ashrrev_i32_e32 v204, 5, v191
	v_mad_u64_u32 v[164:165], s[4:5], v204, s29, v[0:1]
	s_waitcnt vmcnt(23)
	ds_write_b128 v164, v[100:103]
	v_add_u32_e32 v164, 0x200, v191
	v_ashrrev_i32_e32 v202, 5, v164
	v_add_u32_e32 v165, 0x400, v191
	v_mad_u64_u32 v[100:101], s[4:5], v202, s29, v[0:1]
	v_ashrrev_i32_e32 v200, 5, v165
	v_add_u32_e32 v167, 0x600, v191
	s_waitcnt vmcnt(22)
	ds_write_b128 v100, v[104:107]
	v_mad_u64_u32 v[100:101], s[4:5], v200, s29, v[0:1]
	v_ashrrev_i32_e32 v198, 5, v167
	s_waitcnt vmcnt(21)
	ds_write_b128 v100, v[108:111]
	v_mad_u64_u32 v[100:101], s[4:5], v198, s29, v[0:1]
	s_waitcnt vmcnt(20)
	ds_write_b128 v100, v[116:119]
	v_add_u32_e32 v100, 0x800, v191
	v_ashrrev_i32_e32 v196, 5, v100
	v_mad_u64_u32 v[100:101], s[4:5], v196, s29, v[0:1]
	s_waitcnt vmcnt(19)
	ds_write_b128 v100, v[124:127]
	v_add_u32_e32 v100, 0xa00, v191
	v_ashrrev_i32_e32 v194, 5, v100
	v_mad_u64_u32 v[100:101], s[4:5], v194, s29, v[0:1]
	s_waitcnt vmcnt(18)
	ds_write_b128 v100, v[128:131]
	v_add_u32_e32 v100, 0xc00, v191
	v_ashrrev_i32_e32 v192, 5, v100
	v_mad_u64_u32 v[100:101], s[4:5], v192, s29, v[0:1]
	s_waitcnt vmcnt(17)
	ds_write_b128 v100, v[132:135]
	v_add_u32_e32 v100, 0xe00, v191
	v_ashrrev_i32_e32 v190, 5, v100
	v_mad_u64_u32 v[100:101], s[4:5], v190, s29, v[0:1]
	v_readlane_b32 s4, v252, 61
	v_and_b32_e32 v0, 0xf0, v166
	v_readlane_b32 s5, v252, 62
	v_ashrrev_i32_e32 v208, 4, v191
	v_ashrrev_i32_e32 v210, 4, v164
	v_lshl_add_u64 v[116:117], s[4:5], 0, v[0:1]
	s_add_u32 s4, s2, s68
	v_ashrrev_i32_e32 v212, 4, v165
	v_ashrrev_i32_e32 v214, 4, v167
	v_ashrrev_i32_e32 v209, 31, v208
	s_addc_u32 s5, s3, s69
	v_ashrrev_i32_e32 v211, 31, v210
	v_ashrrev_i32_e32 v213, 31, v212
	v_ashrrev_i32_e32 v215, 31, v214
	v_bfe_u32 v195, v191, 4, 2
	s_waitcnt vmcnt(16)
	ds_write_b128 v100, v[136:139]
	v_and_b32_e32 v189, 15, v191
	v_lshl_add_u64 v[100:101], s[4:5], 0, v[208:209]
	v_lshl_add_u64 v[104:105], s[4:5], 0, v[210:211]
	v_lshl_add_u64 v[108:109], s[4:5], 0, v[212:213]
	v_lshl_add_u64 v[118:119], s[4:5], 0, v[214:215]
	v_lshlrev_b32_e32 v206, 4, v195
	v_lshlrev_b64 v[100:101], 8, v[100:101]
	v_lshlrev_b64 v[104:105], 8, v[104:105]
	v_lshlrev_b64 v[108:109], 8, v[108:109]
	v_lshlrev_b64 v[118:119], 8, v[118:119]
	v_or_b32_e32 v193, v189, v241
	v_add_u32_e32 v209, 0, v206
	v_lshl_add_u64 v[100:101], v[116:117], 0, v[100:101]
	v_lshl_add_u64 v[104:105], v[116:117], 0, v[104:105]
	v_lshl_add_u64 v[108:109], v[116:117], 0, v[108:109]
	v_lshl_add_u64 v[116:117], v[116:117], 0, v[118:119]
	v_mad_u32_u24 v188, v193, s29, v209
	global_load_dwordx4 v[100:103], v[100:101], off
	s_nop 0
	global_load_dwordx4 v[104:107], v[104:105], off
	s_nop 0
	global_load_dwordx4 v[108:111], v[108:109], off
	s_nop 0
	global_load_dwordx4 v[116:119], v[116:117], off
	s_waitcnt lgkmcnt(0)
	s_barrier
	ds_read_b128 v[124:127], v188
	ds_read_b128 v[228:231], v188 offset:64
	s_waitcnt vmcnt(19) lgkmcnt(1)
	v_mfma_f32_16x16x32_bf16 v[128:131], v[124:127], v[156:159], 0
	s_waitcnt vmcnt(11)
	v_mfma_f32_16x16x32_bf16 v[132:135], v[124:127], v[160:163], 0
	v_mov_b32_e32 v124, 0x2100
	v_mad_u32_u24 v201, v193, s29, v124
	v_add_u32_e32 v199, v209, v201
	ds_read_b128 v[124:127], v199
	s_waitcnt lgkmcnt(0)
	v_mfma_f32_16x16x32_bf16 v[136:139], v[124:127], v[156:159], 0
	v_mfma_f32_16x16x32_bf16 v[164:167], v[124:127], v[160:163], 0
	v_mov_b32_e32 v124, 0x4200
	v_mad_u32_u24 v203, v193, s29, v124
	v_add_u32_e32 v207, v209, v203
	ds_read_b128 v[124:127], v207
	s_waitcnt lgkmcnt(0)
	v_mfma_f32_16x16x32_bf16 v[168:171], v[124:127], v[156:159], 0
	v_mfma_f32_16x16x32_bf16 v[172:175], v[124:127], v[160:163], 0
	v_mov_b32_e32 v124, 0x6300
	v_mad_u32_u24 v205, v193, s29, v124
	v_add_u32_e32 v124, v209, v205
	v_mfma_f32_16x16x32_bf16 v[126:129], v[228:231], v[144:147], v[128:131]
	ds_read_b128 v[220:223], v124
	s_waitcnt vmcnt(10)
	v_mfma_f32_16x16x32_bf16 v[130:133], v[228:231], v[152:155], v[132:135]
	ds_read_b128 v[228:231], v199 offset:64
	s_waitcnt lgkmcnt(0)
	v_mfma_f32_16x16x32_bf16 v[134:137], v[228:231], v[144:147], v[136:139]
	v_mfma_f32_16x16x32_bf16 v[164:167], v[228:231], v[152:155], v[164:167]
	ds_read_b128 v[228:231], v207 offset:64
	s_waitcnt lgkmcnt(0)
	v_mfma_f32_16x16x32_bf16 v[168:171], v[228:231], v[144:147], v[168:171]
	v_mfma_f32_16x16x32_bf16 v[172:175], v[228:231], v[152:155], v[172:175]
	ds_read_b128 v[228:231], v124 offset:64
	v_mfma_f32_16x16x32_bf16 v[224:227], v[220:223], v[156:159], 0
	v_mfma_f32_16x16x32_bf16 v[220:223], v[220:223], v[160:163], 0
	s_waitcnt lgkmcnt(0)
	v_mfma_f32_16x16x32_bf16 v[224:227], v[228:231], v[144:147], v[224:227]
	v_mfma_f32_16x16x32_bf16 v[220:223], v[228:231], v[152:155], v[220:223]
	ds_read_b128 v[228:231], v188 offset:128
	s_waitcnt lgkmcnt(0)
	v_mfma_f32_16x16x32_bf16 v[126:129], v[228:231], v[140:143], v[126:129]
	s_waitcnt vmcnt(9)
	v_mfma_f32_16x16x32_bf16 v[130:133], v[228:231], v[148:151], v[130:133]
	ds_read_b128 v[228:231], v199 offset:128
	s_waitcnt lgkmcnt(0)
	v_mfma_f32_16x16x32_bf16 v[134:137], v[228:231], v[140:143], v[134:137]
	v_mfma_f32_16x16x32_bf16 v[164:167], v[228:231], v[148:151], v[164:167]
	ds_read_b128 v[228:231], v207 offset:128
	s_waitcnt lgkmcnt(0)
	v_mfma_f32_16x16x32_bf16 v[168:171], v[228:231], v[140:143], v[168:171]
	v_mfma_f32_16x16x32_bf16 v[172:175], v[228:231], v[148:151], v[172:175]
	ds_read_b128 v[228:231], v124 offset:128
	s_waitcnt lgkmcnt(0)
; __device__ __forceinline__ void ret_core_phase(const Params& p, const PD& d, char* shm, const int wave_s) {
;     ...
;       for (int ks = 0; ks < 8; ++ks) {
; #pragma unroll
;         for (int jf = 0; jf < 4; ++jf) {
;           bf16x8 Kf = *(const bf16x8*)(R1 + (64 * wj + 16 * jf + frv) * 528 + (ks * 32 + fqv * 8) * 2);
; #pragma unroll
;           for (int f = 0; f < 2; ++f) PT[jf][f] = __builtin_amdgcn_mfma_f32_16x16x32_bf16(Kf, Qf[f][ks], PT[jf][f], 0, 0, 0);
;         }
;       }
	v_mfma_f32_16x16x32_bf16 v[224:227], v[228:231], v[140:143], v[224:227]
	v_mfma_f32_16x16x32_bf16 v[220:223], v[228:231], v[148:151], v[220:223]
	ds_read_b128 v[228:231], v188 offset:192
	s_waitcnt lgkmcnt(0)
	v_mfma_f32_16x16x32_bf16 v[126:129], v[228:231], v[96:99], v[126:129]
	s_waitcnt vmcnt(8)
	v_mfma_f32_16x16x32_bf16 v[130:133], v[228:231], v[120:123], v[130:133]
	ds_read_b128 v[228:231], v199 offset:192
	s_waitcnt lgkmcnt(0)
	v_mfma_f32_16x16x32_bf16 v[134:137], v[228:231], v[96:99], v[134:137]
	v_mfma_f32_16x16x32_bf16 v[164:167], v[228:231], v[120:123], v[164:167]
	ds_read_b128 v[228:231], v207 offset:192
	s_waitcnt lgkmcnt(0)
	v_mfma_f32_16x16x32_bf16 v[168:171], v[228:231], v[96:99], v[168:171]
	v_mfma_f32_16x16x32_bf16 v[172:175], v[228:231], v[120:123], v[172:175]
	ds_read_b128 v[228:231], v124 offset:192
	s_waitcnt lgkmcnt(0)
	v_mfma_f32_16x16x32_bf16 v[224:227], v[228:231], v[96:99], v[224:227]
	v_mfma_f32_16x16x32_bf16 v[220:223], v[228:231], v[120:123], v[220:223]
	ds_read_b128 v[228:231], v188 offset:256
	s_waitcnt lgkmcnt(0)
	v_mfma_f32_16x16x32_bf16 v[126:129], v[228:231], v[92:95], v[126:129]
	s_waitcnt vmcnt(7)
	v_mfma_f32_16x16x32_bf16 v[130:133], v[228:231], v[112:115], v[130:133]
	ds_read_b128 v[228:231], v199 offset:256
	s_waitcnt lgkmcnt(0)
	v_mfma_f32_16x16x32_bf16 v[134:137], v[228:231], v[92:95], v[134:137]
	v_mfma_f32_16x16x32_bf16 v[164:167], v[228:231], v[112:115], v[164:167]
	ds_read_b128 v[228:231], v207 offset:256
	s_waitcnt lgkmcnt(0)
	v_mfma_f32_16x16x32_bf16 v[168:171], v[228:231], v[92:95], v[168:171]
	v_mfma_f32_16x16x32_bf16 v[172:175], v[228:231], v[112:115], v[172:175]
	ds_read_b128 v[228:231], v124 offset:256
	s_waitcnt lgkmcnt(0)
	v_mfma_f32_16x16x32_bf16 v[224:227], v[228:231], v[92:95], v[224:227]
	v_mfma_f32_16x16x32_bf16 v[220:223], v[228:231], v[112:115], v[220:223]
	ds_read_b128 v[228:231], v188 offset:320
	s_waitcnt lgkmcnt(0)
	v_mfma_f32_16x16x32_bf16 v[126:129], v[228:231], v[80:83], v[126:129]
	s_waitcnt vmcnt(6)
	v_mfma_f32_16x16x32_bf16 v[130:133], v[228:231], v[88:91], v[130:133]
	ds_read_b128 v[228:231], v199 offset:320
	s_waitcnt lgkmcnt(0)
	v_mfma_f32_16x16x32_bf16 v[134:137], v[228:231], v[80:83], v[134:137]
	v_mfma_f32_16x16x32_bf16 v[164:167], v[228:231], v[88:91], v[164:167]
	ds_read_b128 v[228:231], v207 offset:320
	s_waitcnt lgkmcnt(0)
	v_mfma_f32_16x16x32_bf16 v[168:171], v[228:231], v[80:83], v[168:171]
	v_mfma_f32_16x16x32_bf16 v[172:175], v[228:231], v[88:91], v[172:175]
	ds_read_b128 v[228:231], v124 offset:320
	s_waitcnt lgkmcnt(0)
	v_mfma_f32_16x16x32_bf16 v[224:227], v[228:231], v[80:83], v[224:227]
	v_mfma_f32_16x16x32_bf16 v[220:223], v[228:231], v[88:91], v[220:223]
	ds_read_b128 v[228:231], v188 offset:384
	s_waitcnt lgkmcnt(0)
	v_mfma_f32_16x16x32_bf16 v[126:129], v[228:231], v[76:79], v[126:129]
	s_waitcnt vmcnt(5)
	v_mfma_f32_16x16x32_bf16 v[130:133], v[228:231], v[84:87], v[130:133]
	ds_read_b128 v[228:231], v199 offset:384
	s_waitcnt lgkmcnt(0)
	v_mfma_f32_16x16x32_bf16 v[134:137], v[228:231], v[76:79], v[134:137]
	v_mfma_f32_16x16x32_bf16 v[164:167], v[228:231], v[84:87], v[164:167]
	ds_read_b128 v[228:231], v207 offset:384
	s_waitcnt lgkmcnt(0)
	v_mfma_f32_16x16x32_bf16 v[244:247], v[228:231], v[76:79], v[168:171]
	s_nop 2
	ds_read_b128 v[168:171], v124 offset:384
	s_waitcnt lgkmcnt(0)
	v_mfma_f32_16x16x32_bf16 v[224:227], v[168:171], v[76:79], v[224:227]
	v_mfma_f32_16x16x32_bf16 v[220:223], v[168:171], v[84:87], v[220:223]
	ds_read_b128 v[168:171], v188 offset:448
	s_waitcnt lgkmcnt(0)
	v_mfma_f32_16x16x32_bf16 v[248:251], v[168:171], v[68:71], v[126:129]
	s_nop 2
	ds_read_b128 v[126:129], v199 offset:448
	v_mfma_f32_16x16x32_bf16 v[228:231], v[228:231], v[84:87], v[172:175]
	s_waitcnt vmcnt(4)
	v_mfma_f32_16x16x32_bf16 v[172:175], v[168:171], v[72:75], v[130:133]
	s_waitcnt lgkmcnt(0)
	v_mfma_f32_16x16x32_bf16 v[168:171], v[126:129], v[68:71], v[134:137]
	v_mfma_f32_16x16x32_bf16 v[164:167], v[126:129], v[72:75], v[164:167]
	ds_read_b128 v[126:129], v207 offset:448
	s_waitcnt lgkmcnt(0)
	v_mfma_f32_16x16x32_bf16 v[136:139], v[126:129], v[68:71], v[244:247]
	v_mfma_f32_16x16x32_bf16 v[128:131], v[126:129], v[72:75], v[228:231]
	ds_read_b128 v[124:127], v124 offset:448
	s_waitcnt lgkmcnt(0)
; __device__ __forceinline__ unsigned pack2(float a, float b) { return (unsigned)f2bf(a) | ((unsigned)f2bf(b) << 16); }
; __device__ __forceinline__ float fexp2(float x) { return __builtin_amdgcn_exp2f(x); }
; #define SCHED __builtin_amdgcn_sched_barrier(0)
; __device__ __forceinline__ void ret_core_phase(const Params& p, const PD& d, char* shm, const int wave_s) {
;     ...
; #pragma unroll
;       for (int jf = 0; jf < 4; ++jf)
; #pragma unroll
;         for (int f = 0; f < 2; ++f)
; #pragma unroll
;           for (int r = 0; r < 4; ++r) {
;             int j = 64 * wj + 16 * jf + 4 * fqv + r, i = 32 * wi + 16 * f + frv;
;             int df = i - j;
;             float fac = (df >= 0) ? fexp2(lg2v * (float)df) : 0.0f;
;             PT[jf][f][r] *= fac;
;           }
;       __syncthreads();
;       SCHED;
; #pragma unroll
;       for (int jf = 0; jf < 4; ++jf)
; #pragma unroll
;         for (int f = 0; f < 2; ++f) {
;           uint2 pk; pk.x = pack2(PT[jf][f][0], PT[jf][f][1]); pk.y = pack2(PT[jf][f][2], PT[jf][f][3]);
;           *(uint2*)(Pl + (32 * wi + 16 * f + frv) * 272 + (64 * wj + 16 * jf + 4 * fqv) * 2) = pk;
;         }
	v_mfma_f32_16x16x32_bf16 v[132:135], v[124:127], v[68:71], v[224:227]
	v_mfma_f32_16x16x32_bf16 v[124:127], v[124:127], v[72:75], v[220:223]
	v_mul_i32_i24_e32 v188, -4, v195
	v_or_b32_e32 v199, v189, v2
	v_sub_u32_e32 v188, v188, v241
	v_add_u32_e32 v207, v188, v199
	v_cvt_f32_u32_e32 v188, v207
	v_add_u32_e32 v211, -1, v207
	v_cvt_f32_u32_e32 v211, v211
	v_add_u32_e32 v215, -3, v207
	v_mul_f32_e32 v188, v197, v188
	v_exp_f32_e32 v213, v188
	v_mul_f32_e32 v188, v197, v211
	v_add_u32_e32 v211, -2, v207
	v_cvt_f32_u32_e32 v211, v211
	v_cvt_f32_u32_e32 v215, v215
	v_exp_f32_e32 v220, v188
	v_add_u32_e32 v216, 15, v207
	v_mul_f32_e32 v188, v197, v211
	v_exp_f32_e32 v211, v188
	v_mul_f32_e32 v188, v197, v215
	v_add_u32_e32 v215, 16, v207
	v_cvt_f32_u32_e32 v215, v215
	v_cvt_f32_u32_e32 v216, v216
	v_exp_f32_e32 v221, v188
	v_add_u32_e32 v217, 13, v207
	v_mul_f32_e32 v188, v197, v215
	v_exp_f32_e32 v215, v188
	v_mul_f32_e32 v188, v197, v216
	v_add_u32_e32 v216, 14, v207
	v_cvt_f32_u32_e32 v216, v216
	v_cvt_f32_u32_e32 v217, v217
	v_exp_f32_e32 v222, v188
	s_mov_b32 s4, 0x80000010
	v_mul_f32_e32 v188, v197, v216
	v_sub_u32_e32 v216, v199, v241
	v_mad_i32_i24 v216, v195, -4, v216
	v_add_u32_e32 v224, -16, v216
	v_exp_f32_e32 v223, v188
	v_mul_f32_e32 v188, v197, v217
	v_cvt_f32_u32_e32 v217, v224
	v_subrev_u32_e32 v218, 17, v216
	v_cvt_f32_u32_e32 v218, v218
	v_exp_f32_e32 v225, v188
	v_mul_f32_e32 v188, v197, v217
	v_subrev_u32_e32 v217, 18, v216
	v_exp_f32_e32 v226, v188
	v_mul_f32_e32 v188, v197, v218
	v_cvt_f32_u32_e32 v217, v217
	v_subrev_u32_e32 v218, 19, v216
	v_cvt_f32_u32_e32 v218, v218
	v_exp_f32_e32 v227, v188
	v_mul_f32_e32 v188, v197, v217
	v_exp_f32_e32 v228, v188
	v_mul_f32_e32 v188, v197, v218
	v_exp_f32_e32 v229, v188
	v_cvt_f32_u32_e32 v188, v216
	v_add_u32_e32 v217, -1, v216
	v_cvt_f32_u32_e32 v217, v217
	v_subrev_u32_e32 v233, 32, v216
	v_mul_f32_e32 v188, v197, v188
	v_exp_f32_e32 v230, v188
	v_mul_f32_e32 v188, v197, v217
	v_exp_f32_e32 v231, v188
	v_add_u32_e32 v188, -2, v216
	v_cvt_f32_u32_e32 v188, v188
	v_add_u32_e32 v217, -3, v216
	v_cvt_f32_u32_e32 v217, v217
	v_subrev_u32_e32 v218, 33, v216
	v_mul_f32_e32 v188, v197, v188
	v_exp_f32_e32 v232, v188
	v_mul_f32_e32 v188, v197, v217
	v_cvt_f32_u32_e32 v217, v233
	v_cvt_f32_u32_e32 v218, v218
	v_exp_f32_e32 v234, v188
	v_subrev_u32_e32 v238, 48, v216
	v_mul_f32_e32 v188, v197, v217
	v_subrev_u32_e32 v217, 34, v216
	v_cvt_f32_u32_e32 v217, v217
	v_exp_f32_e32 v235, v188
	v_mul_f32_e32 v188, v197, v218
	v_subrev_u32_e32 v218, 35, v216
	v_cvt_f32_u32_e32 v218, v218
	v_exp_f32_e32 v236, v188
	v_mul_f32_e32 v188, v197, v217
	v_cvt_f32_u32_e32 v217, v238
	v_exp_f32_e32 v237, v188
	v_mul_f32_e32 v188, v197, v218
	v_subrev_u32_e32 v218, 49, v216
	v_cvt_f32_u32_e32 v218, v218
	v_exp_f32_e32 v239, v188
	v_mul_f32_e32 v188, v197, v217
	v_subrev_u32_e32 v217, 50, v216
	v_cmp_gt_u32_e32 vcc, s4, v216
	v_cvt_f32_u32_e32 v217, v217
	v_subrev_u32_e32 v216, 51, v216
	v_cvt_f32_u32_e32 v216, v216
	v_exp_f32_e32 v240, v188
	v_mul_f32_e32 v188, v197, v218
	v_exp_f32_e32 v243, v188
	v_mul_f32_e32 v188, v197, v217
	v_cmp_lt_i32_e64 s[4:5], -15, v224
	v_exp_f32_e32 v244, v188
	v_mul_f32_e32 v188, v197, v216
	v_exp_f32_e32 v245, v188
	s_barrier
	v_cmp_lt_i32_e64 s[6:7], -1, v207
	v_mov_b32_e32 v218, v248
	v_mov_b32_e32 v219, v250
	v_cndmask_b32_e64 v216, 0, v213, s[6:7]
	v_cmp_lt_i32_e64 s[6:7], 1, v207
	v_mov_b32_e32 v250, v249
	s_movk_i32 s12, 0xffef
	v_cndmask_b32_e64 v217, 0, v211, s[6:7]
	v_cmp_lt_i32_e64 s[6:7], 2, v207
	v_pk_mul_f32 v[216:217], v[216:217], v[218:219]
	v_lshlrev_b32_e32 v188, 3, v195
	v_cndmask_b32_e64 v219, 0, v221, s[6:7]
	v_cmp_lt_i32_e64 s[6:7], 0, v207
	s_nop 0
	v_and_b32_sdwa v213, v216, v178 dst_sel:DWORD dst_unused:UNUSED_PAD src0_sel:WORD_1 src1_sel:DWORD
	v_cndmask_b32_e64 v218, 0, v220, s[6:7]
	v_pk_mul_f32 v[218:219], v[218:219], v[250:251]
	v_add3_u32 v213, v216, v213, s81
	v_cvt_pk_bf16_f32 v211, v217, v217
	s_nop 0
	s_nop 0
	v_cvt_pk_bf16_f32 v216, v219, v219
	v_cvt_pk_bf16_f32 v217, v218, v218
	v_cmp_lt_i32_e64 s[6:7], -15, v207
	v_and_b32_e32 v216, 0xffff0000, v216
	v_and_b32_e32 v218, 0xffff0000, v217
	v_cndmask_b32_e64 v219, 0, v223, s[6:7]
	v_cmp_lt_i32_e64 s[6:7], s12, v207
	v_or_b32_sdwa v217, v216, v211 dst_sel:DWORD dst_unused:UNUSED_PAD src0_sel:DWORD src1_sel:WORD_1
	v_or_b32_sdwa v216, v218, v213 dst_sel:DWORD dst_unused:UNUSED_PAD src0_sel:DWORD src1_sel:WORD_1
	v_cndmask_b32_e64 v218, 0, v215, s[6:7]
	v_mov_b32_e32 v220, v172
	v_mov_b32_e32 v221, v174
	v_cmp_lt_i32_e64 s[6:7], -14, v207
	v_pk_mul_f32 v[218:219], v[218:219], v[220:221]
	v_mov_b32_e32 v174, v173
	v_cndmask_b32_e64 v221, 0, v225, s[6:7]
	v_cmp_lt_i32_e64 s[6:7], -16, v207
	v_mul_lo_u32 v199, v199, s94
	v_add3_u32 v246, v242, v188, v199
	v_cndmask_b32_e64 v220, 0, v222, s[6:7]
	v_pk_mul_f32 v[172:173], v[220:221], v[174:175]
	s_nop 0
	v_and_b32_sdwa v211, v172, v178 dst_sel:DWORD dst_unused:UNUSED_PAD src0_sel:WORD_1 src1_sel:DWORD
	s_nop 0
	v_add3_u32 v172, v172, v211, s81
	v_cvt_pk_bf16_f32 v175, v218, v218
	v_cvt_pk_bf16_f32 v173, v173, v173
	v_and_b32_e32 v172, 0xffff0000, v172
	v_cmp_lt_i32_e64 s[6:7], 1, v224
	v_cvt_pk_bf16_f32 v174, v219, v219
	v_and_b32_e32 v173, 0xffff0000, v173
	v_or_b32_sdwa v172, v172, v175 dst_sel:DWORD dst_unused:UNUSED_PAD src0_sel:DWORD src1_sel:WORD_1
	v_cndmask_b32_e64 v175, 0, v228, s[6:7]
	v_cmp_lt_i32_e64 s[6:7], -1, v224
	v_or_b32_sdwa v173, v173, v174 dst_sel:DWORD dst_unused:UNUSED_PAD src0_sel:DWORD src1_sel:WORD_1
	v_mov_b32_e32 v218, v168
	v_cndmask_b32_e64 v174, 0, v226, s[6:7]
	v_mov_b32_e32 v219, v170
	v_cmp_lt_i32_e64 s[6:7], 2, v224
; __device__ __forceinline__ unsigned pack2(float a, float b) { return (unsigned)f2bf(a) | ((unsigned)f2bf(b) << 16); }
; __device__ __forceinline__ float fexp2(float x) { return __builtin_amdgcn_exp2f(x); }
; #define SCHED __builtin_amdgcn_sched_barrier(0)
; __device__ __forceinline__ void ret_core_phase(const Params& p, const PD& d, char* shm, const int wave_s) {
;     ...
;       for (int jf = 0; jf < 4; ++jf)
; #pragma unroll
;         for (int f = 0; f < 2; ++f)
; #pragma unroll
;           for (int r = 0; r < 4; ++r) {
;             int j = 64 * wj + 16 * jf + 4 * fqv + r, i = 32 * wi + 16 * f + frv;
;             int df = i - j;
;             float fac = (df >= 0) ? fexp2(lg2v * (float)df) : 0.0f;
;             PT[jf][f][r] *= fac;
;           }
;       __syncthreads();
;       SCHED;
; #pragma unroll
;       for (int jf = 0; jf < 4; ++jf)
; #pragma unroll
;         for (int f = 0; f < 2; ++f) {
;           uint2 pk; pk.x = pack2(PT[jf][f][0], PT[jf][f][1]); pk.y = pack2(PT[jf][f][2], PT[jf][f][3]);
;           *(uint2*)(Pl + (32 * wi + 16 * f + frv) * 272 + (64 * wj + 16 * jf + 4 * fqv) * 2) = pk;
;         }
	v_pk_mul_f32 v[174:175], v[174:175], v[218:219]
	v_mov_b32_e32 v170, v169
	v_cndmask_b32_e64 v219, 0, v229, s[6:7]
	v_cmp_lt_i32_e64 s[6:7], 0, v224
	v_add_u32_e32 v0, 0, v0
	s_nop 0
	v_cndmask_b32_e64 v218, 0, v227, s[6:7]
	v_pk_mul_f32 v[168:169], v[218:219], v[170:171]
	s_nop 0
	s_nop 0
	v_cvt_pk_bf16_f32 v171, v174, v174
	v_cvt_pk_bf16_f32 v170, v175, v175
	v_and_b32_sdwa v174, v169, v178 dst_sel:DWORD dst_unused:UNUSED_PAD src0_sel:WORD_1 src1_sel:DWORD
	v_and_b32_sdwa v175, v168, v178 dst_sel:DWORD dst_unused:UNUSED_PAD src0_sel:WORD_1 src1_sel:DWORD
	v_add3_u32 v169, v169, v174, s81
	v_add3_u32 v168, v168, v175, s81
	v_and_b32_e32 v169, 0xffff0000, v169
	v_and_b32_e32 v168, 0xffff0000, v168
	v_or_b32_sdwa v169, v169, v170 dst_sel:DWORD dst_unused:UNUSED_PAD src0_sel:DWORD src1_sel:WORD_1
	v_or_b32_sdwa v168, v168, v171 dst_sel:DWORD dst_unused:UNUSED_PAD src0_sel:DWORD src1_sel:WORD_1
	ds_write2_b64 v246, v[216:217], v[168:169] offset1:4
	v_cndmask_b32_e32 v168, 0, v230, vcc
	v_cndmask_b32_e64 v169, 0, v232, s[4:5]
	v_mov_b32_e32 v170, v164
	v_mov_b32_e32 v171, v166
	v_cmp_lt_i32_e32 vcc, -14, v224
	v_pk_mul_f32 v[168:169], v[168:169], v[170:171]
	v_mov_b32_e32 v166, v165
	v_cndmask_b32_e32 v171, 0, v234, vcc
	v_cmp_lt_i32_e32 vcc, -16, v224
	s_nop 1
	v_cndmask_b32_e32 v170, 0, v231, vcc
	v_pk_mul_f32 v[164:165], v[170:171], v[166:167]
	s_nop 0
	s_nop 0
	v_cvt_pk_bf16_f32 v167, v168, v168
	v_cvt_pk_bf16_f32 v166, v169, v169
	v_cvt_pk_bf16_f32 v165, v165, v165
	v_cvt_pk_bf16_f32 v164, v164, v164
	v_and_b32_e32 v165, 0xffff0000, v165
	v_and_b32_e32 v164, 0xffff0000, v164
	v_or_b32_sdwa v165, v165, v166 dst_sel:DWORD dst_unused:UNUSED_PAD src0_sel:DWORD src1_sel:WORD_1
	v_or_b32_sdwa v164, v164, v167 dst_sel:DWORD dst_unused:UNUSED_PAD src0_sel:DWORD src1_sel:WORD_1
	v_add_u32_e32 v168, 0x1000, v246
	v_cmp_lt_i32_e32 vcc, 1, v233
	ds_write2_b64 v168, v[172:173], v[164:165] offset0:32 offset1:36
	v_mov_b32_e32 v166, v136
	v_cndmask_b32_e32 v165, 0, v237, vcc
	v_cmp_lt_i32_e32 vcc, -1, v233
	v_mov_b32_e32 v167, v138
	v_mov_b32_e32 v138, v137
	v_cndmask_b32_e32 v164, 0, v235, vcc
	v_cmp_lt_i32_e32 vcc, 2, v233
	v_pk_mul_f32 v[164:165], v[164:165], v[166:167]
	s_nop 0
	v_cndmask_b32_e32 v167, 0, v239, vcc
	v_cmp_lt_i32_e32 vcc, 0, v233
	s_nop 1
	v_cndmask_b32_e32 v166, 0, v236, vcc
	v_pk_mul_f32 v[136:137], v[166:167], v[138:139]
	s_nop 0
	s_nop 0
	v_cvt_pk_bf16_f32 v138, v165, v165
	s_nop 0
	v_cvt_pk_bf16_f32 v139, v164, v164
	v_cvt_pk_bf16_f32 v136, v136, v136
	v_cvt_pk_bf16_f32 v137, v137, v137
	v_and_b32_e32 v136, 0xffff0000, v136
	v_cmp_lt_i32_e32 vcc, -15, v233
	v_and_b32_e32 v137, 0xffff0000, v137
	v_or_b32_sdwa v136, v136, v139 dst_sel:DWORD dst_unused:UNUSED_PAD src0_sel:DWORD src1_sel:WORD_1
	v_cndmask_b32_e32 v139, 0, v228, vcc
	v_cmp_lt_i32_e32 vcc, s12, v233
	v_or_b32_sdwa v137, v137, v138 dst_sel:DWORD dst_unused:UNUSED_PAD src0_sel:DWORD src1_sel:WORD_1
	v_mov_b32_e32 v164, v128
	v_cndmask_b32_e32 v138, 0, v226, vcc
	v_mov_b32_e32 v165, v130
	v_cmp_lt_i32_e32 vcc, -14, v233
	v_pk_mul_f32 v[138:139], v[138:139], v[164:165]
	v_mov_b32_e32 v130, v129
	v_cndmask_b32_e32 v165, 0, v229, vcc
	v_cmp_lt_i32_e32 vcc, -16, v233
	s_nop 1
	v_cndmask_b32_e32 v164, 0, v227, vcc
	v_pk_mul_f32 v[128:129], v[164:165], v[130:131]
	s_nop 0
	s_nop 0
	v_cvt_pk_bf16_f32 v130, v139, v139
	s_nop 0
	v_cvt_pk_bf16_f32 v131, v138, v138
	v_cvt_pk_bf16_f32 v128, v128, v128
	v_cvt_pk_bf16_f32 v129, v129, v129
	v_and_b32_e32 v128, 0xffff0000, v128
	v_cmp_lt_i32_e32 vcc, 1, v238
	v_and_b32_e32 v129, 0xffff0000, v129
	v_or_b32_sdwa v128, v128, v131 dst_sel:DWORD dst_unused:UNUSED_PAD src0_sel:DWORD src1_sel:WORD_1
	v_cndmask_b32_e32 v131, 0, v244, vcc
	v_cmp_lt_i32_e32 vcc, -1, v238
	v_or_b32_sdwa v129, v129, v130 dst_sel:DWORD dst_unused:UNUSED_PAD src0_sel:DWORD src1_sel:WORD_1
	v_mov_b32_e32 v138, v132
	v_cndmask_b32_e32 v130, 0, v240, vcc
	v_mov_b32_e32 v139, v134
	v_cmp_lt_i32_e32 vcc, 2, v238
	v_pk_mul_f32 v[130:131], v[130:131], v[138:139]
	v_mov_b32_e32 v134, v133
	v_cndmask_b32_e32 v139, 0, v245, vcc
	v_cmp_lt_i32_e32 vcc, 0, v238
	s_nop 1
	v_cndmask_b32_e32 v138, 0, v243, vcc
	v_pk_mul_f32 v[132:133], v[138:139], v[134:135]
	s_nop 0
	s_nop 0
	v_cvt_pk_bf16_f32 v130, v130, v130
	v_cvt_pk_bf16_f32 v131, v131, v131
	v_cvt_pk_bf16_f32 v133, v133, v133
	v_cvt_pk_bf16_f32 v132, v132, v132
	v_and_b32_e32 v133, 0xffff0000, v133
	v_and_b32_e32 v132, 0xffff0000, v132
	v_or_b32_sdwa v131, v133, v131 dst_sel:DWORD dst_unused:UNUSED_PAD src0_sel:DWORD src1_sel:WORD_1
	v_or_b32_sdwa v130, v132, v130 dst_sel:DWORD dst_unused:UNUSED_PAD src0_sel:DWORD src1_sel:WORD_1
	v_cmp_lt_i32_e32 vcc, -15, v238
	ds_write2_b64 v246, v[136:137], v[130:131] offset0:8 offset1:12
	v_mov_b32_e32 v132, v124
	v_cndmask_b32_e32 v131, 0, v237, vcc
	v_cmp_lt_i32_e32 vcc, s12, v238
	v_mov_b32_e32 v133, v126
	v_mov_b32_e32 v126, v125
	v_cndmask_b32_e32 v130, 0, v235, vcc
	v_cmp_lt_i32_e32 vcc, -14, v238
	v_pk_mul_f32 v[130:131], v[130:131], v[132:133]
	s_nop 0
	v_cndmask_b32_e32 v133, 0, v239, vcc
	v_cmp_lt_i32_e32 vcc, -16, v238
	s_nop 1
	v_cndmask_b32_e32 v132, 0, v236, vcc
	v_pk_mul_f32 v[124:125], v[132:133], v[126:127]
	s_nop 0
	s_nop 0
	v_cvt_pk_bf16_f32 v127, v130, v130
	v_cvt_pk_bf16_f32 v126, v131, v131
	v_and_b32_sdwa v130, v125, v178 dst_sel:DWORD dst_unused:UNUSED_PAD src0_sel:WORD_1 src1_sel:DWORD
	v_and_b32_sdwa v131, v124, v178 dst_sel:DWORD dst_unused:UNUSED_PAD src0_sel:WORD_1 src1_sel:DWORD
	v_add3_u32 v125, v125, v130, s81
	v_add3_u32 v124, v124, v131, s81
	v_and_b32_e32 v125, 0xffff0000, v125
	v_and_b32_e32 v124, 0xffff0000, v124
	v_or_b32_sdwa v125, v125, v126 dst_sel:DWORD dst_unused:UNUSED_PAD src0_sel:DWORD src1_sel:WORD_1
	v_or_b32_sdwa v124, v124, v127 dst_sel:DWORD dst_unused:UNUSED_PAD src0_sel:DWORD src1_sel:WORD_1
	ds_write2_b64 v168, v[128:129], v[124:125] offset0:40 offset1:44
	v_mad_u64_u32 v[124:125], s[4:5], v208, s94, v[0:1]
	s_waitcnt vmcnt(3)
; #define SCHED __builtin_amdgcn_sched_barrier(0)
; __device__ __forceinline__ void ret_core_phase(const Params& p, const PD& d, char* shm, const int wave_s) {
;     ...
; #pragma unroll
;       for (int i = 0; i < 4; ++i) {
;         int c = i * 512 + tidv, row = c >> 4, cc = c & 15;
;         *(bf16x8*)(Vl + row * 272 + cc * 16) = vpre[i];
;       }
;       SCHED;
;       f32x4 OT[4][2];
; #pragma unroll
;       for (int a = 0; a < 4; ++a)
; #pragma unroll
;         for (int c = 0; c < 2; ++c) OT[a][c] = f32x4{0.f, 0.f, 0.f, 0.f};
; #pragma unroll
;       for (int ks = 0; ks < 8; ++ks) {
; #pragma unroll
;         for (int vf = 0; vf < 4; ++vf) {
;           bf16x8 Sf = *(const bf16x8*)(R2 + (64 * wj + 16 * vf + frv) * 528 + (ks * 32 + fqv * 8) * 2);
; #pragma unroll
;           for (int f = 0; f < 2; ++f) OT[vf][f] = __builtin_amdgcn_mfma_f32_16x16x32_bf16(Sf, Qf[f][ks], OT[vf][f], 0, 0, 0);
;         }
;       }
	ds_write_b128 v124, v[100:103] offset:34816
	v_mad_u64_u32 v[100:101], s[4:5], v210, s94, v[0:1]
	s_waitcnt vmcnt(2)
	ds_write_b128 v100, v[104:107] offset:34816
	v_mad_u64_u32 v[100:101], s[4:5], v212, s94, v[0:1]
	s_waitcnt vmcnt(1)
	ds_write_b128 v100, v[108:111] offset:34816
	v_mad_u64_u32 v[100:101], s[4:5], v214, s94, v[0:1]
	s_waitcnt vmcnt(0)
	ds_write_b128 v100, v[116:119] offset:34816
	v_add_u32_e32 v0, s73, v206
	v_mad_u32_u24 v164, v193, s29, v0
	v_add_u32_e32 v165, v0, v201
	v_add_u32_e32 v166, v0, v203
	v_add_u32_e32 v0, v0, v205
	ds_read_b128 v[100:103], v164
	ds_read_b128 v[132:135], v0
	ds_read_b128 v[108:111], v165
	ds_read_b128 v[124:127], v166
	s_waitcnt lgkmcnt(3)
	v_mfma_f32_16x16x32_bf16 v[104:107], v[100:103], v[156:159], 0
	s_waitcnt lgkmcnt(1)
	v_mfma_f32_16x16x32_bf16 v[116:119], v[108:111], v[156:159], 0
	s_waitcnt lgkmcnt(0)
	v_mfma_f32_16x16x32_bf16 v[128:131], v[124:127], v[156:159], 0
	v_mfma_f32_16x16x32_bf16 v[136:139], v[132:135], v[156:159], 0
	ds_read_b128 v[156:159], v164 offset:64
	v_mfma_f32_16x16x32_bf16 v[100:103], v[100:103], v[160:163], 0
	s_waitcnt lgkmcnt(0)
	v_mfma_f32_16x16x32_bf16 v[104:107], v[156:159], v[144:147], v[104:107]
	v_mfma_f32_16x16x32_bf16 v[100:103], v[156:159], v[152:155], v[100:103]
	ds_read_b128 v[156:159], v165 offset:64
	v_mfma_f32_16x16x32_bf16 v[108:111], v[108:111], v[160:163], 0
	s_waitcnt lgkmcnt(0)
	v_mfma_f32_16x16x32_bf16 v[116:119], v[156:159], v[144:147], v[116:119]
	v_mfma_f32_16x16x32_bf16 v[108:111], v[156:159], v[152:155], v[108:111]
	ds_read_b128 v[156:159], v166 offset:64
	v_mfma_f32_16x16x32_bf16 v[124:127], v[124:127], v[160:163], 0
	s_waitcnt lgkmcnt(0)
	v_mfma_f32_16x16x32_bf16 v[128:131], v[156:159], v[144:147], v[128:131]
	v_mfma_f32_16x16x32_bf16 v[124:127], v[156:159], v[152:155], v[124:127]
	ds_read_b128 v[156:159], v0 offset:64
	s_waitcnt lgkmcnt(0)
	v_mfma_f32_16x16x32_bf16 v[136:139], v[156:159], v[144:147], v[136:139]
	ds_read_b128 v[144:147], v164 offset:128
	s_waitcnt lgkmcnt(0)
	v_mfma_f32_16x16x32_bf16 v[104:107], v[144:147], v[140:143], v[104:107]
	v_mfma_f32_16x16x32_bf16 v[100:103], v[144:147], v[148:151], v[100:103]
	ds_read_b128 v[144:147], v165 offset:128
	s_waitcnt lgkmcnt(0)
	v_mfma_f32_16x16x32_bf16 v[116:119], v[144:147], v[140:143], v[116:119]
	v_mfma_f32_16x16x32_bf16 v[108:111], v[144:147], v[148:151], v[108:111]
	ds_read_b128 v[144:147], v166 offset:128
	s_waitcnt lgkmcnt(0)
	v_mfma_f32_16x16x32_bf16 v[128:131], v[144:147], v[140:143], v[128:131]
	v_mfma_f32_16x16x32_bf16 v[124:127], v[144:147], v[148:151], v[124:127]
	ds_read_b128 v[144:147], v0 offset:128
	s_waitcnt lgkmcnt(0)
	v_mfma_f32_16x16x32_bf16 v[136:139], v[144:147], v[140:143], v[136:139]
	ds_read_b128 v[140:143], v164 offset:192
	s_waitcnt lgkmcnt(0)
	v_mfma_f32_16x16x32_bf16 v[104:107], v[140:143], v[96:99], v[104:107]
	v_mfma_f32_16x16x32_bf16 v[100:103], v[140:143], v[120:123], v[100:103]
	ds_read_b128 v[140:143], v165 offset:192
	s_waitcnt lgkmcnt(0)
	v_mfma_f32_16x16x32_bf16 v[116:119], v[140:143], v[96:99], v[116:119]
	v_mfma_f32_16x16x32_bf16 v[108:111], v[140:143], v[120:123], v[108:111]
	ds_read_b128 v[140:143], v166 offset:192
	v_mfma_f32_16x16x32_bf16 v[132:135], v[132:135], v[160:163], 0
	s_waitcnt lgkmcnt(0)
	v_mfma_f32_16x16x32_bf16 v[128:131], v[140:143], v[96:99], v[128:131]
	v_mfma_f32_16x16x32_bf16 v[124:127], v[140:143], v[120:123], v[124:127]
	ds_read_b128 v[140:143], v0 offset:192
	v_mfma_f32_16x16x32_bf16 v[132:135], v[156:159], v[152:155], v[132:135]
	v_mfma_f32_16x16x32_bf16 v[132:135], v[144:147], v[148:151], v[132:135]
	s_waitcnt lgkmcnt(0)
	v_mfma_f32_16x16x32_bf16 v[120:123], v[140:143], v[120:123], v[132:135]
	v_mfma_f32_16x16x32_bf16 v[96:99], v[140:143], v[96:99], v[136:139]
	s_nop 4
	ds_read_b128 v[132:135], v164 offset:256
	s_waitcnt lgkmcnt(0)
	v_mfma_f32_16x16x32_bf16 v[104:107], v[132:135], v[92:95], v[104:107]
	v_mfma_f32_16x16x32_bf16 v[100:103], v[132:135], v[112:115], v[100:103]
	ds_read_b128 v[132:135], v165 offset:256
	s_waitcnt lgkmcnt(0)
	v_mfma_f32_16x16x32_bf16 v[116:119], v[132:135], v[92:95], v[116:119]
	v_mfma_f32_16x16x32_bf16 v[108:111], v[132:135], v[112:115], v[108:111]
	ds_read_b128 v[132:135], v166 offset:256
	s_waitcnt lgkmcnt(0)
	v_mfma_f32_16x16x32_bf16 v[128:131], v[132:135], v[92:95], v[128:131]
	v_mfma_f32_16x16x32_bf16 v[124:127], v[132:135], v[112:115], v[124:127]
	ds_read_b128 v[132:135], v0 offset:256
	s_waitcnt lgkmcnt(0)
	v_mfma_f32_16x16x32_bf16 v[92:95], v[132:135], v[92:95], v[96:99]
	v_mfma_f32_16x16x32_bf16 v[96:99], v[132:135], v[112:115], v[120:123]
	ds_read_b128 v[112:115], v164 offset:320
	s_waitcnt lgkmcnt(0)
	v_mfma_f32_16x16x32_bf16 v[104:107], v[112:115], v[80:83], v[104:107]
	v_mfma_f32_16x16x32_bf16 v[100:103], v[112:115], v[88:91], v[100:103]
	ds_read_b128 v[112:115], v165 offset:320
	s_waitcnt lgkmcnt(0)
	v_mfma_f32_16x16x32_bf16 v[116:119], v[112:115], v[80:83], v[116:119]
	v_mfma_f32_16x16x32_bf16 v[108:111], v[112:115], v[88:91], v[108:111]
	ds_read_b128 v[112:115], v166 offset:320
	s_waitcnt lgkmcnt(0)
	v_mfma_f32_16x16x32_bf16 v[120:123], v[112:115], v[80:83], v[128:131]
	v_mfma_f32_16x16x32_bf16 v[112:115], v[112:115], v[88:91], v[124:127]
	s_nop 2
	ds_read_b128 v[124:127], v0 offset:320
	s_waitcnt lgkmcnt(0)
	v_mfma_f32_16x16x32_bf16 v[80:83], v[124:127], v[80:83], v[92:95]
	s_nop 2
	ds_read_b128 v[92:95], v164 offset:384
	v_mfma_f32_16x16x32_bf16 v[88:91], v[124:127], v[88:91], v[96:99]
	s_waitcnt lgkmcnt(0)
	v_mfma_f32_16x16x32_bf16 v[96:99], v[92:95], v[76:79], v[104:107]
	v_mfma_f32_16x16x32_bf16 v[92:95], v[92:95], v[84:87], v[100:103]
	s_nop 2
	ds_read_b128 v[100:103], v165 offset:384
	s_waitcnt lgkmcnt(0)
; __device__ __forceinline__ float fexp2(float x) { return __builtin_amdgcn_exp2f(x); }
; #define SCHED __builtin_amdgcn_sched_barrier(0)
; __device__ __forceinline__ void ret_core_phase(const Params& p, const PD& d, char* shm, const int wave_s) {
;     ...
;       for (int ks = 0; ks < 8; ++ks) {
; #pragma unroll
;         for (int vf = 0; vf < 4; ++vf) {
;           bf16x8 Sf = *(const bf16x8*)(R2 + (64 * wj + 16 * vf + frv) * 528 + (ks * 32 + fqv * 8) * 2);
; #pragma unroll
;           for (int f = 0; f < 2; ++f) OT[vf][f] = __builtin_amdgcn_mfma_f32_16x16x32_bf16(Sf, Qf[f][ks], OT[vf][f], 0, 0, 0);
;         }
;       }
; #pragma unroll
;       for (int f = 0; f < 2; ++f) {
;         float qd = fexp2(lg2v * (float)(32 * wi + 16 * f + frv + 1));
; #pragma unroll
;         for (int vf = 0; vf < 4; ++vf) OT[vf][f] *= qd;
;       }
;       SCHED;
;       u16* got = GOb + (lt0 + 32 * wi + frv) * 2048 + hh * 512 + vs * 128 + 64 * wj + 4 * fqv;
;       uint2 gpre[4][2];
; #pragma unroll
;       for (int vf = 0; vf < 4; ++vf)
; #pragma unroll
;         for (int f = 0; f < 2; ++f) gpre[vf][f] = *(const uint2*)(got + f * 16 * 2048 + vf * 16);
;       bf16x8 ktf[4][4];
;       const u16* KTw = KTb + ((size_t)(bh * 16 + lc) * 256 + 64 * wi + frv) * 128 + fqv * 8;
; #pragma unroll
;       for (int ks = 0; ks < 2; ++ks)
; #pragma unroll
;         for (int df = 0; df < 4; ++df) ktf[ks][df] = *(const bf16x8*)(KTw + df * 16 * 128 + ks * 32);
	v_mfma_f32_16x16x32_bf16 v[104:107], v[100:103], v[76:79], v[116:119]
	v_mfma_f32_16x16x32_bf16 v[100:103], v[100:103], v[84:87], v[108:111]
	s_nop 2
	ds_read_b128 v[108:111], v166 offset:384
	s_waitcnt lgkmcnt(0)
	v_mfma_f32_16x16x32_bf16 v[116:119], v[108:111], v[76:79], v[120:123]
	v_mfma_f32_16x16x32_bf16 v[108:111], v[108:111], v[84:87], v[112:115]
	s_nop 2
	ds_read_b128 v[112:115], v0 offset:384
	s_waitcnt lgkmcnt(0)
	v_mfma_f32_16x16x32_bf16 v[76:79], v[112:115], v[76:79], v[80:83]
	v_mfma_f32_16x16x32_bf16 v[80:83], v[112:115], v[84:87], v[88:91]
	ds_read_b128 v[84:87], v164 offset:448
	s_waitcnt lgkmcnt(0)
	v_mfma_f32_16x16x32_bf16 v[88:91], v[84:87], v[68:71], v[96:99]
	v_mfma_f32_16x16x32_bf16 v[84:87], v[84:87], v[72:75], v[92:95]
	s_nop 2
	ds_read_b128 v[92:95], v165 offset:448
	s_waitcnt lgkmcnt(0)
	v_mfma_f32_16x16x32_bf16 v[96:99], v[92:95], v[68:71], v[104:107]
	v_mfma_f32_16x16x32_bf16 v[92:95], v[92:95], v[72:75], v[100:103]
	s_nop 2
	ds_read_b128 v[100:103], v166 offset:448
	s_waitcnt lgkmcnt(0)
	v_mfma_f32_16x16x32_bf16 v[104:107], v[100:103], v[68:71], v[116:119]
	v_mfma_f32_16x16x32_bf16 v[100:103], v[100:103], v[72:75], v[108:111]
	s_nop 2
	ds_read_b128 v[108:111], v0 offset:448
	v_or_b32_e32 v0, 1, v2
	s_waitcnt lgkmcnt(0)
	v_mfma_f32_16x16x32_bf16 v[68:71], v[108:111], v[68:71], v[76:79]
	s_nop 2
	v_add_u32_e32 v76, v189, v0
	v_cvt_f32_i32_e32 v0, v76
	v_mul_f32_e32 v0, v197, v0
	v_exp_f32_e32 v0, v0
	v_mfma_f32_16x16x32_bf16 v[72:75], v[108:111], v[72:75], v[80:83]
	v_mul_f32_e64 v110, v0, v90
	v_mul_f32_e64 v111, v0, v91
	v_pk_mul_f32 v[108:109], v[0:1], v[88:89] op_sel_hi:[0,1]
	v_pk_mul_f32 v[114:115], v[0:1], v[98:99] op_sel_hi:[0,1]
	v_pk_mul_f32 v[112:113], v[0:1], v[96:97] op_sel_hi:[0,1]
	v_pk_mul_f32 v[106:107], v[0:1], v[106:107] op_sel_hi:[0,1]
	v_pk_mul_f32 v[104:105], v[0:1], v[104:105] op_sel_hi:[0,1]
	v_pk_mul_f32 v[118:119], v[0:1], v[70:71] op_sel_hi:[0,1]
	v_pk_mul_f32 v[116:117], v[0:1], v[68:69] op_sel_hi:[0,1]
	v_add_u32_e32 v0, 16, v76
	v_cvt_f32_i32_e32 v0, v0
	v_mul_f32_e32 v0, v197, v0
	v_exp_f32_e32 v0, v0
	s_nop 0
	v_pk_mul_f32 v[122:123], v[0:1], v[86:87] op_sel_hi:[0,1]
	v_pk_mul_f32 v[120:121], v[0:1], v[84:85] op_sel_hi:[0,1]
	v_pk_mul_f32 v[126:127], v[0:1], v[94:95] op_sel_hi:[0,1]
	v_pk_mul_f32 v[124:125], v[0:1], v[92:93] op_sel_hi:[0,1]
	v_pk_mul_f32 v[102:103], v[0:1], v[102:103] op_sel_hi:[0,1]
	v_pk_mul_f32 v[100:101], v[0:1], v[100:101] op_sel_hi:[0,1]
	v_pk_mul_f32 v[130:131], v[0:1], v[74:75] op_sel_hi:[0,1]
	v_pk_mul_f32 v[128:129], v[0:1], v[72:73] op_sel_hi:[0,1]
	v_mov_b32_e32 v0, v189
	v_lshl_add_u64 v[68:69], v[176:177], 0, s[8:9]
	v_lshl_add_u64 v[152:153], v[68:69], 0, v[0:1]
	v_lshlrev_b64 v[68:69], 12, v[152:153]
	v_lshl_add_u64 v[68:69], v[180:181], 0, v[68:69]
	v_mov_b32_e32 v189, v1
	v_lshl_add_u64 v[148:149], v[68:69], 0, v[188:189]
	v_add_co_u32_e32 v68, vcc, s51, v148
	v_mov_b32_e32 v207, v1
	s_nop 0
	v_addc_co_u32_e32 v69, vcc, 0, v149, vcc
	global_load_dwordx2 v[158:159], v[148:149], off
	global_load_dwordx2 v[156:157], v[148:149], off offset:32
	global_load_dwordx2 v[154:155], v[148:149], off offset:64
	global_load_dwordx2 v[150:151], v[148:149], off offset:96
	global_load_dwordx2 v[146:147], v[68:69], off
	global_load_dwordx2 v[144:145], v[68:69], off offset:32
	global_load_dwordx2 v[142:143], v[68:69], off offset:64
	global_load_dwordx2 v[140:141], v[68:69], off offset:96
	v_lshl_add_u64 v[68:69], v[186:187], 0, v[0:1]
	v_lshlrev_b64 v[68:69], 8, v[68:69]
	v_lshl_add_u64 v[68:69], s[46:47], 0, v[68:69]
	v_lshl_add_u64 v[132:133], v[68:69], 0, v[206:207]
	s_movk_i32 s4, 0x1000
	v_add_co_u32_e32 v134, vcc, s4, v132
	s_movk_i32 s4, 0x2000
	s_nop 0
	v_addc_co_u32_e32 v135, vcc, 0, v133, vcc
	v_add_co_u32_e32 v136, vcc, s4, v132
	s_movk_i32 s4, 0x3000
	s_nop 0
	v_addc_co_u32_e32 v137, vcc, 0, v133, vcc
	v_add_co_u32_e32 v138, vcc, s4, v132
	s_nop 1
	v_addc_co_u32_e32 v139, vcc, 0, v133, vcc
	global_load_dwordx4 v[92:95], v[132:133], off
	global_load_dwordx4 v[80:83], v[132:133], off offset:64
	global_load_dwordx4 v[96:99], v[136:137], off offset:-4096
	global_load_dwordx4 v[76:79], v[134:135], off offset:64
	global_load_dwordx4 v[88:91], v[136:137], off
	global_load_dwordx4 v[72:75], v[136:137], off offset:64
	global_load_dwordx4 v[84:87], v[138:139], off
	global_load_dwordx4 v[68:71], v[138:139], off offset:64
	s_barrier
; __device__ __forceinline__ void ret_core_phase(const Params& p, const PD& d, char* shm, const int wave_s) {
;     ...
; #pragma unroll
;       for (int ks = 0; ks < 4; ++ks) {
;         bf16x8 Pf[2];
; #pragma unroll
;         for (int f = 0; f < 2; ++f) Pf[f] = *(const bf16x8*)(Pl + (32 * wi + 16 * f + frv) * 272 + (ks * 32 + fqv * 8) * 2);
; #pragma unroll
;         for (int vf = 0; vf < 4; ++vf) {
;           bf16x8 Vf = *(const bf16x8*)(Vl + (64 * wj + 16 * vf + frv) * 272 + (ks * 32 + fqv * 8) * 2);
; #pragma unroll
;           for (int f = 0; f < 2; ++f) OT[vf][f] = __builtin_amdgcn_mfma_f32_16x16x32_bf16(Vf, Pf[f], OT[vf][f], 0, 0, 0);
;         }
;       }
;       {
;         float* sst = p.sspart + ((lt0 + 32 * wi + frv) * 4 + hh) * 8 + vs * 2 + wj;
; #pragma unroll
;         for (int f = 0; f < 2; ++f) {
;           float ss = 0.f;
; #pragma unroll
;           for (int vf = 0; vf < 4; ++vf)
; #pragma unroll
;             for (int r = 0; r < 4; ++r) ss += OT[vf][f][r] * OT[vf][f][r];
;           ss += shfl_xor_l(ss, 16, fqv * 16 + frv); ss += shfl_xor_l(ss, 32, fqv * 16 + frv);
;           if (fqv == 0) sst[(16 * f) * 32] = ss;
	v_add_u32_e32 v189, v209, v199
	v_mad_u32_u24 v197, v193, s94, v209
	ds_read_b128 v[160:163], v189
	ds_read_b128 v[164:167], v189 offset:4352
	ds_read_b128 v[168:171], v197 offset:34816
	s_movk_i32 s4, 0x80
	v_lshlrev_b64 v[152:153], 7, v[152:153]
	v_lshl_add_u64 v[152:153], v[184:185], 0, v[152:153]
	v_cmp_eq_u32_e32 vcc, 0, v195
	s_waitcnt lgkmcnt(0)
	v_mfma_f32_16x16x32_bf16 v[108:111], v[168:171], v[160:163], v[108:111]
	v_mfma_f32_16x16x32_bf16 v[120:123], v[168:171], v[164:167], v[120:123]
	ds_read_b128 v[168:171], v197 offset:39168
	s_waitcnt lgkmcnt(0)
	v_mfma_f32_16x16x32_bf16 v[112:115], v[168:171], v[160:163], v[112:115]
	v_mfma_f32_16x16x32_bf16 v[124:127], v[168:171], v[164:167], v[124:127]
	ds_read_b128 v[168:171], v197 offset:43520
	s_waitcnt lgkmcnt(0)
	v_mfma_f32_16x16x32_bf16 v[104:107], v[168:171], v[160:163], v[104:107]
	v_mfma_f32_16x16x32_bf16 v[100:103], v[168:171], v[164:167], v[100:103]
	ds_read_b128 v[168:171], v197 offset:47872
	s_waitcnt lgkmcnt(0)
	v_mfma_f32_16x16x32_bf16 v[116:119], v[168:171], v[160:163], v[116:119]
	v_mfma_f32_16x16x32_bf16 v[128:131], v[168:171], v[164:167], v[128:131]
	ds_read_b128 v[160:163], v189 offset:64
	ds_read_b128 v[164:167], v189 offset:4416
	ds_read_b128 v[168:171], v197 offset:34880
	s_waitcnt lgkmcnt(0)
	v_mfma_f32_16x16x32_bf16 v[108:111], v[168:171], v[160:163], v[108:111]
	v_mfma_f32_16x16x32_bf16 v[120:123], v[168:171], v[164:167], v[120:123]
	ds_read_b128 v[168:171], v197 offset:39232
	s_waitcnt lgkmcnt(0)
	v_mfma_f32_16x16x32_bf16 v[112:115], v[168:171], v[160:163], v[112:115]
	v_mfma_f32_16x16x32_bf16 v[124:127], v[168:171], v[164:167], v[124:127]
	ds_read_b128 v[168:171], v197 offset:43584
	s_waitcnt lgkmcnt(0)
	v_mfma_f32_16x16x32_bf16 v[104:107], v[168:171], v[160:163], v[104:107]
	v_mfma_f32_16x16x32_bf16 v[100:103], v[168:171], v[164:167], v[100:103]
	ds_read_b128 v[168:171], v197 offset:47936
	s_waitcnt lgkmcnt(0)
	v_mfma_f32_16x16x32_bf16 v[116:119], v[168:171], v[160:163], v[116:119]
	v_mfma_f32_16x16x32_bf16 v[128:131], v[168:171], v[164:167], v[128:131]
	ds_read_b128 v[160:163], v189 offset:128
	ds_read_b128 v[164:167], v189 offset:4480
	ds_read_b128 v[168:171], v197 offset:34944
	s_waitcnt lgkmcnt(0)
	v_mfma_f32_16x16x32_bf16 v[108:111], v[168:171], v[160:163], v[108:111]
	v_mfma_f32_16x16x32_bf16 v[120:123], v[168:171], v[164:167], v[120:123]
	ds_read_b128 v[168:171], v197 offset:39296
	s_waitcnt lgkmcnt(0)
	v_mfma_f32_16x16x32_bf16 v[172:175], v[168:171], v[160:163], v[112:115]
	s_nop 2
	ds_read_b128 v[112:115], v197 offset:43648
	s_waitcnt lgkmcnt(0)
	v_mfma_f32_16x16x32_bf16 v[104:107], v[112:115], v[160:163], v[104:107]
	v_mfma_f32_16x16x32_bf16 v[100:103], v[112:115], v[164:167], v[100:103]
	ds_read_b128 v[112:115], v197 offset:48000
	v_mfma_f32_16x16x32_bf16 v[168:171], v[168:171], v[164:167], v[124:127]
	s_waitcnt lgkmcnt(0)
	v_mfma_f32_16x16x32_bf16 v[116:119], v[112:115], v[160:163], v[116:119]
	v_mfma_f32_16x16x32_bf16 v[160:163], v[112:115], v[164:167], v[128:131]
	ds_read_b128 v[164:167], v189 offset:192
	ds_read_b128 v[210:213], v189 offset:4544
	ds_read_b128 v[112:115], v197 offset:35008
	s_waitcnt lgkmcnt(0)
	v_mfma_f32_16x16x32_bf16 v[128:131], v[112:115], v[164:167], v[108:111]
	s_nop 2
	ds_read_b128 v[108:111], v197 offset:39360
	s_waitcnt lgkmcnt(0)
	v_mfma_f32_16x16x32_bf16 v[124:127], v[108:111], v[164:167], v[172:175]
	v_mfma_f32_16x16x32_bf16 v[108:111], v[108:111], v[210:213], v[168:171]
	s_nop 2
	ds_read_b128 v[168:171], v197 offset:43712
	v_mfma_f32_16x16x32_bf16 v[112:115], v[112:115], v[210:213], v[120:123]
	s_waitcnt lgkmcnt(0)
	v_mfma_f32_16x16x32_bf16 v[120:123], v[168:171], v[164:167], v[104:107]
	v_mfma_f32_16x16x32_bf16 v[104:107], v[168:171], v[210:213], v[100:103]
	s_nop 2
	ds_read_b128 v[100:103], v197 offset:48064
	s_waitcnt lgkmcnt(0)
	v_mfma_f32_16x16x32_bf16 v[116:119], v[100:103], v[164:167], v[116:119]
	v_mfma_f32_16x16x32_bf16 v[100:103], v[100:103], v[210:213], v[160:163]
	s_nop 2
	v_mul_f32_e32 v162, v129, v129
	v_fmac_f32_e32 v162, v128, v128
	v_fmac_f32_e32 v162, v130, v130
	v_fmac_f32_e32 v162, v131, v131
	v_fmac_f32_e32 v162, v124, v124
	v_fmac_f32_e32 v162, v125, v125
	v_fmac_f32_e32 v162, v126, v126
	v_fmac_f32_e32 v162, v127, v127
	v_fmac_f32_e32 v162, v120, v120
	v_fmac_f32_e32 v162, v121, v121
	v_fmac_f32_e32 v162, v122, v122
	v_fmac_f32_e32 v162, v123, v123
	v_fmac_f32_e32 v162, v116, v116
	v_fmac_f32_e32 v162, v117, v117
	v_lshlrev_b32_e32 v160, 2, v191
	v_fmac_f32_e32 v162, v118, v118
	v_bitop3_b32 v161, v160, 64, v179 bitop3:0x6c
	v_fmac_f32_e32 v162, v119, v119
	ds_bpermute_b32 v163, v161, v162
	v_bitop3_b32 v160, v160, s4, v179 bitop3:0x6c
	s_waitcnt lgkmcnt(0)
	v_add_f32_e32 v162, v162, v163
	ds_bpermute_b32 v163, v160, v162
	s_and_saveexec_b64 s[4:5], vcc
	s_cbranch_execz .LBB0_565
	s_waitcnt lgkmcnt(0)
	v_add_f32_e32 v162, v162, v163
	global_store_dword v[152:153], v162, off
; __device__ __forceinline__ unsigned pack2(float a, float b) { return (unsigned)f2bf(a) | ((unsigned)f2bf(b) << 16); }
; __device__ __forceinline__ void ret_core_phase(const Params& p, const PD& d, char* shm, const int wave_s) {
;     ...
;         for (int f = 0; f < 2; ++f) {
;           float ss = 0.f;
; #pragma unroll
;           for (int vf = 0; vf < 4; ++vf)
; #pragma unroll
;             for (int r = 0; r < 4; ++r) ss += OT[vf][f][r] * OT[vf][f][r];
;           ss += shfl_xor_l(ss, 16, fqv * 16 + frv); ss += shfl_xor_l(ss, 32, fqv * 16 + frv);
;           if (fqv == 0) sst[(16 * f) * 32] = ss;
; #pragma unroll
;           for (int vf = 0; vf < 4; ++vf) {
;             uint2 gq = gpre[vf][f];
;             float g0 = __uint_as_float(gq.x << 16), g1 = __uint_as_float(gq.x & 0xffff0000u);
;             float g2 = __uint_as_float(gq.y << 16), g3 = __uint_as_float(gq.y & 0xffff0000u);
;             uint2 o;
;             o.x = pack2(silu_f(g0) * OT[vf][f][0], silu_f(g1) * OT[vf][f][1]);
;             o.y = pack2(silu_f(g2) * OT[vf][f][2], silu_f(g3) * OT[vf][f][3]);
;             *(uint2*)(got + f * 16 * 2048 + vf * 16) = o;
;           }
.LBB0_565:
	s_or_b64 exec, exec, s[4:5]
	s_waitcnt vmcnt(15)
	v_lshlrev_b32_e32 v162, 16, v158
	v_and_b32_e32 v158, 0xffff0000, v158
	v_mul_f32_e32 v165, 0xbfb8aa3b, v158
	v_exp_f32_e32 v165, v165
	s_waitcnt lgkmcnt(0)
	v_lshlrev_b32_e32 v163, 16, v159
	v_mul_f32_e32 v164, 0xbfb8aa3b, v162
	v_exp_f32_e32 v164, v164
	v_add_f32_e32 v165, 1.0, v165
	v_rcp_f32_e32 v166, v165
	v_mul_f32_e32 v165, 0xbfb8aa3b, v163
	v_exp_f32_e32 v165, v165
	v_add_f32_e32 v164, 1.0, v164
	v_rcp_f32_e32 v164, v164
	v_and_b32_e32 v159, 0xffff0000, v159
	v_add_f32_e32 v165, 1.0, v165
	v_rcp_f32_e32 v165, v165
	s_nop 0
	v_pk_mul_f32 v[162:163], v[164:165], v[162:163]
	v_mov_b32_e32 v164, v128
	v_mul_f32_e32 v128, 0xbfb8aa3b, v159
	v_exp_f32_e32 v128, v128
	v_mov_b32_e32 v165, v130
	v_mov_b32_e32 v130, v129
	v_pk_mul_f32 v[162:163], v[162:163], v[164:165]
	v_add_f32_e32 v128, 1.0, v128
	v_rcp_f32_e32 v167, v128
	s_nop 0
	v_pk_mul_f32 v[158:159], v[166:167], v[158:159]
	s_nop 0
	v_pk_mul_f32 v[128:129], v[158:159], v[130:131]
	s_nop 0
	v_cvt_pk_bf16_f32 v129, v129, v129
	v_cvt_pk_bf16_f32 v128, v128, v128
	v_cvt_pk_bf16_f32 v131, v162, v162
	v_cvt_pk_bf16_f32 v130, v163, v163
	v_and_b32_e32 v129, 0xffff0000, v129
	v_and_b32_e32 v128, 0xffff0000, v128
	v_or_b32_sdwa v129, v129, v130 dst_sel:DWORD dst_unused:UNUSED_PAD src0_sel:DWORD src1_sel:WORD_1
	v_or_b32_sdwa v128, v128, v131 dst_sel:DWORD dst_unused:UNUSED_PAD src0_sel:DWORD src1_sel:WORD_1
	s_waitcnt vmcnt(14)
	v_and_b32_e32 v130, 0xffff0000, v156
	global_store_dwordx2 v[148:149], v[128:129], off
	v_lshlrev_b32_e32 v129, 16, v157
	v_and_b32_e32 v131, 0xffff0000, v157
	v_mul_f32_e32 v157, 0xbfb8aa3b, v130
	v_exp_f32_e32 v157, v157
	v_lshlrev_b32_e32 v128, 16, v156
	v_mul_f32_e32 v156, 0xbfb8aa3b, v128
	v_exp_f32_e32 v156, v156
	v_add_f32_e32 v157, 1.0, v157
	v_rcp_f32_e32 v158, v157
	v_mul_f32_e32 v157, 0xbfb8aa3b, v129
	v_exp_f32_e32 v157, v157
	v_add_f32_e32 v156, 1.0, v156
	v_rcp_f32_e32 v156, v156
	v_add_f32_e32 v157, 1.0, v157
	v_rcp_f32_e32 v157, v157
	s_nop 0
	v_pk_mul_f32 v[128:129], v[156:157], v[128:129]
	v_mov_b32_e32 v156, v124
	v_mul_f32_e32 v124, 0xbfb8aa3b, v131
	v_exp_f32_e32 v124, v124
	v_mov_b32_e32 v157, v126
	v_pk_mul_f32 v[128:129], v[128:129], v[156:157]
	v_mov_b32_e32 v126, v125
	v_add_f32_e32 v124, 1.0, v124
	v_rcp_f32_e32 v159, v124
	s_nop 0
	v_pk_mul_f32 v[130:131], v[158:159], v[130:131]
	s_nop 0
	v_pk_mul_f32 v[124:125], v[130:131], v[126:127]
	s_nop 0
	v_cvt_pk_bf16_f32 v127, v128, v128
	v_cvt_pk_bf16_f32 v125, v125, v125
	v_cvt_pk_bf16_f32 v126, v129, v129
	v_and_b32_e32 v125, 0xffff0000, v125
	v_or_b32_sdwa v125, v125, v126 dst_sel:DWORD dst_unused:UNUSED_PAD src0_sel:DWORD src1_sel:WORD_1
	s_waitcnt vmcnt(14)
	v_and_b32_e32 v126, 0xffff0000, v154
	v_cvt_pk_bf16_f32 v124, v124, v124
	v_mul_f32_e32 v129, 0xbfb8aa3b, v126
	v_exp_f32_e32 v129, v129
	v_and_b32_e32 v124, 0xffff0000, v124
	v_or_b32_sdwa v124, v124, v127 dst_sel:DWORD dst_unused:UNUSED_PAD src0_sel:DWORD src1_sel:WORD_1
	global_store_dwordx2 v[148:149], v[124:125], off offset:32
	v_lshlrev_b32_e32 v125, 16, v155
	v_lshlrev_b32_e32 v124, 16, v154
	v_add_f32_e32 v129, 1.0, v129
	v_mul_f32_e32 v128, 0xbfb8aa3b, v124
	v_rcp_f32_e32 v130, v129
	v_mul_f32_e32 v129, 0xbfb8aa3b, v125
	v_exp_f32_e32 v128, v128
	v_exp_f32_e32 v129, v129
	v_and_b32_e32 v127, 0xffff0000, v155
	v_add_f32_e32 v128, 1.0, v128
	v_add_f32_e32 v129, 1.0, v129
	v_rcp_f32_e32 v128, v128
	v_rcp_f32_e32 v129, v129
	s_nop 0
	v_pk_mul_f32 v[124:125], v[128:129], v[124:125]
	v_mov_b32_e32 v128, v120
	v_mul_f32_e32 v120, 0xbfb8aa3b, v127
	v_exp_f32_e32 v120, v120
	v_mov_b32_e32 v129, v122
	v_pk_mul_f32 v[124:125], v[124:125], v[128:129]
	v_mov_b32_e32 v122, v121
	v_add_f32_e32 v120, 1.0, v120
	v_rcp_f32_e32 v131, v120
	s_nop 0
	v_pk_mul_f32 v[126:127], v[130:131], v[126:127]
	s_nop 0
	v_pk_mul_f32 v[120:121], v[126:127], v[122:123]
	s_nop 0
	v_cvt_pk_bf16_f32 v123, v124, v124
	v_cvt_pk_bf16_f32 v121, v121, v121
	v_cvt_pk_bf16_f32 v122, v125, v125
	v_and_b32_e32 v121, 0xffff0000, v121
	v_or_b32_sdwa v121, v121, v122 dst_sel:DWORD dst_unused:UNUSED_PAD src0_sel:DWORD src1_sel:WORD_1
	s_waitcnt vmcnt(14)
	v_and_b32_e32 v122, 0xffff0000, v150
	v_cvt_pk_bf16_f32 v120, v120, v120
	v_mul_f32_e32 v125, 0xbfb8aa3b, v122
	v_exp_f32_e32 v125, v125
	v_and_b32_e32 v120, 0xffff0000, v120
	v_or_b32_sdwa v120, v120, v123 dst_sel:DWORD dst_unused:UNUSED_PAD src0_sel:DWORD src1_sel:WORD_1
	global_store_dwordx2 v[148:149], v[120:121], off offset:64
	v_lshlrev_b32_e32 v121, 16, v151
	v_lshlrev_b32_e32 v120, 16, v150
	v_add_f32_e32 v125, 1.0, v125
	v_mul_f32_e32 v124, 0xbfb8aa3b, v120
	v_rcp_f32_e32 v126, v125
	v_mul_f32_e32 v125, 0xbfb8aa3b, v121
	v_exp_f32_e32 v124, v124
	v_exp_f32_e32 v125, v125
	v_and_b32_e32 v123, 0xffff0000, v151
	v_add_f32_e32 v124, 1.0, v124
	v_add_f32_e32 v125, 1.0, v125
	v_rcp_f32_e32 v124, v124
	v_rcp_f32_e32 v125, v125
	s_nop 0
	v_pk_mul_f32 v[120:121], v[124:125], v[120:121]
	v_mov_b32_e32 v124, v116
	v_mul_f32_e32 v116, 0xbfb8aa3b, v123
	v_exp_f32_e32 v116, v116
	v_mov_b32_e32 v125, v118
	v_pk_mul_f32 v[120:121], v[120:121], v[124:125]
	v_mov_b32_e32 v118, v117
	v_add_f32_e32 v116, 1.0, v116
	v_rcp_f32_e32 v127, v116
	s_nop 0
	v_pk_mul_f32 v[122:123], v[126:127], v[122:123]
	s_nop 0
	v_pk_mul_f32 v[116:117], v[122:123], v[118:119]
	v_and_b32_sdwa v118, v121, v178 dst_sel:DWORD dst_unused:UNUSED_PAD src0_sel:WORD_1 src1_sel:DWORD
	v_and_b32_sdwa v119, v120, v178 dst_sel:DWORD dst_unused:UNUSED_PAD src0_sel:WORD_1 src1_sel:DWORD
	v_add3_u32 v119, v120, v119, s81
	v_add3_u32 v118, v121, v118, s81
	v_and_b32_sdwa v120, v117, v178 dst_sel:DWORD dst_unused:UNUSED_PAD src0_sel:WORD_1 src1_sel:DWORD
	v_and_b32_sdwa v121, v116, v178 dst_sel:DWORD dst_unused:UNUSED_PAD src0_sel:WORD_1 src1_sel:DWORD
	v_add3_u32 v117, v117, v120, s81
	v_add3_u32 v116, v116, v121, s81
	v_and_b32_e32 v117, 0xffff0000, v117
	v_and_b32_e32 v116, 0xffff0000, v116
	v_or_b32_sdwa v117, v117, v118 dst_sel:DWORD dst_unused:UNUSED_PAD src0_sel:DWORD src1_sel:WORD_1
	v_or_b32_sdwa v116, v116, v119 dst_sel:DWORD dst_unused:UNUSED_PAD src0_sel:DWORD src1_sel:WORD_1
	global_store_dwordx2 v[148:149], v[116:117], off offset:96
	v_mul_f32_e32 v116, v113, v113
	v_fmac_f32_e32 v116, v112, v112
	v_fmac_f32_e32 v116, v114, v114
	v_fmac_f32_e32 v116, v115, v115
	v_fmac_f32_e32 v116, v108, v108
	v_fmac_f32_e32 v116, v109, v109
	v_fmac_f32_e32 v116, v110, v110
	v_fmac_f32_e32 v116, v111, v111
	v_fmac_f32_e32 v116, v104, v104
	v_fmac_f32_e32 v116, v105, v105
	v_fmac_f32_e32 v116, v106, v106
	v_fmac_f32_e32 v116, v107, v107
	v_fmac_f32_e32 v116, v100, v100
	v_fmac_f32_e32 v116, v101, v101
	v_fmac_f32_e32 v116, v102, v102
	v_fmac_f32_e32 v116, v103, v103
	ds_bpermute_b32 v117, v161, v116
	s_waitcnt lgkmcnt(0)
	v_add_f32_e32 v116, v116, v117
	ds_bpermute_b32 v117, v160, v116
	s_and_saveexec_b64 s[4:5], vcc
	s_cbranch_execz .LBB0_562
	s_waitcnt lgkmcnt(0)
	v_add_f32_e32 v116, v116, v117
	global_store_dword v[152:153], v116, off offset:2048
	s_branch .LBB0_562

; __device__ __forceinline__ unsigned pack2(float a, float b) { return (unsigned)f2bf(a) | ((unsigned)f2bf(b) << 16); }
; #define SCHED __builtin_amdgcn_sched_barrier(0)
; template <int EPI, bool HS = false>
; __device__ __forceinline__ void gemm_phase(const Params& p, const GemmCfg& g, char* shm, const int wave_s) {
;     ...
;       } else if (pn < 16) {
;         const int hh = (pn - 8) >> 1, vb = ((pn - 8) & 1) * 256;
;         u16* vt_t = VTb + ((size_t)((b * 4 + hh) * 16 + (mt & 7) * 2) * 512 + vb) * 128;
;         const unsigned kb = (unsigned)((wc * 32 + fr) * 128 + wr * 64 + fq * 4);
; #pragma unroll
;         for (int ai = 0; ai < 2; ++ai)
; #pragma unroll
;           for (int m = 0; m < 4; ++m) {
;             const f32x4 r4 = *(const f32x4*)(rsw + ai * 128 + m * 16);
; #pragma unroll
;             for (int bj = 0; bj < 2; ++bj)
; #pragma unroll
;               for (int n = 0; n < 2; ++n) {
;                 uint2 pk;
;                 pk.x = pack2(r4[0] * acc[ai][bj][m][n][0] + swv[bj][n], r4[1] * acc[ai][bj][m][n][1] + swv[bj][n]);
;                 pk.y = pack2(r4[2] * acc[ai][bj][m][n][2] + swv[bj][n], r4[3] * acc[ai][bj][m][n][3] + swv[bj][n]);
;                 *(uint2*)(vt_t + kb + ai * 512 * 128 + (bj * 128 + n * 16) * 128 + m * 16) = pk;
;               }
;             SCHED;
;           }
.LBB0_592:
	s_andn2_b64 vcc, exec, s[6:7]
	s_cbranch_vccnz .LBB0_594
	s_lshl_b32 s4, s2, 3
	s_and_b32 s4, s4, 0x70
	s_lshl_b32 s5, s3, 1
	s_lshl_b32 s1, s10, 6
	s_or_b32 s4, s4, s5
	ds_read_b128 v[148:151], v154
	s_add_i32 s4, s4, s1
	s_sub_i32 s4, s4, 64
	s_ashr_i32 s5, s4, 31
	s_lshl_b64 s[4:5], s[4:5], 17
	v_readlane_b32 s6, v252, 61
	v_readlane_b32 s7, v252, 62
	s_add_u32 s1, s6, s4
	s_waitcnt lgkmcnt(0)
	v_pk_mul_f32 v[132:133], v[124:125], v[150:151]
	v_pk_mul_f32 v[142:143], v[122:123], v[148:149]
	s_addc_u32 s5, s7, s5
	s_lshl_b32 s4, s2, 16
	v_mov_b32_e32 v144, v142
	v_mov_b32_e32 v145, v132
	s_and_b32 s4, s4, 0x10000
	v_lshl_add_u32 v0, v135, 7, v139
	v_pk_add_f32 v[144:145], v[138:139], v[144:145] op_sel_hi:[0,1]
	v_mov_b32_e32 v132, v143
	s_add_u32 s4, s1, s4
	v_or_b32_e32 v0, v0, v141
	v_pk_add_f32 v[132:133], v[138:139], v[132:133] op_sel_hi:[0,1]
	s_nop 0
	s_addc_u32 s5, s5, 0
	v_lshl_add_u32 v0, v137, 12, v0
	v_cvt_pk_bf16_f32 v142, v144, v144
	s_nop 0
	s_nop 0
	v_lshl_add_u64 v[130:131], v[0:1], 1, s[4:5]
	s_nop 0
	v_cvt_pk_bf16_f32 v133, v133, v133
	v_cvt_pk_bf16_f32 v132, v132, v132
	v_cvt_pk_bf16_f32 v0, v145, v145
	v_and_b32_e32 v133, 0xffff0000, v133
	v_and_b32_e32 v132, 0xffff0000, v132
	v_or_b32_sdwa v133, v133, v0 dst_sel:DWORD dst_unused:UNUSED_PAD src0_sel:DWORD src1_sel:WORD_1
	v_or_b32_sdwa v132, v132, v142 dst_sel:DWORD dst_unused:UNUSED_PAD src0_sel:DWORD src1_sel:WORD_1
	global_store_dwordx2 v[130:131], v[132:133], off
	v_pk_mul_f32 v[132:133], v[128:129], v[150:151]
	v_pk_mul_f32 v[142:143], v[126:127], v[148:149]
	v_mov_b32_e32 v145, v132
	v_mov_b32_e32 v144, v142
	v_pk_add_f32 v[144:145], v[140:141], v[144:145] op_sel_hi:[0,1]
	v_mov_b32_e32 v132, v143
	v_pk_add_f32 v[132:133], v[140:141], v[132:133] op_sel_hi:[0,1]
	v_cvt_pk_bf16_f32 v142, v144, v144
	v_cvt_pk_bf16_f32 v132, v132, v132
	s_nop 0
	v_cvt_pk_bf16_f32 v133, v133, v133
	v_and_b32_e32 v132, 0xffff0000, v132
	s_movk_i32 s1, 0x1000
	v_cvt_pk_bf16_f32 v0, v145, v145
	v_and_b32_e32 v133, 0xffff0000, v133
	v_or_b32_sdwa v132, v132, v142 dst_sel:DWORD dst_unused:UNUSED_PAD src0_sel:DWORD src1_sel:WORD_1
	v_add_co_u32_e32 v142, vcc, s1, v130
	v_or_b32_sdwa v133, v133, v0 dst_sel:DWORD dst_unused:UNUSED_PAD src0_sel:DWORD src1_sel:WORD_1
	s_nop 0
	v_addc_co_u32_e32 v143, vcc, 0, v131, vcc
	global_store_dwordx2 v[142:143], v[132:133], off
	v_pk_mul_f32 v[132:133], v[116:117], v[150:151]
	v_pk_mul_f32 v[144:145], v[114:115], v[148:149]
	v_mov_b32_e32 v153, v132
	v_mov_b32_e32 v152, v144
	v_pk_add_f32 v[152:153], v[134:135], v[152:153] op_sel_hi:[0,1]
	v_mov_b32_e32 v132, v145
	v_pk_add_f32 v[132:133], v[134:135], v[132:133] op_sel_hi:[0,1]
	v_cvt_pk_bf16_f32 v144, v152, v152
	s_nop 0
	v_cvt_pk_bf16_f32 v132, v132, v132
	v_and_b32_e32 v132, 0xffff0000, v132
	s_mov_b32 s1, 0x8000
	s_nop 0
	v_or_b32_sdwa v152, v132, v144 dst_sel:DWORD dst_unused:UNUSED_PAD src0_sel:DWORD src1_sel:WORD_1
	v_add_co_u32_e32 v144, vcc, s1, v130
	s_nop 0
	v_cvt_pk_bf16_f32 v133, v133, v133
	v_addc_co_u32_e32 v145, vcc, 0, v131, vcc
	v_cvt_pk_bf16_f32 v0, v153, v153
	v_and_b32_e32 v133, 0xffff0000, v133
	v_add_co_u32_e32 v132, vcc, s80, v130
	v_or_b32_sdwa v153, v133, v0 dst_sel:DWORD dst_unused:UNUSED_PAD src0_sel:DWORD src1_sel:WORD_1
	s_nop 0
	v_addc_co_u32_e32 v133, vcc, 0, v131, vcc
	v_pk_mul_f32 v[150:151], v[120:121], v[150:151]
	v_pk_mul_f32 v[148:149], v[118:119], v[148:149]
	global_store_dwordx2 v[132:133], v[152:153], off offset:-4096
	v_mov_b32_e32 v152, v148
	v_mov_b32_e32 v153, v150
	v_pk_add_f32 v[152:153], v[136:137], v[152:153] op_sel_hi:[0,1]
	v_mov_b32_e32 v150, v149
	v_pk_add_f32 v[148:149], v[136:137], v[150:151] op_sel_hi:[0,1]
	v_cvt_pk_bf16_f32 v150, v152, v152
	v_cvt_pk_bf16_f32 v149, v149, v149
	v_cvt_pk_bf16_f32 v148, v148, v148
	v_cvt_pk_bf16_f32 v0, v153, v153
	v_and_b32_e32 v149, 0xffff0000, v149
	v_and_b32_e32 v148, 0xffff0000, v148
	v_or_b32_sdwa v149, v149, v0 dst_sel:DWORD dst_unused:UNUSED_PAD src0_sel:DWORD src1_sel:WORD_1
	v_or_b32_sdwa v148, v148, v150 dst_sel:DWORD dst_unused:UNUSED_PAD src0_sel:DWORD src1_sel:WORD_1
	global_store_dwordx2 v[132:133], v[148:149], off
	ds_read_b128 v[148:151], v154 offset:64
	s_waitcnt lgkmcnt(0)
	v_pk_mul_f32 v[152:153], v[108:109], v[150:151]
	v_pk_mul_f32 v[156:157], v[106:107], v[148:149]
	v_mov_b32_e32 v159, v152
	v_mov_b32_e32 v158, v156
	v_mov_b32_e32 v152, v157
	v_pk_add_f32 v[156:157], v[138:139], v[158:159] op_sel_hi:[0,1]
	v_pk_add_f32 v[152:153], v[138:139], v[152:153] op_sel_hi:[0,1]
	v_cvt_pk_bf16_f32 v155, v156, v156
	v_cvt_pk_bf16_f32 v0, v157, v157
	v_cvt_pk_bf16_f32 v153, v153, v153
	v_cvt_pk_bf16_f32 v152, v152, v152
	v_and_b32_e32 v153, 0xffff0000, v153
	v_and_b32_e32 v152, 0xffff0000, v152
	v_or_b32_sdwa v153, v153, v0 dst_sel:DWORD dst_unused:UNUSED_PAD src0_sel:DWORD src1_sel:WORD_1
	v_or_b32_sdwa v152, v152, v155 dst_sel:DWORD dst_unused:UNUSED_PAD src0_sel:DWORD src1_sel:WORD_1
	global_store_dwordx2 v[130:131], v[152:153], off offset:32
	v_pk_mul_f32 v[152:153], v[112:113], v[150:151]
	v_pk_mul_f32 v[156:157], v[110:111], v[148:149]
	v_mov_b32_e32 v159, v152
	v_mov_b32_e32 v152, v157
	v_mov_b32_e32 v158, v156
	v_pk_add_f32 v[152:153], v[140:141], v[152:153] op_sel_hi:[0,1]
	v_pk_add_f32 v[158:159], v[140:141], v[158:159] op_sel_hi:[0,1]
	v_cvt_pk_bf16_f32 v153, v153, v153
	v_cvt_pk_bf16_f32 v152, v152, v152
	v_cvt_pk_bf16_f32 v155, v158, v158
	v_cvt_pk_bf16_f32 v0, v159, v159
	v_and_b32_e32 v153, 0xffff0000, v153
	v_and_b32_e32 v152, 0xffff0000, v152
	v_or_b32_sdwa v153, v153, v0 dst_sel:DWORD dst_unused:UNUSED_PAD src0_sel:DWORD src1_sel:WORD_1
; __device__ __forceinline__ unsigned pack2(float a, float b) { return (unsigned)f2bf(a) | ((unsigned)f2bf(b) << 16); }
; #define SCHED __builtin_amdgcn_sched_barrier(0)
; template <int EPI, bool HS = false>
; __device__ __forceinline__ void gemm_phase(const Params& p, const GemmCfg& g, char* shm, const int wave_s) {
;     ...
;           for (int m = 0; m < 4; ++m) {
;             const f32x4 r4 = *(const f32x4*)(rsw + ai * 128 + m * 16);
; #pragma unroll
;             for (int bj = 0; bj < 2; ++bj)
; #pragma unroll
;               for (int n = 0; n < 2; ++n) {
;                 uint2 pk;
;                 pk.x = pack2(r4[0] * acc[ai][bj][m][n][0] + swv[bj][n], r4[1] * acc[ai][bj][m][n][1] + swv[bj][n]);
;                 pk.y = pack2(r4[2] * acc[ai][bj][m][n][2] + swv[bj][n], r4[3] * acc[ai][bj][m][n][3] + swv[bj][n]);
;                 *(uint2*)(vt_t + kb + ai * 512 * 128 + (bj * 128 + n * 16) * 128 + m * 16) = pk;
;               }
;             SCHED;
	v_or_b32_sdwa v152, v152, v155 dst_sel:DWORD dst_unused:UNUSED_PAD src0_sel:DWORD src1_sel:WORD_1
	global_store_dwordx2 v[142:143], v[152:153], off offset:32
	v_pk_mul_f32 v[152:153], v[100:101], v[150:151]
	v_pk_mul_f32 v[156:157], v[98:99], v[148:149]
	v_mov_b32_e32 v159, v152
	v_mov_b32_e32 v152, v157
	v_mov_b32_e32 v158, v156
	v_pk_add_f32 v[152:153], v[134:135], v[152:153] op_sel_hi:[0,1]
	v_pk_add_f32 v[158:159], v[134:135], v[158:159] op_sel_hi:[0,1]
	v_cvt_pk_bf16_f32 v153, v153, v153
	v_cvt_pk_bf16_f32 v152, v152, v152
	v_cvt_pk_bf16_f32 v155, v158, v158
	v_cvt_pk_bf16_f32 v0, v159, v159
	v_and_b32_e32 v153, 0xffff0000, v153
	v_and_b32_e32 v152, 0xffff0000, v152
	v_or_b32_sdwa v153, v153, v0 dst_sel:DWORD dst_unused:UNUSED_PAD src0_sel:DWORD src1_sel:WORD_1
	v_or_b32_sdwa v152, v152, v155 dst_sel:DWORD dst_unused:UNUSED_PAD src0_sel:DWORD src1_sel:WORD_1
	v_pk_mul_f32 v[150:151], v[104:105], v[150:151]
	v_pk_mul_f32 v[148:149], v[102:103], v[148:149]
	global_store_dwordx2 v[144:145], v[152:153], off offset:32
	v_mov_b32_e32 v152, v148
	v_mov_b32_e32 v153, v150
	v_pk_add_f32 v[152:153], v[136:137], v[152:153] op_sel_hi:[0,1]
	v_mov_b32_e32 v150, v149
	v_pk_add_f32 v[148:149], v[136:137], v[150:151] op_sel_hi:[0,1]
	v_cvt_pk_bf16_f32 v150, v152, v152
	v_cvt_pk_bf16_f32 v149, v149, v149
	v_cvt_pk_bf16_f32 v148, v148, v148
	v_cvt_pk_bf16_f32 v0, v153, v153
	v_and_b32_e32 v149, 0xffff0000, v149
	v_and_b32_e32 v148, 0xffff0000, v148
	v_or_b32_sdwa v149, v149, v0 dst_sel:DWORD dst_unused:UNUSED_PAD src0_sel:DWORD src1_sel:WORD_1
	v_or_b32_sdwa v148, v148, v150 dst_sel:DWORD dst_unused:UNUSED_PAD src0_sel:DWORD src1_sel:WORD_1
	global_store_dwordx2 v[132:133], v[148:149], off offset:32
	ds_read_b128 v[148:151], v154 offset:128
	s_waitcnt lgkmcnt(0)
	v_pk_mul_f32 v[152:153], v[92:93], v[150:151]
	v_pk_mul_f32 v[156:157], v[90:91], v[148:149]
	v_mov_b32_e32 v159, v152
	v_mov_b32_e32 v158, v156
	v_mov_b32_e32 v152, v157
	v_pk_add_f32 v[156:157], v[138:139], v[158:159] op_sel_hi:[0,1]
	v_pk_add_f32 v[152:153], v[138:139], v[152:153] op_sel_hi:[0,1]
	v_cvt_pk_bf16_f32 v155, v156, v156
	v_cvt_pk_bf16_f32 v0, v157, v157
	v_cvt_pk_bf16_f32 v153, v153, v153
	v_cvt_pk_bf16_f32 v152, v152, v152
	v_and_b32_e32 v153, 0xffff0000, v153
	v_and_b32_e32 v152, 0xffff0000, v152
	v_or_b32_sdwa v153, v153, v0 dst_sel:DWORD dst_unused:UNUSED_PAD src0_sel:DWORD src1_sel:WORD_1
	v_or_b32_sdwa v152, v152, v155 dst_sel:DWORD dst_unused:UNUSED_PAD src0_sel:DWORD src1_sel:WORD_1
	global_store_dwordx2 v[130:131], v[152:153], off offset:64
	v_pk_mul_f32 v[152:153], v[96:97], v[150:151]
	v_pk_mul_f32 v[156:157], v[94:95], v[148:149]
	v_mov_b32_e32 v159, v152
	v_mov_b32_e32 v152, v157
	v_mov_b32_e32 v158, v156
	v_pk_add_f32 v[152:153], v[140:141], v[152:153] op_sel_hi:[0,1]
	v_pk_add_f32 v[158:159], v[140:141], v[158:159] op_sel_hi:[0,1]
	v_cvt_pk_bf16_f32 v153, v153, v153
	v_cvt_pk_bf16_f32 v152, v152, v152
	v_cvt_pk_bf16_f32 v155, v158, v158
	v_cvt_pk_bf16_f32 v0, v159, v159
	v_and_b32_e32 v153, 0xffff0000, v153
	v_and_b32_e32 v152, 0xffff0000, v152
	v_or_b32_sdwa v153, v153, v0 dst_sel:DWORD dst_unused:UNUSED_PAD src0_sel:DWORD src1_sel:WORD_1
	v_or_b32_sdwa v152, v152, v155 dst_sel:DWORD dst_unused:UNUSED_PAD src0_sel:DWORD src1_sel:WORD_1
	global_store_dwordx2 v[142:143], v[152:153], off offset:64
	v_pk_mul_f32 v[152:153], v[84:85], v[150:151]
	v_pk_mul_f32 v[156:157], v[82:83], v[148:149]
	v_mov_b32_e32 v159, v152
	v_mov_b32_e32 v152, v157
	v_mov_b32_e32 v158, v156
	v_pk_add_f32 v[152:153], v[134:135], v[152:153] op_sel_hi:[0,1]
	v_pk_add_f32 v[158:159], v[134:135], v[158:159] op_sel_hi:[0,1]
	v_cvt_pk_bf16_f32 v153, v153, v153
	v_cvt_pk_bf16_f32 v152, v152, v152
	v_cvt_pk_bf16_f32 v155, v158, v158
	v_cvt_pk_bf16_f32 v0, v159, v159
	v_and_b32_e32 v153, 0xffff0000, v153
	v_and_b32_e32 v152, 0xffff0000, v152
	v_or_b32_sdwa v153, v153, v0 dst_sel:DWORD dst_unused:UNUSED_PAD src0_sel:DWORD src1_sel:WORD_1
	v_or_b32_sdwa v152, v152, v155 dst_sel:DWORD dst_unused:UNUSED_PAD src0_sel:DWORD src1_sel:WORD_1
	v_pk_mul_f32 v[150:151], v[88:89], v[150:151]
	v_pk_mul_f32 v[148:149], v[86:87], v[148:149]
	global_store_dwordx2 v[144:145], v[152:153], off offset:64
	v_mov_b32_e32 v152, v148
	v_mov_b32_e32 v153, v150
	v_pk_add_f32 v[152:153], v[136:137], v[152:153] op_sel_hi:[0,1]
	v_mov_b32_e32 v150, v149
	v_pk_add_f32 v[148:149], v[136:137], v[150:151] op_sel_hi:[0,1]
	v_cvt_pk_bf16_f32 v150, v152, v152
	v_cvt_pk_bf16_f32 v149, v149, v149
	v_cvt_pk_bf16_f32 v148, v148, v148
	v_cvt_pk_bf16_f32 v0, v153, v153
	v_and_b32_e32 v149, 0xffff0000, v149
	v_and_b32_e32 v148, 0xffff0000, v148
	v_or_b32_sdwa v149, v149, v0 dst_sel:DWORD dst_unused:UNUSED_PAD src0_sel:DWORD src1_sel:WORD_1
	v_or_b32_sdwa v148, v148, v150 dst_sel:DWORD dst_unused:UNUSED_PAD src0_sel:DWORD src1_sel:WORD_1
	global_store_dwordx2 v[132:133], v[148:149], off offset:64
	ds_read_b128 v[148:151], v154 offset:192
	s_waitcnt lgkmcnt(0)
; __device__ __forceinline__ unsigned pack2(float a, float b) { return (unsigned)f2bf(a) | ((unsigned)f2bf(b) << 16); }
; #define SCHED __builtin_amdgcn_sched_barrier(0)
; template <int EPI, bool HS = false>
; __device__ __forceinline__ void gemm_phase(const Params& p, const GemmCfg& g, char* shm, const int wave_s) {
;     ...
;           for (int m = 0; m < 4; ++m) {
;             const f32x4 r4 = *(const f32x4*)(rsw + ai * 128 + m * 16);
; #pragma unroll
;             for (int bj = 0; bj < 2; ++bj)
; #pragma unroll
;               for (int n = 0; n < 2; ++n) {
;                 uint2 pk;
;                 pk.x = pack2(r4[0] * acc[ai][bj][m][n][0] + swv[bj][n], r4[1] * acc[ai][bj][m][n][1] + swv[bj][n]);
;                 pk.y = pack2(r4[2] * acc[ai][bj][m][n][2] + swv[bj][n], r4[3] * acc[ai][bj][m][n][3] + swv[bj][n]);
;                 *(uint2*)(vt_t + kb + ai * 512 * 128 + (bj * 128 + n * 16) * 128 + m * 16) = pk;
;               }
;             SCHED;
	v_pk_mul_f32 v[152:153], v[76:77], v[150:151]
	v_pk_mul_f32 v[156:157], v[74:75], v[148:149]
	v_mov_b32_e32 v159, v152
	v_mov_b32_e32 v158, v156
	v_mov_b32_e32 v152, v157
	v_pk_add_f32 v[156:157], v[138:139], v[158:159] op_sel_hi:[0,1]
	v_pk_add_f32 v[152:153], v[138:139], v[152:153] op_sel_hi:[0,1]
	v_cvt_pk_bf16_f32 v155, v156, v156
	v_cvt_pk_bf16_f32 v0, v157, v157
	v_cvt_pk_bf16_f32 v153, v153, v153
	v_cvt_pk_bf16_f32 v152, v152, v152
	v_and_b32_e32 v153, 0xffff0000, v153
	v_and_b32_e32 v152, 0xffff0000, v152
	v_or_b32_sdwa v153, v153, v0 dst_sel:DWORD dst_unused:UNUSED_PAD src0_sel:DWORD src1_sel:WORD_1
	v_or_b32_sdwa v152, v152, v155 dst_sel:DWORD dst_unused:UNUSED_PAD src0_sel:DWORD src1_sel:WORD_1
	global_store_dwordx2 v[130:131], v[152:153], off offset:96
	v_pk_mul_f32 v[152:153], v[80:81], v[150:151]
	v_pk_mul_f32 v[156:157], v[78:79], v[148:149]
	v_mov_b32_e32 v159, v152
	v_mov_b32_e32 v152, v157
	v_mov_b32_e32 v158, v156
	v_pk_add_f32 v[152:153], v[140:141], v[152:153] op_sel_hi:[0,1]
	v_pk_add_f32 v[158:159], v[140:141], v[158:159] op_sel_hi:[0,1]
	v_cvt_pk_bf16_f32 v153, v153, v153
	v_cvt_pk_bf16_f32 v152, v152, v152
	v_cvt_pk_bf16_f32 v155, v158, v158
	v_cvt_pk_bf16_f32 v0, v159, v159
	v_and_b32_e32 v153, 0xffff0000, v153
	v_and_b32_e32 v152, 0xffff0000, v152
	v_or_b32_sdwa v153, v153, v0 dst_sel:DWORD dst_unused:UNUSED_PAD src0_sel:DWORD src1_sel:WORD_1
	v_or_b32_sdwa v152, v152, v155 dst_sel:DWORD dst_unused:UNUSED_PAD src0_sel:DWORD src1_sel:WORD_1
	global_store_dwordx2 v[142:143], v[152:153], off offset:96
	v_pk_mul_f32 v[142:143], v[68:69], v[150:151]
	v_pk_mul_f32 v[152:153], v[66:67], v[148:149]
	v_mov_b32_e32 v157, v142
	v_mov_b32_e32 v142, v153
	v_mov_b32_e32 v156, v152
	v_pk_add_f32 v[142:143], v[134:135], v[142:143] op_sel_hi:[0,1]
	v_pk_add_f32 v[156:157], v[134:135], v[156:157] op_sel_hi:[0,1]
	v_cvt_pk_bf16_f32 v143, v143, v143
	v_cvt_pk_bf16_f32 v142, v142, v142
	v_cvt_pk_bf16_f32 v152, v156, v156
	v_cvt_pk_bf16_f32 v0, v157, v157
	v_and_b32_e32 v143, 0xffff0000, v143
	v_and_b32_e32 v142, 0xffff0000, v142
	v_or_b32_sdwa v143, v143, v0 dst_sel:DWORD dst_unused:UNUSED_PAD src0_sel:DWORD src1_sel:WORD_1
	v_or_b32_sdwa v142, v142, v152 dst_sel:DWORD dst_unused:UNUSED_PAD src0_sel:DWORD src1_sel:WORD_1
	global_store_dwordx2 v[144:145], v[142:143], off offset:96
	v_pk_mul_f32 v[142:143], v[72:73], v[150:151]
	v_pk_mul_f32 v[144:145], v[70:71], v[148:149]
	v_mov_b32_e32 v149, v142
	v_mov_b32_e32 v148, v144
	v_pk_add_f32 v[148:149], v[136:137], v[148:149] op_sel_hi:[0,1]
	v_mov_b32_e32 v142, v145
	v_pk_add_f32 v[142:143], v[136:137], v[142:143] op_sel_hi:[0,1]
	v_cvt_pk_bf16_f32 v144, v148, v148
	v_cvt_pk_bf16_f32 v143, v143, v143
	v_cvt_pk_bf16_f32 v142, v142, v142
	v_cvt_pk_bf16_f32 v0, v149, v149
	v_and_b32_e32 v143, 0xffff0000, v143
	v_and_b32_e32 v142, 0xffff0000, v142
	v_or_b32_sdwa v143, v143, v0 dst_sel:DWORD dst_unused:UNUSED_PAD src0_sel:DWORD src1_sel:WORD_1
	v_or_b32_sdwa v142, v142, v144 dst_sel:DWORD dst_unused:UNUSED_PAD src0_sel:DWORD src1_sel:WORD_1
	global_store_dwordx2 v[132:133], v[142:143], off offset:96
	ds_read_b128 v[148:151], v154 offset:512
	s_mov_b32 s1, 0x20000
	s_waitcnt lgkmcnt(0)
	v_pk_mul_f32 v[132:133], v[60:61], v[150:151]
	v_pk_mul_f32 v[142:143], v[58:59], v[148:149]
	v_mov_b32_e32 v145, v132
	v_mov_b32_e32 v144, v142
	v_mov_b32_e32 v132, v143
	v_pk_add_f32 v[142:143], v[138:139], v[144:145] op_sel_hi:[0,1]
	v_pk_add_f32 v[132:133], v[138:139], v[132:133] op_sel_hi:[0,1]
	v_cvt_pk_bf16_f32 v142, v142, v142
	v_cvt_pk_bf16_f32 v132, v132, v132
	v_and_b32_e32 v132, 0xffff0000, v132
	v_cvt_pk_bf16_f32 v0, v143, v143
	s_nop 0
	v_or_b32_sdwa v144, v132, v142 dst_sel:DWORD dst_unused:UNUSED_PAD src0_sel:DWORD src1_sel:WORD_1
	v_add_co_u32_e32 v142, vcc, s1, v130
	v_cvt_pk_bf16_f32 v133, v133, v133
	s_nop 0
	v_addc_co_u32_e32 v143, vcc, 0, v131, vcc
	s_mov_b32 s1, 0x21000
	v_and_b32_e32 v133, 0xffff0000, v133
	v_add_co_u32_e32 v132, vcc, s1, v130
	v_or_b32_sdwa v145, v133, v0 dst_sel:DWORD dst_unused:UNUSED_PAD src0_sel:DWORD src1_sel:WORD_1
	s_nop 0
	v_addc_co_u32_e32 v133, vcc, 0, v131, vcc
	global_store_dwordx2 v[132:133], v[144:145], off offset:-4096
	v_pk_mul_f32 v[144:145], v[64:65], v[150:151]
	v_pk_mul_f32 v[152:153], v[62:63], v[148:149]
	v_mov_b32_e32 v157, v144
	v_mov_b32_e32 v144, v153
	v_mov_b32_e32 v156, v152
	v_pk_add_f32 v[144:145], v[140:141], v[144:145] op_sel_hi:[0,1]
	v_pk_add_f32 v[156:157], v[140:141], v[156:157] op_sel_hi:[0,1]
	v_cvt_pk_bf16_f32 v145, v145, v145
	v_cvt_pk_bf16_f32 v144, v144, v144
	v_cvt_pk_bf16_f32 v152, v156, v156
	v_cvt_pk_bf16_f32 v0, v157, v157
	v_and_b32_e32 v145, 0xffff0000, v145
	v_and_b32_e32 v144, 0xffff0000, v144
	v_or_b32_sdwa v145, v145, v0 dst_sel:DWORD dst_unused:UNUSED_PAD src0_sel:DWORD src1_sel:WORD_1
	v_or_b32_sdwa v144, v144, v152 dst_sel:DWORD dst_unused:UNUSED_PAD src0_sel:DWORD src1_sel:WORD_1
	global_store_dwordx2 v[132:133], v[144:145], off
	v_pk_mul_f32 v[144:145], v[52:53], v[150:151]
	v_pk_mul_f32 v[152:153], v[50:51], v[148:149]
	v_mov_b32_e32 v157, v144
	v_mov_b32_e32 v144, v153
	v_mov_b32_e32 v156, v152
	v_pk_add_f32 v[144:145], v[134:135], v[144:145] op_sel_hi:[0,1]
	v_pk_add_f32 v[156:157], v[134:135], v[156:157] op_sel_hi:[0,1]
	v_cvt_pk_bf16_f32 v144, v144, v144
	v_cvt_pk_bf16_f32 v152, v156, v156
	v_cvt_pk_bf16_f32 v145, v145, v145
	v_and_b32_e32 v144, 0xffff0000, v144
	s_mov_b32 s1, 0x28000
	v_cvt_pk_bf16_f32 v0, v157, v157
	v_and_b32_e32 v145, 0xffff0000, v145
	v_or_b32_sdwa v152, v144, v152 dst_sel:DWORD dst_unused:UNUSED_PAD src0_sel:DWORD src1_sel:WORD_1
	v_add_co_u32_e32 v144, vcc, s1, v130
	v_or_b32_sdwa v153, v145, v0 dst_sel:DWORD dst_unused:UNUSED_PAD src0_sel:DWORD src1_sel:WORD_1
	s_nop 0
	v_addc_co_u32_e32 v145, vcc, 0, v131, vcc
	s_mov_b32 s1, 0x29000
	v_add_co_u32_e32 v130, vcc, s1, v130
	v_pk_mul_f32 v[150:151], v[56:57], v[150:151]
	s_nop 0
	v_addc_co_u32_e32 v131, vcc, 0, v131, vcc
	v_pk_mul_f32 v[148:149], v[54:55], v[148:149]
	global_store_dwordx2 v[130:131], v[152:153], off offset:-4096
	v_mov_b32_e32 v152, v148
	v_mov_b32_e32 v153, v150
	v_pk_add_f32 v[152:153], v[136:137], v[152:153] op_sel_hi:[0,1]
	v_mov_b32_e32 v150, v149
	v_pk_add_f32 v[148:149], v[136:137], v[150:151] op_sel_hi:[0,1]
	v_cvt_pk_bf16_f32 v150, v152, v152
	v_cvt_pk_bf16_f32 v149, v149, v149
	v_cvt_pk_bf16_f32 v148, v148, v148
	v_cvt_pk_bf16_f32 v0, v153, v153
	v_and_b32_e32 v149, 0xffff0000, v149
	v_and_b32_e32 v148, 0xffff0000, v148
	v_or_b32_sdwa v149, v149, v0 dst_sel:DWORD dst_unused:UNUSED_PAD src0_sel:DWORD src1_sel:WORD_1
	v_or_b32_sdwa v148, v148, v150 dst_sel:DWORD dst_unused:UNUSED_PAD src0_sel:DWORD src1_sel:WORD_1
	global_store_dwordx2 v[130:131], v[148:149], off
	ds_read_b128 v[148:151], v154 offset:576
	s_waitcnt lgkmcnt(0)
; __device__ __forceinline__ unsigned pack2(float a, float b) { return (unsigned)f2bf(a) | ((unsigned)f2bf(b) << 16); }
; #define SCHED __builtin_amdgcn_sched_barrier(0)
; template <int EPI, bool HS = false>
; __device__ __forceinline__ void gemm_phase(const Params& p, const GemmCfg& g, char* shm, const int wave_s) {
;     ...
;           for (int m = 0; m < 4; ++m) {
;             const f32x4 r4 = *(const f32x4*)(rsw + ai * 128 + m * 16);
; #pragma unroll
;             for (int bj = 0; bj < 2; ++bj)
; #pragma unroll
;               for (int n = 0; n < 2; ++n) {
;                 uint2 pk;
;                 pk.x = pack2(r4[0] * acc[ai][bj][m][n][0] + swv[bj][n], r4[1] * acc[ai][bj][m][n][1] + swv[bj][n]);
;                 pk.y = pack2(r4[2] * acc[ai][bj][m][n][2] + swv[bj][n], r4[3] * acc[ai][bj][m][n][3] + swv[bj][n]);
;                 *(uint2*)(vt_t + kb + ai * 512 * 128 + (bj * 128 + n * 16) * 128 + m * 16) = pk;
;               }
;             SCHED;
	v_pk_mul_f32 v[152:153], v[44:45], v[150:151]
	v_pk_mul_f32 v[156:157], v[42:43], v[148:149]
	v_mov_b32_e32 v159, v152
	v_mov_b32_e32 v158, v156
	v_mov_b32_e32 v152, v157
	v_pk_add_f32 v[156:157], v[138:139], v[158:159] op_sel_hi:[0,1]
	v_pk_add_f32 v[152:153], v[138:139], v[152:153] op_sel_hi:[0,1]
	v_cvt_pk_bf16_f32 v155, v156, v156
	v_cvt_pk_bf16_f32 v0, v157, v157
	v_cvt_pk_bf16_f32 v153, v153, v153
	v_cvt_pk_bf16_f32 v152, v152, v152
	v_and_b32_e32 v153, 0xffff0000, v153
	v_and_b32_e32 v152, 0xffff0000, v152
	v_or_b32_sdwa v153, v153, v0 dst_sel:DWORD dst_unused:UNUSED_PAD src0_sel:DWORD src1_sel:WORD_1
	v_or_b32_sdwa v152, v152, v155 dst_sel:DWORD dst_unused:UNUSED_PAD src0_sel:DWORD src1_sel:WORD_1
	global_store_dwordx2 v[142:143], v[152:153], off offset:32
	v_pk_mul_f32 v[152:153], v[48:49], v[150:151]
	v_pk_mul_f32 v[156:157], v[46:47], v[148:149]
	v_mov_b32_e32 v159, v152
	v_mov_b32_e32 v152, v157
	v_mov_b32_e32 v158, v156
	v_pk_add_f32 v[152:153], v[140:141], v[152:153] op_sel_hi:[0,1]
	v_pk_add_f32 v[158:159], v[140:141], v[158:159] op_sel_hi:[0,1]
	v_cvt_pk_bf16_f32 v153, v153, v153
	v_cvt_pk_bf16_f32 v152, v152, v152
	v_cvt_pk_bf16_f32 v155, v158, v158
	v_cvt_pk_bf16_f32 v0, v159, v159
	v_and_b32_e32 v153, 0xffff0000, v153
	v_and_b32_e32 v152, 0xffff0000, v152
	v_or_b32_sdwa v153, v153, v0 dst_sel:DWORD dst_unused:UNUSED_PAD src0_sel:DWORD src1_sel:WORD_1
	v_or_b32_sdwa v152, v152, v155 dst_sel:DWORD dst_unused:UNUSED_PAD src0_sel:DWORD src1_sel:WORD_1
	global_store_dwordx2 v[132:133], v[152:153], off offset:32
	v_pk_mul_f32 v[152:153], v[36:37], v[150:151]
	v_pk_mul_f32 v[156:157], v[34:35], v[148:149]
	v_mov_b32_e32 v159, v152
	v_mov_b32_e32 v152, v157
	v_mov_b32_e32 v158, v156
	v_pk_add_f32 v[152:153], v[134:135], v[152:153] op_sel_hi:[0,1]
	v_pk_add_f32 v[158:159], v[134:135], v[158:159] op_sel_hi:[0,1]
	v_cvt_pk_bf16_f32 v153, v153, v153
	v_cvt_pk_bf16_f32 v152, v152, v152
	v_cvt_pk_bf16_f32 v155, v158, v158
	v_cvt_pk_bf16_f32 v0, v159, v159
	v_and_b32_e32 v153, 0xffff0000, v153
	v_and_b32_e32 v152, 0xffff0000, v152
	v_or_b32_sdwa v153, v153, v0 dst_sel:DWORD dst_unused:UNUSED_PAD src0_sel:DWORD src1_sel:WORD_1
	v_or_b32_sdwa v152, v152, v155 dst_sel:DWORD dst_unused:UNUSED_PAD src0_sel:DWORD src1_sel:WORD_1
	v_pk_mul_f32 v[150:151], v[40:41], v[150:151]
	v_pk_mul_f32 v[148:149], v[38:39], v[148:149]
	global_store_dwordx2 v[144:145], v[152:153], off offset:32
	v_mov_b32_e32 v152, v148
	v_mov_b32_e32 v153, v150
	v_pk_add_f32 v[152:153], v[136:137], v[152:153] op_sel_hi:[0,1]
	v_mov_b32_e32 v150, v149
	v_pk_add_f32 v[148:149], v[136:137], v[150:151] op_sel_hi:[0,1]
	v_cvt_pk_bf16_f32 v150, v152, v152
	v_cvt_pk_bf16_f32 v149, v149, v149
	v_cvt_pk_bf16_f32 v148, v148, v148
	v_cvt_pk_bf16_f32 v0, v153, v153
	v_and_b32_e32 v149, 0xffff0000, v149
	v_and_b32_e32 v148, 0xffff0000, v148
	v_or_b32_sdwa v149, v149, v0 dst_sel:DWORD dst_unused:UNUSED_PAD src0_sel:DWORD src1_sel:WORD_1
	v_or_b32_sdwa v148, v148, v150 dst_sel:DWORD dst_unused:UNUSED_PAD src0_sel:DWORD src1_sel:WORD_1
	global_store_dwordx2 v[130:131], v[148:149], off offset:32
	ds_read_b128 v[148:151], v154 offset:640
	s_waitcnt lgkmcnt(0)
	v_pk_mul_f32 v[152:153], v[28:29], v[150:151]
	v_pk_mul_f32 v[156:157], v[26:27], v[148:149]
	v_mov_b32_e32 v159, v152
	v_mov_b32_e32 v158, v156
	v_mov_b32_e32 v152, v157
	v_pk_add_f32 v[156:157], v[138:139], v[158:159] op_sel_hi:[0,1]
	v_pk_add_f32 v[152:153], v[138:139], v[152:153] op_sel_hi:[0,1]
	v_cvt_pk_bf16_f32 v155, v156, v156
	v_cvt_pk_bf16_f32 v0, v157, v157
	v_cvt_pk_bf16_f32 v153, v153, v153
	v_cvt_pk_bf16_f32 v152, v152, v152
	v_and_b32_e32 v153, 0xffff0000, v153
	v_and_b32_e32 v152, 0xffff0000, v152
	v_or_b32_sdwa v153, v153, v0 dst_sel:DWORD dst_unused:UNUSED_PAD src0_sel:DWORD src1_sel:WORD_1
	v_or_b32_sdwa v152, v152, v155 dst_sel:DWORD dst_unused:UNUSED_PAD src0_sel:DWORD src1_sel:WORD_1
	global_store_dwordx2 v[142:143], v[152:153], off offset:64
	v_pk_mul_f32 v[152:153], v[32:33], v[150:151]
	v_pk_mul_f32 v[156:157], v[30:31], v[148:149]
	v_mov_b32_e32 v159, v152
	v_mov_b32_e32 v152, v157
	v_mov_b32_e32 v158, v156
	v_pk_add_f32 v[152:153], v[140:141], v[152:153] op_sel_hi:[0,1]
	v_pk_add_f32 v[158:159], v[140:141], v[158:159] op_sel_hi:[0,1]
	v_cvt_pk_bf16_f32 v153, v153, v153
	v_cvt_pk_bf16_f32 v152, v152, v152
	v_cvt_pk_bf16_f32 v155, v158, v158
	v_cvt_pk_bf16_f32 v0, v159, v159
	v_and_b32_e32 v153, 0xffff0000, v153
	v_and_b32_e32 v152, 0xffff0000, v152
	v_or_b32_sdwa v153, v153, v0 dst_sel:DWORD dst_unused:UNUSED_PAD src0_sel:DWORD src1_sel:WORD_1
	v_or_b32_sdwa v152, v152, v155 dst_sel:DWORD dst_unused:UNUSED_PAD src0_sel:DWORD src1_sel:WORD_1
	global_store_dwordx2 v[132:133], v[152:153], off offset:64
	v_pk_mul_f32 v[152:153], v[20:21], v[150:151]
	v_pk_mul_f32 v[156:157], v[18:19], v[148:149]
	v_mov_b32_e32 v159, v152
	v_mov_b32_e32 v152, v157
	v_mov_b32_e32 v158, v156
	v_pk_add_f32 v[152:153], v[134:135], v[152:153] op_sel_hi:[0,1]
	v_pk_add_f32 v[158:159], v[134:135], v[158:159] op_sel_hi:[0,1]
	v_cvt_pk_bf16_f32 v153, v153, v153
	v_cvt_pk_bf16_f32 v152, v152, v152
	v_cvt_pk_bf16_f32 v155, v158, v158
	v_cvt_pk_bf16_f32 v0, v159, v159
	v_and_b32_e32 v153, 0xffff0000, v153
	v_and_b32_e32 v152, 0xffff0000, v152
	v_or_b32_sdwa v153, v153, v0 dst_sel:DWORD dst_unused:UNUSED_PAD src0_sel:DWORD src1_sel:WORD_1
	v_or_b32_sdwa v152, v152, v155 dst_sel:DWORD dst_unused:UNUSED_PAD src0_sel:DWORD src1_sel:WORD_1
	v_pk_mul_f32 v[150:151], v[24:25], v[150:151]
	v_pk_mul_f32 v[148:149], v[22:23], v[148:149]
	global_store_dwordx2 v[144:145], v[152:153], off offset:64
	v_mov_b32_e32 v152, v148
	v_mov_b32_e32 v153, v150
	v_pk_add_f32 v[152:153], v[136:137], v[152:153] op_sel_hi:[0,1]
	v_mov_b32_e32 v150, v149
	v_pk_add_f32 v[148:149], v[136:137], v[150:151] op_sel_hi:[0,1]
	v_cvt_pk_bf16_f32 v150, v152, v152
	v_cvt_pk_bf16_f32 v149, v149, v149
	v_cvt_pk_bf16_f32 v148, v148, v148
	v_cvt_pk_bf16_f32 v0, v153, v153
	v_and_b32_e32 v149, 0xffff0000, v149
	v_and_b32_e32 v148, 0xffff0000, v148
	v_or_b32_sdwa v149, v149, v0 dst_sel:DWORD dst_unused:UNUSED_PAD src0_sel:DWORD src1_sel:WORD_1
	v_or_b32_sdwa v148, v148, v150 dst_sel:DWORD dst_unused:UNUSED_PAD src0_sel:DWORD src1_sel:WORD_1
	global_store_dwordx2 v[130:131], v[148:149], off offset:64
	ds_read_b128 v[148:151], v154 offset:704
	s_waitcnt lgkmcnt(0)
; __device__ __forceinline__ unsigned pack2(float a, float b) { return (unsigned)f2bf(a) | ((unsigned)f2bf(b) << 16); }
; #define SCHED __builtin_amdgcn_sched_barrier(0)
; template <int EPI, bool HS = false>
; __device__ __forceinline__ void gemm_phase(const Params& p, const GemmCfg& g, char* shm, const int wave_s) {
;     ...
;           for (int m = 0; m < 4; ++m) {
;             const f32x4 r4 = *(const f32x4*)(rsw + ai * 128 + m * 16);
; #pragma unroll
;             for (int bj = 0; bj < 2; ++bj)
; #pragma unroll
;               for (int n = 0; n < 2; ++n) {
;                 uint2 pk;
;                 pk.x = pack2(r4[0] * acc[ai][bj][m][n][0] + swv[bj][n], r4[1] * acc[ai][bj][m][n][1] + swv[bj][n]);
;                 pk.y = pack2(r4[2] * acc[ai][bj][m][n][2] + swv[bj][n], r4[3] * acc[ai][bj][m][n][3] + swv[bj][n]);
;                 *(uint2*)(vt_t + kb + ai * 512 * 128 + (bj * 128 + n * 16) * 128 + m * 16) = pk;
;               }
;             SCHED;
	v_pk_mul_f32 v[152:153], v[12:13], v[150:151]
	v_pk_mul_f32 v[156:157], v[10:11], v[148:149]
	v_mov_b32_e32 v159, v152
	v_mov_b32_e32 v158, v156
	v_mov_b32_e32 v152, v157
	v_pk_add_f32 v[156:157], v[138:139], v[158:159] op_sel_hi:[0,1]
	v_pk_add_f32 v[152:153], v[138:139], v[152:153] op_sel_hi:[0,1]
	v_cvt_pk_bf16_f32 v155, v156, v156
	v_cvt_pk_bf16_f32 v0, v157, v157
	v_cvt_pk_bf16_f32 v153, v153, v153
	v_cvt_pk_bf16_f32 v152, v152, v152
	v_and_b32_e32 v153, 0xffff0000, v153
	v_and_b32_e32 v152, 0xffff0000, v152
	v_or_b32_sdwa v153, v153, v0 dst_sel:DWORD dst_unused:UNUSED_PAD src0_sel:DWORD src1_sel:WORD_1
	v_or_b32_sdwa v152, v152, v155 dst_sel:DWORD dst_unused:UNUSED_PAD src0_sel:DWORD src1_sel:WORD_1
	global_store_dwordx2 v[142:143], v[152:153], off offset:96
	v_pk_mul_f32 v[142:143], v[16:17], v[150:151]
	v_pk_mul_f32 v[152:153], v[14:15], v[148:149]
	v_mov_b32_e32 v157, v142
	v_mov_b32_e32 v142, v153
	v_mov_b32_e32 v156, v152
	v_pk_add_f32 v[142:143], v[140:141], v[142:143] op_sel_hi:[0,1]
	v_pk_add_f32 v[156:157], v[140:141], v[156:157] op_sel_hi:[0,1]
	v_and_b32_sdwa v155, v142, v178 dst_sel:DWORD dst_unused:UNUSED_PAD src0_sel:WORD_1 src1_sel:DWORD
	v_cvt_pk_bf16_f32 v143, v143, v143
	v_add3_u32 v142, v142, v155, s81
	v_cvt_pk_bf16_f32 v152, v156, v156
	v_cvt_pk_bf16_f32 v0, v157, v157
	v_and_b32_e32 v143, 0xffff0000, v143
	v_and_b32_e32 v142, 0xffff0000, v142
	v_or_b32_sdwa v143, v143, v0 dst_sel:DWORD dst_unused:UNUSED_PAD src0_sel:DWORD src1_sel:WORD_1
	v_or_b32_sdwa v142, v142, v152 dst_sel:DWORD dst_unused:UNUSED_PAD src0_sel:DWORD src1_sel:WORD_1
	global_store_dwordx2 v[132:133], v[142:143], off offset:96
	v_pk_mul_f32 v[132:133], v[4:5], v[150:151]
	v_pk_mul_f32 v[142:143], v[2:3], v[148:149]
	v_mov_b32_e32 v153, v132
	v_mov_b32_e32 v152, v142
	v_pk_add_f32 v[152:153], v[134:135], v[152:153] op_sel_hi:[0,1]
	v_mov_b32_e32 v132, v143
	v_pk_add_f32 v[132:133], v[134:135], v[132:133] op_sel_hi:[0,1]
	v_cvt_pk_bf16_f32 v142, v152, v152
	v_and_b32_sdwa v152, v132, v178 dst_sel:DWORD dst_unused:UNUSED_PAD src0_sel:WORD_1 src1_sel:DWORD
	v_cvt_pk_bf16_f32 v133, v133, v133
	v_add3_u32 v132, v132, v152, s81
	v_cvt_pk_bf16_f32 v0, v153, v153
	v_and_b32_e32 v133, 0xffff0000, v133
	v_and_b32_e32 v132, 0xffff0000, v132
	v_or_b32_sdwa v133, v133, v0 dst_sel:DWORD dst_unused:UNUSED_PAD src0_sel:DWORD src1_sel:WORD_1
	v_or_b32_sdwa v132, v132, v142 dst_sel:DWORD dst_unused:UNUSED_PAD src0_sel:DWORD src1_sel:WORD_1
	global_store_dwordx2 v[144:145], v[132:133], off offset:96
	v_pk_mul_f32 v[132:133], v[8:9], v[150:151]
	v_pk_mul_f32 v[142:143], v[6:7], v[148:149]
	v_mov_b32_e32 v145, v132
	v_mov_b32_e32 v144, v142
	v_pk_add_f32 v[144:145], v[136:137], v[144:145] op_sel_hi:[0,1]
	v_mov_b32_e32 v132, v143
	v_pk_add_f32 v[132:133], v[136:137], v[132:133] op_sel_hi:[0,1]
	v_and_b32_sdwa v142, v144, v178 dst_sel:DWORD dst_unused:UNUSED_PAD src0_sel:WORD_1 src1_sel:DWORD
	v_add3_u32 v142, v144, v142, s81
	v_and_b32_sdwa v143, v133, v178 dst_sel:DWORD dst_unused:UNUSED_PAD src0_sel:WORD_1 src1_sel:DWORD
	v_and_b32_sdwa v144, v132, v178 dst_sel:DWORD dst_unused:UNUSED_PAD src0_sel:WORD_1 src1_sel:DWORD
	v_and_b32_sdwa v0, v145, v178 dst_sel:DWORD dst_unused:UNUSED_PAD src0_sel:WORD_1 src1_sel:DWORD
	v_add3_u32 v133, v133, v143, s81
	v_add3_u32 v132, v132, v144, s81
	v_add3_u32 v0, v145, v0, s81
	v_and_b32_e32 v133, 0xffff0000, v133
	v_and_b32_e32 v132, 0xffff0000, v132
	v_or_b32_sdwa v133, v133, v0 dst_sel:DWORD dst_unused:UNUSED_PAD src0_sel:DWORD src1_sel:WORD_1
	v_or_b32_sdwa v132, v132, v142 dst_sel:DWORD dst_unused:UNUSED_PAD src0_sel:DWORD src1_sel:WORD_1
	global_store_dwordx2 v[130:131], v[132:133], off offset:96

; #define WAIT_V(n) asm volatile("s_waitcnt vmcnt(" #n ")" ::: "memory")
; template <int EPI, bool HS = false>
; __device__ __forceinline__ void gemm_phase(const Params& p, const GemmCfg& g, char* shm, const int wave_s) {
;     ...
;       if (pn < 8) {
;         const int hh = pn & 3;
;         const bool isk = pn >= 4;
;         u16* dst = (isk ? Kb : Qb) + (size_t)orow0 * 1024 + hh * 256;
;         u16* kt_t = KTb + ((size_t)((b * 4 + hh) * 16 + (mt & 7) * 2) * 256) * 128;
;         const float lg2 = log2f(1.0f - exp2f(-5.0f - (float)hh));
;         const float scl = isk ? 0.0625f : 1.0f;
;         const float* rc_t = p.ropec + (size_t)s0 * 128;
;         const float* rs_t = p.ropes + (size_t)s0 * 128;
;         const unsigned tb = (unsigned)((wr * 64 + fq * 4) * 1024 + wc * 32 + fr);
;         const unsigned kb = (unsigned)((wc * 32 + fr) * 128 + wr * 64 + fq * 4);
;         const unsigned ldsb = (unsigned)(size_t)(__attribute__((address_space(3))) char*)shm;
;         const int wv_s = __builtin_amdgcn_readfirstlane(wid);
;         const char* rl = shm + ((wr * 64 + fq * 4) * 128 + wc * 16 + fr) * 4;
; #pragma unroll
;         for (int ai = 0; ai < 2; ++ai) {
; #pragma unroll
;           for (int i = 0; i < 8; ++i) {
;             const int ch = wv_s * 8 + i;
;             glds_row(rc_t + (size_t)(ai * 128) * 128 + ch * 256, (unsigned)lane * 16u, ldsb + (unsigned)(ch * 1024));
;             glds_row(rs_t + (size_t)(ai * 128) * 128 + ch * 256, (unsigned)lane * 16u, ldsb + 65536u + (unsigned)(ch * 1024));
;           }
;           WAIT_V(0);
;           __syncthreads();
.LBB0_595:
	s_andn2_b64 vcc, exec, s[8:9]
	s_cbranch_vccnz .LBB0_577
	s_lshl_b32 s1, s3, 8
	s_or_b32 s6, s1, s43
	s_and_b32 s2, s2, 3
	s_cmp_gt_i32 s88, 31
	s_cselect_b64 s[4:5], -1, 0
	v_readlane_b32 s12, v254, 47
	s_and_b64 s[8:9], s[4:5], exec
	v_readlane_b32 s14, v254, 49
	s_cselect_b32 s1, 0x4000000, 0
	v_readlane_b32 s15, v254, 50
	s_add_u32 s7, s14, s1
	s_addc_u32 s8, s15, 0
	s_ashr_i32 s1, s0, 31
	s_lshl_b64 s[0:1], s[0:1], 11
	s_add_u32 s0, s7, s0
	s_addc_u32 s1, s8, s1
	s_lshl_b32 s7, s2, 9
	v_mov_b32_e32 v0, 0x3d800000
	s_add_u32 s0, s0, s7
	v_cndmask_b32_e64 v142, 1.0, v0, s[4:5]
	s_addc_u32 s1, s1, 0
	s_lshl_b32 s7, s10, 6
	s_lshl_b32 s8, s2, 4
	v_cvt_f32_ubyte0_e32 v0, s2
	s_or_b32 s7, s7, s8
	s_lshl_b32 s3, s3, 1
	v_sub_f32_e32 v0, 0xc0a00000, v0
	s_mov_b32 s2, 0xc2fc0000
	s_or_b32 s8, s7, s3
	v_cmp_gt_f32_e32 vcc, s2, v0
	v_mov_b32_e32 v130, 0x42800000
	s_ashr_i32 s9, s8, 31
	v_cndmask_b32_e32 v130, 0, v130, vcc
	s_mov_b64 s[16:17], s[46:47]
	s_lshl_b64 s[8:9], s[8:9], 16
	v_add_f32_e32 v0, v0, v130
	s_add_u32 s10, s16, s8
	v_exp_f32_e32 v0, v0
	s_addc_u32 s11, s17, s9
	s_and_b64 s[2:3], vcc, exec
	s_cselect_b32 s2, 0xffffffc0, 0
	v_ldexp_f32 v0, v0, s2
	v_sub_f32_e32 v130, 1.0, v0
	v_cmp_gt_f32_e32 vcc, s42, v130
	s_and_b64 s[2:3], vcc, exec
	s_mov_b32 s92, s45
	s_cselect_b32 s45, 32, 0
	s_ashr_i32 s7, s6, 31
	v_readlane_b32 s52, v252, 26
	s_lshl_b64 s[2:3], s[6:7], 9
	v_readlane_b32 s64, v252, 38
	v_readlane_b32 s65, v252, 39
	s_add_u32 s27, s64, s2
	v_readlane_b32 s66, v252, 40
	s_addc_u32 s90, s65, s3
	v_readlane_b32 s67, v252, 41
	s_add_u32 s91, s66, s2
	v_readfirstlane_b32 s8, v147
	s_addc_u32 s84, s67, s3
	s_lshl_b32 s2, s8, 11
	s_ashr_i32 s3, s2, 31
	s_mov_b32 s47, s44
	s_lshl_b32 s44, s8, 3
	s_lshl_b64 s[76:77], s[2:3], 2
	s_add_u32 s6, s27, s76
	s_addc_u32 s7, s90, s77
	s_lshl_b32 s2, s8, 13
	s_add_i32 s85, s2, 0
	s_add_u32 s68, s91, s76
	v_readlane_b32 s62, v252, 36
	s_addc_u32 s69, s84, s77
	s_or_b32 s8, s44, 1
	s_add_i32 s62, s2, s89
	s_lshl_b32 s2, s8, 8
	s_ashr_i32 s3, s2, 31
	s_lshl_b64 s[74:75], s[2:3], 2
	v_readlane_b32 s13, v254, 48
	s_add_u32 s12, s27, s74
	s_addc_u32 s13, s90, s75
	s_lshl_b32 s2, s8, 10
	s_add_i32 s26, s2, 0
	s_add_u32 s14, s91, s74
	v_readlane_b32 s60, v252, 34
	s_addc_u32 s15, s84, s75
	s_or_b32 s8, s44, 2
	s_add_i32 s60, s2, s89
	s_lshl_b32 s2, s8, 8
	s_ashr_i32 s3, s2, 31
	s_lshl_b64 s[72:73], s[2:3], 2
	s_mov_b64 s[48:49], s[16:17]
	s_add_u32 s16, s27, s72
	v_readlane_b32 s61, v252, 35
	s_addc_u32 s17, s90, s73
	s_lshl_b32 s2, s8, 10
	s_add_i32 s61, s2, 0
	s_add_u32 s18, s91, s72
	v_readlane_b32 s57, v252, 31
	s_addc_u32 s19, s84, s73
	s_or_b32 s8, s44, 3
	s_add_i32 s57, s2, s89
	s_lshl_b32 s2, s8, 8
	s_ashr_i32 s3, s2, 31
	s_lshl_b64 s[70:71], s[2:3], 2
	s_add_u32 s20, s27, s70
	v_readlane_b32 s58, v252, 32
	s_addc_u32 s21, s90, s71
	s_lshl_b32 s2, s8, 10
	s_add_i32 s58, s2, 0
	s_add_u32 s22, s91, s70
	v_readlane_b32 s55, v252, 29
	s_addc_u32 s23, s84, s71
	s_or_b32 s36, s44, 4
	s_add_i32 s55, s2, s89
	s_lshl_b32 s2, s36, 8
	s_ashr_i32 s3, s2, 31
	s_lshl_b64 s[8:9], s[2:3], 2
	s_add_u32 s24, s27, s8
	v_readlane_b32 s56, v252, 30
	s_addc_u32 s25, s90, s9
	s_lshl_b32 s2, s36, 10
	s_add_i32 s56, s2, 0
	s_add_u32 s36, s91, s8
	v_readlane_b32 s53, v252, 27
	s_addc_u32 s37, s84, s9
	s_or_b32 s40, s44, 5
	s_add_i32 s53, s2, s89
	s_lshl_b32 s2, s40, 8
	s_ashr_i32 s3, s2, 31
	s_lshl_b64 s[2:3], s[2:3], 2
	v_mov_b32_e32 v0, 0x42000000
	s_add_u32 s38, s27, s2
	v_lshlrev_b32_e32 v132, 5, v137
	v_cndmask_b32_e32 v131, 0, v0, vcc
	v_readlane_b32 s54, v252, 28
	s_addc_u32 s39, s90, s3
	s_lshl_b32 s42, s40, 10
	v_or_b32_e32 v0, v132, v135
	s_add_i32 s54, s42, 0
	v_lshl_add_u32 v0, v0, 7, v139
	s_add_u32 s40, s91, s2
	v_or_b32_e32 v0, v0, v141
	s_addc_u32 s41, s84, s3
	s_add_i32 s52, s42, s89
	v_lshl_add_u64 v[144:145], v[0:1], 1, s[10:11]
	s_or_b32 s42, s44, 6
	v_lshlrev_b32_e32 v0, 4, v146
	v_and_b32_e32 v156, 0x3f0, v0
	s_mov_b32 m0, s85
	s_nop 0
	global_load_lds_dwordx4 v156, s[6:7]
	s_lshl_b32 s6, s42, 8
	s_ashr_i32 s7, s6, 31
	s_lshl_b64 s[10:11], s[6:7], 2
	s_mov_b32 m0, s62
	s_nop 0
	global_load_lds_dwordx4 v156, s[68:69]
	s_add_u32 s6, s27, s10
	v_readlane_b32 s59, v252, 33
	s_addc_u32 s7, s90, s11
	s_lshl_b32 s46, s42, 10
	v_ldexp_f32 v0, v130, s45
	s_add_i32 s59, s46, 0
	s_mov_b32 m0, s26
	s_nop 0
	global_load_lds_dwordx4 v156, s[12:13]
	v_log_f32_e32 v0, v0
	s_add_u32 s42, s91, s10
	s_mov_b32 s50, s43
	s_addc_u32 s43, s84, s11
	s_or_b32 s13, s44, 7
	s_mov_b32 m0, s60
	s_nop 0
	global_load_lds_dwordx4 v156, s[14:15]
	s_lshl_b32 s14, s13, 8
	v_or_b32_e32 v161, v139, v141
	s_ashr_i32 s15, s14, 31
	v_sub_f32_e32 v160, v0, v131
	v_lshlrev_b32_e32 v0, 10, v161
	v_lshlrev_b32_e32 v130, 7, v161
	v_lshlrev_b32_e32 v131, 4, v137
	s_lshl_b64 s[68:69], s[14:15], 2
	s_mov_b32 m0, s61
	s_nop 0
	global_load_lds_dwordx4 v156, s[16:17]
	v_or3_b32 v130, v130, v131, v135
	v_or3_b32 v146, v0, v135, v132
	v_sub_u32_e32 v0, 0x7f, v161
	v_lshl_add_u32 v155, v130, 2, 0
	s_mov_b32 m0, s57
	s_nop 0
	global_load_lds_dwordx4 v156, s[18:19]
	v_cvt_f32_i32_e32 v0, v0
	v_sub_u32_e32 v130, 0x7e, v161
	s_mov_b32 m0, s58
	s_nop 0
	global_load_lds_dwordx4 v156, s[20:21]
	v_cvt_f32_i32_e32 v130, v130
	s_mov_b32 m0, s55
	s_nop 0
	global_load_lds_dwordx4 v156, s[22:23]
	v_mul_f32_e32 v0, v160, v0
	s_mov_b32 m0, s56
	s_nop 0
	global_load_lds_dwordx4 v156, s[24:25]
	s_add_i32 s12, s46, s89
	s_mov_b32 m0, s53
	s_nop 0
	global_load_lds_dwordx4 v156, s[36:37]
	v_exp_f32_e32 v148, v0
	s_mov_b32 m0, s54
	s_nop 0
	global_load_lds_dwordx4 v156, s[38:39]
	v_mul_f32_e32 v0, v160, v130
	v_sub_u32_e32 v130, 0x7d, v161
	s_add_u32 s16, s27, s68
	s_mov_b32 m0, s52
	s_nop 0
	global_load_lds_dwordx4 v156, s[40:41]
	v_cvt_f32_i32_e32 v130, v130
	v_sub_u32_e32 v131, 0x7c, v161
	s_addc_u32 s17, s90, s69
	s_lshl_b32 s13, s13, 10
	s_mov_b32 m0, s59
	s_nop 0
	global_load_lds_dwordx4 v156, s[6:7]
	v_cvt_f32_i32_e32 v131, v131
	s_add_i32 s14, s13, 0
	s_mov_b32 m0, s12
	s_nop 0
	global_load_lds_dwordx4 v156, s[42:43]
	s_add_u32 s44, s91, s68
	s_mov_b32 m0, s14
	s_nop 0
	global_load_lds_dwordx4 v156, s[16:17]
	s_addc_u32 s45, s84, s69
	s_add_i32 s13, s13, s89
	s_mov_b32 m0, s13
	s_nop 0
	global_load_lds_dwordx4 v156, s[44:45]
	v_exp_f32_e32 v150, v0
	v_mul_f32_e32 v0, v160, v130
	v_mov_b32_e32 v147, v1
	v_add_u32_e32 v157, 0x10000, v155
	s_waitcnt vmcnt(0)
	s_waitcnt vmcnt(63) expcnt(7) lgkmcnt(15)
	s_barrier
; __device__ __forceinline__ unsigned pack2(float a, float b) { return (unsigned)f2bf(a) | ((unsigned)f2bf(b) << 16); }
; __device__ __forceinline__ float fexp2(float x) { return __builtin_amdgcn_exp2f(x); }
; template <int EPI, bool HS = false>
; __device__ __forceinline__ void gemm_phase(const Params& p, const GemmCfg& g, char* shm, const int wave_s) {
;     ...
; #pragma unroll
;           for (int m = 0; m < 4; ++m) {
;             const int jj0 = wr * 64 + m * 16 + fq * 4;
;             const float k0 = fexp2(lg2 * (float)(127 - jj0));
;             const f32x4 r4 = *(const f32x4*)(rsw + ai * 128 + m * 16);
; #pragma unroll
;             for (int bj = 0; bj < 2; ++bj) {
;               float y1[4], y2[4];
; #pragma unroll
;               for (int j = 0; j < 4; ++j) {
;                 const int lr = ai * 128 + m * 16 + j;
;                 float cs = *(const float*)(rl + ((m * 16 + j) * 128 + bj * 64) * 4), sn = *(const float*)(rl + 65536 + ((m * 16 + j) * 128 + bj * 64) * 4);
;                 float x1 = r4[j] * acc[ai][bj][m][0][j] + swv[bj][0], x2 = r4[j] * acc[ai][bj][m][1][j] + swv[bj][1];
;                 y1[j] = (x1 * cs - x2 * sn) * scl;
;                 y2[j] = (x2 * cs + x1 * sn) * scl;
;                 dst[tb + lr * 1024 + bj * 128] = f2bf(y1[j]);
;                 dst[tb + lr * 1024 + bj * 128 + 16] = f2bf(y2[j]);
;               }
;               if (isk) {
;                 float d0 = k0, d1 = fexp2(lg2 * (float)(126 - jj0)), d2 = fexp2(lg2 * (float)(125 - jj0)),
;                       d3 = fexp2(lg2 * (float)(124 - jj0));
;                 uint2 v1, v2;
;                 v1.x = pack2(y1[0] * d0, y1[1] * d1); v1.y = pack2(y1[2] * d2, y1[3] * d3);
;                 v2.x = pack2(y2[0] * d0, y2[1] * d1); v2.y = pack2(y2[2] * d2, y2[3] * d3);
;                 *(uint2*)(kt_t + kb + ai * 256 * 128 + (bj * 128) * 128 + m * 16) = v1;
;                 *(uint2*)(kt_t + kb + ai * 256 * 128 + (bj * 128 + 16) * 128 + m * 16) = v2;
;               }
	v_exp_f32_e32 v149, v0
	v_mul_f32_e32 v0, v160, v131
	ds_read2st64_b32 v[164:165], v155 offset1:2
	v_lshl_add_u64 v[152:153], v[146:147], 1, s[0:1]
	v_add_u32_e32 v147, 0x10200, v155
	ds_read2st64_b32 v[166:167], v155 offset0:4 offset1:6
	v_add_u32_e32 v158, 0x10400, v155
	ds_read_b128 v[130:133], v154
	ds_read_b32 v168, v157
	ds_read_b32 v170, v147
	ds_read_b32 v169, v158
	v_add_u32_e32 v159, 0x10600, v155
	ds_read_b32 v171, v159
	s_waitcnt lgkmcnt(4)
	v_pk_mul_f32 v[128:129], v[128:129], v[132:133]
	v_pk_mul_f32 v[126:127], v[126:127], v[130:131]
	v_mov_b32_e32 v177, v128
	v_mov_b32_e32 v176, v126
	v_pk_mul_f32 v[124:125], v[124:125], v[132:133]
	v_pk_mul_f32 v[180:181], v[122:123], v[130:131]
	v_pk_add_f32 v[176:177], v[140:141], v[176:177] op_sel_hi:[0,1]
	v_mov_b32_e32 v122, v180
	v_mov_b32_e32 v123, v124
	v_pk_add_f32 v[182:183], v[138:139], v[122:123] op_sel_hi:[0,1]
	v_mov_b32_e32 v184, v164
	v_mov_b32_e32 v185, v166
	s_waitcnt lgkmcnt(1)
	v_pk_mul_f32 v[122:123], v[168:169], v[176:177]
	v_mov_b32_e32 v128, v127
	v_exp_f32_e32 v151, v0
	v_or_b32_e32 v0, 0x800, v146
	v_pk_fma_f32 v[122:123], v[184:185], v[182:183], v[122:123] neg_lo:[0,0,1] neg_hi:[0,0,1]
	v_pk_add_f32 v[128:129], v[140:141], v[128:129] op_sel_hi:[0,1]
	v_mov_b32_e32 v124, v181
	v_lshl_add_u64 v[172:173], v[0:1], 1, s[0:1]
	v_or_b32_e32 v0, 0x810, v146
	v_pk_mul_f32 v[122:123], v[142:143], v[122:123] op_sel_hi:[0,1]
	v_pk_add_f32 v[180:181], v[138:139], v[124:125] op_sel_hi:[0,1]
	v_mov_b32_e32 v166, v165
	s_waitcnt lgkmcnt(0)
	v_pk_mul_f32 v[124:125], v[128:129], v[170:171]
	v_lshl_add_u64 v[174:175], v[0:1], 1, s[0:1]
	s_nop 0
	v_pk_fma_f32 v[124:125], v[180:181], v[166:167], v[124:125] neg_lo:[0,0,1] neg_hi:[0,0,1]
	v_cvt_pk_bf16_f32 v0, v122, v122
	v_pk_mul_f32 v[124:125], v[142:143], v[124:125] op_sel_hi:[0,1]
	global_store_short_d16_hi v[152:153], v0, off
	v_cvt_pk_bf16_f32 v0, v124, v124
	v_pk_mul_f32 v[126:127], v[168:169], v[182:183]
	global_store_short_d16_hi v[152:153], v0, off offset:2048
	v_pk_fma_f32 v[126:127], v[184:185], v[176:177], v[126:127]
	v_cvt_pk_bf16_f32 v0, v123, v123
	v_pk_mul_f32 v[126:127], v[142:143], v[126:127] op_sel_hi:[0,1]
	v_pk_mul_f32 v[164:165], v[180:181], v[170:171]
	global_store_short_d16_hi v[172:173], v0, off
	v_pk_fma_f32 v[128:129], v[128:129], v[166:167], v[164:165]
	v_cvt_pk_bf16_f32 v0, v126, v126
	v_pk_mul_f32 v[128:129], v[142:143], v[128:129] op_sel_hi:[0,1]
	global_store_short_d16_hi v[152:153], v0, off offset:32
	v_cvt_pk_bf16_f32 v0, v128, v128
	global_store_short_d16_hi v[152:153], v0, off offset:2080
	v_cvt_pk_bf16_f32 v0, v127, v127
	global_store_short_d16_hi v[174:175], v0, off
	s_nop 0
	v_cvt_pk_bf16_f32 v135, v125, v125
	v_or_b32_e32 v0, 0xc00, v146
	v_lshl_add_u64 v[164:165], v[0:1], 1, s[0:1]
	v_bfe_u32 v0, v129, 16, 1
	global_store_short_d16_hi v[164:165], v135, off
	v_add3_u32 v135, v129, v0, s81
	v_or_b32_e32 v0, 0xc10, v146
	s_cmp_lt_i32 s88, 32
	v_lshl_add_u64 v[164:165], v[0:1], 1, s[0:1]
	v_readlane_b32 s63, v252, 37
	global_store_short_d16_hi v[164:165], v135, off
	s_cbranch_scc1 .LBB0_598
	v_pk_mul_f32 v[122:123], v[148:149], v[122:123]
	v_pk_mul_f32 v[124:125], v[150:151], v[124:125]
	s_nop 0
	s_nop 0
	v_cvt_pk_bf16_f32 v122, v122, v122
	v_cvt_pk_bf16_f32 v0, v123, v123
	v_and_b32_sdwa v135, v124, v178 dst_sel:DWORD dst_unused:UNUSED_PAD src0_sel:WORD_1 src1_sel:DWORD
	v_cvt_pk_bf16_f32 v123, v125, v125
	v_add3_u32 v124, v124, v135, s81
	v_pk_mul_f32 v[128:129], v[150:151], v[128:129]
	v_and_b32_e32 v123, 0xffff0000, v123
	v_and_b32_e32 v124, 0xffff0000, v124
	v_pk_mul_f32 v[126:127], v[148:149], v[126:127]
	v_or_b32_sdwa v123, v123, v0 dst_sel:DWORD dst_unused:UNUSED_PAD src0_sel:DWORD src1_sel:WORD_1
	v_or_b32_sdwa v122, v124, v122 dst_sel:DWORD dst_unused:UNUSED_PAD src0_sel:DWORD src1_sel:WORD_1
	global_store_dwordx2 v[144:145], v[122:123], off
	v_cvt_pk_bf16_f32 v124, v128, v128
	v_cvt_pk_bf16_f32 v122, v126, v126
	v_cvt_pk_bf16_f32 v123, v129, v129
	v_and_b32_e32 v124, 0xffff0000, v124
	v_cvt_pk_bf16_f32 v0, v127, v127
	v_and_b32_e32 v123, 0xffff0000, v123
	v_or_b32_sdwa v122, v124, v122 dst_sel:DWORD dst_unused:UNUSED_PAD src0_sel:DWORD src1_sel:WORD_1
	v_add_co_u32_e32 v124, vcc, 0x1000, v144
	v_or_b32_sdwa v123, v123, v0 dst_sel:DWORD dst_unused:UNUSED_PAD src0_sel:DWORD src1_sel:WORD_1
	s_nop 0
	v_addc_co_u32_e32 v125, vcc, 0, v145, vcc
	global_store_dwordx2 v[124:125], v[122:123], off
; __device__ __forceinline__ unsigned pack2(float a, float b) { return (unsigned)f2bf(a) | ((unsigned)f2bf(b) << 16); }
; __device__ __forceinline__ float fexp2(float x) { return __builtin_amdgcn_exp2f(x); }
; template <int EPI, bool HS = false>
; __device__ __forceinline__ void gemm_phase(const Params& p, const GemmCfg& g, char* shm, const int wave_s) {
;     ...
;             for (int bj = 0; bj < 2; ++bj) {
;               float y1[4], y2[4];
; #pragma unroll
;               for (int j = 0; j < 4; ++j) {
;                 const int lr = ai * 128 + m * 16 + j;
;                 float cs = *(const float*)(rl + ((m * 16 + j) * 128 + bj * 64) * 4), sn = *(const float*)(rl + 65536 + ((m * 16 + j) * 128 + bj * 64) * 4);
;                 float x1 = r4[j] * acc[ai][bj][m][0][j] + swv[bj][0], x2 = r4[j] * acc[ai][bj][m][1][j] + swv[bj][1];
;                 y1[j] = (x1 * cs - x2 * sn) * scl;
;                 y2[j] = (x2 * cs + x1 * sn) * scl;
;                 dst[tb + lr * 1024 + bj * 128] = f2bf(y1[j]);
;                 dst[tb + lr * 1024 + bj * 128 + 16] = f2bf(y2[j]);
;               }
;               if (isk) {
;                 float d0 = k0, d1 = fexp2(lg2 * (float)(126 - jj0)), d2 = fexp2(lg2 * (float)(125 - jj0)),
;                       d3 = fexp2(lg2 * (float)(124 - jj0));
;                 uint2 v1, v2;
;                 v1.x = pack2(y1[0] * d0, y1[1] * d1); v1.y = pack2(y1[2] * d2, y1[3] * d3);
;                 v2.x = pack2(y2[0] * d0, y2[1] * d1); v2.y = pack2(y2[2] * d2, y2[3] * d3);
;                 *(uint2*)(kt_t + kb + ai * 256 * 128 + (bj * 128) * 128 + m * 16) = v1;
;                 *(uint2*)(kt_t + kb + ai * 256 * 128 + (bj * 128 + 16) * 128 + m * 16) = v2;
;               }
.LBB0_598:
	ds_read2st64_b32 v[126:127], v155 offset0:1 offset1:3
	v_add_u32_e32 v122, 0x10100, v155
	ds_read2st64_b32 v[128:129], v155 offset0:5 offset1:7
	v_add_u32_e32 v123, 0x10300, v155
	v_add_u32_e32 v124, 0x10500, v155
	v_add_u32_e32 v125, 0x10700, v155
	ds_read_b32 v168, v122
	ds_read_b32 v170, v123
	ds_read_b32 v169, v124
	ds_read_b32 v171, v125
	v_pk_mul_f32 v[120:121], v[120:121], v[132:133]
	v_pk_mul_f32 v[118:119], v[118:119], v[130:131]
	v_mov_b32_e32 v173, v120
	v_mov_b32_e32 v172, v118
	v_pk_mul_f32 v[116:117], v[116:117], v[132:133]
	v_pk_mul_f32 v[130:131], v[114:115], v[130:131]
	v_pk_add_f32 v[172:173], v[136:137], v[172:173] op_sel_hi:[0,1]
	v_mov_b32_e32 v114, v130
	v_mov_b32_e32 v115, v116
	v_pk_add_f32 v[132:133], v[134:135], v[114:115] op_sel_hi:[0,1]
	s_waitcnt lgkmcnt(5)
	v_mov_b32_e32 v174, v126
	s_waitcnt lgkmcnt(4)
	v_mov_b32_e32 v175, v128
	s_waitcnt lgkmcnt(1)
	v_pk_mul_f32 v[114:115], v[172:173], v[168:169]
	v_mov_b32_e32 v120, v119
	v_mov_b32_e32 v143, v142
	v_or_b32_e32 v0, 0x880, v146
	v_pk_fma_f32 v[114:115], v[132:133], v[174:175], v[114:115] neg_lo:[0,0,1] neg_hi:[0,0,1]
	v_pk_add_f32 v[120:121], v[136:137], v[120:121] op_sel_hi:[0,1]
	v_mov_b32_e32 v116, v131
	v_lshl_add_u64 v[164:165], v[0:1], 1, s[0:1]
	v_or_b32_e32 v0, 0x890, v146
	v_pk_mul_f32 v[114:115], v[142:143], v[114:115]
	v_pk_add_f32 v[130:131], v[134:135], v[116:117] op_sel_hi:[0,1]
	v_mov_b32_e32 v128, v127
	s_waitcnt lgkmcnt(0)
	v_pk_mul_f32 v[116:117], v[120:121], v[170:171]
	v_lshl_add_u64 v[166:167], v[0:1], 1, s[0:1]
	s_nop 0
	v_pk_fma_f32 v[116:117], v[130:131], v[128:129], v[116:117] neg_lo:[0,0,1] neg_hi:[0,0,1]
	v_cvt_pk_bf16_f32 v0, v114, v114
	v_pk_mul_f32 v[116:117], v[142:143], v[116:117]
	global_store_short_d16_hi v[152:153], v0, off offset:256
	v_cvt_pk_bf16_f32 v0, v116, v116
	v_pk_mul_f32 v[118:119], v[132:133], v[168:169]
	global_store_short_d16_hi v[152:153], v0, off offset:2304
	v_pk_fma_f32 v[118:119], v[172:173], v[174:175], v[118:119]
	v_cvt_pk_bf16_f32 v0, v115, v115
	v_pk_mul_f32 v[118:119], v[142:143], v[118:119]
	v_pk_mul_f32 v[126:127], v[130:131], v[170:171]
	global_store_short_d16_hi v[164:165], v0, off
	v_pk_fma_f32 v[120:121], v[120:121], v[128:129], v[126:127]
	v_cvt_pk_bf16_f32 v0, v118, v118
	v_pk_mul_f32 v[120:121], v[142:143], v[120:121]
	global_store_short_d16_hi v[152:153], v0, off offset:288
	v_cvt_pk_bf16_f32 v0, v120, v120
	global_store_short_d16_hi v[152:153], v0, off offset:2336
	v_cvt_pk_bf16_f32 v0, v119, v119
	global_store_short_d16_hi v[166:167], v0, off
	s_nop 0
	v_cvt_pk_bf16_f32 v128, v117, v117
	v_or_b32_e32 v0, 0xc80, v146
	v_lshl_add_u64 v[126:127], v[0:1], 1, s[0:1]
	v_bfe_u32 v0, v121, 16, 1
	global_store_short_d16_hi v[126:127], v128, off
	v_add3_u32 v128, v121, v0, s81
	v_or_b32_e32 v0, 0xc90, v146
	v_lshl_add_u64 v[126:127], v[0:1], 1, s[0:1]
	v_cndmask_b32_e64 v0, 0, 1, s[4:5]
	v_cmp_ne_u32_e64 s[6:7], 1, v0
	s_andn2_b64 vcc, exec, s[4:5]
	global_store_short_d16_hi v[126:127], v128, off
	s_cbranch_vccnz .LBB0_600
	v_pk_mul_f32 v[114:115], v[148:149], v[114:115]
	v_pk_mul_f32 v[116:117], v[150:151], v[116:117]
	s_nop 0
	s_nop 0
	v_cvt_pk_bf16_f32 v114, v114, v114
	v_cvt_pk_bf16_f32 v0, v115, v115
	v_cvt_pk_bf16_f32 v116, v116, v116
	v_cvt_pk_bf16_f32 v115, v117, v117
	v_and_b32_e32 v116, 0xffff0000, v116
	s_mov_b32 s4, 0x8000
	v_and_b32_e32 v115, 0xffff0000, v115
	v_or_b32_sdwa v114, v116, v114 dst_sel:DWORD dst_unused:UNUSED_PAD src0_sel:DWORD src1_sel:WORD_1
	v_add_co_u32_e32 v116, vcc, s4, v144
	v_pk_mul_f32 v[120:121], v[150:151], v[120:121]
	v_or_b32_sdwa v115, v115, v0 dst_sel:DWORD dst_unused:UNUSED_PAD src0_sel:DWORD src1_sel:WORD_1
	v_addc_co_u32_e32 v117, vcc, 0, v145, vcc
	v_pk_mul_f32 v[118:119], v[148:149], v[118:119]
	global_store_dwordx2 v[116:117], v[114:115], off
	s_nop 0
	s_nop 0
	s_nop 0
	v_cvt_pk_bf16_f32 v116, v120, v120
	v_cvt_pk_bf16_f32 v114, v118, v118
	v_cvt_pk_bf16_f32 v115, v121, v121
	v_and_b32_e32 v116, 0xffff0000, v116
	v_cvt_pk_bf16_f32 v0, v119, v119
	v_and_b32_e32 v115, 0xffff0000, v115
	v_or_b32_sdwa v114, v116, v114 dst_sel:DWORD dst_unused:UNUSED_PAD src0_sel:DWORD src1_sel:WORD_1
	v_add_co_u32_e32 v116, vcc, 0x9000, v144
	v_or_b32_sdwa v115, v115, v0 dst_sel:DWORD dst_unused:UNUSED_PAD src0_sel:DWORD src1_sel:WORD_1
	s_nop 0
	v_addc_co_u32_e32 v117, vcc, 0, v145, vcc
	global_store_dwordx2 v[116:117], v[114:115], off
; __device__ __forceinline__ unsigned pack2(float a, float b) { return (unsigned)f2bf(a) | ((unsigned)f2bf(b) << 16); }
; __device__ __forceinline__ float fexp2(float x) { return __builtin_amdgcn_exp2f(x); }
; template <int EPI, bool HS = false>
; __device__ __forceinline__ void gemm_phase(const Params& p, const GemmCfg& g, char* shm, const int wave_s) {
;     ...
;           for (int m = 0; m < 4; ++m) {
;             const int jj0 = wr * 64 + m * 16 + fq * 4;
;             const float k0 = fexp2(lg2 * (float)(127 - jj0));
;             const f32x4 r4 = *(const f32x4*)(rsw + ai * 128 + m * 16);
; #pragma unroll
;             for (int bj = 0; bj < 2; ++bj) {
;               float y1[4], y2[4];
; #pragma unroll
;               for (int j = 0; j < 4; ++j) {
;                 const int lr = ai * 128 + m * 16 + j;
;                 float cs = *(const float*)(rl + ((m * 16 + j) * 128 + bj * 64) * 4), sn = *(const float*)(rl + 65536 + ((m * 16 + j) * 128 + bj * 64) * 4);
;                 float x1 = r4[j] * acc[ai][bj][m][0][j] + swv[bj][0], x2 = r4[j] * acc[ai][bj][m][1][j] + swv[bj][1];
;                 y1[j] = (x1 * cs - x2 * sn) * scl;
;                 y2[j] = (x2 * cs + x1 * sn) * scl;
;                 dst[tb + lr * 1024 + bj * 128] = f2bf(y1[j]);
;                 dst[tb + lr * 1024 + bj * 128 + 16] = f2bf(y2[j]);
;               }
;               if (isk) {
;                 float d0 = k0, d1 = fexp2(lg2 * (float)(126 - jj0)), d2 = fexp2(lg2 * (float)(125 - jj0)),
;                       d3 = fexp2(lg2 * (float)(124 - jj0));
;                 uint2 v1, v2;
;                 v1.x = pack2(y1[0] * d0, y1[1] * d1); v1.y = pack2(y1[2] * d2, y1[3] * d3);
;                 v2.x = pack2(y2[0] * d0, y2[1] * d1); v2.y = pack2(y2[2] * d2, y2[3] * d3);
;                 *(uint2*)(kt_t + kb + ai * 256 * 128 + (bj * 128) * 128 + m * 16) = v1;
;                 *(uint2*)(kt_t + kb + ai * 256 * 128 + (bj * 128 + 16) * 128 + m * 16) = v2;
;               }
.LBB0_600:
	v_mov_b32_e32 v141, v140
	v_mov_b32_e32 v139, v138
	v_or_b32_e32 v0, 16, v161
	v_sub_u32_e32 v114, 0x7f, v0
	v_cvt_f32_i32_e32 v114, v114
	v_sub_u32_e32 v115, 0x7e, v0
	v_cvt_f32_i32_e32 v115, v115
	ds_read2st64_b32 v[130:131], v155 offset0:32 offset1:34
	v_mul_f32_e32 v114, v160, v114
	v_exp_f32_e32 v118, v114
	v_sub_u32_e32 v114, 0x7d, v0
	v_cvt_f32_i32_e32 v114, v114
	v_sub_u32_e32 v0, 0x7c, v0
	v_cvt_f32_i32_e32 v0, v0
	v_mul_f32_e32 v115, v160, v115
	v_mul_f32_e32 v114, v160, v114
	v_exp_f32_e32 v120, v115
	v_exp_f32_e32 v119, v114
	v_add_u32_e32 v126, 0x12000, v155
	v_add_u32_e32 v127, 0x12200, v155
	ds_read2st64_b32 v[168:169], v155 offset0:36 offset1:38
	v_add_u32_e32 v128, 0x12400, v155
	ds_read_b128 v[114:117], v154 offset:64
	ds_read_b32 v170, v126
	ds_read_b32 v172, v127
	ds_read_b32 v171, v128
	v_mul_f32_e32 v0, v160, v0
	v_exp_f32_e32 v121, v0
	v_or_b32_e32 v0, 0x4000, v146
	s_waitcnt lgkmcnt(3)
	v_pk_mul_f32 v[112:113], v[112:113], v[116:117]
	v_pk_mul_f32 v[110:111], v[110:111], v[114:115]
	v_lshl_add_u64 v[132:133], v[0:1], 1, s[0:1]
	v_or_b32_e32 v0, 0x4010, v146
	v_mov_b32_e32 v180, v110
	v_mov_b32_e32 v181, v112
	v_pk_mul_f32 v[108:109], v[108:109], v[116:117]
	v_pk_mul_f32 v[182:183], v[106:107], v[114:115]
	v_lshl_add_u64 v[152:153], v[0:1], 1, s[0:1]
	v_or_b32_e32 v0, 0x4400, v146
	v_add_u32_e32 v129, 0x12600, v155
	v_pk_add_f32 v[180:181], v[140:141], v[180:181]
	v_mov_b32_e32 v106, v182
	v_mov_b32_e32 v107, v108
	v_lshl_add_u64 v[164:165], v[0:1], 1, s[0:1]
	v_or_b32_e32 v0, 0x4410, v146
	ds_read_b32 v173, v129
	v_pk_add_f32 v[184:185], v[138:139], v[106:107]
	v_mov_b32_e32 v186, v130
	v_mov_b32_e32 v187, v168
	s_waitcnt lgkmcnt(1)
	v_pk_mul_f32 v[106:107], v[170:171], v[180:181]
	v_lshl_add_u64 v[166:167], v[0:1], 1, s[0:1]
	v_or_b32_e32 v0, 0x4800, v146
	v_pk_fma_f32 v[106:107], v[186:187], v[184:185], v[106:107] neg_lo:[0,0,1] neg_hi:[0,0,1]
	v_lshl_add_u64 v[174:175], v[0:1], 1, s[0:1]
	v_or_b32_e32 v0, 0x4810, v146
	v_pk_mul_f32 v[106:107], v[142:143], v[106:107]
	v_lshl_add_u64 v[176:177], v[0:1], 1, s[0:1]
	s_nop 0
	v_mov_b32_e32 v112, v111
	v_cvt_pk_bf16_f32 v0, v106, v106
	v_pk_add_f32 v[112:113], v[140:141], v[112:113]
	v_mov_b32_e32 v108, v183
	global_store_short_d16_hi v[132:133], v0, off
	v_pk_add_f32 v[132:133], v[138:139], v[108:109]
	v_mov_b32_e32 v168, v131
	s_waitcnt lgkmcnt(0)
	v_pk_mul_f32 v[108:109], v[112:113], v[172:173]
	v_pk_mul_f32 v[110:111], v[170:171], v[184:185]
	v_pk_fma_f32 v[108:109], v[132:133], v[168:169], v[108:109] neg_lo:[0,0,1] neg_hi:[0,0,1]
	v_pk_fma_f32 v[110:111], v[186:187], v[180:181], v[110:111]
	v_pk_mul_f32 v[108:109], v[142:143], v[108:109]
	v_pk_mul_f32 v[110:111], v[142:143], v[110:111]
	v_cvt_pk_bf16_f32 v0, v108, v108
	global_store_short_d16_hi v[164:165], v0, off
	v_cvt_pk_bf16_f32 v0, v107, v107
	v_pk_mul_f32 v[130:131], v[132:133], v[172:173]
	global_store_short_d16_hi v[174:175], v0, off
	v_pk_fma_f32 v[112:113], v[112:113], v[168:169], v[130:131]
	v_cvt_pk_bf16_f32 v0, v110, v110
	v_pk_mul_f32 v[112:113], v[142:143], v[112:113]
	global_store_short_d16_hi v[152:153], v0, off
	v_cvt_pk_bf16_f32 v0, v112, v112
	global_store_short_d16_hi v[166:167], v0, off
	v_cvt_pk_bf16_f32 v0, v111, v111
	global_store_short_d16_hi v[176:177], v0, off
	s_nop 0
	v_cvt_pk_bf16_f32 v132, v109, v109
	v_or_b32_e32 v0, 0x4c00, v146
	v_lshl_add_u64 v[130:131], v[0:1], 1, s[0:1]
	v_bfe_u32 v0, v113, 16, 1
	global_store_short_d16_hi v[130:131], v132, off
	v_add3_u32 v132, v113, v0, s81
	v_or_b32_e32 v0, 0x4c10, v146
	v_lshl_add_u64 v[130:131], v[0:1], 1, s[0:1]
	s_and_b64 vcc, exec, s[6:7]
	s_mov_b32 s44, s47
	s_mov_b32 s45, s92
	s_mov_b32 s42, 0x800000
	s_mov_b32 s43, s50
	global_store_short_d16_hi v[130:131], v132, off
	s_cbranch_vccnz .LBB0_602
	v_pk_mul_f32 v[106:107], v[118:119], v[106:107]
	v_pk_mul_f32 v[108:109], v[120:121], v[108:109]
	s_nop 0
	s_nop 0
	v_cvt_pk_bf16_f32 v106, v106, v106
	v_cvt_pk_bf16_f32 v0, v107, v107
	v_cvt_pk_bf16_f32 v107, v109, v109
	v_cvt_pk_bf16_f32 v108, v108, v108
	v_pk_mul_f32 v[112:113], v[120:121], v[112:113]
	v_and_b32_e32 v107, 0xffff0000, v107
	v_and_b32_e32 v108, 0xffff0000, v108
	v_pk_mul_f32 v[110:111], v[118:119], v[110:111]
	v_or_b32_sdwa v107, v107, v0 dst_sel:DWORD dst_unused:UNUSED_PAD src0_sel:DWORD src1_sel:WORD_1
	v_or_b32_sdwa v106, v108, v106 dst_sel:DWORD dst_unused:UNUSED_PAD src0_sel:DWORD src1_sel:WORD_1
	global_store_dwordx2 v[144:145], v[106:107], off offset:32
	v_cvt_pk_bf16_f32 v108, v112, v112
	v_cvt_pk_bf16_f32 v106, v110, v110
	v_cvt_pk_bf16_f32 v107, v113, v113
	v_and_b32_e32 v108, 0xffff0000, v108
	v_cvt_pk_bf16_f32 v0, v111, v111
	v_and_b32_e32 v107, 0xffff0000, v107
	v_or_b32_sdwa v106, v108, v106 dst_sel:DWORD dst_unused:UNUSED_PAD src0_sel:DWORD src1_sel:WORD_1
	v_add_co_u32_e32 v108, vcc, 0x1000, v144
	v_or_b32_sdwa v107, v107, v0 dst_sel:DWORD dst_unused:UNUSED_PAD src0_sel:DWORD src1_sel:WORD_1
	s_nop 0
	v_addc_co_u32_e32 v109, vcc, 0, v145, vcc
	global_store_dwordx2 v[108:109], v[106:107], off offset:32
; __device__ __forceinline__ unsigned pack2(float a, float b) { return (unsigned)f2bf(a) | ((unsigned)f2bf(b) << 16); }
; __device__ __forceinline__ float fexp2(float x) { return __builtin_amdgcn_exp2f(x); }
; template <int EPI, bool HS = false>
; __device__ __forceinline__ void gemm_phase(const Params& p, const GemmCfg& g, char* shm, const int wave_s) {
;     ...
;             for (int bj = 0; bj < 2; ++bj) {
;               float y1[4], y2[4];
; #pragma unroll
;               for (int j = 0; j < 4; ++j) {
;                 const int lr = ai * 128 + m * 16 + j;
;                 float cs = *(const float*)(rl + ((m * 16 + j) * 128 + bj * 64) * 4), sn = *(const float*)(rl + 65536 + ((m * 16 + j) * 128 + bj * 64) * 4);
;                 float x1 = r4[j] * acc[ai][bj][m][0][j] + swv[bj][0], x2 = r4[j] * acc[ai][bj][m][1][j] + swv[bj][1];
;                 y1[j] = (x1 * cs - x2 * sn) * scl;
;                 y2[j] = (x2 * cs + x1 * sn) * scl;
;                 dst[tb + lr * 1024 + bj * 128] = f2bf(y1[j]);
;                 dst[tb + lr * 1024 + bj * 128 + 16] = f2bf(y2[j]);
;               }
;               if (isk) {
;                 float d0 = k0, d1 = fexp2(lg2 * (float)(126 - jj0)), d2 = fexp2(lg2 * (float)(125 - jj0)),
;                       d3 = fexp2(lg2 * (float)(124 - jj0));
;                 uint2 v1, v2;
;                 v1.x = pack2(y1[0] * d0, y1[1] * d1); v1.y = pack2(y1[2] * d2, y1[3] * d3);
;                 v2.x = pack2(y2[0] * d0, y2[1] * d1); v2.y = pack2(y2[2] * d2, y2[3] * d3);
;                 *(uint2*)(kt_t + kb + ai * 256 * 128 + (bj * 128) * 128 + m * 16) = v1;
;                 *(uint2*)(kt_t + kb + ai * 256 * 128 + (bj * 128 + 16) * 128 + m * 16) = v2;
;               }
.LBB0_602:
	ds_read2st64_b32 v[110:111], v155 offset0:33 offset1:35
	v_add_u32_e32 v106, 0x12100, v155
	ds_read2st64_b32 v[164:165], v155 offset0:37 offset1:39
	v_add_u32_e32 v107, 0x12300, v155
	v_add_u32_e32 v108, 0x12500, v155
	v_add_u32_e32 v109, 0x12700, v155
	ds_read_b32 v170, v106
	ds_read_b32 v172, v107
	ds_read_b32 v171, v108
	ds_read_b32 v173, v109
	v_or_b32_e32 v0, 0x4080, v146
	v_pk_mul_f32 v[104:105], v[104:105], v[116:117]
	v_pk_mul_f32 v[102:103], v[102:103], v[114:115]
	v_mov_b32_e32 v137, v136
	v_lshl_add_u64 v[112:113], v[0:1], 1, s[0:1]
	v_or_b32_e32 v0, 0x4090, v146
	v_mov_b32_e32 v174, v102
	v_mov_b32_e32 v175, v104
	v_pk_mul_f32 v[100:101], v[100:101], v[116:117]
	v_pk_mul_f32 v[114:115], v[98:99], v[114:115]
	v_mov_b32_e32 v135, v134
	v_lshl_add_u64 v[130:131], v[0:1], 1, s[0:1]
	v_or_b32_e32 v0, 0x4480, v146
	v_pk_add_f32 v[174:175], v[136:137], v[174:175]
	v_mov_b32_e32 v98, v114
	v_mov_b32_e32 v99, v100
	v_lshl_add_u64 v[132:133], v[0:1], 1, s[0:1]
	v_or_b32_e32 v0, 0x4490, v146
	v_pk_add_f32 v[116:117], v[134:135], v[98:99]
	s_waitcnt lgkmcnt(5)
	v_mov_b32_e32 v176, v110
	s_waitcnt lgkmcnt(4)
	v_mov_b32_e32 v177, v164
	s_waitcnt lgkmcnt(1)
	v_pk_mul_f32 v[98:99], v[174:175], v[170:171]
	v_lshl_add_u64 v[152:153], v[0:1], 1, s[0:1]
	v_or_b32_e32 v0, 0x4880, v146
	v_pk_fma_f32 v[98:99], v[116:117], v[176:177], v[98:99] neg_lo:[0,0,1] neg_hi:[0,0,1]
	v_lshl_add_u64 v[166:167], v[0:1], 1, s[0:1]
	v_or_b32_e32 v0, 0x4890, v146
	v_pk_mul_f32 v[98:99], v[142:143], v[98:99]
	v_lshl_add_u64 v[168:169], v[0:1], 1, s[0:1]
	s_nop 0
	v_mov_b32_e32 v104, v103
	v_cvt_pk_bf16_f32 v0, v98, v98
	v_pk_add_f32 v[104:105], v[136:137], v[104:105]
	v_mov_b32_e32 v100, v115
	global_store_short_d16_hi v[112:113], v0, off
	v_pk_add_f32 v[112:113], v[134:135], v[100:101]
	v_mov_b32_e32 v164, v111
	s_waitcnt lgkmcnt(0)
	v_pk_mul_f32 v[100:101], v[104:105], v[172:173]
	v_pk_mul_f32 v[102:103], v[116:117], v[170:171]
	v_pk_fma_f32 v[100:101], v[112:113], v[164:165], v[100:101] neg_lo:[0,0,1] neg_hi:[0,0,1]
	v_pk_fma_f32 v[102:103], v[174:175], v[176:177], v[102:103]
	v_pk_mul_f32 v[100:101], v[142:143], v[100:101]
	v_pk_mul_f32 v[102:103], v[142:143], v[102:103]
	v_cvt_pk_bf16_f32 v0, v100, v100
	global_store_short_d16_hi v[132:133], v0, off
	v_cvt_pk_bf16_f32 v0, v99, v99
	v_pk_mul_f32 v[110:111], v[112:113], v[172:173]
	global_store_short_d16_hi v[166:167], v0, off
	v_pk_fma_f32 v[104:105], v[104:105], v[164:165], v[110:111]
	v_cvt_pk_bf16_f32 v0, v102, v102
	v_pk_mul_f32 v[104:105], v[142:143], v[104:105]
	global_store_short_d16_hi v[130:131], v0, off
	v_cvt_pk_bf16_f32 v0, v104, v104
	global_store_short_d16_hi v[152:153], v0, off
	v_cvt_pk_bf16_f32 v0, v103, v103
	global_store_short_d16_hi v[168:169], v0, off
	s_nop 0
	v_cvt_pk_bf16_f32 v112, v101, v101
	v_or_b32_e32 v0, 0x4c80, v146
	v_lshl_add_u64 v[110:111], v[0:1], 1, s[0:1]
	v_bfe_u32 v0, v105, 16, 1
	global_store_short_d16_hi v[110:111], v112, off
	v_add3_u32 v112, v105, v0, s81
	v_or_b32_e32 v0, 0x4c90, v146
	v_lshl_add_u64 v[110:111], v[0:1], 1, s[0:1]
	s_and_b64 vcc, exec, s[6:7]
	s_mov_b64 s[46:47], s[48:49]
	global_store_short_d16_hi v[110:111], v112, off
	s_cbranch_vccnz .LBB0_604
	v_pk_mul_f32 v[98:99], v[118:119], v[98:99]
	v_pk_mul_f32 v[100:101], v[120:121], v[100:101]
	s_nop 0
	s_nop 0
	v_cvt_pk_bf16_f32 v98, v98, v98
	v_cvt_pk_bf16_f32 v0, v99, v99
	v_cvt_pk_bf16_f32 v100, v100, v100
	v_cvt_pk_bf16_f32 v99, v101, v101
	v_and_b32_e32 v100, 0xffff0000, v100
	s_mov_b32 s4, 0x8000
	v_and_b32_e32 v99, 0xffff0000, v99
	v_or_b32_sdwa v98, v100, v98 dst_sel:DWORD dst_unused:UNUSED_PAD src0_sel:DWORD src1_sel:WORD_1
	v_add_co_u32_e32 v100, vcc, s4, v144
	v_pk_mul_f32 v[104:105], v[120:121], v[104:105]
	v_or_b32_sdwa v99, v99, v0 dst_sel:DWORD dst_unused:UNUSED_PAD src0_sel:DWORD src1_sel:WORD_1
	v_addc_co_u32_e32 v101, vcc, 0, v145, vcc
	v_pk_mul_f32 v[102:103], v[118:119], v[102:103]
	global_store_dwordx2 v[100:101], v[98:99], off offset:32
	s_nop 0
	s_nop 0
	s_nop 0
	v_cvt_pk_bf16_f32 v100, v104, v104
	v_cvt_pk_bf16_f32 v98, v102, v102
	v_cvt_pk_bf16_f32 v99, v105, v105
	v_and_b32_e32 v100, 0xffff0000, v100
	v_cvt_pk_bf16_f32 v0, v103, v103
	v_and_b32_e32 v99, 0xffff0000, v99
	v_or_b32_sdwa v98, v100, v98 dst_sel:DWORD dst_unused:UNUSED_PAD src0_sel:DWORD src1_sel:WORD_1
	v_add_co_u32_e32 v100, vcc, 0x9000, v144
	v_or_b32_sdwa v99, v99, v0 dst_sel:DWORD dst_unused:UNUSED_PAD src0_sel:DWORD src1_sel:WORD_1
	s_nop 0
	v_addc_co_u32_e32 v101, vcc, 0, v145, vcc
	global_store_dwordx2 v[100:101], v[98:99], off offset:32
; __device__ __forceinline__ unsigned pack2(float a, float b) { return (unsigned)f2bf(a) | ((unsigned)f2bf(b) << 16); }
; __device__ __forceinline__ float fexp2(float x) { return __builtin_amdgcn_exp2f(x); }
; template <int EPI, bool HS = false>
; __device__ __forceinline__ void gemm_phase(const Params& p, const GemmCfg& g, char* shm, const int wave_s) {
;     ...
;           for (int m = 0; m < 4; ++m) {
;             const int jj0 = wr * 64 + m * 16 + fq * 4;
;             const float k0 = fexp2(lg2 * (float)(127 - jj0));
;             const f32x4 r4 = *(const f32x4*)(rsw + ai * 128 + m * 16);
; #pragma unroll
;             for (int bj = 0; bj < 2; ++bj) {
;               float y1[4], y2[4];
; #pragma unroll
;               for (int j = 0; j < 4; ++j) {
;                 const int lr = ai * 128 + m * 16 + j;
;                 float cs = *(const float*)(rl + ((m * 16 + j) * 128 + bj * 64) * 4), sn = *(const float*)(rl + 65536 + ((m * 16 + j) * 128 + bj * 64) * 4);
;                 float x1 = r4[j] * acc[ai][bj][m][0][j] + swv[bj][0], x2 = r4[j] * acc[ai][bj][m][1][j] + swv[bj][1];
;                 y1[j] = (x1 * cs - x2 * sn) * scl;
;                 y2[j] = (x2 * cs + x1 * sn) * scl;
;                 dst[tb + lr * 1024 + bj * 128] = f2bf(y1[j]);
;                 dst[tb + lr * 1024 + bj * 128 + 16] = f2bf(y2[j]);
;               }
;               if (isk) {
;                 float d0 = k0, d1 = fexp2(lg2 * (float)(126 - jj0)), d2 = fexp2(lg2 * (float)(125 - jj0)),
;                       d3 = fexp2(lg2 * (float)(124 - jj0));
;                 uint2 v1, v2;
;                 v1.x = pack2(y1[0] * d0, y1[1] * d1); v1.y = pack2(y1[2] * d2, y1[3] * d3);
;                 v2.x = pack2(y2[0] * d0, y2[1] * d1); v2.y = pack2(y2[2] * d2, y2[3] * d3);
;                 *(uint2*)(kt_t + kb + ai * 256 * 128 + (bj * 128) * 128 + m * 16) = v1;
;                 *(uint2*)(kt_t + kb + ai * 256 * 128 + (bj * 128 + 16) * 128 + m * 16) = v2;
;               }
.LBB0_604:
	v_or_b32_e32 v0, 32, v161
	v_sub_u32_e32 v98, 0x7f, v0
	v_cvt_f32_i32_e32 v98, v98
	v_sub_u32_e32 v99, 0x7e, v0
	v_cvt_f32_i32_e32 v99, v99
	ds_read2st64_b32 v[114:115], v155 offset0:64 offset1:66
	v_mul_f32_e32 v98, v160, v98
	v_exp_f32_e32 v102, v98
	v_sub_u32_e32 v98, 0x7d, v0
	v_cvt_f32_i32_e32 v98, v98
	v_sub_u32_e32 v0, 0x7c, v0
	v_cvt_f32_i32_e32 v0, v0
	v_mul_f32_e32 v99, v160, v99
	v_mul_f32_e32 v98, v160, v98
	v_exp_f32_e32 v104, v99
	v_exp_f32_e32 v103, v98
	v_add_u32_e32 v110, 0x14000, v155
	v_add_u32_e32 v111, 0x14200, v155
	ds_read2st64_b32 v[164:165], v155 offset0:68 offset1:70
	v_add_u32_e32 v112, 0x14400, v155
	ds_read_b128 v[98:101], v154 offset:128
	ds_read_b32 v166, v110
	ds_read_b32 v168, v111
	ds_read_b32 v167, v112
	v_mul_f32_e32 v0, v160, v0
	v_exp_f32_e32 v105, v0
	v_or_b32_e32 v0, 0x8000, v146
	s_waitcnt lgkmcnt(3)
	v_pk_mul_f32 v[96:97], v[96:97], v[100:101]
	v_pk_mul_f32 v[94:95], v[94:95], v[98:99]
	v_lshl_add_u64 v[116:117], v[0:1], 1, s[0:1]
	v_or_b32_e32 v0, 0x8010, v146
	v_mov_b32_e32 v174, v94
	v_mov_b32_e32 v175, v96
	v_pk_mul_f32 v[92:93], v[92:93], v[100:101]
	v_pk_mul_f32 v[176:177], v[90:91], v[98:99]
	v_lshl_add_u64 v[130:131], v[0:1], 1, s[0:1]
	v_or_b32_e32 v0, 0x8400, v146
	v_add_u32_e32 v113, 0x14600, v155
	v_pk_add_f32 v[174:175], v[140:141], v[174:175]
	v_mov_b32_e32 v90, v176
	v_mov_b32_e32 v91, v92
	v_lshl_add_u64 v[132:133], v[0:1], 1, s[0:1]
	v_or_b32_e32 v0, 0x8410, v146
	ds_read_b32 v169, v113
	v_pk_add_f32 v[180:181], v[138:139], v[90:91]
	v_mov_b32_e32 v182, v114
	v_mov_b32_e32 v183, v164
	s_waitcnt lgkmcnt(1)
	v_pk_mul_f32 v[90:91], v[166:167], v[174:175]
	v_lshl_add_u64 v[152:153], v[0:1], 1, s[0:1]
	v_or_b32_e32 v0, 0x8800, v146
	v_pk_fma_f32 v[90:91], v[182:183], v[180:181], v[90:91] neg_lo:[0,0,1] neg_hi:[0,0,1]
	v_lshl_add_u64 v[170:171], v[0:1], 1, s[0:1]
	v_or_b32_e32 v0, 0x8810, v146
	v_pk_mul_f32 v[90:91], v[142:143], v[90:91]
	v_lshl_add_u64 v[172:173], v[0:1], 1, s[0:1]
	s_nop 0
	v_mov_b32_e32 v96, v95
	v_cvt_pk_bf16_f32 v0, v90, v90
	v_pk_add_f32 v[96:97], v[140:141], v[96:97]
	v_mov_b32_e32 v92, v177
	global_store_short_d16_hi v[116:117], v0, off
	v_pk_add_f32 v[116:117], v[138:139], v[92:93]
	v_mov_b32_e32 v164, v115
	s_waitcnt lgkmcnt(0)
	v_pk_mul_f32 v[92:93], v[96:97], v[168:169]
	v_pk_mul_f32 v[94:95], v[166:167], v[180:181]
	v_pk_fma_f32 v[92:93], v[116:117], v[164:165], v[92:93] neg_lo:[0,0,1] neg_hi:[0,0,1]
	v_pk_fma_f32 v[94:95], v[182:183], v[174:175], v[94:95]
	v_pk_mul_f32 v[92:93], v[142:143], v[92:93]
	v_pk_mul_f32 v[94:95], v[142:143], v[94:95]
	v_cvt_pk_bf16_f32 v0, v92, v92
	global_store_short_d16_hi v[132:133], v0, off
	v_cvt_pk_bf16_f32 v0, v91, v91
	v_pk_mul_f32 v[114:115], v[116:117], v[168:169]
	global_store_short_d16_hi v[170:171], v0, off
	v_pk_fma_f32 v[96:97], v[96:97], v[164:165], v[114:115]
	v_cvt_pk_bf16_f32 v0, v94, v94
	v_pk_mul_f32 v[96:97], v[142:143], v[96:97]
	global_store_short_d16_hi v[130:131], v0, off
	v_cvt_pk_bf16_f32 v0, v96, v96
	global_store_short_d16_hi v[152:153], v0, off
	v_cvt_pk_bf16_f32 v0, v95, v95
	global_store_short_d16_hi v[172:173], v0, off
	s_nop 0
	v_cvt_pk_bf16_f32 v116, v93, v93
	v_or_b32_e32 v0, 0x8c00, v146
	v_lshl_add_u64 v[114:115], v[0:1], 1, s[0:1]
	v_bfe_u32 v0, v97, 16, 1
	global_store_short_d16_hi v[114:115], v116, off
	v_add3_u32 v116, v97, v0, s81
	v_or_b32_e32 v0, 0x8c10, v146
	v_lshl_add_u64 v[114:115], v[0:1], 1, s[0:1]
	s_and_b64 vcc, exec, s[6:7]
	v_readlane_b32 s49, v254, 53
	global_store_short_d16_hi v[114:115], v116, off
	s_cbranch_vccnz .LBB0_606
	v_pk_mul_f32 v[90:91], v[102:103], v[90:91]
	v_pk_mul_f32 v[92:93], v[104:105], v[92:93]
	s_nop 0
	s_nop 0
	v_cvt_pk_bf16_f32 v90, v90, v90
	v_cvt_pk_bf16_f32 v0, v91, v91
	v_cvt_pk_bf16_f32 v91, v93, v93
	v_cvt_pk_bf16_f32 v92, v92, v92
	v_pk_mul_f32 v[96:97], v[104:105], v[96:97]
	v_and_b32_e32 v91, 0xffff0000, v91
	v_and_b32_e32 v92, 0xffff0000, v92
	v_pk_mul_f32 v[94:95], v[102:103], v[94:95]
	v_or_b32_sdwa v91, v91, v0 dst_sel:DWORD dst_unused:UNUSED_PAD src0_sel:DWORD src1_sel:WORD_1
	v_or_b32_sdwa v90, v92, v90 dst_sel:DWORD dst_unused:UNUSED_PAD src0_sel:DWORD src1_sel:WORD_1
	global_store_dwordx2 v[144:145], v[90:91], off offset:64
	v_cvt_pk_bf16_f32 v92, v96, v96
	v_cvt_pk_bf16_f32 v90, v94, v94
	v_cvt_pk_bf16_f32 v91, v97, v97
	v_and_b32_e32 v92, 0xffff0000, v92
	v_cvt_pk_bf16_f32 v0, v95, v95
	v_and_b32_e32 v91, 0xffff0000, v91
	v_or_b32_sdwa v90, v92, v90 dst_sel:DWORD dst_unused:UNUSED_PAD src0_sel:DWORD src1_sel:WORD_1
	v_add_co_u32_e32 v92, vcc, 0x1000, v144
	v_or_b32_sdwa v91, v91, v0 dst_sel:DWORD dst_unused:UNUSED_PAD src0_sel:DWORD src1_sel:WORD_1
	s_nop 0
	v_addc_co_u32_e32 v93, vcc, 0, v145, vcc
	global_store_dwordx2 v[92:93], v[90:91], off offset:64
; __device__ __forceinline__ unsigned pack2(float a, float b) { return (unsigned)f2bf(a) | ((unsigned)f2bf(b) << 16); }
; __device__ __forceinline__ float fexp2(float x) { return __builtin_amdgcn_exp2f(x); }
; template <int EPI, bool HS = false>
; __device__ __forceinline__ void gemm_phase(const Params& p, const GemmCfg& g, char* shm, const int wave_s) {
;     ...
;             for (int bj = 0; bj < 2; ++bj) {
;               float y1[4], y2[4];
; #pragma unroll
;               for (int j = 0; j < 4; ++j) {
;                 const int lr = ai * 128 + m * 16 + j;
;                 float cs = *(const float*)(rl + ((m * 16 + j) * 128 + bj * 64) * 4), sn = *(const float*)(rl + 65536 + ((m * 16 + j) * 128 + bj * 64) * 4);
;                 float x1 = r4[j] * acc[ai][bj][m][0][j] + swv[bj][0], x2 = r4[j] * acc[ai][bj][m][1][j] + swv[bj][1];
;                 y1[j] = (x1 * cs - x2 * sn) * scl;
;                 y2[j] = (x2 * cs + x1 * sn) * scl;
;                 dst[tb + lr * 1024 + bj * 128] = f2bf(y1[j]);
;                 dst[tb + lr * 1024 + bj * 128 + 16] = f2bf(y2[j]);
;               }
;               if (isk) {
;                 float d0 = k0, d1 = fexp2(lg2 * (float)(126 - jj0)), d2 = fexp2(lg2 * (float)(125 - jj0)),
;                       d3 = fexp2(lg2 * (float)(124 - jj0));
;                 uint2 v1, v2;
;                 v1.x = pack2(y1[0] * d0, y1[1] * d1); v1.y = pack2(y1[2] * d2, y1[3] * d3);
;                 v2.x = pack2(y2[0] * d0, y2[1] * d1); v2.y = pack2(y2[2] * d2, y2[3] * d3);
;                 *(uint2*)(kt_t + kb + ai * 256 * 128 + (bj * 128) * 128 + m * 16) = v1;
;                 *(uint2*)(kt_t + kb + ai * 256 * 128 + (bj * 128 + 16) * 128 + m * 16) = v2;
;               }
.LBB0_606:
	ds_read2st64_b32 v[94:95], v155 offset0:65 offset1:67
	v_add_u32_e32 v90, 0x14100, v155
	ds_read2st64_b32 v[132:133], v155 offset0:69 offset1:71
	v_add_u32_e32 v91, 0x14300, v155
	v_add_u32_e32 v92, 0x14500, v155
	v_add_u32_e32 v93, 0x14700, v155
	ds_read_b32 v166, v90
	ds_read_b32 v168, v91
	ds_read_b32 v167, v92
	ds_read_b32 v169, v93
	v_or_b32_e32 v0, 0x8080, v146
	v_pk_mul_f32 v[88:89], v[88:89], v[100:101]
	v_pk_mul_f32 v[86:87], v[86:87], v[98:99]
	v_lshl_add_u64 v[96:97], v[0:1], 1, s[0:1]
	v_or_b32_e32 v0, 0x8090, v146
	v_mov_b32_e32 v170, v86
	v_mov_b32_e32 v171, v88
	v_pk_mul_f32 v[84:85], v[84:85], v[100:101]
	v_pk_mul_f32 v[98:99], v[82:83], v[98:99]
	v_lshl_add_u64 v[114:115], v[0:1], 1, s[0:1]
	v_or_b32_e32 v0, 0x8480, v146
	v_pk_add_f32 v[170:171], v[136:137], v[170:171]
	v_mov_b32_e32 v82, v98
	v_mov_b32_e32 v83, v84
	v_lshl_add_u64 v[116:117], v[0:1], 1, s[0:1]
	v_or_b32_e32 v0, 0x8490, v146
	v_pk_add_f32 v[100:101], v[134:135], v[82:83]
	s_waitcnt lgkmcnt(5)
	v_mov_b32_e32 v172, v94
	s_waitcnt lgkmcnt(4)
	v_mov_b32_e32 v173, v132
	s_waitcnt lgkmcnt(1)
	v_pk_mul_f32 v[82:83], v[170:171], v[166:167]
	v_lshl_add_u64 v[130:131], v[0:1], 1, s[0:1]
	v_or_b32_e32 v0, 0x8880, v146
	v_pk_fma_f32 v[82:83], v[100:101], v[172:173], v[82:83] neg_lo:[0,0,1] neg_hi:[0,0,1]
	v_lshl_add_u64 v[152:153], v[0:1], 1, s[0:1]
	v_or_b32_e32 v0, 0x8890, v146
	v_pk_mul_f32 v[82:83], v[142:143], v[82:83]
	v_lshl_add_u64 v[164:165], v[0:1], 1, s[0:1]
	s_nop 0
	v_mov_b32_e32 v88, v87
	v_cvt_pk_bf16_f32 v0, v82, v82
	v_pk_add_f32 v[88:89], v[136:137], v[88:89]
	v_mov_b32_e32 v84, v99
	global_store_short_d16_hi v[96:97], v0, off
	v_pk_add_f32 v[96:97], v[134:135], v[84:85]
	v_mov_b32_e32 v132, v95
	s_waitcnt lgkmcnt(0)
	v_pk_mul_f32 v[84:85], v[88:89], v[168:169]
	v_pk_mul_f32 v[86:87], v[100:101], v[166:167]
	v_pk_fma_f32 v[84:85], v[96:97], v[132:133], v[84:85] neg_lo:[0,0,1] neg_hi:[0,0,1]
	v_pk_fma_f32 v[86:87], v[170:171], v[172:173], v[86:87]
	v_pk_mul_f32 v[84:85], v[142:143], v[84:85]
	v_pk_mul_f32 v[86:87], v[142:143], v[86:87]
	v_cvt_pk_bf16_f32 v0, v84, v84
	global_store_short_d16_hi v[116:117], v0, off
	v_cvt_pk_bf16_f32 v0, v83, v83
	v_pk_mul_f32 v[94:95], v[96:97], v[168:169]
	global_store_short_d16_hi v[152:153], v0, off
	v_pk_fma_f32 v[88:89], v[88:89], v[132:133], v[94:95]
	v_cvt_pk_bf16_f32 v0, v86, v86
	v_pk_mul_f32 v[88:89], v[142:143], v[88:89]
	global_store_short_d16_hi v[114:115], v0, off
	v_cvt_pk_bf16_f32 v0, v88, v88
	global_store_short_d16_hi v[130:131], v0, off
	v_cvt_pk_bf16_f32 v0, v87, v87
	global_store_short_d16_hi v[164:165], v0, off
	s_nop 0
	v_cvt_pk_bf16_f32 v96, v85, v85
	v_or_b32_e32 v0, 0x8c80, v146
	v_lshl_add_u64 v[94:95], v[0:1], 1, s[0:1]
	v_bfe_u32 v0, v89, 16, 1
	global_store_short_d16_hi v[94:95], v96, off
	v_add3_u32 v96, v89, v0, s81
	v_or_b32_e32 v0, 0x8c90, v146
	v_lshl_add_u64 v[94:95], v[0:1], 1, s[0:1]
	s_and_b64 vcc, exec, s[6:7]
	global_store_short_d16_hi v[94:95], v96, off
	s_cbranch_vccnz .LBB0_608
	v_pk_mul_f32 v[82:83], v[102:103], v[82:83]
	v_pk_mul_f32 v[84:85], v[104:105], v[84:85]
	s_nop 0
	s_nop 0
	v_cvt_pk_bf16_f32 v82, v82, v82
	v_cvt_pk_bf16_f32 v0, v83, v83
	v_cvt_pk_bf16_f32 v84, v84, v84
	v_cvt_pk_bf16_f32 v83, v85, v85
	v_and_b32_e32 v84, 0xffff0000, v84
	s_mov_b32 s4, 0x8000
	v_and_b32_e32 v83, 0xffff0000, v83
	v_or_b32_sdwa v82, v84, v82 dst_sel:DWORD dst_unused:UNUSED_PAD src0_sel:DWORD src1_sel:WORD_1
	v_add_co_u32_e32 v84, vcc, s4, v144
	v_pk_mul_f32 v[88:89], v[104:105], v[88:89]
	v_or_b32_sdwa v83, v83, v0 dst_sel:DWORD dst_unused:UNUSED_PAD src0_sel:DWORD src1_sel:WORD_1
	v_addc_co_u32_e32 v85, vcc, 0, v145, vcc
	v_pk_mul_f32 v[86:87], v[102:103], v[86:87]
	global_store_dwordx2 v[84:85], v[82:83], off offset:64
	s_nop 0
	s_nop 0
	s_nop 0
	v_cvt_pk_bf16_f32 v84, v88, v88
	v_cvt_pk_bf16_f32 v82, v86, v86
	v_cvt_pk_bf16_f32 v83, v89, v89
	v_and_b32_e32 v84, 0xffff0000, v84
	v_cvt_pk_bf16_f32 v0, v87, v87
	v_and_b32_e32 v83, 0xffff0000, v83
	v_or_b32_sdwa v82, v84, v82 dst_sel:DWORD dst_unused:UNUSED_PAD src0_sel:DWORD src1_sel:WORD_1
	v_add_co_u32_e32 v84, vcc, 0x9000, v144
	v_or_b32_sdwa v83, v83, v0 dst_sel:DWORD dst_unused:UNUSED_PAD src0_sel:DWORD src1_sel:WORD_1
	s_nop 0
	v_addc_co_u32_e32 v85, vcc, 0, v145, vcc
	global_store_dwordx2 v[84:85], v[82:83], off offset:64
; __device__ __forceinline__ unsigned pack2(float a, float b) { return (unsigned)f2bf(a) | ((unsigned)f2bf(b) << 16); }
; __device__ __forceinline__ float fexp2(float x) { return __builtin_amdgcn_exp2f(x); }
; template <int EPI, bool HS = false>
; __device__ __forceinline__ void gemm_phase(const Params& p, const GemmCfg& g, char* shm, const int wave_s) {
;     ...
;           for (int m = 0; m < 4; ++m) {
;             const int jj0 = wr * 64 + m * 16 + fq * 4;
;             const float k0 = fexp2(lg2 * (float)(127 - jj0));
;             const f32x4 r4 = *(const f32x4*)(rsw + ai * 128 + m * 16);
; #pragma unroll
;             for (int bj = 0; bj < 2; ++bj) {
;               float y1[4], y2[4];
; #pragma unroll
;               for (int j = 0; j < 4; ++j) {
;                 const int lr = ai * 128 + m * 16 + j;
;                 float cs = *(const float*)(rl + ((m * 16 + j) * 128 + bj * 64) * 4), sn = *(const float*)(rl + 65536 + ((m * 16 + j) * 128 + bj * 64) * 4);
;                 float x1 = r4[j] * acc[ai][bj][m][0][j] + swv[bj][0], x2 = r4[j] * acc[ai][bj][m][1][j] + swv[bj][1];
;                 y1[j] = (x1 * cs - x2 * sn) * scl;
;                 y2[j] = (x2 * cs + x1 * sn) * scl;
;                 dst[tb + lr * 1024 + bj * 128] = f2bf(y1[j]);
;                 dst[tb + lr * 1024 + bj * 128 + 16] = f2bf(y2[j]);
;               }
;               if (isk) {
;                 float d0 = k0, d1 = fexp2(lg2 * (float)(126 - jj0)), d2 = fexp2(lg2 * (float)(125 - jj0)),
;                       d3 = fexp2(lg2 * (float)(124 - jj0));
;                 uint2 v1, v2;
;                 v1.x = pack2(y1[0] * d0, y1[1] * d1); v1.y = pack2(y1[2] * d2, y1[3] * d3);
;                 v2.x = pack2(y2[0] * d0, y2[1] * d1); v2.y = pack2(y2[2] * d2, y2[3] * d3);
;                 *(uint2*)(kt_t + kb + ai * 256 * 128 + (bj * 128) * 128 + m * 16) = v1;
;                 *(uint2*)(kt_t + kb + ai * 256 * 128 + (bj * 128 + 16) * 128 + m * 16) = v2;
;               }
.LBB0_608:
	v_or_b32_e32 v0, 48, v161
	v_sub_u32_e32 v82, 0x7f, v0
	v_cvt_f32_i32_e32 v82, v82
	v_sub_u32_e32 v83, 0x7e, v0
	v_cvt_f32_i32_e32 v83, v83
	ds_read2st64_b32 v[98:99], v155 offset0:96 offset1:98
	v_mul_f32_e32 v82, v160, v82
	v_exp_f32_e32 v86, v82
	v_sub_u32_e32 v82, 0x7d, v0
	v_cvt_f32_i32_e32 v82, v82
	v_sub_u32_e32 v0, 0x7c, v0
	v_cvt_f32_i32_e32 v0, v0
	v_mul_f32_e32 v83, v160, v83
	v_mul_f32_e32 v82, v160, v82
	v_exp_f32_e32 v88, v83
	v_exp_f32_e32 v87, v82
	v_mul_f32_e32 v0, v160, v0
	v_add_u32_e32 v94, 0x16000, v155
	v_add_u32_e32 v95, 0x16200, v155
	ds_read2st64_b32 v[132:133], v155 offset0:100 offset1:102
	v_add_u32_e32 v96, 0x16400, v155
	ds_read_b128 v[82:85], v154 offset:192
	ds_read_b32 v152, v94
	ds_read_b32 v160, v95
	ds_read_b32 v153, v96
	v_exp_f32_e32 v89, v0
	v_or_b32_e32 v0, 0xc000, v146
	s_waitcnt lgkmcnt(3)
	v_pk_mul_f32 v[80:81], v[80:81], v[84:85]
	v_pk_mul_f32 v[78:79], v[78:79], v[82:83]
	v_lshl_add_u64 v[100:101], v[0:1], 1, s[0:1]
	v_or_b32_e32 v0, 0xc010, v146
	v_mov_b32_e32 v168, v78
	v_mov_b32_e32 v169, v80
	v_pk_mul_f32 v[76:77], v[76:77], v[84:85]
	v_pk_mul_f32 v[170:171], v[74:75], v[82:83]
	v_lshl_add_u64 v[114:115], v[0:1], 1, s[0:1]
	v_or_b32_e32 v0, 0xc400, v146
	v_add_u32_e32 v97, 0x16600, v155
	v_pk_add_f32 v[168:169], v[140:141], v[168:169]
	v_mov_b32_e32 v74, v170
	v_mov_b32_e32 v75, v76
	v_lshl_add_u64 v[116:117], v[0:1], 1, s[0:1]
	v_or_b32_e32 v0, 0xc410, v146
	ds_read_b32 v161, v97
	v_pk_add_f32 v[172:173], v[138:139], v[74:75]
	v_mov_b32_e32 v174, v98
	v_mov_b32_e32 v175, v132
	s_waitcnt lgkmcnt(1)
	v_pk_mul_f32 v[74:75], v[152:153], v[168:169]
	v_lshl_add_u64 v[130:131], v[0:1], 1, s[0:1]
	v_or_b32_e32 v0, 0xc800, v146
	v_pk_fma_f32 v[74:75], v[174:175], v[172:173], v[74:75] neg_lo:[0,0,1] neg_hi:[0,0,1]
	v_lshl_add_u64 v[164:165], v[0:1], 1, s[0:1]
	v_or_b32_e32 v0, 0xc810, v146
	v_pk_mul_f32 v[74:75], v[142:143], v[74:75]
	v_lshl_add_u64 v[166:167], v[0:1], 1, s[0:1]
	s_nop 0
	v_mov_b32_e32 v80, v79
	v_cvt_pk_bf16_f32 v0, v74, v74
	v_pk_add_f32 v[80:81], v[140:141], v[80:81]
	v_mov_b32_e32 v76, v171
	global_store_short_d16_hi v[100:101], v0, off
	v_pk_add_f32 v[100:101], v[138:139], v[76:77]
	v_mov_b32_e32 v132, v99
	s_waitcnt lgkmcnt(0)
	v_pk_mul_f32 v[76:77], v[80:81], v[160:161]
	v_pk_mul_f32 v[78:79], v[152:153], v[172:173]
	v_pk_fma_f32 v[76:77], v[100:101], v[132:133], v[76:77] neg_lo:[0,0,1] neg_hi:[0,0,1]
	v_pk_fma_f32 v[78:79], v[174:175], v[168:169], v[78:79]
	v_pk_mul_f32 v[76:77], v[142:143], v[76:77]
	v_pk_mul_f32 v[78:79], v[142:143], v[78:79]
	v_cvt_pk_bf16_f32 v0, v76, v76
	global_store_short_d16_hi v[116:117], v0, off
	v_cvt_pk_bf16_f32 v0, v75, v75
	v_pk_mul_f32 v[98:99], v[100:101], v[160:161]
	global_store_short_d16_hi v[164:165], v0, off
	v_pk_fma_f32 v[80:81], v[80:81], v[132:133], v[98:99]
	v_cvt_pk_bf16_f32 v0, v78, v78
	v_pk_mul_f32 v[80:81], v[142:143], v[80:81]
	global_store_short_d16_hi v[114:115], v0, off
	v_cvt_pk_bf16_f32 v0, v80, v80
	global_store_short_d16_hi v[130:131], v0, off
	v_cvt_pk_bf16_f32 v0, v79, v79
	global_store_short_d16_hi v[166:167], v0, off
	s_nop 0
	v_cvt_pk_bf16_f32 v100, v77, v77
	v_or_b32_e32 v0, 0xcc00, v146
	v_lshl_add_u64 v[98:99], v[0:1], 1, s[0:1]
	v_bfe_u32 v0, v81, 16, 1
	global_store_short_d16_hi v[98:99], v100, off
	v_add3_u32 v100, v81, v0, s81
	v_or_b32_e32 v0, 0xcc10, v146
	v_lshl_add_u64 v[98:99], v[0:1], 1, s[0:1]
	s_and_b64 vcc, exec, s[6:7]
	global_store_short_d16_hi v[98:99], v100, off
	s_cbranch_vccnz .LBB0_610
	v_pk_mul_f32 v[74:75], v[86:87], v[74:75]
	v_pk_mul_f32 v[76:77], v[88:89], v[76:77]
	s_nop 0
	s_nop 0
	v_cvt_pk_bf16_f32 v74, v74, v74
	v_cvt_pk_bf16_f32 v0, v75, v75
	v_cvt_pk_bf16_f32 v75, v77, v77
	v_cvt_pk_bf16_f32 v76, v76, v76
	v_pk_mul_f32 v[80:81], v[88:89], v[80:81]
	v_and_b32_e32 v75, 0xffff0000, v75
	v_and_b32_e32 v76, 0xffff0000, v76
	v_pk_mul_f32 v[78:79], v[86:87], v[78:79]
	v_or_b32_sdwa v75, v75, v0 dst_sel:DWORD dst_unused:UNUSED_PAD src0_sel:DWORD src1_sel:WORD_1
	v_or_b32_sdwa v74, v76, v74 dst_sel:DWORD dst_unused:UNUSED_PAD src0_sel:DWORD src1_sel:WORD_1
	global_store_dwordx2 v[144:145], v[74:75], off offset:96
	v_cvt_pk_bf16_f32 v76, v80, v80
	v_cvt_pk_bf16_f32 v74, v78, v78
	v_cvt_pk_bf16_f32 v75, v81, v81
	v_and_b32_e32 v76, 0xffff0000, v76
	v_cvt_pk_bf16_f32 v0, v79, v79
	v_and_b32_e32 v75, 0xffff0000, v75
	v_or_b32_sdwa v74, v76, v74 dst_sel:DWORD dst_unused:UNUSED_PAD src0_sel:DWORD src1_sel:WORD_1
	v_add_co_u32_e32 v76, vcc, 0x1000, v144
	v_or_b32_sdwa v75, v75, v0 dst_sel:DWORD dst_unused:UNUSED_PAD src0_sel:DWORD src1_sel:WORD_1
	s_nop 0
	v_addc_co_u32_e32 v77, vcc, 0, v145, vcc
	global_store_dwordx2 v[76:77], v[74:75], off offset:96
; __device__ __forceinline__ unsigned pack2(float a, float b) { return (unsigned)f2bf(a) | ((unsigned)f2bf(b) << 16); }
; __device__ __forceinline__ float fexp2(float x) { return __builtin_amdgcn_exp2f(x); }
; template <int EPI, bool HS = false>
; __device__ __forceinline__ void gemm_phase(const Params& p, const GemmCfg& g, char* shm, const int wave_s) {
;     ...
;             for (int bj = 0; bj < 2; ++bj) {
;               float y1[4], y2[4];
; #pragma unroll
;               for (int j = 0; j < 4; ++j) {
;                 const int lr = ai * 128 + m * 16 + j;
;                 float cs = *(const float*)(rl + ((m * 16 + j) * 128 + bj * 64) * 4), sn = *(const float*)(rl + 65536 + ((m * 16 + j) * 128 + bj * 64) * 4);
;                 float x1 = r4[j] * acc[ai][bj][m][0][j] + swv[bj][0], x2 = r4[j] * acc[ai][bj][m][1][j] + swv[bj][1];
;                 y1[j] = (x1 * cs - x2 * sn) * scl;
;                 y2[j] = (x2 * cs + x1 * sn) * scl;
;                 dst[tb + lr * 1024 + bj * 128] = f2bf(y1[j]);
;                 dst[tb + lr * 1024 + bj * 128 + 16] = f2bf(y2[j]);
;               }
;               if (isk) {
;                 float d0 = k0, d1 = fexp2(lg2 * (float)(126 - jj0)), d2 = fexp2(lg2 * (float)(125 - jj0)),
;                       d3 = fexp2(lg2 * (float)(124 - jj0));
;                 uint2 v1, v2;
;                 v1.x = pack2(y1[0] * d0, y1[1] * d1); v1.y = pack2(y1[2] * d2, y1[3] * d3);
;                 v2.x = pack2(y2[0] * d0, y2[1] * d1); v2.y = pack2(y2[2] * d2, y2[3] * d3);
;                 *(uint2*)(kt_t + kb + ai * 256 * 128 + (bj * 128) * 128 + m * 16) = v1;
;                 *(uint2*)(kt_t + kb + ai * 256 * 128 + (bj * 128 + 16) * 128 + m * 16) = v2;
;               }
.LBB0_610:
	ds_read2st64_b32 v[78:79], v155 offset0:97 offset1:99
	v_add_u32_e32 v74, 0x16100, v155
	ds_read2st64_b32 v[116:117], v155 offset0:101 offset1:103
	v_add_u32_e32 v75, 0x16300, v155
	v_add_u32_e32 v76, 0x16500, v155
	v_add_u32_e32 v77, 0x16700, v155
	ds_read_b32 v152, v74
	ds_read_b32 v160, v75
	ds_read_b32 v153, v76
	ds_read_b32 v161, v77
	v_or_b32_e32 v0, 0xc080, v146
	v_pk_mul_f32 v[72:73], v[72:73], v[84:85]
	v_pk_mul_f32 v[70:71], v[70:71], v[82:83]
	v_lshl_add_u64 v[80:81], v[0:1], 1, s[0:1]
	v_or_b32_e32 v0, 0xc090, v146
	v_mov_b32_e32 v164, v70
	v_mov_b32_e32 v165, v72
	v_pk_mul_f32 v[68:69], v[68:69], v[84:85]
	v_pk_mul_f32 v[82:83], v[66:67], v[82:83]
	v_lshl_add_u64 v[98:99], v[0:1], 1, s[0:1]
	v_or_b32_e32 v0, 0xc480, v146
	v_pk_add_f32 v[164:165], v[136:137], v[164:165]
	v_mov_b32_e32 v66, v82
	v_mov_b32_e32 v67, v68
	v_lshl_add_u64 v[100:101], v[0:1], 1, s[0:1]
	v_or_b32_e32 v0, 0xc490, v146
	v_pk_add_f32 v[84:85], v[134:135], v[66:67]
	s_waitcnt lgkmcnt(5)
	v_mov_b32_e32 v166, v78
	s_waitcnt lgkmcnt(4)
	v_mov_b32_e32 v167, v116
	s_waitcnt lgkmcnt(1)
	v_pk_mul_f32 v[66:67], v[164:165], v[152:153]
	v_lshl_add_u64 v[114:115], v[0:1], 1, s[0:1]
	v_or_b32_e32 v0, 0xc880, v146
	v_pk_fma_f32 v[66:67], v[84:85], v[166:167], v[66:67] neg_lo:[0,0,1] neg_hi:[0,0,1]
	v_lshl_add_u64 v[130:131], v[0:1], 1, s[0:1]
	v_or_b32_e32 v0, 0xc890, v146
	v_pk_mul_f32 v[66:67], v[142:143], v[66:67]
	v_lshl_add_u64 v[132:133], v[0:1], 1, s[0:1]
	s_nop 0
	v_mov_b32_e32 v72, v71
	v_cvt_pk_bf16_f32 v0, v66, v66
	v_pk_add_f32 v[72:73], v[136:137], v[72:73]
	v_mov_b32_e32 v68, v83
	global_store_short_d16_hi v[80:81], v0, off
	v_pk_add_f32 v[80:81], v[134:135], v[68:69]
	v_mov_b32_e32 v116, v79
	s_waitcnt lgkmcnt(0)
	v_pk_mul_f32 v[68:69], v[72:73], v[160:161]
	v_pk_mul_f32 v[70:71], v[84:85], v[152:153]
	v_pk_fma_f32 v[68:69], v[80:81], v[116:117], v[68:69] neg_lo:[0,0,1] neg_hi:[0,0,1]
	v_pk_fma_f32 v[70:71], v[164:165], v[166:167], v[70:71]
	v_pk_mul_f32 v[68:69], v[142:143], v[68:69]
	v_pk_mul_f32 v[70:71], v[142:143], v[70:71]
	v_cvt_pk_bf16_f32 v0, v68, v68
	global_store_short_d16_hi v[100:101], v0, off
	v_cvt_pk_bf16_f32 v0, v67, v67
	v_pk_mul_f32 v[78:79], v[80:81], v[160:161]
	global_store_short_d16_hi v[130:131], v0, off
	v_pk_fma_f32 v[72:73], v[72:73], v[116:117], v[78:79]
	v_cvt_pk_bf16_f32 v0, v70, v70
	v_pk_mul_f32 v[72:73], v[142:143], v[72:73]
	global_store_short_d16_hi v[98:99], v0, off
	v_cvt_pk_bf16_f32 v0, v72, v72
	global_store_short_d16_hi v[114:115], v0, off
	v_cvt_pk_bf16_f32 v0, v71, v71
	global_store_short_d16_hi v[132:133], v0, off
	s_nop 0
	v_cvt_pk_bf16_f32 v80, v69, v69
	v_or_b32_e32 v0, 0xcc80, v146
	v_lshl_add_u64 v[78:79], v[0:1], 1, s[0:1]
	v_bfe_u32 v0, v73, 16, 1
	global_store_short_d16_hi v[78:79], v80, off
	v_add3_u32 v80, v73, v0, s81
	v_or_b32_e32 v0, 0xcc90, v146
	v_lshl_add_u64 v[78:79], v[0:1], 1, s[0:1]
	s_and_b64 vcc, exec, s[6:7]
	global_store_short_d16_hi v[78:79], v80, off
	s_cbranch_vccnz .LBB0_612
	v_pk_mul_f32 v[66:67], v[86:87], v[66:67]
	v_pk_mul_f32 v[68:69], v[88:89], v[68:69]
	s_nop 0
	s_nop 0
	v_cvt_pk_bf16_f32 v66, v66, v66
	v_cvt_pk_bf16_f32 v0, v67, v67
	v_cvt_pk_bf16_f32 v68, v68, v68
	v_cvt_pk_bf16_f32 v67, v69, v69
	v_and_b32_e32 v68, 0xffff0000, v68
	s_mov_b32 s4, 0x8000
	v_and_b32_e32 v67, 0xffff0000, v67
	v_or_b32_sdwa v66, v68, v66 dst_sel:DWORD dst_unused:UNUSED_PAD src0_sel:DWORD src1_sel:WORD_1
	v_add_co_u32_e32 v68, vcc, s4, v144
	v_pk_mul_f32 v[72:73], v[88:89], v[72:73]
	v_or_b32_sdwa v67, v67, v0 dst_sel:DWORD dst_unused:UNUSED_PAD src0_sel:DWORD src1_sel:WORD_1
	v_addc_co_u32_e32 v69, vcc, 0, v145, vcc
	v_pk_mul_f32 v[70:71], v[86:87], v[70:71]
	global_store_dwordx2 v[68:69], v[66:67], off offset:96
	s_nop 0
	s_nop 0
	s_nop 0
	v_cvt_pk_bf16_f32 v68, v72, v72
	v_cvt_pk_bf16_f32 v66, v70, v70
	v_cvt_pk_bf16_f32 v67, v73, v73
	v_and_b32_e32 v68, 0xffff0000, v68
	v_cvt_pk_bf16_f32 v0, v71, v71
	v_and_b32_e32 v67, 0xffff0000, v67
	v_or_b32_sdwa v66, v68, v66 dst_sel:DWORD dst_unused:UNUSED_PAD src0_sel:DWORD src1_sel:WORD_1
	v_add_co_u32_e32 v68, vcc, 0x9000, v144
	v_or_b32_sdwa v67, v67, v0 dst_sel:DWORD dst_unused:UNUSED_PAD src0_sel:DWORD src1_sel:WORD_1
	s_nop 0
	v_addc_co_u32_e32 v69, vcc, 0, v145, vcc
	global_store_dwordx2 v[68:69], v[66:67], off offset:96
; __device__ __forceinline__ unsigned pack2(float a, float b) { return (unsigned)f2bf(a) | ((unsigned)f2bf(b) << 16); }
; template <int EPI, bool HS = false>
; __device__ __forceinline__ void gemm_phase(const Params& p, const GemmCfg& g, char* shm, const int wave_s) {
;     ...
;         for (int ai = 0; ai < 2; ++ai) {
; #pragma unroll
;           for (int i = 0; i < 8; ++i) {
;             const int ch = wv_s * 8 + i;
;             glds_row(rc_t + (size_t)(ai * 128) * 128 + ch * 256, (unsigned)lane * 16u, ldsb + (unsigned)(ch * 1024));
;             glds_row(rs_t + (size_t)(ai * 128) * 128 + ch * 256, (unsigned)lane * 16u, ldsb + 65536u + (unsigned)(ch * 1024));
;           }
;           WAIT_V(0);
;           __syncthreads();
; #pragma unroll
;           for (int m = 0; m < 4; ++m) {
;             const int jj0 = wr * 64 + m * 16 + fq * 4;
;             const float k0 = fexp2(lg2 * (float)(127 - jj0));
;             const f32x4 r4 = *(const f32x4*)(rsw + ai * 128 + m * 16);
; #pragma unroll
;             for (int bj = 0; bj < 2; ++bj) {
;               float y1[4], y2[4];
; #pragma unroll
;               for (int j = 0; j < 4; ++j) {
;                 const int lr = ai * 128 + m * 16 + j;
;                 float cs = *(const float*)(rl + ((m * 16 + j) * 128 + bj * 64) * 4), sn = *(const float*)(rl + 65536 + ((m * 16 + j) * 128 + bj * 64) * 4);
;                 float x1 = r4[j] * acc[ai][bj][m][0][j] + swv[bj][0], x2 = r4[j] * acc[ai][bj][m][1][j] + swv[bj][1];
;                 y1[j] = (x1 * cs - x2 * sn) * scl;
;                 y2[j] = (x2 * cs + x1 * sn) * scl;
;                 dst[tb + lr * 1024 + bj * 128] = f2bf(y1[j]);
;                 dst[tb + lr * 1024 + bj * 128 + 16] = f2bf(y2[j]);
;               }
;               if (isk) {
;                 float d0 = k0, d1 = fexp2(lg2 * (float)(126 - jj0)), d2 = fexp2(lg2 * (float)(125 - jj0)),
;                       d3 = fexp2(lg2 * (float)(124 - jj0));
;                 uint2 v1, v2;
;                 v1.x = pack2(y1[0] * d0, y1[1] * d1); v1.y = pack2(y1[2] * d2, y1[3] * d3);
;                 v2.x = pack2(y2[0] * d0, y2[1] * d1); v2.y = pack2(y2[2] * d2, y2[3] * d3);
;                 *(uint2*)(kt_t + kb + ai * 256 * 128 + (bj * 128) * 128 + m * 16) = v1;
;                 *(uint2*)(kt_t + kb + ai * 256 * 128 + (bj * 128 + 16) * 128 + m * 16) = v2;
;               }
.LBB0_612:
	s_add_u32 s15, s27, 0x10000
	s_addc_u32 s16, s90, 0
	s_add_u32 s17, s91, 0x10000
	s_addc_u32 s18, s84, 0
	s_add_u32 s4, s15, s76
	s_addc_u32 s5, s16, s77
	s_waitcnt vmcnt(63) expcnt(7) lgkmcnt(15)
	s_barrier
	s_mov_b32 m0, s85
	s_nop 0
	global_load_lds_dwordx4 v156, s[4:5]
	s_add_u32 s4, s17, s76
	s_addc_u32 s5, s18, s77
	s_mov_b32 m0, s62
	s_nop 0
	global_load_lds_dwordx4 v156, s[4:5]
	s_add_u32 s4, s15, s74
	s_addc_u32 s5, s16, s75
	s_mov_b32 m0, s26
	s_nop 0
	global_load_lds_dwordx4 v156, s[4:5]
	s_add_u32 s4, s17, s74
	s_addc_u32 s5, s18, s75
	s_mov_b32 m0, s60
	s_nop 0
	global_load_lds_dwordx4 v156, s[4:5]
	s_add_u32 s4, s15, s72
	s_addc_u32 s5, s16, s73
	s_mov_b32 m0, s61
	s_nop 0
	global_load_lds_dwordx4 v156, s[4:5]
	s_add_u32 s4, s17, s72
	s_addc_u32 s5, s18, s73
	s_mov_b32 m0, s57
	s_nop 0
	global_load_lds_dwordx4 v156, s[4:5]
	s_add_u32 s4, s15, s70
	s_addc_u32 s5, s16, s71
	s_mov_b32 m0, s58
	s_nop 0
	global_load_lds_dwordx4 v156, s[4:5]
	s_add_u32 s4, s17, s70
	s_addc_u32 s5, s18, s71
	s_mov_b32 m0, s55
	s_nop 0
	global_load_lds_dwordx4 v156, s[4:5]
	s_add_u32 s4, s15, s8
	s_addc_u32 s5, s16, s9
	s_mov_b32 m0, s56
	s_nop 0
	global_load_lds_dwordx4 v156, s[4:5]
	s_add_u32 s4, s17, s8
	s_addc_u32 s5, s18, s9
	s_mov_b32 m0, s53
	s_nop 0
	global_load_lds_dwordx4 v156, s[4:5]
	s_add_u32 s4, s15, s2
	s_addc_u32 s5, s16, s3
	s_add_u32 s2, s17, s2
	s_mov_b32 m0, s54
	s_nop 0
	global_load_lds_dwordx4 v156, s[4:5]
	s_addc_u32 s3, s18, s3
	s_mov_b32 m0, s52
	s_nop 0
	global_load_lds_dwordx4 v156, s[2:3]
	s_add_u32 s2, s15, s10
	s_addc_u32 s3, s16, s11
	s_mov_b32 m0, s59
	s_nop 0
	global_load_lds_dwordx4 v156, s[2:3]
	s_add_u32 s2, s17, s10
	s_addc_u32 s3, s18, s11
	s_mov_b32 m0, s12
	s_nop 0
	global_load_lds_dwordx4 v156, s[2:3]
	s_add_u32 s2, s15, s68
	s_addc_u32 s3, s16, s69
	s_mov_b32 m0, s14
	s_nop 0
	global_load_lds_dwordx4 v156, s[2:3]
	s_add_u32 s2, s17, s68
	s_addc_u32 s3, s18, s69
	s_mov_b32 m0, s13
	s_nop 0
	global_load_lds_dwordx4 v156, s[2:3]
	s_waitcnt vmcnt(0)
	s_barrier
	ds_read2st64_b32 v[70:71], v155 offset1:2
	ds_read2st64_b32 v[80:81], v155 offset0:4 offset1:6
	ds_read_b128 v[66:69], v154 offset:512
	ds_read_b32 v82, v157
	ds_read_b32 v84, v147
	ds_read_b32 v83, v158
	ds_read_b32 v85, v159
	s_waitcnt lgkmcnt(4)
	v_pk_mul_f32 v[64:65], v[64:65], v[68:69]
	v_pk_mul_f32 v[62:63], v[62:63], v[66:67]
	v_mov_b32_e32 v101, v64
	v_mov_b32_e32 v100, v62
	v_pk_mul_f32 v[60:61], v[60:61], v[68:69]
	v_pk_mul_f32 v[114:115], v[58:59], v[66:67]
	v_pk_add_f32 v[100:101], v[140:141], v[100:101]
	v_mov_b32_e32 v58, v114
	v_mov_b32_e32 v59, v60
	v_add_u32_e32 v0, 0x20000, v146
	v_pk_add_f32 v[116:117], v[138:139], v[58:59]
	v_mov_b32_e32 v130, v70
	v_mov_b32_e32 v131, v80
	s_waitcnt lgkmcnt(1)
	v_pk_mul_f32 v[58:59], v[82:83], v[100:101]
	v_mov_b32_e32 v64, v63
	v_lshl_add_u64 v[72:73], v[0:1], 1, s[0:1]
	v_add_u32_e32 v0, 0x20400, v146
	v_pk_fma_f32 v[58:59], v[130:131], v[116:117], v[58:59] neg_lo:[0,0,1] neg_hi:[0,0,1]
	v_pk_add_f32 v[64:65], v[140:141], v[64:65]
	v_mov_b32_e32 v60, v115
	v_lshl_add_u64 v[78:79], v[0:1], 1, s[0:1]
	v_add_u32_e32 v0, 0x20800, v146
	v_pk_mul_f32 v[58:59], v[142:143], v[58:59]
	v_pk_add_f32 v[114:115], v[138:139], v[60:61]
	v_mov_b32_e32 v80, v71
	s_waitcnt lgkmcnt(0)
	v_pk_mul_f32 v[60:61], v[64:65], v[84:85]
	v_lshl_add_u64 v[98:99], v[0:1], 1, s[0:1]
	s_nop 0
	v_pk_fma_f32 v[60:61], v[114:115], v[80:81], v[60:61] neg_lo:[0,0,1] neg_hi:[0,0,1]
	v_cvt_pk_bf16_f32 v0, v58, v58
	v_pk_mul_f32 v[60:61], v[142:143], v[60:61]
	global_store_short_d16_hi v[72:73], v0, off
	v_cvt_pk_bf16_f32 v0, v60, v60
	v_pk_mul_f32 v[62:63], v[82:83], v[116:117]
	global_store_short_d16_hi v[78:79], v0, off
	v_pk_fma_f32 v[62:63], v[130:131], v[100:101], v[62:63]
	v_cvt_pk_bf16_f32 v0, v59, v59
	v_pk_mul_f32 v[62:63], v[142:143], v[62:63]
	v_pk_mul_f32 v[70:71], v[114:115], v[84:85]
	global_store_short_d16_hi v[98:99], v0, off
	v_pk_fma_f32 v[64:65], v[64:65], v[80:81], v[70:71]
	v_cvt_pk_bf16_f32 v0, v62, v62
	v_pk_mul_f32 v[64:65], v[142:143], v[64:65]
	global_store_short_d16_hi v[72:73], v0, off offset:32
	v_cvt_pk_bf16_f32 v0, v64, v64
	global_store_short_d16_hi v[78:79], v0, off offset:32
	v_cvt_pk_bf16_f32 v0, v63, v63
	global_store_short_d16_hi v[98:99], v0, off offset:32
	v_bfe_u32 v0, v61, 16, 1
	v_add3_u32 v72, v61, v0, s81
	v_add_u32_e32 v0, 0x20c00, v146
	v_lshl_add_u64 v[70:71], v[0:1], 1, s[0:1]
	v_bfe_u32 v0, v65, 16, 1
	v_add3_u32 v0, v65, v0, s81
	s_and_b64 vcc, exec, s[6:7]
	global_store_short_d16_hi v[70:71], v72, off
	global_store_short_d16_hi v[70:71], v0, off offset:32
	s_cbranch_vccnz .LBB0_614
	v_pk_mul_f32 v[58:59], v[148:149], v[58:59]
	v_pk_mul_f32 v[60:61], v[150:151], v[60:61]
	s_nop 0
	s_nop 0
	v_cvt_pk_bf16_f32 v58, v58, v58
	v_cvt_pk_bf16_f32 v0, v59, v59
	v_cvt_pk_bf16_f32 v60, v60, v60
	v_cvt_pk_bf16_f32 v59, v61, v61
	v_and_b32_e32 v60, 0xffff0000, v60
	v_and_b32_e32 v59, 0xffff0000, v59
	v_or_b32_sdwa v58, v60, v58 dst_sel:DWORD dst_unused:UNUSED_PAD src0_sel:DWORD src1_sel:WORD_1
	v_add_co_u32_e32 v60, vcc, s51, v144
	v_pk_mul_f32 v[64:65], v[150:151], v[64:65]
	v_or_b32_sdwa v59, v59, v0 dst_sel:DWORD dst_unused:UNUSED_PAD src0_sel:DWORD src1_sel:WORD_1
	v_addc_co_u32_e32 v61, vcc, 0, v145, vcc
	v_pk_mul_f32 v[62:63], v[148:149], v[62:63]
	global_store_dwordx2 v[60:61], v[58:59], off
	s_nop 0
	s_nop 0
	s_nop 0
	v_cvt_pk_bf16_f32 v60, v64, v64
	v_cvt_pk_bf16_f32 v58, v62, v62
	v_cvt_pk_bf16_f32 v59, v65, v65
	v_and_b32_e32 v60, 0xffff0000, v60
	v_cvt_pk_bf16_f32 v0, v63, v63
	v_and_b32_e32 v59, 0xffff0000, v59
	v_or_b32_sdwa v58, v60, v58 dst_sel:DWORD dst_unused:UNUSED_PAD src0_sel:DWORD src1_sel:WORD_1
	v_add_co_u32_e32 v60, vcc, 0x11000, v144
	v_or_b32_sdwa v59, v59, v0 dst_sel:DWORD dst_unused:UNUSED_PAD src0_sel:DWORD src1_sel:WORD_1
	s_nop 0
	v_addc_co_u32_e32 v61, vcc, 0, v145, vcc
	global_store_dwordx2 v[60:61], v[58:59], off
; __device__ __forceinline__ unsigned pack2(float a, float b) { return (unsigned)f2bf(a) | ((unsigned)f2bf(b) << 16); }
; __device__ __forceinline__ float fexp2(float x) { return __builtin_amdgcn_exp2f(x); }
; template <int EPI, bool HS = false>
; __device__ __forceinline__ void gemm_phase(const Params& p, const GemmCfg& g, char* shm, const int wave_s) {
;     ...
;             for (int bj = 0; bj < 2; ++bj) {
;               float y1[4], y2[4];
; #pragma unroll
;               for (int j = 0; j < 4; ++j) {
;                 const int lr = ai * 128 + m * 16 + j;
;                 float cs = *(const float*)(rl + ((m * 16 + j) * 128 + bj * 64) * 4), sn = *(const float*)(rl + 65536 + ((m * 16 + j) * 128 + bj * 64) * 4);
;                 float x1 = r4[j] * acc[ai][bj][m][0][j] + swv[bj][0], x2 = r4[j] * acc[ai][bj][m][1][j] + swv[bj][1];
;                 y1[j] = (x1 * cs - x2 * sn) * scl;
;                 y2[j] = (x2 * cs + x1 * sn) * scl;
;                 dst[tb + lr * 1024 + bj * 128] = f2bf(y1[j]);
;                 dst[tb + lr * 1024 + bj * 128 + 16] = f2bf(y2[j]);
;               }
;               if (isk) {
;                 float d0 = k0, d1 = fexp2(lg2 * (float)(126 - jj0)), d2 = fexp2(lg2 * (float)(125 - jj0)),
;                       d3 = fexp2(lg2 * (float)(124 - jj0));
;                 uint2 v1, v2;
;                 v1.x = pack2(y1[0] * d0, y1[1] * d1); v1.y = pack2(y1[2] * d2, y1[3] * d3);
;                 v2.x = pack2(y2[0] * d0, y2[1] * d1); v2.y = pack2(y2[2] * d2, y2[3] * d3);
;                 *(uint2*)(kt_t + kb + ai * 256 * 128 + (bj * 128) * 128 + m * 16) = v1;
;                 *(uint2*)(kt_t + kb + ai * 256 * 128 + (bj * 128 + 16) * 128 + m * 16) = v2;
;               }
.LBB0_614:
	ds_read2st64_b32 v[58:59], v155 offset0:1 offset1:3
	ds_read2st64_b32 v[64:65], v155 offset0:5 offset1:7
	ds_read_b32 v72, v122
	ds_read_b32 v78, v123
	ds_read_b32 v73, v124
	ds_read_b32 v79, v125
	v_pk_mul_f32 v[56:57], v[56:57], v[68:69]
	v_pk_mul_f32 v[54:55], v[54:55], v[66:67]
	v_mov_b32_e32 v81, v56
	v_mov_b32_e32 v80, v54
	v_pk_mul_f32 v[52:53], v[52:53], v[68:69]
	v_pk_mul_f32 v[66:67], v[50:51], v[66:67]
	v_pk_add_f32 v[80:81], v[136:137], v[80:81]
	v_mov_b32_e32 v50, v66
	v_mov_b32_e32 v51, v52
	v_add_u32_e32 v0, 0x20080, v146
	v_pk_add_f32 v[68:69], v[134:135], v[50:51]
	s_waitcnt lgkmcnt(5)
	v_mov_b32_e32 v82, v58
	s_waitcnt lgkmcnt(4)
	v_mov_b32_e32 v83, v64
	s_waitcnt lgkmcnt(1)
	v_pk_mul_f32 v[50:51], v[80:81], v[72:73]
	v_mov_b32_e32 v56, v55
	v_lshl_add_u64 v[60:61], v[0:1], 1, s[0:1]
	v_add_u32_e32 v0, 0x20480, v146
	v_pk_fma_f32 v[50:51], v[68:69], v[82:83], v[50:51] neg_lo:[0,0,1] neg_hi:[0,0,1]
	v_pk_add_f32 v[56:57], v[136:137], v[56:57]
	v_mov_b32_e32 v52, v67
	v_lshl_add_u64 v[62:63], v[0:1], 1, s[0:1]
	v_add_u32_e32 v0, 0x20880, v146
	v_pk_mul_f32 v[50:51], v[142:143], v[50:51]
	v_pk_add_f32 v[66:67], v[134:135], v[52:53]
	v_mov_b32_e32 v64, v59
	s_waitcnt lgkmcnt(0)
	v_pk_mul_f32 v[52:53], v[56:57], v[78:79]
	v_lshl_add_u64 v[70:71], v[0:1], 1, s[0:1]
	s_nop 0
	v_pk_fma_f32 v[52:53], v[66:67], v[64:65], v[52:53] neg_lo:[0,0,1] neg_hi:[0,0,1]
	v_cvt_pk_bf16_f32 v0, v50, v50
	v_pk_mul_f32 v[52:53], v[142:143], v[52:53]
	global_store_short_d16_hi v[60:61], v0, off
	v_cvt_pk_bf16_f32 v0, v52, v52
	v_pk_mul_f32 v[54:55], v[68:69], v[72:73]
	global_store_short_d16_hi v[62:63], v0, off
	v_pk_fma_f32 v[54:55], v[80:81], v[82:83], v[54:55]
	v_cvt_pk_bf16_f32 v0, v51, v51
	v_pk_mul_f32 v[54:55], v[142:143], v[54:55]
	v_pk_mul_f32 v[58:59], v[66:67], v[78:79]
	global_store_short_d16_hi v[70:71], v0, off
	v_pk_fma_f32 v[56:57], v[56:57], v[64:65], v[58:59]
	v_cvt_pk_bf16_f32 v0, v54, v54
	v_pk_mul_f32 v[56:57], v[142:143], v[56:57]
	global_store_short_d16_hi v[60:61], v0, off offset:32
	v_cvt_pk_bf16_f32 v0, v56, v56
	global_store_short_d16_hi v[62:63], v0, off offset:32
	v_cvt_pk_bf16_f32 v0, v55, v55
	global_store_short_d16_hi v[70:71], v0, off offset:32
	v_bfe_u32 v0, v53, 16, 1
	v_add3_u32 v60, v53, v0, s81
	v_add_u32_e32 v0, 0x20c80, v146
	v_lshl_add_u64 v[58:59], v[0:1], 1, s[0:1]
	v_bfe_u32 v0, v57, 16, 1
	v_readlane_b32 s8, v254, 47
	v_add3_u32 v0, v57, v0, s81
	s_and_b64 vcc, exec, s[6:7]
	v_readlane_b32 s9, v254, 48
	global_store_short_d16_hi v[58:59], v60, off
	global_store_short_d16_hi v[58:59], v0, off offset:32
	v_readlane_b32 s10, v254, 49
	v_readlane_b32 s11, v254, 50
	s_cbranch_vccnz .LBB0_616
	v_pk_mul_f32 v[50:51], v[148:149], v[50:51]
	v_pk_mul_f32 v[52:53], v[150:151], v[52:53]
	s_nop 0
	s_nop 0
	v_cvt_pk_bf16_f32 v50, v50, v50
	v_cvt_pk_bf16_f32 v0, v51, v51
	v_cvt_pk_bf16_f32 v52, v52, v52
	v_cvt_pk_bf16_f32 v51, v53, v53
	v_and_b32_e32 v52, 0xffff0000, v52
	s_mov_b32 s2, 0x18000
	v_and_b32_e32 v51, 0xffff0000, v51
	v_or_b32_sdwa v50, v52, v50 dst_sel:DWORD dst_unused:UNUSED_PAD src0_sel:DWORD src1_sel:WORD_1
	v_add_co_u32_e32 v52, vcc, s2, v144
	v_pk_mul_f32 v[56:57], v[150:151], v[56:57]
	v_or_b32_sdwa v51, v51, v0 dst_sel:DWORD dst_unused:UNUSED_PAD src0_sel:DWORD src1_sel:WORD_1
	v_addc_co_u32_e32 v53, vcc, 0, v145, vcc
	v_pk_mul_f32 v[54:55], v[148:149], v[54:55]
	global_store_dwordx2 v[52:53], v[50:51], off
	s_nop 0
	s_nop 0
	s_nop 0
	v_cvt_pk_bf16_f32 v52, v56, v56
	v_cvt_pk_bf16_f32 v50, v54, v54
	v_cvt_pk_bf16_f32 v51, v57, v57
	v_and_b32_e32 v52, 0xffff0000, v52
	v_cvt_pk_bf16_f32 v0, v55, v55
	v_and_b32_e32 v51, 0xffff0000, v51
	v_or_b32_sdwa v50, v52, v50 dst_sel:DWORD dst_unused:UNUSED_PAD src0_sel:DWORD src1_sel:WORD_1
	v_add_co_u32_e32 v52, vcc, 0x19000, v144
	v_or_b32_sdwa v51, v51, v0 dst_sel:DWORD dst_unused:UNUSED_PAD src0_sel:DWORD src1_sel:WORD_1
	s_nop 0
	v_addc_co_u32_e32 v53, vcc, 0, v145, vcc
	global_store_dwordx2 v[52:53], v[50:51], off
.LBB0_616:
	ds_read2st64_b32 v[54:55], v155 offset0:32 offset1:34
	ds_read2st64_b32 v[60:61], v155 offset0:36 offset1:38
	ds_read_b128 v[50:53], v154 offset:576
	ds_read_b32 v62, v126
	ds_read_b32 v64, v127
	ds_read_b32 v63, v128
	ds_read_b32 v65, v129
	s_waitcnt lgkmcnt(4)
	v_pk_mul_f32 v[48:49], v[48:49], v[52:53]
	v_pk_mul_f32 v[46:47], v[46:47], v[50:51]
	v_mov_b32_e32 v69, v48
	v_mov_b32_e32 v68, v46
	v_pk_mul_f32 v[44:45], v[44:45], v[52:53]
	v_pk_mul_f32 v[70:71], v[42:43], v[50:51]
	v_pk_add_f32 v[68:69], v[140:141], v[68:69]
	v_mov_b32_e32 v42, v70
	v_mov_b32_e32 v43, v44
	v_add_u32_e32 v0, 0x24000, v146
	v_pk_add_f32 v[72:73], v[138:139], v[42:43]
	v_mov_b32_e32 v78, v54
	v_mov_b32_e32 v79, v60
	s_waitcnt lgkmcnt(1)
	v_pk_mul_f32 v[42:43], v[62:63], v[68:69]
	v_mov_b32_e32 v48, v47
	v_lshl_add_u64 v[56:57], v[0:1], 1, s[0:1]
	v_add_u32_e32 v0, 0x24400, v146
	v_pk_fma_f32 v[42:43], v[78:79], v[72:73], v[42:43] neg_lo:[0,0,1] neg_hi:[0,0,1]
	v_pk_add_f32 v[48:49], v[140:141], v[48:49]
	v_mov_b32_e32 v44, v71
	v_lshl_add_u64 v[58:59], v[0:1], 1, s[0:1]
	v_add_u32_e32 v0, 0x24800, v146
	v_pk_mul_f32 v[42:43], v[142:143], v[42:43]
	v_pk_add_f32 v[70:71], v[138:139], v[44:45]
	v_mov_b32_e32 v60, v55
	s_waitcnt lgkmcnt(0)
	v_pk_mul_f32 v[44:45], v[48:49], v[64:65]
	v_lshl_add_u64 v[66:67], v[0:1], 1, s[0:1]
	s_nop 0
	v_pk_fma_f32 v[44:45], v[70:71], v[60:61], v[44:45] neg_lo:[0,0,1] neg_hi:[0,0,1]
	v_cvt_pk_bf16_f32 v0, v42, v42
	v_pk_mul_f32 v[44:45], v[142:143], v[44:45]
	global_store_short_d16_hi v[56:57], v0, off
	v_cvt_pk_bf16_f32 v0, v44, v44
	v_pk_mul_f32 v[46:47], v[62:63], v[72:73]
	global_store_short_d16_hi v[58:59], v0, off
	v_pk_fma_f32 v[46:47], v[78:79], v[68:69], v[46:47]
	v_cvt_pk_bf16_f32 v0, v43, v43
	v_pk_mul_f32 v[46:47], v[142:143], v[46:47]
	v_pk_mul_f32 v[54:55], v[70:71], v[64:65]
	global_store_short_d16_hi v[66:67], v0, off
	v_pk_fma_f32 v[48:49], v[48:49], v[60:61], v[54:55]
	v_cvt_pk_bf16_f32 v0, v46, v46
	v_pk_mul_f32 v[48:49], v[142:143], v[48:49]
	global_store_short_d16_hi v[56:57], v0, off offset:32
	v_cvt_pk_bf16_f32 v0, v48, v48
	global_store_short_d16_hi v[58:59], v0, off offset:32
	v_cvt_pk_bf16_f32 v0, v47, v47
	global_store_short_d16_hi v[66:67], v0, off offset:32
	v_bfe_u32 v0, v45, 16, 1
	v_add3_u32 v56, v45, v0, s81
	v_add_u32_e32 v0, 0x24c00, v146
	v_lshl_add_u64 v[54:55], v[0:1], 1, s[0:1]
	v_bfe_u32 v0, v49, 16, 1
	v_add3_u32 v0, v49, v0, s81
	s_and_b64 vcc, exec, s[6:7]
	global_store_short_d16_hi v[54:55], v56, off
	global_store_short_d16_hi v[54:55], v0, off offset:32
	s_cbranch_vccnz .LBB0_618
; __device__ __forceinline__ unsigned pack2(float a, float b) { return (unsigned)f2bf(a) | ((unsigned)f2bf(b) << 16); }
; __device__ __forceinline__ float fexp2(float x) { return __builtin_amdgcn_exp2f(x); }
; template <int EPI, bool HS = false>
; __device__ __forceinline__ void gemm_phase(const Params& p, const GemmCfg& g, char* shm, const int wave_s) {
;     ...
;             for (int bj = 0; bj < 2; ++bj) {
;               float y1[4], y2[4];
; #pragma unroll
;               for (int j = 0; j < 4; ++j) {
;                 const int lr = ai * 128 + m * 16 + j;
;                 float cs = *(const float*)(rl + ((m * 16 + j) * 128 + bj * 64) * 4), sn = *(const float*)(rl + 65536 + ((m * 16 + j) * 128 + bj * 64) * 4);
;                 float x1 = r4[j] * acc[ai][bj][m][0][j] + swv[bj][0], x2 = r4[j] * acc[ai][bj][m][1][j] + swv[bj][1];
;                 y1[j] = (x1 * cs - x2 * sn) * scl;
;                 y2[j] = (x2 * cs + x1 * sn) * scl;
;                 dst[tb + lr * 1024 + bj * 128] = f2bf(y1[j]);
;                 dst[tb + lr * 1024 + bj * 128 + 16] = f2bf(y2[j]);
;               }
;               if (isk) {
;                 float d0 = k0, d1 = fexp2(lg2 * (float)(126 - jj0)), d2 = fexp2(lg2 * (float)(125 - jj0)),
;                       d3 = fexp2(lg2 * (float)(124 - jj0));
;                 uint2 v1, v2;
;                 v1.x = pack2(y1[0] * d0, y1[1] * d1); v1.y = pack2(y1[2] * d2, y1[3] * d3);
;                 v2.x = pack2(y2[0] * d0, y2[1] * d1); v2.y = pack2(y2[2] * d2, y2[3] * d3);
;                 *(uint2*)(kt_t + kb + ai * 256 * 128 + (bj * 128) * 128 + m * 16) = v1;
;                 *(uint2*)(kt_t + kb + ai * 256 * 128 + (bj * 128 + 16) * 128 + m * 16) = v2;
;               }
	v_pk_mul_f32 v[42:43], v[118:119], v[42:43]
	v_pk_mul_f32 v[44:45], v[120:121], v[44:45]
	s_nop 0
	s_nop 0
	v_cvt_pk_bf16_f32 v42, v42, v42
	v_cvt_pk_bf16_f32 v0, v43, v43
	v_cvt_pk_bf16_f32 v44, v44, v44
	v_cvt_pk_bf16_f32 v43, v45, v45
	v_and_b32_e32 v44, 0xffff0000, v44
	v_and_b32_e32 v43, 0xffff0000, v43
	v_or_b32_sdwa v42, v44, v42 dst_sel:DWORD dst_unused:UNUSED_PAD src0_sel:DWORD src1_sel:WORD_1
	v_add_co_u32_e32 v44, vcc, s51, v144
	v_pk_mul_f32 v[48:49], v[120:121], v[48:49]
	v_or_b32_sdwa v43, v43, v0 dst_sel:DWORD dst_unused:UNUSED_PAD src0_sel:DWORD src1_sel:WORD_1
	v_addc_co_u32_e32 v45, vcc, 0, v145, vcc
	v_pk_mul_f32 v[46:47], v[118:119], v[46:47]
	global_store_dwordx2 v[44:45], v[42:43], off offset:32
	s_nop 0
	s_nop 0
	s_nop 0
	v_cvt_pk_bf16_f32 v44, v48, v48
	v_cvt_pk_bf16_f32 v42, v46, v46
	v_cvt_pk_bf16_f32 v43, v49, v49
	v_and_b32_e32 v44, 0xffff0000, v44
	v_cvt_pk_bf16_f32 v0, v47, v47
	v_and_b32_e32 v43, 0xffff0000, v43
	v_or_b32_sdwa v42, v44, v42 dst_sel:DWORD dst_unused:UNUSED_PAD src0_sel:DWORD src1_sel:WORD_1
	v_add_co_u32_e32 v44, vcc, 0x11000, v144
	v_or_b32_sdwa v43, v43, v0 dst_sel:DWORD dst_unused:UNUSED_PAD src0_sel:DWORD src1_sel:WORD_1
	s_nop 0
	v_addc_co_u32_e32 v45, vcc, 0, v145, vcc
	global_store_dwordx2 v[44:45], v[42:43], off offset:32
.LBB0_618:
	ds_read2st64_b32 v[42:43], v155 offset0:33 offset1:35
	ds_read2st64_b32 v[48:49], v155 offset0:37 offset1:39
	ds_read_b32 v56, v106
	ds_read_b32 v58, v107
	ds_read_b32 v57, v108
	ds_read_b32 v59, v109
	v_pk_mul_f32 v[40:41], v[40:41], v[52:53]
	v_pk_mul_f32 v[38:39], v[38:39], v[50:51]
	v_mov_b32_e32 v61, v40
	v_mov_b32_e32 v60, v38
	v_pk_mul_f32 v[36:37], v[36:37], v[52:53]
	v_pk_mul_f32 v[50:51], v[34:35], v[50:51]
	v_pk_add_f32 v[60:61], v[136:137], v[60:61]
	v_mov_b32_e32 v34, v50
	v_mov_b32_e32 v35, v36
	v_add_u32_e32 v0, 0x24080, v146
	v_pk_add_f32 v[52:53], v[134:135], v[34:35]
	s_waitcnt lgkmcnt(5)
	v_mov_b32_e32 v62, v42
	s_waitcnt lgkmcnt(4)
	v_mov_b32_e32 v63, v48
	s_waitcnt lgkmcnt(1)
	v_pk_mul_f32 v[34:35], v[60:61], v[56:57]
	v_mov_b32_e32 v40, v39
	v_lshl_add_u64 v[44:45], v[0:1], 1, s[0:1]
	v_add_u32_e32 v0, 0x24480, v146
	v_pk_fma_f32 v[34:35], v[52:53], v[62:63], v[34:35] neg_lo:[0,0,1] neg_hi:[0,0,1]
	v_pk_add_f32 v[40:41], v[136:137], v[40:41]
	v_mov_b32_e32 v36, v51
	v_lshl_add_u64 v[46:47], v[0:1], 1, s[0:1]
	v_add_u32_e32 v0, 0x24880, v146
	v_pk_mul_f32 v[34:35], v[142:143], v[34:35]
	v_pk_add_f32 v[50:51], v[134:135], v[36:37]
	v_mov_b32_e32 v48, v43
	s_waitcnt lgkmcnt(0)
	v_pk_mul_f32 v[36:37], v[40:41], v[58:59]
	v_lshl_add_u64 v[54:55], v[0:1], 1, s[0:1]
	s_nop 0
	v_pk_fma_f32 v[36:37], v[50:51], v[48:49], v[36:37] neg_lo:[0,0,1] neg_hi:[0,0,1]
	v_cvt_pk_bf16_f32 v0, v34, v34
	v_pk_mul_f32 v[36:37], v[142:143], v[36:37]
	global_store_short_d16_hi v[44:45], v0, off
	v_cvt_pk_bf16_f32 v0, v36, v36
	v_pk_mul_f32 v[38:39], v[52:53], v[56:57]
	global_store_short_d16_hi v[46:47], v0, off
	v_pk_fma_f32 v[38:39], v[60:61], v[62:63], v[38:39]
	v_cvt_pk_bf16_f32 v0, v35, v35
	v_pk_mul_f32 v[38:39], v[142:143], v[38:39]
	v_pk_mul_f32 v[42:43], v[50:51], v[58:59]
	global_store_short_d16_hi v[54:55], v0, off
	v_pk_fma_f32 v[40:41], v[40:41], v[48:49], v[42:43]
	v_cvt_pk_bf16_f32 v0, v38, v38
	v_pk_mul_f32 v[40:41], v[142:143], v[40:41]
	global_store_short_d16_hi v[44:45], v0, off offset:32
	v_cvt_pk_bf16_f32 v0, v40, v40
	global_store_short_d16_hi v[46:47], v0, off offset:32
	v_cvt_pk_bf16_f32 v0, v39, v39
	global_store_short_d16_hi v[54:55], v0, off offset:32
	v_bfe_u32 v0, v37, 16, 1
	v_add3_u32 v44, v37, v0, s81
	v_add_u32_e32 v0, 0x24c80, v146
	v_lshl_add_u64 v[42:43], v[0:1], 1, s[0:1]
	v_bfe_u32 v0, v41, 16, 1
	v_add3_u32 v0, v41, v0, s81
	s_and_b64 vcc, exec, s[6:7]
	global_store_short_d16_hi v[42:43], v44, off
	global_store_short_d16_hi v[42:43], v0, off offset:32
	s_cbranch_vccnz .LBB0_620
	v_pk_mul_f32 v[34:35], v[118:119], v[34:35]
	v_pk_mul_f32 v[36:37], v[120:121], v[36:37]
	s_nop 0
	s_nop 0
	v_cvt_pk_bf16_f32 v34, v34, v34
	v_cvt_pk_bf16_f32 v0, v35, v35
	v_cvt_pk_bf16_f32 v36, v36, v36
	v_cvt_pk_bf16_f32 v35, v37, v37
	v_and_b32_e32 v36, 0xffff0000, v36
	s_mov_b32 s2, 0x18000
	v_and_b32_e32 v35, 0xffff0000, v35
	v_or_b32_sdwa v34, v36, v34 dst_sel:DWORD dst_unused:UNUSED_PAD src0_sel:DWORD src1_sel:WORD_1
	v_add_co_u32_e32 v36, vcc, s2, v144
	v_pk_mul_f32 v[40:41], v[120:121], v[40:41]
	v_or_b32_sdwa v35, v35, v0 dst_sel:DWORD dst_unused:UNUSED_PAD src0_sel:DWORD src1_sel:WORD_1
	v_addc_co_u32_e32 v37, vcc, 0, v145, vcc
	v_pk_mul_f32 v[38:39], v[118:119], v[38:39]
	global_store_dwordx2 v[36:37], v[34:35], off offset:32
	s_nop 0
	s_nop 0
	s_nop 0
	v_cvt_pk_bf16_f32 v36, v40, v40
	v_cvt_pk_bf16_f32 v34, v38, v38
	v_cvt_pk_bf16_f32 v35, v41, v41
	v_and_b32_e32 v36, 0xffff0000, v36
	v_cvt_pk_bf16_f32 v0, v39, v39
	v_and_b32_e32 v35, 0xffff0000, v35
	v_or_b32_sdwa v34, v36, v34 dst_sel:DWORD dst_unused:UNUSED_PAD src0_sel:DWORD src1_sel:WORD_1
	v_add_co_u32_e32 v36, vcc, 0x19000, v144
	v_or_b32_sdwa v35, v35, v0 dst_sel:DWORD dst_unused:UNUSED_PAD src0_sel:DWORD src1_sel:WORD_1
	s_nop 0
	v_addc_co_u32_e32 v37, vcc, 0, v145, vcc
	global_store_dwordx2 v[36:37], v[34:35], off offset:32
; __device__ __forceinline__ unsigned pack2(float a, float b) { return (unsigned)f2bf(a) | ((unsigned)f2bf(b) << 16); }
; __device__ __forceinline__ float fexp2(float x) { return __builtin_amdgcn_exp2f(x); }
; template <int EPI, bool HS = false>
; __device__ __forceinline__ void gemm_phase(const Params& p, const GemmCfg& g, char* shm, const int wave_s) {
;     ...
;           for (int m = 0; m < 4; ++m) {
;             const int jj0 = wr * 64 + m * 16 + fq * 4;
;             const float k0 = fexp2(lg2 * (float)(127 - jj0));
;             const f32x4 r4 = *(const f32x4*)(rsw + ai * 128 + m * 16);
; #pragma unroll
;             for (int bj = 0; bj < 2; ++bj) {
;               float y1[4], y2[4];
; #pragma unroll
;               for (int j = 0; j < 4; ++j) {
;                 const int lr = ai * 128 + m * 16 + j;
;                 float cs = *(const float*)(rl + ((m * 16 + j) * 128 + bj * 64) * 4), sn = *(const float*)(rl + 65536 + ((m * 16 + j) * 128 + bj * 64) * 4);
;                 float x1 = r4[j] * acc[ai][bj][m][0][j] + swv[bj][0], x2 = r4[j] * acc[ai][bj][m][1][j] + swv[bj][1];
;                 y1[j] = (x1 * cs - x2 * sn) * scl;
;                 y2[j] = (x2 * cs + x1 * sn) * scl;
;                 dst[tb + lr * 1024 + bj * 128] = f2bf(y1[j]);
;                 dst[tb + lr * 1024 + bj * 128 + 16] = f2bf(y2[j]);
;               }
;               if (isk) {
;                 float d0 = k0, d1 = fexp2(lg2 * (float)(126 - jj0)), d2 = fexp2(lg2 * (float)(125 - jj0)),
;                       d3 = fexp2(lg2 * (float)(124 - jj0));
;                 uint2 v1, v2;
;                 v1.x = pack2(y1[0] * d0, y1[1] * d1); v1.y = pack2(y1[2] * d2, y1[3] * d3);
;                 v2.x = pack2(y2[0] * d0, y2[1] * d1); v2.y = pack2(y2[2] * d2, y2[3] * d3);
;                 *(uint2*)(kt_t + kb + ai * 256 * 128 + (bj * 128) * 128 + m * 16) = v1;
;                 *(uint2*)(kt_t + kb + ai * 256 * 128 + (bj * 128 + 16) * 128 + m * 16) = v2;
;               }
.LBB0_620:
	ds_read2st64_b32 v[38:39], v155 offset0:64 offset1:66
	ds_read2st64_b32 v[44:45], v155 offset0:68 offset1:70
	ds_read_b128 v[34:37], v154 offset:640
	ds_read_b32 v46, v110
	ds_read_b32 v48, v111
	ds_read_b32 v47, v112
	ds_read_b32 v49, v113
	s_waitcnt lgkmcnt(4)
	v_pk_mul_f32 v[32:33], v[32:33], v[36:37]
	v_pk_mul_f32 v[30:31], v[30:31], v[34:35]
	v_mov_b32_e32 v53, v32
	v_mov_b32_e32 v52, v30
	v_pk_mul_f32 v[28:29], v[28:29], v[36:37]
	v_pk_mul_f32 v[54:55], v[26:27], v[34:35]
	v_pk_add_f32 v[52:53], v[140:141], v[52:53]
	v_mov_b32_e32 v26, v54
	v_mov_b32_e32 v27, v28
	v_add_u32_e32 v0, 0x28000, v146
	v_pk_add_f32 v[56:57], v[138:139], v[26:27]
	v_mov_b32_e32 v58, v38
	v_mov_b32_e32 v59, v44
	s_waitcnt lgkmcnt(1)
	v_pk_mul_f32 v[26:27], v[46:47], v[52:53]
	v_mov_b32_e32 v32, v31
	v_lshl_add_u64 v[40:41], v[0:1], 1, s[0:1]
	v_add_u32_e32 v0, 0x28400, v146
	v_pk_fma_f32 v[26:27], v[58:59], v[56:57], v[26:27] neg_lo:[0,0,1] neg_hi:[0,0,1]
	v_pk_add_f32 v[32:33], v[140:141], v[32:33]
	v_mov_b32_e32 v28, v55
	v_lshl_add_u64 v[42:43], v[0:1], 1, s[0:1]
	v_add_u32_e32 v0, 0x28800, v146
	v_pk_mul_f32 v[26:27], v[142:143], v[26:27]
	v_pk_add_f32 v[54:55], v[138:139], v[28:29]
	v_mov_b32_e32 v44, v39
	s_waitcnt lgkmcnt(0)
	v_pk_mul_f32 v[28:29], v[32:33], v[48:49]
	v_lshl_add_u64 v[50:51], v[0:1], 1, s[0:1]
	s_nop 0
	v_pk_fma_f32 v[28:29], v[54:55], v[44:45], v[28:29] neg_lo:[0,0,1] neg_hi:[0,0,1]
	v_cvt_pk_bf16_f32 v0, v26, v26
	v_pk_mul_f32 v[28:29], v[142:143], v[28:29]
	global_store_short_d16_hi v[40:41], v0, off
	v_cvt_pk_bf16_f32 v0, v28, v28
	v_pk_mul_f32 v[30:31], v[46:47], v[56:57]
	global_store_short_d16_hi v[42:43], v0, off
	v_pk_fma_f32 v[30:31], v[58:59], v[52:53], v[30:31]
	v_cvt_pk_bf16_f32 v0, v27, v27
	v_pk_mul_f32 v[30:31], v[142:143], v[30:31]
	v_pk_mul_f32 v[38:39], v[54:55], v[48:49]
	global_store_short_d16_hi v[50:51], v0, off
	v_pk_fma_f32 v[32:33], v[32:33], v[44:45], v[38:39]
	v_cvt_pk_bf16_f32 v0, v30, v30
	v_pk_mul_f32 v[32:33], v[142:143], v[32:33]
	global_store_short_d16_hi v[40:41], v0, off offset:32
	v_cvt_pk_bf16_f32 v0, v32, v32
	global_store_short_d16_hi v[42:43], v0, off offset:32
	v_cvt_pk_bf16_f32 v0, v31, v31
	global_store_short_d16_hi v[50:51], v0, off offset:32
	v_bfe_u32 v0, v29, 16, 1
	v_add3_u32 v40, v29, v0, s81
	v_add_u32_e32 v0, 0x28c00, v146
	v_lshl_add_u64 v[38:39], v[0:1], 1, s[0:1]
	v_bfe_u32 v0, v33, 16, 1
	v_add3_u32 v0, v33, v0, s81
	s_and_b64 vcc, exec, s[6:7]
	global_store_short_d16_hi v[38:39], v40, off
	global_store_short_d16_hi v[38:39], v0, off offset:32
	s_cbranch_vccnz .LBB0_622
	v_pk_mul_f32 v[26:27], v[102:103], v[26:27]
	v_pk_mul_f32 v[28:29], v[104:105], v[28:29]
	s_nop 0
	s_nop 0
	v_cvt_pk_bf16_f32 v26, v26, v26
	v_cvt_pk_bf16_f32 v0, v27, v27
	v_cvt_pk_bf16_f32 v28, v28, v28
	v_cvt_pk_bf16_f32 v27, v29, v29
	v_and_b32_e32 v28, 0xffff0000, v28
	v_and_b32_e32 v27, 0xffff0000, v27
	v_or_b32_sdwa v26, v28, v26 dst_sel:DWORD dst_unused:UNUSED_PAD src0_sel:DWORD src1_sel:WORD_1
	v_add_co_u32_e32 v28, vcc, s51, v144
	v_pk_mul_f32 v[32:33], v[104:105], v[32:33]
	v_or_b32_sdwa v27, v27, v0 dst_sel:DWORD dst_unused:UNUSED_PAD src0_sel:DWORD src1_sel:WORD_1
	v_addc_co_u32_e32 v29, vcc, 0, v145, vcc
	v_pk_mul_f32 v[30:31], v[102:103], v[30:31]
	global_store_dwordx2 v[28:29], v[26:27], off offset:64
	s_nop 0
	s_nop 0
	s_nop 0
	v_cvt_pk_bf16_f32 v28, v32, v32
	v_cvt_pk_bf16_f32 v26, v30, v30
	v_cvt_pk_bf16_f32 v27, v33, v33
	v_and_b32_e32 v28, 0xffff0000, v28
	v_cvt_pk_bf16_f32 v0, v31, v31
	v_and_b32_e32 v27, 0xffff0000, v27
	v_or_b32_sdwa v26, v28, v26 dst_sel:DWORD dst_unused:UNUSED_PAD src0_sel:DWORD src1_sel:WORD_1
	v_add_co_u32_e32 v28, vcc, 0x11000, v144
	v_or_b32_sdwa v27, v27, v0 dst_sel:DWORD dst_unused:UNUSED_PAD src0_sel:DWORD src1_sel:WORD_1
	s_nop 0
	v_addc_co_u32_e32 v29, vcc, 0, v145, vcc
	global_store_dwordx2 v[28:29], v[26:27], off offset:64
.LBB0_622:
	ds_read2st64_b32 v[26:27], v155 offset0:65 offset1:67
	ds_read2st64_b32 v[32:33], v155 offset0:69 offset1:71
	ds_read_b32 v40, v90
	ds_read_b32 v42, v91
	ds_read_b32 v41, v92
	ds_read_b32 v43, v93
	v_pk_mul_f32 v[24:25], v[24:25], v[36:37]
	v_pk_mul_f32 v[22:23], v[22:23], v[34:35]
	v_mov_b32_e32 v45, v24
	v_mov_b32_e32 v44, v22
	v_pk_mul_f32 v[20:21], v[20:21], v[36:37]
	v_pk_mul_f32 v[34:35], v[18:19], v[34:35]
	v_pk_add_f32 v[44:45], v[136:137], v[44:45]
	v_mov_b32_e32 v18, v34
	v_mov_b32_e32 v19, v20
	v_add_u32_e32 v0, 0x28080, v146
	v_pk_add_f32 v[36:37], v[134:135], v[18:19]
	s_waitcnt lgkmcnt(5)
	v_mov_b32_e32 v46, v26
	s_waitcnt lgkmcnt(4)
	v_mov_b32_e32 v47, v32
	s_waitcnt lgkmcnt(1)
	v_pk_mul_f32 v[18:19], v[44:45], v[40:41]
	v_mov_b32_e32 v24, v23
	v_lshl_add_u64 v[28:29], v[0:1], 1, s[0:1]
	v_add_u32_e32 v0, 0x28480, v146
	v_pk_fma_f32 v[18:19], v[36:37], v[46:47], v[18:19] neg_lo:[0,0,1] neg_hi:[0,0,1]
	v_pk_add_f32 v[24:25], v[136:137], v[24:25]
	v_mov_b32_e32 v20, v35
	v_lshl_add_u64 v[30:31], v[0:1], 1, s[0:1]
	v_add_u32_e32 v0, 0x28880, v146
	v_pk_mul_f32 v[18:19], v[142:143], v[18:19]
	v_pk_add_f32 v[34:35], v[134:135], v[20:21]
	v_mov_b32_e32 v32, v27
	s_waitcnt lgkmcnt(0)
	v_pk_mul_f32 v[20:21], v[24:25], v[42:43]
	v_lshl_add_u64 v[38:39], v[0:1], 1, s[0:1]
	s_nop 0
	v_pk_fma_f32 v[20:21], v[34:35], v[32:33], v[20:21] neg_lo:[0,0,1] neg_hi:[0,0,1]
	v_cvt_pk_bf16_f32 v0, v18, v18
	v_pk_mul_f32 v[20:21], v[142:143], v[20:21]
	global_store_short_d16_hi v[28:29], v0, off
	v_cvt_pk_bf16_f32 v0, v20, v20
	v_pk_mul_f32 v[22:23], v[36:37], v[40:41]
	global_store_short_d16_hi v[30:31], v0, off
	v_pk_fma_f32 v[22:23], v[44:45], v[46:47], v[22:23]
	v_cvt_pk_bf16_f32 v0, v19, v19
	v_pk_mul_f32 v[22:23], v[142:143], v[22:23]
	v_pk_mul_f32 v[26:27], v[34:35], v[42:43]
	global_store_short_d16_hi v[38:39], v0, off
	v_pk_fma_f32 v[24:25], v[24:25], v[32:33], v[26:27]
	v_cvt_pk_bf16_f32 v0, v22, v22
	v_pk_mul_f32 v[24:25], v[142:143], v[24:25]
	global_store_short_d16_hi v[28:29], v0, off offset:32
	v_cvt_pk_bf16_f32 v0, v24, v24
	global_store_short_d16_hi v[30:31], v0, off offset:32
	v_cvt_pk_bf16_f32 v0, v23, v23
	global_store_short_d16_hi v[38:39], v0, off offset:32
	v_bfe_u32 v0, v21, 16, 1
	v_add3_u32 v28, v21, v0, s81
	v_add_u32_e32 v0, 0x28c80, v146
	v_lshl_add_u64 v[26:27], v[0:1], 1, s[0:1]
	v_bfe_u32 v0, v25, 16, 1
	v_add3_u32 v0, v25, v0, s81
	s_and_b64 vcc, exec, s[6:7]
	global_store_short_d16_hi v[26:27], v28, off
	global_store_short_d16_hi v[26:27], v0, off offset:32
	s_cbranch_vccnz .LBB0_624
; __device__ __forceinline__ unsigned pack2(float a, float b) { return (unsigned)f2bf(a) | ((unsigned)f2bf(b) << 16); }
; __device__ __forceinline__ float fexp2(float x) { return __builtin_amdgcn_exp2f(x); }
; template <int EPI, bool HS = false>
; __device__ __forceinline__ void gemm_phase(const Params& p, const GemmCfg& g, char* shm, const int wave_s) {
;     ...
;             for (int bj = 0; bj < 2; ++bj) {
;               float y1[4], y2[4];
; #pragma unroll
;               for (int j = 0; j < 4; ++j) {
;                 const int lr = ai * 128 + m * 16 + j;
;                 float cs = *(const float*)(rl + ((m * 16 + j) * 128 + bj * 64) * 4), sn = *(const float*)(rl + 65536 + ((m * 16 + j) * 128 + bj * 64) * 4);
;                 float x1 = r4[j] * acc[ai][bj][m][0][j] + swv[bj][0], x2 = r4[j] * acc[ai][bj][m][1][j] + swv[bj][1];
;                 y1[j] = (x1 * cs - x2 * sn) * scl;
;                 y2[j] = (x2 * cs + x1 * sn) * scl;
;                 dst[tb + lr * 1024 + bj * 128] = f2bf(y1[j]);
;                 dst[tb + lr * 1024 + bj * 128 + 16] = f2bf(y2[j]);
;               }
;               if (isk) {
;                 float d0 = k0, d1 = fexp2(lg2 * (float)(126 - jj0)), d2 = fexp2(lg2 * (float)(125 - jj0)),
;                       d3 = fexp2(lg2 * (float)(124 - jj0));
;                 uint2 v1, v2;
;                 v1.x = pack2(y1[0] * d0, y1[1] * d1); v1.y = pack2(y1[2] * d2, y1[3] * d3);
;                 v2.x = pack2(y2[0] * d0, y2[1] * d1); v2.y = pack2(y2[2] * d2, y2[3] * d3);
;                 *(uint2*)(kt_t + kb + ai * 256 * 128 + (bj * 128) * 128 + m * 16) = v1;
;                 *(uint2*)(kt_t + kb + ai * 256 * 128 + (bj * 128 + 16) * 128 + m * 16) = v2;
;               }
	v_pk_mul_f32 v[18:19], v[102:103], v[18:19]
	v_pk_mul_f32 v[20:21], v[104:105], v[20:21]
	s_nop 0
	s_nop 0
	v_cvt_pk_bf16_f32 v18, v18, v18
	v_cvt_pk_bf16_f32 v0, v19, v19
	v_cvt_pk_bf16_f32 v20, v20, v20
	v_cvt_pk_bf16_f32 v19, v21, v21
	v_and_b32_e32 v20, 0xffff0000, v20
	s_mov_b32 s2, 0x18000
	v_and_b32_e32 v19, 0xffff0000, v19
	v_or_b32_sdwa v18, v20, v18 dst_sel:DWORD dst_unused:UNUSED_PAD src0_sel:DWORD src1_sel:WORD_1
	v_add_co_u32_e32 v20, vcc, s2, v144
	v_pk_mul_f32 v[24:25], v[104:105], v[24:25]
	v_or_b32_sdwa v19, v19, v0 dst_sel:DWORD dst_unused:UNUSED_PAD src0_sel:DWORD src1_sel:WORD_1
	v_addc_co_u32_e32 v21, vcc, 0, v145, vcc
	v_pk_mul_f32 v[22:23], v[102:103], v[22:23]
	global_store_dwordx2 v[20:21], v[18:19], off offset:64
	s_nop 0
	s_nop 0
	s_nop 0
	v_cvt_pk_bf16_f32 v20, v24, v24
	v_cvt_pk_bf16_f32 v18, v22, v22
	v_cvt_pk_bf16_f32 v19, v25, v25
	v_and_b32_e32 v20, 0xffff0000, v20
	v_cvt_pk_bf16_f32 v0, v23, v23
	v_and_b32_e32 v19, 0xffff0000, v19
	v_or_b32_sdwa v18, v20, v18 dst_sel:DWORD dst_unused:UNUSED_PAD src0_sel:DWORD src1_sel:WORD_1
	v_add_co_u32_e32 v20, vcc, 0x19000, v144
	v_or_b32_sdwa v19, v19, v0 dst_sel:DWORD dst_unused:UNUSED_PAD src0_sel:DWORD src1_sel:WORD_1
	s_nop 0
	v_addc_co_u32_e32 v21, vcc, 0, v145, vcc
	global_store_dwordx2 v[20:21], v[18:19], off offset:64
.LBB0_624:
	ds_read2st64_b32 v[22:23], v155 offset0:96 offset1:98
	ds_read2st64_b32 v[28:29], v155 offset0:100 offset1:102
	ds_read_b128 v[18:21], v154 offset:704
	ds_read_b32 v30, v94
	ds_read_b32 v32, v95
	ds_read_b32 v31, v96
	ds_read_b32 v33, v97
	s_waitcnt lgkmcnt(4)
	v_pk_mul_f32 v[16:17], v[16:17], v[20:21]
	v_pk_mul_f32 v[14:15], v[14:15], v[18:19]
	v_mov_b32_e32 v37, v16
	v_mov_b32_e32 v36, v14
	v_pk_mul_f32 v[12:13], v[12:13], v[20:21]
	v_pk_mul_f32 v[38:39], v[10:11], v[18:19]
	v_pk_add_f32 v[36:37], v[140:141], v[36:37]
	v_mov_b32_e32 v10, v38
	v_mov_b32_e32 v11, v12
	v_add_u32_e32 v0, 0x2c000, v146
	v_pk_add_f32 v[40:41], v[138:139], v[10:11]
	v_mov_b32_e32 v42, v22
	v_mov_b32_e32 v43, v28
	s_waitcnt lgkmcnt(1)
	v_pk_mul_f32 v[10:11], v[30:31], v[36:37]
	v_mov_b32_e32 v16, v15
	v_lshl_add_u64 v[24:25], v[0:1], 1, s[0:1]
	v_add_u32_e32 v0, 0x2c400, v146
	v_pk_fma_f32 v[10:11], v[42:43], v[40:41], v[10:11] neg_lo:[0,0,1] neg_hi:[0,0,1]
	v_pk_add_f32 v[16:17], v[140:141], v[16:17]
	v_mov_b32_e32 v12, v39
	v_lshl_add_u64 v[26:27], v[0:1], 1, s[0:1]
	v_add_u32_e32 v0, 0x2c800, v146
	v_pk_mul_f32 v[10:11], v[142:143], v[10:11]
	v_pk_add_f32 v[38:39], v[138:139], v[12:13]
	v_mov_b32_e32 v28, v23
	s_waitcnt lgkmcnt(0)
	v_pk_mul_f32 v[12:13], v[16:17], v[32:33]
	v_lshl_add_u64 v[34:35], v[0:1], 1, s[0:1]
	s_nop 0
	v_pk_fma_f32 v[12:13], v[38:39], v[28:29], v[12:13] neg_lo:[0,0,1] neg_hi:[0,0,1]
	v_cvt_pk_bf16_f32 v0, v10, v10
	v_pk_mul_f32 v[12:13], v[142:143], v[12:13]
	global_store_short_d16_hi v[24:25], v0, off
	v_cvt_pk_bf16_f32 v0, v12, v12
	v_pk_mul_f32 v[14:15], v[30:31], v[40:41]
	global_store_short_d16_hi v[26:27], v0, off
	v_pk_fma_f32 v[14:15], v[42:43], v[36:37], v[14:15]
	v_cvt_pk_bf16_f32 v0, v11, v11
	v_pk_mul_f32 v[14:15], v[142:143], v[14:15]
	v_pk_mul_f32 v[22:23], v[38:39], v[32:33]
	global_store_short_d16_hi v[34:35], v0, off
	v_pk_fma_f32 v[16:17], v[16:17], v[28:29], v[22:23]
	v_cvt_pk_bf16_f32 v0, v14, v14
	v_pk_mul_f32 v[16:17], v[142:143], v[16:17]
	global_store_short_d16_hi v[24:25], v0, off offset:32
	v_cvt_pk_bf16_f32 v0, v16, v16
	global_store_short_d16_hi v[26:27], v0, off offset:32
	v_cvt_pk_bf16_f32 v0, v15, v15
	global_store_short_d16_hi v[34:35], v0, off offset:32
	v_bfe_u32 v0, v13, 16, 1
	v_add3_u32 v24, v13, v0, s81
	v_add_u32_e32 v0, 0x2cc00, v146
	v_lshl_add_u64 v[22:23], v[0:1], 1, s[0:1]
	v_bfe_u32 v0, v17, 16, 1
	v_add3_u32 v0, v17, v0, s81
	s_and_b64 vcc, exec, s[6:7]
	global_store_short_d16_hi v[22:23], v24, off
	global_store_short_d16_hi v[22:23], v0, off offset:32
	s_cbranch_vccnz .LBB0_626
	v_pk_mul_f32 v[10:11], v[86:87], v[10:11]
	v_pk_mul_f32 v[12:13], v[88:89], v[12:13]
	s_nop 0
	s_nop 0
	v_cvt_pk_bf16_f32 v10, v10, v10
	v_cvt_pk_bf16_f32 v0, v11, v11
	v_cvt_pk_bf16_f32 v12, v12, v12
	v_cvt_pk_bf16_f32 v11, v13, v13
	v_and_b32_e32 v12, 0xffff0000, v12
	v_and_b32_e32 v11, 0xffff0000, v11
	v_or_b32_sdwa v10, v12, v10 dst_sel:DWORD dst_unused:UNUSED_PAD src0_sel:DWORD src1_sel:WORD_1
	v_add_co_u32_e32 v12, vcc, s51, v144
	v_pk_mul_f32 v[16:17], v[88:89], v[16:17]
	v_or_b32_sdwa v11, v11, v0 dst_sel:DWORD dst_unused:UNUSED_PAD src0_sel:DWORD src1_sel:WORD_1
	v_addc_co_u32_e32 v13, vcc, 0, v145, vcc
	v_pk_mul_f32 v[14:15], v[86:87], v[14:15]
	global_store_dwordx2 v[12:13], v[10:11], off offset:96
	s_nop 0
	s_nop 0
	s_nop 0
	v_cvt_pk_bf16_f32 v12, v16, v16
	v_cvt_pk_bf16_f32 v10, v14, v14
	v_cvt_pk_bf16_f32 v11, v17, v17
	v_and_b32_e32 v12, 0xffff0000, v12
	v_cvt_pk_bf16_f32 v0, v15, v15
	v_and_b32_e32 v11, 0xffff0000, v11
	v_or_b32_sdwa v10, v12, v10 dst_sel:DWORD dst_unused:UNUSED_PAD src0_sel:DWORD src1_sel:WORD_1
	v_add_co_u32_e32 v12, vcc, 0x11000, v144
	v_or_b32_sdwa v11, v11, v0 dst_sel:DWORD dst_unused:UNUSED_PAD src0_sel:DWORD src1_sel:WORD_1
	s_nop 0
	v_addc_co_u32_e32 v13, vcc, 0, v145, vcc
	global_store_dwordx2 v[12:13], v[10:11], off offset:96
; __device__ __forceinline__ unsigned pack2(float a, float b) { return (unsigned)f2bf(a) | ((unsigned)f2bf(b) << 16); }
; __device__ __forceinline__ float fexp2(float x) { return __builtin_amdgcn_exp2f(x); }
; template <int EPI, bool HS = false>
; __device__ __forceinline__ void gemm_phase(const Params& p, const GemmCfg& g, char* shm, const int wave_s) {
;     ...
;             for (int bj = 0; bj < 2; ++bj) {
;               float y1[4], y2[4];
; #pragma unroll
;               for (int j = 0; j < 4; ++j) {
;                 const int lr = ai * 128 + m * 16 + j;
;                 float cs = *(const float*)(rl + ((m * 16 + j) * 128 + bj * 64) * 4), sn = *(const float*)(rl + 65536 + ((m * 16 + j) * 128 + bj * 64) * 4);
;                 float x1 = r4[j] * acc[ai][bj][m][0][j] + swv[bj][0], x2 = r4[j] * acc[ai][bj][m][1][j] + swv[bj][1];
;                 y1[j] = (x1 * cs - x2 * sn) * scl;
;                 y2[j] = (x2 * cs + x1 * sn) * scl;
;                 dst[tb + lr * 1024 + bj * 128] = f2bf(y1[j]);
;                 dst[tb + lr * 1024 + bj * 128 + 16] = f2bf(y2[j]);
;               }
;               if (isk) {
;                 float d0 = k0, d1 = fexp2(lg2 * (float)(126 - jj0)), d2 = fexp2(lg2 * (float)(125 - jj0)),
;                       d3 = fexp2(lg2 * (float)(124 - jj0));
;                 uint2 v1, v2;
;                 v1.x = pack2(y1[0] * d0, y1[1] * d1); v1.y = pack2(y1[2] * d2, y1[3] * d3);
;                 v2.x = pack2(y2[0] * d0, y2[1] * d1); v2.y = pack2(y2[2] * d2, y2[3] * d3);
;                 *(uint2*)(kt_t + kb + ai * 256 * 128 + (bj * 128) * 128 + m * 16) = v1;
;                 *(uint2*)(kt_t + kb + ai * 256 * 128 + (bj * 128 + 16) * 128 + m * 16) = v2;
;               }
.LBB0_626:
	ds_read2st64_b32 v[10:11], v155 offset0:97 offset1:99
	ds_read2st64_b32 v[16:17], v155 offset0:101 offset1:103
	ds_read_b32 v24, v74
	ds_read_b32 v26, v75
	ds_read_b32 v25, v76
	ds_read_b32 v27, v77
	v_pk_mul_f32 v[8:9], v[8:9], v[20:21]
	v_pk_mul_f32 v[6:7], v[6:7], v[18:19]
	v_mov_b32_e32 v29, v8
	v_mov_b32_e32 v28, v6
	v_pk_mul_f32 v[4:5], v[4:5], v[20:21]
	v_pk_mul_f32 v[18:19], v[2:3], v[18:19]
	v_pk_add_f32 v[28:29], v[136:137], v[28:29]
	v_mov_b32_e32 v2, v18
	v_mov_b32_e32 v3, v4
	v_add_u32_e32 v0, 0x2c080, v146
	v_pk_add_f32 v[20:21], v[134:135], v[2:3]
	s_waitcnt lgkmcnt(5)
	v_mov_b32_e32 v30, v10
	s_waitcnt lgkmcnt(4)
	v_mov_b32_e32 v31, v16
	s_waitcnt lgkmcnt(1)
	v_pk_mul_f32 v[2:3], v[28:29], v[24:25]
	v_mov_b32_e32 v8, v7
	v_lshl_add_u64 v[12:13], v[0:1], 1, s[0:1]
	v_add_u32_e32 v0, 0x2c480, v146
	v_pk_fma_f32 v[2:3], v[20:21], v[30:31], v[2:3] neg_lo:[0,0,1] neg_hi:[0,0,1]
	v_pk_add_f32 v[8:9], v[136:137], v[8:9]
	v_mov_b32_e32 v4, v19
	v_lshl_add_u64 v[14:15], v[0:1], 1, s[0:1]
	v_add_u32_e32 v0, 0x2c880, v146
	v_pk_mul_f32 v[2:3], v[142:143], v[2:3]
	v_pk_add_f32 v[18:19], v[134:135], v[4:5]
	v_mov_b32_e32 v16, v11
	s_waitcnt lgkmcnt(0)
	v_pk_mul_f32 v[4:5], v[8:9], v[26:27]
	v_lshl_add_u64 v[22:23], v[0:1], 1, s[0:1]
	s_nop 0
	v_pk_fma_f32 v[4:5], v[18:19], v[16:17], v[4:5] neg_lo:[0,0,1] neg_hi:[0,0,1]
	v_cvt_pk_bf16_f32 v0, v2, v2
	v_pk_mul_f32 v[4:5], v[142:143], v[4:5]
	global_store_short_d16_hi v[12:13], v0, off
	v_cvt_pk_bf16_f32 v0, v4, v4
	v_pk_mul_f32 v[6:7], v[20:21], v[24:25]
	global_store_short_d16_hi v[14:15], v0, off
	v_pk_fma_f32 v[6:7], v[28:29], v[30:31], v[6:7]
	v_cvt_pk_bf16_f32 v0, v3, v3
	v_pk_mul_f32 v[6:7], v[142:143], v[6:7]
	v_pk_mul_f32 v[10:11], v[18:19], v[26:27]
	global_store_short_d16_hi v[22:23], v0, off
	v_pk_fma_f32 v[8:9], v[8:9], v[16:17], v[10:11]
	v_cvt_pk_bf16_f32 v0, v6, v6
	v_pk_mul_f32 v[8:9], v[142:143], v[8:9]
	global_store_short_d16_hi v[12:13], v0, off offset:32
	v_cvt_pk_bf16_f32 v0, v8, v8
	global_store_short_d16_hi v[14:15], v0, off offset:32
	v_cvt_pk_bf16_f32 v0, v7, v7
	global_store_short_d16_hi v[22:23], v0, off offset:32
	v_bfe_u32 v0, v5, 16, 1
	v_add3_u32 v12, v5, v0, s81
	v_add_u32_e32 v0, 0x2cc80, v146
	v_lshl_add_u64 v[10:11], v[0:1], 1, s[0:1]
	v_bfe_u32 v0, v9, 16, 1
	v_add3_u32 v0, v9, v0, s81
	s_and_b64 vcc, exec, s[6:7]
	global_store_short_d16_hi v[10:11], v12, off
	global_store_short_d16_hi v[10:11], v0, off offset:32
	s_cbranch_vccnz .LBB0_628
	v_pk_mul_f32 v[2:3], v[86:87], v[2:3]
	v_pk_mul_f32 v[4:5], v[88:89], v[4:5]
	s_nop 0
	s_nop 0
	v_cvt_pk_bf16_f32 v2, v2, v2
	v_and_b32_sdwa v10, v4, v178 dst_sel:DWORD dst_unused:UNUSED_PAD src0_sel:WORD_1 src1_sel:DWORD
	v_cvt_pk_bf16_f32 v0, v3, v3
	v_add3_u32 v4, v4, v10, s81
	v_cvt_pk_bf16_f32 v3, v5, v5
	v_and_b32_e32 v4, 0xffff0000, v4
	s_mov_b32 s0, 0x18000
	v_and_b32_e32 v3, 0xffff0000, v3
	v_or_b32_sdwa v2, v4, v2 dst_sel:DWORD dst_unused:UNUSED_PAD src0_sel:DWORD src1_sel:WORD_1
	v_add_co_u32_e32 v4, vcc, s0, v144
	v_pk_mul_f32 v[8:9], v[88:89], v[8:9]
	v_or_b32_sdwa v3, v3, v0 dst_sel:DWORD dst_unused:UNUSED_PAD src0_sel:DWORD src1_sel:WORD_1
	v_addc_co_u32_e32 v5, vcc, 0, v145, vcc
	v_pk_mul_f32 v[6:7], v[86:87], v[6:7]
	global_store_dwordx2 v[4:5], v[2:3], off offset:96
	s_nop 0
	s_nop 0
	s_nop 0
	v_cvt_pk_bf16_f32 v4, v8, v8
	v_and_b32_sdwa v0, v7, v178 dst_sel:DWORD dst_unused:UNUSED_PAD src0_sel:WORD_1 src1_sel:DWORD
	v_cvt_pk_bf16_f32 v2, v6, v6
	v_cvt_pk_bf16_f32 v3, v9, v9
	v_and_b32_e32 v4, 0xffff0000, v4
	v_add3_u32 v0, v7, v0, s81
	v_and_b32_e32 v3, 0xffff0000, v3
	v_or_b32_sdwa v2, v4, v2 dst_sel:DWORD dst_unused:UNUSED_PAD src0_sel:DWORD src1_sel:WORD_1
	v_add_co_u32_e32 v4, vcc, 0x19000, v144
	v_or_b32_sdwa v3, v3, v0 dst_sel:DWORD dst_unused:UNUSED_PAD src0_sel:DWORD src1_sel:WORD_1
	s_nop 0
	v_addc_co_u32_e32 v5, vcc, 0, v145, vcc
	global_store_dwordx2 v[4:5], v[2:3], off offset:96

; __device__ __forceinline__ unsigned pack2(float a, float b) { return (unsigned)f2bf(a) | ((unsigned)f2bf(b) << 16); }
; template <int EPI, bool HS = false>
; __device__ __forceinline__ void gemm_phase(const Params& p, const GemmCfg& g, char* shm, const int wave_s) {
;     ...
;           for (int j = 0; j < 4; ++j) {
;             float ss = 0.f;
; #pragma unroll
;             for (int bj = 0; bj < 2; ++bj) {
;               float2 xn;
;               xn.x = xv[j][bj].x + gt[bj][0] * acc[ai][bj][m][0][j];
;               xn.y = xv[j][bj].y + gt[bj][1] * acc[ai][bj][m][1][j];
;               const unsigned o = tb + (unsigned)((ai * 128 + m * 16 + j) * 1024 + bj * 128);
;               *(float2*)(xout_t + o) = xn;
;               if (g.has_next) *(unsigned*)(xg_t + o) = pack2(xn.x * gn[bj][0], xn.y * gn[bj][1]);
;               ss += xn.x * xn.x + xn.y * xn.y;
;             }
;             if (g.has_next) {
;               ss = dpp_row_sum16(ss);
;               if (fr == 0) rss_t[(wr * 64 + fq * 4 + ai * 128 + m * 16 + j) * 16] = ss;
;             }
.LBB0_659:
	s_or_b64 exec, exec, s[10:11]
	v_or_b32_e32 v144, 0x400, v0
	v_mov_b32_e32 v126, v123
	v_mov_b32_e32 v145, v1
	s_waitcnt lgkmcnt(2)
	v_pk_fma_f32 v[158:159], v[154:155], v[126:127], v[138:139]
	v_lshl_add_u64 v[144:145], v[144:145], 2, s[0:1]
	global_store_dwordx2 v[144:145], v[158:159], off
	v_pk_mul_f32 v[144:145], v[148:149], v[158:159]
	v_or_b32_e32 v160, 0x480, v0
	s_nop 0
	s_nop 0
	v_cvt_pk_bf16_f32 v118, v144, v144
	v_cvt_pk_bf16_f32 v114, v145, v145
	v_lshrrev_b32_e32 v118, 16, v118
	v_and_or_b32 v114, v114, s28, v118
	v_mov_b32_e32 v118, v115
	v_mov_b32_e32 v161, v1
	v_pk_fma_f32 v[144:145], v[150:151], v[118:119], v[140:141]
	v_lshl_add_u64 v[160:161], v[160:161], 2, s[0:1]
	global_store_dword v[156:157], v114, off offset:2048
	global_store_dwordx2 v[160:161], v[144:145], off
	v_pk_mul_f32 v[160:161], v[152:153], v[144:145]
	v_pk_mul_f32 v[158:159], v[158:159], v[158:159]
	s_nop 0
	v_cvt_pk_bf16_f32 v118, v160, v160
	v_cvt_pk_bf16_f32 v114, v161, v161
	v_lshrrev_b32_e32 v118, 16, v118
	v_and_or_b32 v114, v114, s28, v118
	v_pk_mul_f32 v[144:145], v[144:145], v[144:145]
	global_store_dword v[156:157], v114, off offset:2304
	v_add_f32_e32 v114, v144, v145
	v_add_f32_e32 v118, v158, v159
	v_add_f32_e32 v114, v118, v114
	s_nop 1
	v_add_f32_dpp v114, v114, v114 quad_perm:[1,0,3,2] row_mask:0xf bank_mask:0xf bound_ctrl:1
	s_nop 1
	v_add_f32_dpp v114, v114, v114 quad_perm:[2,3,0,1] row_mask:0xf bank_mask:0xf bound_ctrl:1
	s_nop 1
	v_add_f32_dpp v114, v114, v114 row_half_mirror row_mask:0xf bank_mask:0xf bound_ctrl:1
	s_nop 1
	v_mov_b32_dpp v118, v114 row_mirror row_mask:0xf bank_mask:0xf bound_ctrl:1
	s_and_saveexec_b64 s[10:11], s[4:5]
	s_cbranch_execz .LBB0_661
	v_lshlrev_b32_e32 v144, 4, v163
	v_ashrrev_i32_e32 v145, 31, v144
	v_add_f32_e32 v114, v114, v118
	v_lshl_add_u64 v[144:145], v[144:145], 2, v[142:143]
	global_store_dword v[144:145], v114, off offset:64

; __device__ __forceinline__ unsigned pack2(float a, float b) { return (unsigned)f2bf(a) | ((unsigned)f2bf(b) << 16); }
; __device__ __forceinline__ void prep_phase(const Params& p, char* shm, const int tid) {
;     ...
;       char* shb = (char*)shl;
;       const float* mp = p.mod + (size_t)l * 16 * 9216 + sub * 3072;
;       for (int pi = tid; pi < 16 * 512; pi += 512) {
;         int b = pi >> 9, k = (pi & 511) * 2;
;         float2 mv = *(const float2*)(mp + (size_t)b * 9216 + k);
;         *(unsigned*)(shb + b * 2064 + k * 2) = pack2(mv.x, mv.y);
;       }
.LBB0_880:
	v_ashrrev_i32_e32 v11, 9, v2
	v_lshlrev_b32_e32 v12, 1, v2
	v_ashrrev_i32_e32 v5, 9, v3
	v_lshlrev_b32_e32 v0, 1, v3
	v_and_b32_e32 v17, 0x3fe, v12
	v_mul_hi_i32_i24_e32 v13, 0x9000, v11
	v_mul_i32_i24_e32 v12, 0x9000, v11
	v_and_b32_e32 v16, 0x3fe, v0
	v_mul_hi_i32_i24_e32 v15, 0x9000, v5
	v_mul_i32_i24_e32 v14, 0x9000, v5
	v_lshl_add_u64 v[12:13], s[68:69], 0, v[12:13]
	v_lshlrev_b32_e32 v0, 2, v17
	v_lshl_add_u64 v[14:15], s[68:69], 0, v[14:15]
	v_lshl_add_u64 v[12:13], v[12:13], 0, v[0:1]
	v_lshlrev_b32_e32 v0, 2, v16
	global_load_dwordx2 v[12:13], v[12:13], off
	v_lshl_add_u64 v[14:15], v[14:15], 0, v[0:1]
	global_load_dwordx2 v[14:15], v[14:15], off
	v_mul_i32_i24_e32 v0, 0x810, v11
	v_mul_i32_i24_e32 v5, 0x810, v5
	v_lshlrev_b32_e32 v11, 1, v16
	v_lshlrev_b32_e32 v16, 1, v17
	v_add3_u32 v0, 0, v0, v16
	v_add3_u32 v5, 0, v5, v11
	v_add_u32_e32 v4, -2, v4
	v_cmp_eq_u32_e32 vcc, 0, v4
	v_add_u32_e32 v3, 0x400, v3
	v_add_u32_e32 v2, 0x400, v2
	s_or_b64 s[72:73], vcc, s[72:73]
	s_waitcnt vmcnt(1)
	s_nop 0
	v_and_b32_sdwa v16, v13, v178 dst_sel:DWORD dst_unused:UNUSED_PAD src0_sel:WORD_1 src1_sel:DWORD
	v_cvt_pk_bf16_f32 v11, v12, v12
	s_waitcnt vmcnt(0)
	v_add3_u32 v13, v13, v16, s81
	v_and_b32_sdwa v17, v14, v178 dst_sel:DWORD dst_unused:UNUSED_PAD src0_sel:WORD_1 src1_sel:DWORD
	v_cvt_pk_bf16_f32 v12, v15, v15
	v_and_b32_e32 v13, 0xffff0000, v13
	v_add3_u32 v14, v14, v17, s81
	v_and_b32_e32 v12, 0xffff0000, v12
	v_or_b32_sdwa v11, v13, v11 dst_sel:DWORD dst_unused:UNUSED_PAD src0_sel:DWORD src1_sel:WORD_1
	v_or_b32_sdwa v12, v12, v14 dst_sel:DWORD dst_unused:UNUSED_PAD src0_sel:DWORD src1_sel:WORD_1
	ds_write_b32 v0, v11
	ds_write_b32 v5, v12
	s_andn2_b64 exec, exec, s[72:73]
	s_cbranch_execnz .LBB0_880
	s_or_b64 exec, exec, s[72:73]
	s_orn2_b64 s[72:73], s[6:7], exec
	v_mov_b32_e32 v2, v26

; __device__ __forceinline__ unsigned pack2(float a, float b) { return (unsigned)f2bf(a) | ((unsigned)f2bf(b) << 16); }
; __device__ __forceinline__ void prep_phase(const Params& p, char* shm, const int tid) {
;     ...
;   for (int row0 = (blockIdx.x * 8 + wid) * 2; row0 < TOK; row0 += gridDim.x * 16) {
;     const f32x4* xr = (const f32x4*)(p.x + (size_t)row0 * 1024);
;     f32x4 v[2][4];
; #pragma unroll
;     for (int q = 0; q < 2; ++q)
; #pragma unroll
;       for (int i = 0; i < 4; ++i) v[q][i] = xr[q * 256 + lane + 64 * i];
;     const int b = row0 >> 12;
;     const float* sc = p.mod + (size_t)b * 9216 + 1024;
; #pragma unroll
;     for (int q = 0; q < 2; ++q) {
;       const int row = row0 + q;
;       float ss = 0.f;
; #pragma unroll
;       for (int i = 0; i < 4; ++i) ss += v[q][i][0] * v[q][i][0] + v[q][i][1] * v[q][i][1] + v[q][i][2] * v[q][i][2] + v[q][i][3] * v[q][i][3];
;       ss = wave_sum(ss, lane);
;       if (lane < 16) p.rowss[(size_t)row * 16 + lane] = (lane == 0) ? ss : 0.0f;
; #pragma unroll
;       for (int i = 0; i < 4; ++i) {
;         int col = (lane + 64 * i) * 4;
;         f32x4 gg = *(const f32x4*)(g + col), s4 = *(const f32x4*)(sc + col);
;         uint2 pk;
;         pk.x = pack2(v[q][i][0] * gg[0] * (1.0f + s4[0]), v[q][i][1] * gg[1] * (1.0f + s4[1]));
;         pk.y = pack2(v[q][i][2] * gg[2] * (1.0f + s4[2]), v[q][i][3] * gg[3] * (1.0f + s4[3]));
;         *(uint2*)(p.h + (size_t)row * 1024 + col) = pk;
;       }
;     }
.LBB0_892:
	s_or_b64 exec, exec, s[8:9]
	global_load_dwordx4 v[18:21], v[36:37], off
	s_nop 0
	global_load_dwordx4 v[50:53], v[50:51], off
	v_lshlrev_b64 v[24:25], 11, v[24:25]
	v_lshl_add_u64 v[24:25], v[42:43], 0, v[24:25]
	v_readlane_b32 s8, v253, 18
	s_waitcnt vmcnt(1)
	v_pk_mul_f32 v[16:17], v[16:17], v[20:21]
	v_pk_mul_f32 v[14:15], v[14:15], v[18:19]
	s_waitcnt vmcnt(0)
	v_mov_b32_e32 v19, v52
	v_mov_b32_e32 v52, v51
	v_mov_b32_e32 v18, v50
	v_mov_b32_e32 v20, v14
	v_mov_b32_e32 v21, v16
	v_mov_b32_e32 v16, v15
	v_pk_add_f32 v[14:15], v[52:53], 1.0 op_sel_hi:[1,0]
	v_pk_add_f32 v[18:19], v[18:19], 1.0 op_sel_hi:[1,0]
	v_pk_mul_f32 v[14:15], v[16:17], v[14:15]
	v_pk_mul_f32 v[18:19], v[20:21], v[18:19]
	v_cvt_pk_bf16_f32 v15, v15, v15
	v_cvt_pk_bf16_f32 v14, v14, v14
	v_cvt_pk_bf16_f32 v17, v18, v18
	v_cvt_pk_bf16_f32 v16, v19, v19
	v_and_b32_e32 v15, 0xffff0000, v15
	v_and_b32_e32 v14, 0xffff0000, v14
	v_or_b32_sdwa v15, v15, v16 dst_sel:DWORD dst_unused:UNUSED_PAD src0_sel:DWORD src1_sel:WORD_1
	v_or_b32_sdwa v14, v14, v17 dst_sel:DWORD dst_unused:UNUSED_PAD src0_sel:DWORD src1_sel:WORD_1
	global_store_dwordx2 v[24:25], v[14:15], off
	global_load_dwordx4 v[14:17], v[36:37], off offset:1024
	s_nop 0
	global_load_dwordx4 v[18:21], v[30:31], off
	v_add_u32_e32 v34, s8, v34
	s_mov_b32 s8, 0xffff
	v_cmp_lt_i32_e32 vcc, s8, v34
	s_or_b64 s[2:3], vcc, s[2:3]
	s_waitcnt vmcnt(1)
	v_pk_mul_f32 v[12:13], v[12:13], v[16:17]
	v_pk_mul_f32 v[10:11], v[10:11], v[14:15]
	s_waitcnt vmcnt(0)
	v_mov_b32_e32 v15, v20
	v_mov_b32_e32 v20, v19
	v_mov_b32_e32 v14, v18
	v_mov_b32_e32 v16, v10
	v_mov_b32_e32 v17, v12
	v_mov_b32_e32 v12, v11
	v_pk_add_f32 v[10:11], v[20:21], 1.0 op_sel_hi:[1,0]
	v_pk_add_f32 v[14:15], v[14:15], 1.0 op_sel_hi:[1,0]
	v_pk_mul_f32 v[10:11], v[12:13], v[10:11]
	v_pk_mul_f32 v[14:15], v[16:17], v[14:15]
	v_cvt_pk_bf16_f32 v11, v11, v11
	v_cvt_pk_bf16_f32 v10, v10, v10
	v_cvt_pk_bf16_f32 v13, v14, v14
	v_cvt_pk_bf16_f32 v12, v15, v15
	v_and_b32_e32 v11, 0xffff0000, v11
	v_and_b32_e32 v10, 0xffff0000, v10
	v_or_b32_sdwa v11, v11, v12 dst_sel:DWORD dst_unused:UNUSED_PAD src0_sel:DWORD src1_sel:WORD_1
	v_or_b32_sdwa v10, v10, v13 dst_sel:DWORD dst_unused:UNUSED_PAD src0_sel:DWORD src1_sel:WORD_1
	global_store_dwordx2 v[24:25], v[10:11], off offset:512
	global_load_dwordx4 v[10:13], v[36:37], off offset:2048
	s_nop 0
	global_load_dwordx4 v[14:17], v[26:27], off
	s_waitcnt vmcnt(1)
	v_pk_mul_f32 v[8:9], v[8:9], v[12:13]
	v_pk_mul_f32 v[6:7], v[6:7], v[10:11]
	s_waitcnt vmcnt(0)
	v_mov_b32_e32 v11, v16
	v_mov_b32_e32 v16, v15
	v_mov_b32_e32 v10, v14
	v_mov_b32_e32 v12, v6
	v_mov_b32_e32 v13, v8
	v_mov_b32_e32 v8, v7
	v_pk_add_f32 v[6:7], v[16:17], 1.0 op_sel_hi:[1,0]
	v_pk_add_f32 v[10:11], v[10:11], 1.0 op_sel_hi:[1,0]
	v_pk_mul_f32 v[6:7], v[8:9], v[6:7]
	v_pk_mul_f32 v[10:11], v[12:13], v[10:11]
	v_cvt_pk_bf16_f32 v7, v7, v7
	v_cvt_pk_bf16_f32 v6, v6, v6
	v_cvt_pk_bf16_f32 v9, v10, v10
	v_cvt_pk_bf16_f32 v8, v11, v11
	v_and_b32_e32 v7, 0xffff0000, v7
	v_and_b32_e32 v6, 0xffff0000, v6
	v_or_b32_sdwa v7, v7, v8 dst_sel:DWORD dst_unused:UNUSED_PAD src0_sel:DWORD src1_sel:WORD_1
	v_or_b32_sdwa v6, v6, v9 dst_sel:DWORD dst_unused:UNUSED_PAD src0_sel:DWORD src1_sel:WORD_1
	global_store_dwordx2 v[24:25], v[6:7], off offset:1024
	global_load_dwordx4 v[6:9], v[36:37], off offset:3072
	s_nop 0
	global_load_dwordx4 v[10:13], v[22:23], off
	s_waitcnt vmcnt(1)
	v_pk_mul_f32 v[4:5], v[4:5], v[8:9]
	v_pk_mul_f32 v[2:3], v[2:3], v[6:7]
	s_waitcnt vmcnt(0)
	v_mov_b32_e32 v7, v12
	v_mov_b32_e32 v12, v11
	v_mov_b32_e32 v6, v10
	v_mov_b32_e32 v8, v2
	v_mov_b32_e32 v9, v4
	v_mov_b32_e32 v4, v3
	v_pk_add_f32 v[2:3], v[12:13], 1.0 op_sel_hi:[1,0]
	v_pk_add_f32 v[6:7], v[6:7], 1.0 op_sel_hi:[1,0]
	v_pk_mul_f32 v[2:3], v[4:5], v[2:3]
	v_pk_mul_f32 v[6:7], v[8:9], v[6:7]
	v_and_b32_sdwa v8, v3, v178 dst_sel:DWORD dst_unused:UNUSED_PAD src0_sel:WORD_1 src1_sel:DWORD
	v_and_b32_sdwa v9, v2, v178 dst_sel:DWORD dst_unused:UNUSED_PAD src0_sel:WORD_1 src1_sel:DWORD
	v_and_b32_sdwa v4, v7, v178 dst_sel:DWORD dst_unused:UNUSED_PAD src0_sel:WORD_1 src1_sel:DWORD
	v_and_b32_sdwa v5, v6, v178 dst_sel:DWORD dst_unused:UNUSED_PAD src0_sel:WORD_1 src1_sel:DWORD
	v_add3_u32 v3, v3, v8, s81
	v_add3_u32 v2, v2, v9, s81
	v_add3_u32 v5, v6, v5, s81
	v_add3_u32 v4, v7, v4, s81
	v_and_b32_e32 v3, 0xffff0000, v3
	v_and_b32_e32 v2, 0xffff0000, v2
	v_or_b32_sdwa v3, v3, v4 dst_sel:DWORD dst_unused:UNUSED_PAD src0_sel:DWORD src1_sel:WORD_1
	v_or_b32_sdwa v2, v2, v5 dst_sel:DWORD dst_unused:UNUSED_PAD src0_sel:DWORD src1_sel:WORD_1
	global_store_dwordx2 v[24:25], v[2:3], off offset:1536
	s_andn2_b64 exec, exec, s[2:3]
	s_cbranch_execz .LBB0_897

; __device__ __forceinline__ unsigned pack2(float a, float b) { return (unsigned)f2bf(a) | ((unsigned)f2bf(b) << 16); }
; __device__ __forceinline__ void prep_phase(const Params& p, char* shm, const int tid) {
;     ...
;     for (int q = 0; q < 2; ++q)
; #pragma unroll
;       for (int i = 0; i < 4; ++i) v[q][i] = xr[q * 256 + lane + 64 * i];
;     const int b = row0 >> 12;
;     const float* sc = p.mod + (size_t)b * 9216 + 1024;
; #pragma unroll
;     for (int q = 0; q < 2; ++q) {
;       const int row = row0 + q;
;       float ss = 0.f;
; #pragma unroll
;       for (int i = 0; i < 4; ++i) ss += v[q][i][0] * v[q][i][0] + v[q][i][1] * v[q][i][1] + v[q][i][2] * v[q][i][2] + v[q][i][3] * v[q][i][3];
;       ss = wave_sum(ss, lane);
;       if (lane < 16) p.rowss[(size_t)row * 16 + lane] = (lane == 0) ? ss : 0.0f;
; #pragma unroll
;       for (int i = 0; i < 4; ++i) {
;         int col = (lane + 64 * i) * 4;
;         f32x4 gg = *(const f32x4*)(g + col), s4 = *(const f32x4*)(sc + col);
;         uint2 pk;
;         pk.x = pack2(v[q][i][0] * gg[0] * (1.0f + s4[0]), v[q][i][1] * gg[1] * (1.0f + s4[1]));
;         pk.y = pack2(v[q][i][2] * gg[2] * (1.0f + s4[2]), v[q][i][3] * gg[3] * (1.0f + s4[3]));
;         *(uint2*)(p.h + (size_t)row * 1024 + col) = pk;
;       }
;     }
.LBB0_895:
	s_or_b64 exec, exec, s[8:9]
	v_ashrrev_i32_e32 v45, 12, v34
	v_readlane_b32 s8, v252, 26
	v_mul_hi_i32_i24_e32 v51, 0x9000, v45
	v_mul_i32_i24_e32 v50, 0x9000, v45
	v_readlane_b32 s9, v252, 27
	v_readlane_b32 s18, v252, 36
	v_readlane_b32 s19, v252, 37
	s_mov_b64 s[8:9], 0x1000
	global_load_dwordx4 v[60:63], v[36:37], off
	v_lshl_add_u64 v[50:51], s[18:19], 0, v[50:51]
	v_lshl_add_u64 v[68:69], v[50:51], 0, s[8:9]
	v_lshl_add_u64 v[50:51], v[68:69], 0, v[0:1]
	global_load_dwordx4 v[64:67], v[50:51], off
	v_lshlrev_b64 v[52:53], 11, v[34:35]
	v_mov_b32_e32 v45, v1
	v_lshl_add_u64 v[52:53], v[42:43], 0, v[52:53]
	v_readlane_b32 s10, v252, 28
	v_readlane_b32 s11, v252, 29
	v_readlane_b32 s12, v252, 30
	v_readlane_b32 s13, v252, 31
	v_readlane_b32 s14, v252, 32
	v_readlane_b32 s15, v252, 33
	v_readlane_b32 s16, v252, 34
	v_readlane_b32 s17, v252, 35
	v_readlane_b32 s20, v252, 38
	v_readlane_b32 s21, v252, 39
	v_readlane_b32 s22, v252, 40
	v_readlane_b32 s23, v252, 41
	s_waitcnt vmcnt(1)
	v_pk_mul_f32 v[32:33], v[32:33], v[62:63]
	v_pk_mul_f32 v[30:31], v[30:31], v[60:61]
	v_mov_b32_e32 v61, v32
	v_mov_b32_e32 v32, v31
	s_waitcnt vmcnt(0)
	v_mov_b32_e32 v31, v66
	v_mov_b32_e32 v66, v65
	v_mov_b32_e32 v60, v30
	v_mov_b32_e32 v30, v64
	v_pk_add_f32 v[62:63], v[66:67], 1.0 op_sel_hi:[1,0]
	v_pk_add_f32 v[30:31], v[30:31], 1.0 op_sel_hi:[1,0]
	v_pk_mul_f32 v[32:33], v[32:33], v[62:63]
	v_pk_mul_f32 v[30:31], v[60:61], v[30:31]
	s_waitcnt lgkmcnt(0)
	v_cvt_pk_bf16_f32 v33, v33, v33
	v_cvt_pk_bf16_f32 v32, v32, v32
	v_cvt_pk_bf16_f32 v30, v30, v30
	v_cvt_pk_bf16_f32 v31, v31, v31
	v_and_b32_e32 v33, 0xffff0000, v33
	v_and_b32_e32 v32, 0xffff0000, v32
	v_or_b32_sdwa v31, v33, v31 dst_sel:DWORD dst_unused:UNUSED_PAD src0_sel:DWORD src1_sel:WORD_1
	v_or_b32_sdwa v30, v32, v30 dst_sel:DWORD dst_unused:UNUSED_PAD src0_sel:DWORD src1_sel:WORD_1
	global_store_dwordx2 v[52:53], v[30:31], off
	v_lshl_add_u64 v[30:31], v[68:69], 0, v[44:45]
	global_load_dwordx4 v[60:63], v[36:37], off offset:1024
	global_load_dwordx4 v[64:67], v[30:31], off
	v_mov_b32_e32 v47, v1
	v_mov_b32_e32 v49, v1
	s_waitcnt vmcnt(1)
	v_pk_mul_f32 v[28:29], v[28:29], v[62:63]
	v_pk_mul_f32 v[26:27], v[26:27], v[60:61]
	s_waitcnt vmcnt(0)
	v_mov_b32_e32 v33, v66
	v_mov_b32_e32 v66, v65
	v_mov_b32_e32 v32, v64
	v_mov_b32_e32 v60, v26
	v_mov_b32_e32 v61, v28
	v_mov_b32_e32 v28, v27
	v_pk_add_f32 v[26:27], v[66:67], 1.0 op_sel_hi:[1,0]
	v_pk_add_f32 v[32:33], v[32:33], 1.0 op_sel_hi:[1,0]
	v_pk_mul_f32 v[26:27], v[28:29], v[26:27]
	v_pk_mul_f32 v[32:33], v[60:61], v[32:33]
	v_and_b32_sdwa v45, v26, v178 dst_sel:DWORD dst_unused:UNUSED_PAD src0_sel:WORD_1 src1_sel:DWORD
	v_cvt_pk_bf16_f32 v27, v27, v27
	v_add3_u32 v26, v26, v45, s81
	v_cvt_pk_bf16_f32 v29, v32, v32
	v_cvt_pk_bf16_f32 v28, v33, v33
	v_and_b32_e32 v27, 0xffff0000, v27
	v_and_b32_e32 v26, 0xffff0000, v26
	v_or_b32_sdwa v27, v27, v28 dst_sel:DWORD dst_unused:UNUSED_PAD src0_sel:DWORD src1_sel:WORD_1
	v_or_b32_sdwa v26, v26, v29 dst_sel:DWORD dst_unused:UNUSED_PAD src0_sel:DWORD src1_sel:WORD_1
	global_store_dwordx2 v[52:53], v[26:27], off offset:512
	v_lshl_add_u64 v[26:27], v[68:69], 0, v[46:47]
	global_load_dwordx4 v[60:63], v[36:37], off offset:2048
	global_load_dwordx4 v[64:67], v[26:27], off
	s_waitcnt vmcnt(1)
	v_pk_mul_f32 v[24:25], v[24:25], v[62:63]
	v_pk_mul_f32 v[22:23], v[22:23], v[60:61]
	s_waitcnt vmcnt(0)
	v_mov_b32_e32 v29, v66
	v_mov_b32_e32 v66, v65
	v_mov_b32_e32 v28, v64
	v_mov_b32_e32 v32, v22
	v_mov_b32_e32 v33, v24
	v_mov_b32_e32 v24, v23
	v_pk_add_f32 v[22:23], v[66:67], 1.0 op_sel_hi:[1,0]
	v_pk_add_f32 v[28:29], v[28:29], 1.0 op_sel_hi:[1,0]
	v_pk_mul_f32 v[22:23], v[24:25], v[22:23]
	v_pk_mul_f32 v[28:29], v[32:33], v[28:29]
	v_cvt_pk_bf16_f32 v23, v23, v23
	v_cvt_pk_bf16_f32 v22, v22, v22
	v_cvt_pk_bf16_f32 v25, v28, v28
	v_cvt_pk_bf16_f32 v24, v29, v29
	v_and_b32_e32 v23, 0xffff0000, v23
	v_and_b32_e32 v22, 0xffff0000, v22
	v_or_b32_sdwa v23, v23, v24 dst_sel:DWORD dst_unused:UNUSED_PAD src0_sel:DWORD src1_sel:WORD_1
	v_or_b32_sdwa v22, v22, v25 dst_sel:DWORD dst_unused:UNUSED_PAD src0_sel:DWORD src1_sel:WORD_1
	global_store_dwordx2 v[52:53], v[22:23], off offset:1024
	v_lshl_add_u64 v[22:23], v[68:69], 0, v[48:49]
	global_load_dwordx4 v[60:63], v[36:37], off offset:3072
	global_load_dwordx4 v[64:67], v[22:23], off
	v_mul_f32_e32 v24, v15, v15
	v_mul_f32_e32 v25, v11, v11
	v_mul_f32_e32 v28, v7, v7
	v_fmac_f32_e32 v24, v14, v14
	v_fmac_f32_e32 v25, v10, v10
	v_mul_f32_e32 v29, v3, v3
	v_fmac_f32_e32 v28, v6, v6
	v_fmac_f32_e32 v24, v16, v16
	v_fmac_f32_e32 v25, v12, v12
	v_fmac_f32_e32 v29, v2, v2
	v_fmac_f32_e32 v28, v8, v8
	v_fmac_f32_e32 v24, v17, v17
	v_fmac_f32_e32 v25, v13, v13
	v_fmac_f32_e32 v29, v4, v4
	v_fmac_f32_e32 v28, v9, v9
	v_add_f32_e32 v24, v24, v25
	v_fmac_f32_e32 v29, v5, v5
	v_add_f32_e32 v24, v24, v28
	v_add_f32_e32 v24, v24, v29
	ds_bpermute_b32 v25, v54, v24
	s_waitcnt lgkmcnt(0)
	v_add_f32_e32 v24, v24, v25
	ds_bpermute_b32 v25, v55, v24
	s_waitcnt lgkmcnt(0)
	v_add_f32_e32 v24, v24, v25
	ds_bpermute_b32 v25, v56, v24
	s_waitcnt lgkmcnt(0)
	v_add_f32_e32 v24, v24, v25
	ds_bpermute_b32 v25, v57, v24
	s_waitcnt lgkmcnt(0)
	v_add_f32_e32 v25, v24, v25
	ds_bpermute_b32 v28, v58, v25
	v_add_u32_e32 v24, 1, v34
	s_waitcnt lgkmcnt(0)
	v_add_f32_e32 v28, v25, v28
	ds_bpermute_b32 v29, v59, v28
	s_waitcnt vmcnt(1)
	v_pk_mul_f32 v[20:21], v[20:21], v[62:63]
	v_pk_mul_f32 v[18:19], v[18:19], v[60:61]
	s_waitcnt vmcnt(0)
	v_mov_b32_e32 v33, v66
	v_mov_b32_e32 v66, v65
	v_mov_b32_e32 v32, v64
	v_mov_b32_e32 v60, v18
	v_mov_b32_e32 v61, v20
	v_mov_b32_e32 v20, v19
	v_pk_add_f32 v[18:19], v[66:67], 1.0 op_sel_hi:[1,0]
	v_pk_add_f32 v[32:33], v[32:33], 1.0 op_sel_hi:[1,0]
	v_pk_mul_f32 v[18:19], v[20:21], v[18:19]
	v_pk_mul_f32 v[32:33], v[60:61], v[32:33]
	v_and_b32_sdwa v35, v18, v178 dst_sel:DWORD dst_unused:UNUSED_PAD src0_sel:WORD_1 src1_sel:DWORD
	v_and_b32_sdwa v20, v33, v178 dst_sel:DWORD dst_unused:UNUSED_PAD src0_sel:WORD_1 src1_sel:DWORD
	v_and_b32_sdwa v21, v32, v178 dst_sel:DWORD dst_unused:UNUSED_PAD src0_sel:WORD_1 src1_sel:DWORD
	v_cvt_pk_bf16_f32 v19, v19, v19
	v_add3_u32 v18, v18, v35, s81
	v_add3_u32 v21, v32, v21, s81
	v_add3_u32 v20, v33, v20, s81
	v_and_b32_e32 v19, 0xffff0000, v19
	v_and_b32_e32 v18, 0xffff0000, v18
	v_or_b32_sdwa v19, v19, v20 dst_sel:DWORD dst_unused:UNUSED_PAD src0_sel:DWORD src1_sel:WORD_1
	v_or_b32_sdwa v18, v18, v21 dst_sel:DWORD dst_unused:UNUSED_PAD src0_sel:DWORD src1_sel:WORD_1
	v_ashrrev_i32_e32 v25, 31, v24
	global_store_dwordx2 v[52:53], v[18:19], off offset:1536
	s_and_saveexec_b64 s[8:9], s[6:7]
	s_cbranch_execz .LBB0_892
	v_lshlrev_b64 v[18:19], 6, v[24:25]
	s_waitcnt lgkmcnt(0)
	v_add_f32_e32 v20, v28, v29
	v_lshl_add_u64 v[18:19], v[40:41], 0, v[18:19]
	v_cndmask_b32_e64 v20, 0, v20, s[4:5]
	global_store_dword v[18:19], v20, off
	s_branch .LBB0_892

; __device__ __forceinline__ int srccol(int perm, int n) {
;   if (perm == 1) {
;     int blk = n >> 5, t = (n >> 4) & 1, i = n & 15;
;     int j = blk * 16 + i;
;     return t ? DFF + j : j;
; __device__ __forceinline__ void conv_family(const float* __restrict__ W, u16* __restrict__ Wt, int cnt, int K, int N, int perm,
;                             float* tile, const int tid, const float* __restrict__ kscale = nullptr) {
;     ...
;   for (int t = blockIdx.x; t < total; t += gridDim.x) {
;     int mi = t / per, r = t % per, kt = r / tn, ntile = r % tn;
;     const float* Ws = W + (size_t)mi * K * N;
;     u16* Wd = Wt + (size_t)mi * K * N;
;     int k0 = kt * 64, n0 = ntile * 256;
;     {
;       int n = tid & 255;
;       int sc = srccol(perm, n0 + n);
;       const float* wp = Ws + (size_t)(k0 + (tid >> 8)) * N + sc;
.LBB0_908:
	s_mul_hi_i32 s1, s0, 0x2e8ba2e9
	s_lshr_b32 s2, s1, 31
	s_ashr_i32 s1, s1, 6
	s_add_i32 s1, s1, s2
	s_mul_i32 s6, s1, 0xfffffea0
	s_mul_hi_i32 s3, s1, 0x580000
	s_mul_i32 s2, s1, 0x580000
	s_add_i32 s1, s0, s6
	s_mul_i32 s8, s1, 0xba3
	s_lshr_b32 s9, s8, 31
	s_lshr_b32 s8, s8, 16
	s_add_i32 s8, s8, s9
	s_sext_i32_i16 s9, s8
	s_mul_i32 s8, s8, 22
	s_lshl_b64 s[6:7], s[2:3], 2
	s_sub_i32 s1, s1, s8
	s_add_u32 s6, s18, s6
	s_addc_u32 s7, s19, s7
	s_lshl_b64 s[2:3], s[2:3], 1
	s_sext_i32_i16 s1, s1
	s_add_u32 s8, s66, s2
	s_addc_u32 s10, s67, s3
	s_lshl_b32 s1, s1, 8
	v_or_b32_e32 v11, s1, v3
	v_lshrrev_b32_e32 v13, 5, v3
	v_and_b32_e32 v20, 3, v13
	v_lshrrev_b32_e32 v13, 2, v13
	v_lshl_add_u32 v13, v5, 1, v13
	v_lshl_add_u32 v20, v20, 5, v13
	v_lshrrev_b32_e32 v13, 1, v11
	v_and_b32_e32 v13, 0xffffff80, v13
	v_add_u32_e32 v20, v20, v13
	s_lshl_b32 s2, s9, 6
	v_add_u32_e32 v21, 0xb00, v20
	v_mov_b64_e32 v[8:9], s[6:7]
	v_add_u32_e32 v12, s2, v4
	v_add_u32_e32 v10, s1, v7
	s_movk_i32 s1, 0x5800
	v_cndmask_b32_e64 v20, v21, v20, s[4:5]
	v_mad_i64_i32 v[16:17], s[6:7], v12, s1, v[8:9]
	v_ashrrev_i32_e32 v21, 31, v20
	v_lshl_add_u64 v[48:49], v[20:21], 2, v[16:17]
	v_add_co_u32_e32 v50, vcc, s12, v48
	s_mov_b32 s1, 0x37000
	s_nop 0
	v_addc_co_u32_e32 v51, vcc, 0, v49, vcc
	v_add_co_u32_e32 v52, vcc, s11, v48
	s_ashr_i32 s3, s2, 31
	s_nop 0
	v_addc_co_u32_e32 v53, vcc, 0, v49, vcc
	v_add_co_u32_e32 v54, vcc, s13, v48
	s_lshl_b64 s[2:3], s[2:3], 1
	s_nop 0
	v_addc_co_u32_e32 v55, vcc, 0, v49, vcc
	v_add_co_u32_e32 v56, vcc, s39, v48
	v_add_u32_e32 v8, 64, v10
	s_nop 0
	v_addc_co_u32_e32 v57, vcc, 0, v49, vcc
	v_add_co_u32_e32 v58, vcc, s1, v48
	s_mov_b32 s1, 0x4d000
	s_nop 0
	v_addc_co_u32_e32 v59, vcc, 0, v49, vcc
	v_add_co_u32_e32 v60, vcc, s14, v48
	s_add_u32 s2, s8, s2
	s_nop 0
	v_addc_co_u32_e32 v61, vcc, 0, v49, vcc
	v_add_co_u32_e32 v62, vcc, s1, v48
	s_mov_b32 s1, 0x58000
	s_nop 0
	v_addc_co_u32_e32 v63, vcc, 0, v49, vcc
	v_add_co_u32_e32 v64, vcc, s1, v48
	s_mov_b32 s1, 0x6e000
	s_nop 0
	v_addc_co_u32_e32 v65, vcc, 0, v49, vcc
	v_add_co_u32_e32 v66, vcc, s35, v48
	v_ashrrev_i32_e32 v11, 31, v10
	s_nop 0
	v_addc_co_u32_e32 v67, vcc, 0, v49, vcc
	v_add_co_u32_e32 v68, vcc, s1, v48
	s_mov_b32 s1, 0x79000
	s_nop 0
	v_addc_co_u32_e32 v69, vcc, 0, v49, vcc
	v_add_co_u32_e32 v70, vcc, s1, v48
	s_mov_b32 s1, 0x8f000
	s_nop 0
	v_addc_co_u32_e32 v71, vcc, 0, v49, vcc
	v_add_co_u32_e32 v78, vcc, s15, v48
	v_ashrrev_i32_e32 v9, 31, v8
	s_nop 0
	v_addc_co_u32_e32 v79, vcc, 0, v49, vcc
	v_add_co_u32_e32 v80, vcc, s1, v48
	s_mov_b32 s1, 0x9a000
	s_nop 0
	v_addc_co_u32_e32 v81, vcc, 0, v49, vcc
	v_add_co_u32_e32 v82, vcc, s1, v48
	s_mov_b32 s1, 0xa5000
	s_nop 0
	v_addc_co_u32_e32 v83, vcc, 0, v49, vcc
	v_add_co_u32_e32 v84, vcc, s1, v48
	s_mov_b32 s1, 0xb0000
	s_nop 0
	v_addc_co_u32_e32 v85, vcc, 0, v49, vcc
	v_add_co_u32_e32 v86, vcc, s1, v48
	s_mov_b32 s1, 0xbb000
	s_nop 0
	v_addc_co_u32_e32 v87, vcc, 0, v49, vcc
	v_add_co_u32_e32 v34, vcc, s1, v48
	s_mov_b32 s1, 0xc6000
	s_nop 0
	v_addc_co_u32_e32 v35, vcc, 0, v49, vcc
	v_add_co_u32_e32 v36, vcc, s1, v48
	s_mov_b32 s1, 0xd1000
	s_nop 0
	v_addc_co_u32_e32 v37, vcc, 0, v49, vcc
	v_add_co_u32_e32 v38, vcc, s1, v48
	s_mov_b32 s1, 0xdc000
	s_nop 0
	v_addc_co_u32_e32 v39, vcc, 0, v49, vcc
	v_add_co_u32_e32 v40, vcc, s1, v48
	s_mov_b32 s1, 0xe7000
	s_nop 0
	v_addc_co_u32_e32 v41, vcc, 0, v49, vcc
	v_add_co_u32_e32 v42, vcc, s1, v48
	s_mov_b32 s1, 0xf2000
	s_nop 0
	v_addc_co_u32_e32 v43, vcc, 0, v49, vcc
	v_add_co_u32_e32 v44, vcc, s1, v48
	s_mov_b32 s1, 0xfd000
	s_nop 0
	v_addc_co_u32_e32 v45, vcc, 0, v49, vcc
	s_addc_u32 s3, s10, s3
	v_add_co_u32_e32 v16, vcc, s1, v48
	v_add_u32_e32 v12, 0x80, v10
	v_add_u32_e32 v14, 0xc0, v10
	v_lshlrev_b64 v[10:11], 11, v[10:11]
	v_lshlrev_b64 v[18:19], 11, v[8:9]
	v_lshl_add_u64 v[22:23], s[2:3], 0, v[0:1]
	v_addc_co_u32_e32 v17, vcc, 0, v49, vcc
	v_lshl_add_u64 v[8:9], v[22:23], 0, v[10:11]
	v_lshl_add_u64 v[10:11], v[22:23], 0, v[18:19]
	v_add_co_u32_e32 v18, vcc, s16, v48
	s_mov_b32 s1, 0x113000
	s_nop 0
	v_addc_co_u32_e32 v19, vcc, 0, v49, vcc
	v_ashrrev_i32_e32 v13, 31, v12
	v_ashrrev_i32_e32 v15, 31, v14
	v_add_co_u32_e32 v20, vcc, s1, v48
	v_lshlrev_b64 v[12:13], 11, v[12:13]
	v_lshlrev_b64 v[14:15], 11, v[14:15]
	v_addc_co_u32_e32 v21, vcc, 0, v49, vcc
	s_mov_b32 s1, 0x11e000
	v_lshl_add_u64 v[12:13], v[22:23], 0, v[12:13]
	v_lshl_add_u64 v[14:15], v[22:23], 0, v[14:15]
	v_add_co_u32_e32 v22, vcc, s1, v48
	s_mov_b32 s1, 0x129000
	s_nop 0
	v_addc_co_u32_e32 v23, vcc, 0, v49, vcc
	v_add_co_u32_e32 v24, vcc, s1, v48
	s_mov_b32 s1, 0x134000
	s_nop 0
	v_addc_co_u32_e32 v25, vcc, 0, v49, vcc
	v_add_co_u32_e32 v26, vcc, s1, v48
	s_mov_b32 s1, 0x13f000
	s_nop 0
	v_addc_co_u32_e32 v27, vcc, 0, v49, vcc
	v_add_co_u32_e32 v28, vcc, s1, v48
	s_mov_b32 s1, 0x14a000
	s_waitcnt lgkmcnt(0)
; __device__ __forceinline__ void conv_family(const float* __restrict__ W, u16* __restrict__ Wt, int cnt, int K, int N, int perm,
;                             float* tile, const int tid, const float* __restrict__ kscale = nullptr) {
;     ...
;       float v[32];
; #pragma unroll
;       for (int i = 0; i < 32; ++i) v[i] = wp[(size_t)(2 * i) * N];
;       if (kscale) {
;         const float* ks = kscale + (size_t)mi * K + k0 + (tid >> 8);
; #pragma unroll
;         for (int i = 0; i < 32; ++i) v[i] *= ks[2 * i];
;       }
; #pragma unroll
;       for (int i = 0; i < 32; ++i) tile[(2 * i + (tid >> 8)) * 257 + n] = v[i];
;     }
;     __syncthreads();
	v_addc_co_u32_e32 v29, vcc, 0, v49, vcc
	v_add_co_u32_e32 v30, vcc, s1, v48
	s_mov_b32 s1, 0x155000
	s_nop 0
	v_addc_co_u32_e32 v31, vcc, 0, v49, vcc
	v_add_co_u32_e32 v32, vcc, s1, v48
	s_add_i32 s0, s0, s44
	s_nop 0
	v_addc_co_u32_e32 v33, vcc, 0, v49, vcc
	global_load_dword v48, v[48:49], off
	s_nop 0
	global_load_dword v49, v[50:51], off
	s_nop 0
	global_load_dword v50, v[52:53], off
	global_load_dword v51, v[54:55], off
	s_nop 0
	global_load_dword v52, v[56:57], off
	global_load_dword v53, v[58:59], off
	global_load_dword v54, v[60:61], off
	global_load_dword v55, v[62:63], off
	s_nop 0
	global_load_dword v56, v[64:65], off
	global_load_dword v57, v[66:67], off
	global_load_dword v58, v[68:69], off
	global_load_dword v59, v[70:71], off
	global_load_dword v60, v[78:79], off
	global_load_dword v61, v[80:81], off
	global_load_dword v62, v[82:83], off
	global_load_dword v63, v[84:85], off
	global_load_dword v64, v[86:87], off
	global_load_dword v66, v[34:35], off
	global_load_dword v67, v[36:37], off
	global_load_dword v68, v[38:39], off
	v_add_u32_e32 v65, 4, v46
	global_load_dword v40, v[40:41], off
	v_add_u32_e32 v34, 8, v46
	global_load_dword v41, v[42:43], off
	v_add_u32_e32 v35, 12, v46
	global_load_dword v42, v[44:45], off
	s_nop 0
	global_load_dword v16, v[16:17], off
	s_nop 0
	global_load_dword v17, v[18:19], off
	s_nop 0
	global_load_dword v18, v[20:21], off
	global_load_dword v19, v[22:23], off
	s_nop 0
	global_load_dword v20, v[24:25], off
	global_load_dword v21, v[26:27], off
	global_load_dword v22, v[28:29], off
	global_load_dword v23, v[30:31], off
	s_nop 0
	global_load_dword v24, v[32:33], off
	v_add_u32_e32 v36, 16, v46
	v_add_u32_e32 v37, 20, v46
	v_add_u32_e32 v38, 24, v46
	v_add_u32_e32 v39, 28, v46
	s_waitcnt vmcnt(31)
	ds_write_b32 v47, v48
	s_waitcnt vmcnt(30)
	ds_write_b32 v47, v49 offset:2056
	s_waitcnt vmcnt(29)
	ds_write_b32 v47, v50 offset:4112
	s_waitcnt vmcnt(28)
	ds_write_b32 v47, v51 offset:6168
	s_waitcnt vmcnt(27)
	ds_write_b32 v47, v52 offset:8224
	s_waitcnt vmcnt(26)
	ds_write_b32 v47, v53 offset:10280
	s_waitcnt vmcnt(25)
	ds_write_b32 v47, v54 offset:12336
	s_waitcnt vmcnt(24)
	ds_write_b32 v47, v55 offset:14392
	s_waitcnt vmcnt(23)
	ds_write_b32 v47, v56 offset:16448
	s_waitcnt vmcnt(22)
	ds_write_b32 v47, v57 offset:18504
	s_waitcnt vmcnt(21)
	ds_write_b32 v47, v58 offset:20560
	s_waitcnt vmcnt(20)
	ds_write_b32 v47, v59 offset:22616
	s_waitcnt vmcnt(19)
	ds_write_b32 v47, v60 offset:24672
	s_waitcnt vmcnt(18)
	ds_write_b32 v47, v61 offset:26728
	s_waitcnt vmcnt(17)
	ds_write_b32 v47, v62 offset:28784
	s_waitcnt vmcnt(16)
	ds_write_b32 v47, v63 offset:30840
	s_waitcnt vmcnt(15)
	ds_write_b32 v47, v64 offset:32896
	s_waitcnt vmcnt(14)
	ds_write_b32 v47, v66 offset:34952
	s_waitcnt vmcnt(13)
	ds_write_b32 v47, v67 offset:37008
	s_waitcnt vmcnt(12)
	ds_write_b32 v47, v68 offset:39064
	s_waitcnt vmcnt(11)
	ds_write_b32 v47, v40 offset:41120
	s_waitcnt vmcnt(10)
	ds_write_b32 v47, v41 offset:43176
	s_waitcnt vmcnt(9)
	ds_write_b32 v47, v42 offset:45232
	s_waitcnt vmcnt(8)
	ds_write_b32 v47, v16 offset:47288
	s_waitcnt vmcnt(7)
	ds_write_b32 v47, v17 offset:49344
	s_waitcnt vmcnt(6)
	ds_write_b32 v47, v18 offset:51400
	s_waitcnt vmcnt(5)
	ds_write_b32 v47, v19 offset:53456
	s_waitcnt vmcnt(4)
	ds_write_b32 v47, v20 offset:55512
	s_waitcnt vmcnt(3)
	ds_write_b32 v47, v21 offset:57568
	s_waitcnt vmcnt(2)
	ds_write_b32 v47, v22 offset:59624
	s_waitcnt vmcnt(1)
	ds_write_b32 v47, v23 offset:61680
	s_waitcnt vmcnt(0)
	ds_write_b32 v47, v24 offset:63736
	s_waitcnt lgkmcnt(0)
	s_barrier
; __device__ __forceinline__ unsigned pack2(float a, float b) { return (unsigned)f2bf(a) | ((unsigned)f2bf(b) << 16); }
; __device__ __forceinline__ void conv_family(const float* __restrict__ W, u16* __restrict__ Wt, int cnt, int K, int N, int perm,
;                             float* tile, const int tid, const float* __restrict__ kscale = nullptr) {
;     ...
; #pragma unroll
;     for (int i = 0; i < 4; ++i) {
;       int n = i * 64 + (tid >> 3), ks = (tid & 7) * 8;
;       uint4 pk;
;       pk.x = pack2(tile[(ks + 0) * 257 + n], tile[(ks + 1) * 257 + n]);
;       pk.y = pack2(tile[(ks + 2) * 257 + n], tile[(ks + 3) * 257 + n]);
;       pk.z = pack2(tile[(ks + 4) * 257 + n], tile[(ks + 5) * 257 + n]);
;       pk.w = pack2(tile[(ks + 6) * 257 + n], tile[(ks + 7) * 257 + n]);
;       *(uint4*)(Wd + (size_t)(n0 + n) * K + k0 + ks) = pk;
;     }
;     __syncthreads();
;   }
	ds_read2st64_b32 v[16:17], v46 offset1:1
	ds_read2st64_b32 v[18:19], v46 offset0:2 offset1:3
	ds_read2st64_b32 v[20:21], v65 offset0:4 offset1:5
	ds_read2st64_b32 v[22:23], v65 offset0:6 offset1:7
	ds_read2st64_b32 v[24:25], v34 offset0:8 offset1:9
	ds_read2st64_b32 v[26:27], v34 offset0:10 offset1:11
	ds_read2st64_b32 v[28:29], v35 offset0:12 offset1:13
	ds_read2st64_b32 v[30:31], v35 offset0:14 offset1:15
	ds_read2st64_b32 v[32:33], v36 offset0:16 offset1:17
	ds_read2st64_b32 v[34:35], v36 offset0:18 offset1:19
	ds_read2st64_b32 v[40:41], v37 offset0:20 offset1:21
	ds_read2st64_b32 v[36:37], v37 offset0:22 offset1:23
	ds_read2st64_b32 v[42:43], v38 offset0:24 offset1:25
	ds_read2st64_b32 v[44:45], v38 offset0:26 offset1:27
	ds_read2st64_b32 v[48:49], v39 offset0:28 offset1:29
	ds_read2st64_b32 v[38:39], v39 offset0:30 offset1:31
	s_waitcnt lgkmcnt(11)
	s_waitcnt lgkmcnt(9)
	s_waitcnt lgkmcnt(3)
	v_and_b32_sdwa v54, v42, v178 dst_sel:DWORD dst_unused:UNUSED_PAD src0_sel:WORD_1 src1_sel:DWORD
	v_and_b32_sdwa v55, v32, v178 dst_sel:DWORD dst_unused:UNUSED_PAD src0_sel:WORD_1 src1_sel:DWORD
	s_waitcnt lgkmcnt(1)
	v_and_b32_sdwa v59, v17, v178 dst_sel:DWORD dst_unused:UNUSED_PAD src0_sel:WORD_1 src1_sel:DWORD
	v_and_b32_sdwa v62, v43, v178 dst_sel:DWORD dst_unused:UNUSED_PAD src0_sel:WORD_1 src1_sel:DWORD
	v_and_b32_sdwa v63, v33, v178 dst_sel:DWORD dst_unused:UNUSED_PAD src0_sel:WORD_1 src1_sel:DWORD
	v_cvt_pk_bf16_f32 v16, v16, v16
	v_add3_u32 v51, v17, v59, s81
	v_and_b32_sdwa v59, v18, v178 dst_sel:DWORD dst_unused:UNUSED_PAD src0_sel:WORD_1 src1_sel:DWORD
	v_cvt_pk_bf16_f32 v24, v24, v24
	v_cvt_pk_bf16_f32 v25, v25, v25
	v_and_b32_sdwa v58, v22, v178 dst_sel:DWORD dst_unused:UNUSED_PAD src0_sel:WORD_1 src1_sel:DWORD
	v_cvt_pk_bf16_f32 v28, v28, v28
	v_cvt_pk_bf16_f32 v29, v29, v29
	v_and_b32_sdwa v52, v44, v178 dst_sel:DWORD dst_unused:UNUSED_PAD src0_sel:WORD_1 src1_sel:DWORD
	v_and_b32_sdwa v60, v34, v178 dst_sel:DWORD dst_unused:UNUSED_PAD src0_sel:WORD_1 src1_sel:DWORD
	v_cvt_pk_bf16_f32 v20, v20, v20
	v_cvt_pk_bf16_f32 v21, v21, v21
	s_waitcnt lgkmcnt(0)
	v_and_b32_sdwa v61, v36, v178 dst_sel:DWORD dst_unused:UNUSED_PAD src0_sel:WORD_1 src1_sel:DWORD
	v_add3_u32 v32, v32, v55, s81
	v_add3_u32 v33, v33, v63, s81
	v_and_b32_sdwa v55, v27, v178 dst_sel:DWORD dst_unused:UNUSED_PAD src0_sel:WORD_1 src1_sel:DWORD
	v_and_b32_sdwa v63, v19, v178 dst_sel:DWORD dst_unused:UNUSED_PAD src0_sel:WORD_1 src1_sel:DWORD
	v_add3_u32 v42, v42, v54, s81
	v_add3_u32 v43, v43, v62, s81
	v_and_b32_sdwa v62, v23, v178 dst_sel:DWORD dst_unused:UNUSED_PAD src0_sel:WORD_1 src1_sel:DWORD
	v_cvt_pk_bf16_f32 v48, v48, v48
	v_cvt_pk_bf16_f32 v40, v40, v40
	v_cvt_pk_bf16_f32 v41, v41, v41
	v_and_b32_sdwa v57, v39, v178 dst_sel:DWORD dst_unused:UNUSED_PAD src0_sel:WORD_1 src1_sel:DWORD
	v_and_b32_sdwa v65, v37, v178 dst_sel:DWORD dst_unused:UNUSED_PAD src0_sel:WORD_1 src1_sel:DWORD
	v_cvt_pk_bf16_f32 v49, v49, v49
	v_and_b32_sdwa v56, v45, v178 dst_sel:DWORD dst_unused:UNUSED_PAD src0_sel:WORD_1 src1_sel:DWORD
	v_and_b32_sdwa v64, v35, v178 dst_sel:DWORD dst_unused:UNUSED_PAD src0_sel:WORD_1 src1_sel:DWORD
	v_add3_u32 v59, v18, v59, s81
	v_cvt_pk_bf16_f32 v26, v26, v26
	v_cvt_pk_bf16_f32 v17, v30, v30
	v_add3_u32 v18, v22, v58, s81
	v_add3_u32 v30, v34, v60, s81
	v_add3_u32 v34, v44, v52, s81
	v_cvt_pk_bf16_f32 v22, v38, v38
	v_add3_u32 v36, v36, v61, s81
	v_add3_u32 v38, v19, v63, s81
	v_add3_u32 v44, v27, v55, s81
	v_cvt_pk_bf16_f32 v19, v31, v31
	v_add3_u32 v23, v23, v62, s81
	v_add3_u32 v27, v39, v57, s81
	v_add3_u32 v37, v37, v65, s81
	v_and_b32_e32 v28, 0xffff0000, v28
	v_and_b32_e32 v20, 0xffff0000, v20
	v_and_b32_e32 v39, 0xffff0000, v48
	v_and_b32_e32 v40, 0xffff0000, v40
	s_cmpk_lt_i32 s0, 0xb00
	v_add3_u32 v35, v35, v64, s81
	v_add3_u32 v31, v45, v56, s81
	v_and_b32_e32 v29, 0xffff0000, v29
	v_and_b32_e32 v45, 0xffff0000, v21
	v_and_b32_e32 v48, 0xffff0000, v49
	v_and_b32_e32 v41, 0xffff0000, v41
	v_and_b32_e32 v49, 0xffff0000, v17
	v_and_b32_e32 v50, 0xffff0000, v18
	v_and_b32_e32 v52, 0xffff0000, v22
	v_and_b32_e32 v36, 0xffff0000, v36
	v_and_b32_e32 v53, 0xffff0000, v19
	v_and_b32_e32 v54, 0xffff0000, v23
	v_and_b32_e32 v55, 0xffff0000, v27
	v_and_b32_e32 v37, 0xffff0000, v37
	v_or_b32_sdwa v17, v28, v24 dst_sel:DWORD dst_unused:UNUSED_PAD src0_sel:DWORD src1_sel:WORD_1
	v_or_b32_sdwa v16, v20, v16 dst_sel:DWORD dst_unused:UNUSED_PAD src0_sel:DWORD src1_sel:WORD_1
	v_or_b32_sdwa v19, v39, v42 dst_sel:DWORD dst_unused:UNUSED_PAD src0_sel:DWORD src1_sel:WORD_1
	v_or_b32_sdwa v18, v40, v32 dst_sel:DWORD dst_unused:UNUSED_PAD src0_sel:DWORD src1_sel:WORD_1
	v_or_b32_sdwa v21, v29, v25 dst_sel:DWORD dst_unused:UNUSED_PAD src0_sel:DWORD src1_sel:WORD_1
	v_or_b32_sdwa v20, v45, v51 dst_sel:DWORD dst_unused:UNUSED_PAD src0_sel:DWORD src1_sel:WORD_1
	v_or_b32_sdwa v23, v48, v43 dst_sel:DWORD dst_unused:UNUSED_PAD src0_sel:DWORD src1_sel:WORD_1
	v_or_b32_sdwa v22, v41, v33 dst_sel:DWORD dst_unused:UNUSED_PAD src0_sel:DWORD src1_sel:WORD_1
	v_or_b32_sdwa v25, v49, v26 dst_sel:DWORD dst_unused:UNUSED_PAD src0_sel:DWORD src1_sel:WORD_1
	v_or_b32_sdwa v24, v50, v59 dst_sel:DWORD dst_unused:UNUSED_PAD src0_sel:DWORD src1_sel:WORD_1
	v_or_b32_sdwa v27, v52, v34 dst_sel:DWORD dst_unused:UNUSED_PAD src0_sel:DWORD src1_sel:WORD_1
	v_or_b32_sdwa v26, v36, v30 dst_sel:DWORD dst_unused:UNUSED_PAD src0_sel:DWORD src1_sel:WORD_1
	v_or_b32_sdwa v29, v53, v44 dst_sel:DWORD dst_unused:UNUSED_PAD src0_sel:DWORD src1_sel:WORD_1
	v_or_b32_sdwa v28, v54, v38 dst_sel:DWORD dst_unused:UNUSED_PAD src0_sel:DWORD src1_sel:WORD_1
	v_or_b32_sdwa v31, v55, v31 dst_sel:DWORD dst_unused:UNUSED_PAD src0_sel:DWORD src1_sel:WORD_1
	v_or_b32_sdwa v30, v37, v35 dst_sel:DWORD dst_unused:UNUSED_PAD src0_sel:DWORD src1_sel:WORD_1
	global_store_dwordx4 v[8:9], v[16:19], off
	global_store_dwordx4 v[10:11], v[20:23], off
	global_store_dwordx4 v[12:13], v[24:27], off
	global_store_dwordx4 v[14:15], v[28:31], off
	s_barrier
	s_cbranch_scc1 .LBB0_908

; __device__ __forceinline__ int srccol(int perm, int n) {
;     ...
;     int grp = n >> 5, t = (n >> 4) & 1, i = n & 15;
;     return grp * 32 + 2 * i + t;
; __device__ __forceinline__ void conv_family(const float* __restrict__ W, u16* __restrict__ Wt, int cnt, int K, int N, int perm,
;                             float* tile, const int tid, const float* __restrict__ kscale = nullptr) {
;     ...
;   for (int t = blockIdx.x; t < total; t += gridDim.x) {
;     int mi = t / per, r = t % per, kt = r / tn, ntile = r % tn;
;     const float* Ws = W + (size_t)mi * K * N;
;     u16* Wd = Wt + (size_t)mi * K * N;
;     int k0 = kt * 64, n0 = ntile * 256;
;     {
;       int n = tid & 255;
;       int sc = srccol(perm, n0 + n);
;       const float* wp = Ws + (size_t)(k0 + (tid >> 8)) * N + sc;
;       float v[32];
; #pragma unroll
;       for (int i = 0; i < 32; ++i) v[i] = wp[(size_t)(2 * i) * N];
;       if (kscale) {
;         const float* ks = kscale + (size_t)mi * K + k0 + (tid >> 8);
; #pragma unroll
;         for (int i = 0; i < 32; ++i) v[i] *= ks[2 * i];
;       }
; #pragma unroll
;       for (int i = 0; i < 32; ++i) tile[(2 * i + (tid >> 8)) * 257 + n] = v[i];
;     }
;     __syncthreads();
.LBB0_911:
	s_mul_hi_i32 s0, s4, 0x2e8ba2e9
	s_lshr_b32 s1, s0, 31
	s_ashr_i32 s0, s0, 5
	s_add_i32 s0, s0, s1
	s_mul_i32 s1, s0, 0xffffff50
	s_add_i32 s1, s4, s1
	s_bfe_u32 s2, s1, 0x2001d
	s_add_i32 s2, s1, s2
	s_sext_i32_i16 s5, s2
	s_and_b32 s2, s2, 0xfffc
	s_sub_i32 s1, s1, s2
	s_sext_i32_i16 s8, s1
	s_mul_hi_i32 s1, s0, 0x2c0000
	s_mul_i32 s0, s0, 0x2c0000
	s_lshl_b64 s[2:3], s[0:1], 2
	s_add_u32 s2, s20, s2
	s_addc_u32 s3, s21, s3
	s_lshl_b64 s[0:1], s[0:1], 1
	s_add_u32 s6, s52, s0
	s_addc_u32 s7, s53, s1
	s_lshl_b32 s0, s5, 4
	s_andn2_b32 s0, s0, 63
	s_lshl_b32 s5, s8, 8
	v_lshlrev_b32_e32 v9, 1, v3
	v_add_u32_e32 v10, s0, v4
	v_bitop3_b32 v8, s5, v43, v3 bitop3:0xc8
	v_and_b32_e32 v9, 30, v9
	v_ashrrev_i32_e32 v11, 31, v10
	v_or3_b32 v8, v8, v75, v9
	v_lshlrev_b64 v[10:11], 12, v[10:11]
	v_lshl_add_u64 v[10:11], s[2:3], 0, v[10:11]
	v_ashrrev_i32_e32 v9, 31, v8
	v_lshl_add_u64 v[8:9], v[8:9], 2, v[10:11]
	v_add_co_u32_e32 v10, vcc, s10, v8
	global_load_dword v12, v[8:9], off
	s_nop 0
	v_addc_co_u32_e32 v11, vcc, 0, v9, vcc
	global_load_dword v13, v[10:11], off
	v_add_co_u32_e32 v10, vcc, s14, v8
	s_ashr_i32 s1, s0, 31
	s_nop 0
	v_addc_co_u32_e32 v11, vcc, 0, v9, vcc
	global_load_dword v14, v[10:11], off
	v_add_co_u32_e32 v10, vcc, s15, v8
	s_lshl_b64 s[0:1], s[0:1], 1
	s_nop 0
	v_addc_co_u32_e32 v11, vcc, 0, v9, vcc
	global_load_dword v15, v[10:11], off
	v_add_co_u32_e32 v10, vcc, s84, v8
	s_add_u32 s0, s6, s0
	s_nop 0
	v_addc_co_u32_e32 v11, vcc, 0, v9, vcc
	global_load_dword v16, v[10:11], off
	v_add_co_u32_e32 v10, vcc, s18, v8
	s_addc_u32 s1, s7, s1
	s_nop 0
	v_addc_co_u32_e32 v11, vcc, 0, v9, vcc
	global_load_dword v17, v[10:11], off
	v_add_co_u32_e32 v10, vcc, s22, v8
	s_add_i32 s4, s4, s44
	s_nop 0
	v_addc_co_u32_e32 v11, vcc, 0, v9, vcc
	global_load_dword v18, v[10:11], off
	v_add_co_u32_e32 v10, vcc, s23, v8
	s_cmpk_lt_i32 s4, 0x580
	s_nop 0
	v_addc_co_u32_e32 v11, vcc, 0, v9, vcc
	global_load_dword v19, v[10:11], off
	v_add_co_u32_e32 v10, vcc, s11, v8
	s_nop 1
	v_addc_co_u32_e32 v11, vcc, 0, v9, vcc
	global_load_dword v20, v[10:11], off
	v_add_co_u32_e32 v10, vcc, s95, v8
	s_nop 1
	v_addc_co_u32_e32 v11, vcc, 0, v9, vcc
	global_load_dword v21, v[10:11], off
	v_add_co_u32_e32 v10, vcc, s12, v8
	s_nop 1
	v_addc_co_u32_e32 v11, vcc, 0, v9, vcc
	global_load_dword v22, v[10:11], off
	v_add_co_u32_e32 v10, vcc, s13, v8
	s_nop 1
	v_addc_co_u32_e32 v11, vcc, 0, v9, vcc
	global_load_dword v23, v[10:11], off
	v_add_co_u32_e32 v10, vcc, s16, v8
	s_nop 1
	v_addc_co_u32_e32 v11, vcc, 0, v9, vcc
	global_load_dword v24, v[10:11], off
	v_add_co_u32_e32 v10, vcc, s17, v8
	s_nop 1
	v_addc_co_u32_e32 v11, vcc, 0, v9, vcc
	global_load_dword v25, v[10:11], off
	v_add_co_u32_e32 v10, vcc, s19, v8
	s_nop 1
	v_addc_co_u32_e32 v11, vcc, 0, v9, vcc
	global_load_dword v27, v[10:11], off
	v_add_co_u32_e32 v10, vcc, s38, v8
	s_nop 1
	v_addc_co_u32_e32 v11, vcc, 0, v9, vcc
	global_load_dword v28, v[10:11], off
	v_add_co_u32_e32 v10, vcc, s24, v8
	s_nop 1
	v_addc_co_u32_e32 v11, vcc, 0, v9, vcc
	s_waitcnt lgkmcnt(0)
	global_load_dword v29, v[10:11], off
	v_add_co_u32_e32 v10, vcc, s40, v8
	s_nop 1
	v_addc_co_u32_e32 v11, vcc, 0, v9, vcc
	global_load_dword v30, v[10:11], off
	v_add_co_u32_e32 v10, vcc, s30, v8
	s_nop 1
	v_addc_co_u32_e32 v11, vcc, 0, v9, vcc
	global_load_dword v31, v[10:11], off
	v_add_co_u32_e32 v10, vcc, s41, v8
	s_nop 1
	v_addc_co_u32_e32 v11, vcc, 0, v9, vcc
	global_load_dword v32, v[10:11], off
	v_add_co_u32_e32 v10, vcc, s25, v8
	s_nop 1
	v_addc_co_u32_e32 v11, vcc, 0, v9, vcc
	global_load_dword v33, v[10:11], off
	v_add_co_u32_e32 v10, vcc, s43, v8
	s_nop 1
	v_addc_co_u32_e32 v11, vcc, 0, v9, vcc
	global_load_dword v34, v[10:11], off
	v_add_co_u32_e32 v10, vcc, s39, v8
	s_nop 1
	v_addc_co_u32_e32 v11, vcc, 0, v9, vcc
	global_load_dword v35, v[10:11], off
	v_add_co_u32_e32 v10, vcc, s48, v8
	s_nop 1
	v_addc_co_u32_e32 v11, vcc, 0, v9, vcc
	global_load_dword v36, v[10:11], off
	v_add_co_u32_e32 v10, vcc, s56, v8
	s_nop 1
	v_addc_co_u32_e32 v11, vcc, 0, v9, vcc
	global_load_dword v37, v[10:11], off
	v_add_co_u32_e32 v10, vcc, s54, v8
	s_nop 1
	v_addc_co_u32_e32 v11, vcc, 0, v9, vcc
	global_load_dword v38, v[10:11], off
	v_add_co_u32_e32 v10, vcc, s55, v8
	s_nop 1
	v_addc_co_u32_e32 v11, vcc, 0, v9, vcc
	global_load_dword v39, v[10:11], off
	v_add_co_u32_e32 v10, vcc, s96, v8
	s_nop 1
	v_addc_co_u32_e32 v11, vcc, 0, v9, vcc
	global_load_dword v40, v[10:11], off
	v_add_co_u32_e32 v10, vcc, s57, v8
	s_nop 1
	v_addc_co_u32_e32 v11, vcc, 0, v9, vcc
	global_load_dword v41, v[10:11], off
	v_add_co_u32_e32 v10, vcc, s26, v8
	s_nop 1
	v_addc_co_u32_e32 v11, vcc, 0, v9, vcc
	global_load_dword v42, v[10:11], off
	v_add_co_u32_e32 v10, vcc, s27, v8
	s_nop 1
	v_addc_co_u32_e32 v11, vcc, 0, v9, vcc
	v_add_co_u32_e32 v8, vcc, s36, v8
	global_load_dword v10, v[10:11], off
	s_nop 0
	v_addc_co_u32_e32 v9, vcc, 0, v9, vcc
	global_load_dword v8, v[8:9], off
	s_waitcnt vmcnt(31)
	ds_write_b32 v26, v12
	s_waitcnt vmcnt(30)
	ds_write_b32 v26, v13 offset:2056
	s_waitcnt vmcnt(29)
	ds_write_b32 v26, v14 offset:4112
	s_waitcnt vmcnt(28)
	ds_write_b32 v26, v15 offset:6168
	s_waitcnt vmcnt(27)
	ds_write_b32 v26, v16 offset:8224
	s_waitcnt vmcnt(26)
	ds_write_b32 v26, v17 offset:10280
	s_waitcnt vmcnt(25)
	ds_write_b32 v26, v18 offset:12336
	s_waitcnt vmcnt(24)
	ds_write_b32 v26, v19 offset:14392
	s_waitcnt vmcnt(23)
	ds_write_b32 v26, v20 offset:16448
	s_waitcnt vmcnt(22)
	ds_write_b32 v26, v21 offset:18504
	s_waitcnt vmcnt(21)
	ds_write_b32 v26, v22 offset:20560
	s_waitcnt vmcnt(20)
	ds_write_b32 v26, v23 offset:22616
	s_waitcnt vmcnt(19)
	ds_write_b32 v26, v24 offset:24672
	s_waitcnt vmcnt(18)
	ds_write_b32 v26, v25 offset:26728
	s_waitcnt vmcnt(17)
	ds_write_b32 v26, v27 offset:28784
	s_waitcnt vmcnt(16)
	ds_write_b32 v26, v28 offset:30840
	s_waitcnt vmcnt(15)
	ds_write_b32 v26, v29 offset:32896
	s_waitcnt vmcnt(14)
	ds_write_b32 v26, v30 offset:34952
	s_waitcnt vmcnt(13)
	ds_write_b32 v26, v31 offset:37008
	s_waitcnt vmcnt(12)
	ds_write_b32 v26, v32 offset:39064
	s_waitcnt vmcnt(11)
	ds_write_b32 v26, v33 offset:41120
	s_waitcnt vmcnt(10)
	ds_write_b32 v26, v34 offset:43176
	s_waitcnt vmcnt(9)
	ds_write_b32 v26, v35 offset:45232
	s_waitcnt vmcnt(8)
	ds_write_b32 v26, v36 offset:47288
	s_waitcnt vmcnt(7)
	ds_write_b32 v26, v37 offset:49344
	s_waitcnt vmcnt(6)
	ds_write_b32 v26, v38 offset:51400
	s_waitcnt vmcnt(5)
	ds_write_b32 v26, v39 offset:53456
	s_waitcnt vmcnt(4)
	ds_write_b32 v26, v40 offset:55512
	s_waitcnt vmcnt(3)
	ds_write_b32 v26, v41 offset:57568
	s_waitcnt vmcnt(2)
	ds_write_b32 v26, v42 offset:59624
	s_waitcnt vmcnt(1)
	ds_write_b32 v26, v10 offset:61680
	s_waitcnt vmcnt(0)
	ds_write_b32 v26, v8 offset:63736
	v_add_u32_e32 v34, 8, v5
	s_waitcnt lgkmcnt(0)
	s_barrier
; __device__ __forceinline__ unsigned pack2(float a, float b) { return (unsigned)f2bf(a) | ((unsigned)f2bf(b) << 16); }
; __device__ __forceinline__ void conv_family(const float* __restrict__ W, u16* __restrict__ Wt, int cnt, int K, int N, int perm,
;                             float* tile, const int tid, const float* __restrict__ kscale = nullptr) {
;     ...
; #pragma unroll
;     for (int i = 0; i < 4; ++i) {
;       int n = i * 64 + (tid >> 3), ks = (tid & 7) * 8;
;       uint4 pk;
;       pk.x = pack2(tile[(ks + 0) * 257 + n], tile[(ks + 1) * 257 + n]);
;       pk.y = pack2(tile[(ks + 2) * 257 + n], tile[(ks + 3) * 257 + n]);
;       pk.z = pack2(tile[(ks + 4) * 257 + n], tile[(ks + 5) * 257 + n]);
;       pk.w = pack2(tile[(ks + 6) * 257 + n], tile[(ks + 7) * 257 + n]);
;       *(uint4*)(Wd + (size_t)(n0 + n) * K + k0 + ks) = pk;
;     }
;     __syncthreads();
;   }
	ds_read2st64_b32 v[14:15], v34 offset0:8 offset1:9
	v_add_u32_e32 v35, 12, v5
	ds_read2st64_b32 v[10:11], v5 offset1:1
	v_add_u32_e32 v27, 4, v5
	ds_read2st64_b32 v[16:17], v35 offset0:12 offset1:13
	ds_read2st64_b32 v[12:13], v27 offset0:4 offset1:5
	v_add_u32_e32 v37, 20, v5
	v_add_u32_e32 v36, 16, v5
	ds_read2st64_b32 v[20:21], v37 offset0:20 offset1:21
	v_add_u32_e32 v39, 28, v5
	ds_read2st64_b32 v[18:19], v36 offset0:16 offset1:17
	v_add_u32_e32 v38, 24, v5
	ds_read2st64_b32 v[24:25], v39 offset0:28 offset1:29
	s_waitcnt lgkmcnt(6)
	ds_read2st64_b32 v[22:23], v38 offset0:24 offset1:25
	s_waitcnt lgkmcnt(6)
	v_cvt_pk_bf16_f32 v14, v14, v14
	s_waitcnt lgkmcnt(5)
	v_cvt_pk_bf16_f32 v10, v10, v10
	s_waitcnt lgkmcnt(4)
	v_cvt_pk_bf16_f32 v16, v16, v16
	v_cvt_pk_bf16_f32 v12, v12, v12
	v_and_b32_e32 v16, 0xffff0000, v16
	v_and_b32_e32 v12, 0xffff0000, v12
	v_or_b32_sdwa v29, v16, v14 dst_sel:DWORD dst_unused:UNUSED_PAD src0_sel:DWORD src1_sel:WORD_1
	s_waitcnt lgkmcnt(3)
	v_or_b32_sdwa v28, v12, v10 dst_sel:DWORD dst_unused:UNUSED_PAD src0_sel:DWORD src1_sel:WORD_1
	s_waitcnt lgkmcnt(2)
	s_waitcnt lgkmcnt(1)
	v_cvt_pk_bf16_f32 v16, v20, v20
	s_waitcnt lgkmcnt(0)
	v_cvt_pk_bf16_f32 v12, v18, v18
	v_cvt_pk_bf16_f32 v14, v24, v24
	v_and_b32_e32 v16, 0xffff0000, v16
	v_lshl_add_u64 v[8:9], s[0:1], 0, v[0:1]
	v_add_u32_e32 v40, s5, v7
	v_cvt_pk_bf16_f32 v10, v22, v22
	v_and_b32_e32 v14, 0xffff0000, v14
	v_or_b32_sdwa v30, v16, v12 dst_sel:DWORD dst_unused:UNUSED_PAD src0_sel:DWORD src1_sel:WORD_1
	s_nop 0
	v_mad_i64_i32 v[32:33], s[0:1], v40, s9, v[8:9]
	v_or_b32_sdwa v31, v14, v10 dst_sel:DWORD dst_unused:UNUSED_PAD src0_sel:DWORD src1_sel:WORD_1
	v_add_u32_e32 v10, 64, v40
	v_cvt_pk_bf16_f32 v12, v11, v11
	s_nop 0
	s_nop 0
	global_store_dwordx4 v[32:33], v[28:31], off
	v_cvt_pk_bf16_f32 v11, v17, v17
	v_cvt_pk_bf16_f32 v13, v13, v13
	v_mad_i64_i32 v[28:29], s[0:1], v10, s9, v[8:9]
	s_nop 0
	v_cvt_pk_bf16_f32 v10, v15, v15
	v_and_b32_e32 v11, 0xffff0000, v11
	v_and_b32_e32 v13, 0xffff0000, v13
	v_or_b32_sdwa v11, v11, v10 dst_sel:DWORD dst_unused:UNUSED_PAD src0_sel:DWORD src1_sel:WORD_1
	v_or_b32_sdwa v10, v13, v12 dst_sel:DWORD dst_unused:UNUSED_PAD src0_sel:DWORD src1_sel:WORD_1
	v_cvt_pk_bf16_f32 v14, v19, v19
	v_cvt_pk_bf16_f32 v13, v25, v25
	v_cvt_pk_bf16_f32 v15, v21, v21
	v_cvt_pk_bf16_f32 v12, v23, v23
	v_and_b32_e32 v13, 0xffff0000, v13
	v_and_b32_e32 v15, 0xffff0000, v15
	v_or_b32_sdwa v13, v13, v12 dst_sel:DWORD dst_unused:UNUSED_PAD src0_sel:DWORD src1_sel:WORD_1
	v_or_b32_sdwa v12, v15, v14 dst_sel:DWORD dst_unused:UNUSED_PAD src0_sel:DWORD src1_sel:WORD_1
	global_store_dwordx4 v[28:29], v[10:13], off
	ds_read2st64_b32 v[22:23], v5 offset0:2 offset1:3
	ds_read2st64_b32 v[18:19], v27 offset0:6 offset1:7
	ds_read2st64_b32 v[24:25], v34 offset0:10 offset1:11
	ds_read2st64_b32 v[20:21], v35 offset0:14 offset1:15
	ds_read2st64_b32 v[14:15], v36 offset0:18 offset1:19
	ds_read2st64_b32 v[10:11], v37 offset0:22 offset1:23
	ds_read2st64_b32 v[16:17], v38 offset0:26 offset1:27
	ds_read2st64_b32 v[12:13], v39 offset0:30 offset1:31
	v_add_u32_e32 v27, 0x80, v40
	v_mad_i64_i32 v[32:33], s[0:1], v27, s9, v[8:9]
	s_waitcnt lgkmcnt(5)
	v_and_b32_sdwa v27, v24, v178 dst_sel:DWORD dst_unused:UNUSED_PAD src0_sel:WORD_1 src1_sel:DWORD
	v_and_b32_sdwa v28, v22, v178 dst_sel:DWORD dst_unused:UNUSED_PAD src0_sel:WORD_1 src1_sel:DWORD
	v_add3_u32 v22, v22, v28, s81
	v_add3_u32 v24, v24, v27, s81
	s_waitcnt lgkmcnt(4)
	v_and_b32_sdwa v27, v20, v178 dst_sel:DWORD dst_unused:UNUSED_PAD src0_sel:WORD_1 src1_sel:DWORD
	v_add3_u32 v20, v20, v27, s81
	v_cvt_pk_bf16_f32 v18, v18, v18
	v_and_b32_e32 v20, 0xffff0000, v20
	v_and_b32_e32 v18, 0xffff0000, v18
	v_or_b32_sdwa v29, v20, v24 dst_sel:DWORD dst_unused:UNUSED_PAD src0_sel:DWORD src1_sel:WORD_1
	v_or_b32_sdwa v28, v18, v22 dst_sel:DWORD dst_unused:UNUSED_PAD src0_sel:DWORD src1_sel:WORD_1
	s_waitcnt lgkmcnt(1)
	v_and_b32_sdwa v18, v16, v178 dst_sel:DWORD dst_unused:UNUSED_PAD src0_sel:WORD_1 src1_sel:DWORD
	v_cvt_pk_bf16_f32 v14, v14, v14
	v_add3_u32 v16, v16, v18, s81
	s_waitcnt lgkmcnt(0)
	v_and_b32_sdwa v18, v12, v178 dst_sel:DWORD dst_unused:UNUSED_PAD src0_sel:WORD_1 src1_sel:DWORD
	v_and_b32_sdwa v20, v10, v178 dst_sel:DWORD dst_unused:UNUSED_PAD src0_sel:WORD_1 src1_sel:DWORD
	v_add3_u32 v12, v12, v18, s81
	v_add3_u32 v10, v10, v20, s81
	v_and_b32_e32 v12, 0xffff0000, v12
	v_and_b32_e32 v10, 0xffff0000, v10
	v_or_b32_sdwa v31, v12, v16 dst_sel:DWORD dst_unused:UNUSED_PAD src0_sel:DWORD src1_sel:WORD_1
	v_or_b32_sdwa v30, v10, v14 dst_sel:DWORD dst_unused:UNUSED_PAD src0_sel:DWORD src1_sel:WORD_1
	v_add_u32_e32 v10, 0xc0, v40
	global_store_dwordx4 v[32:33], v[28:31], off
	s_nop 0
	v_cvt_pk_bf16_f32 v12, v19, v19
	v_mad_i64_i32 v[28:29], s[0:1], v10, s9, v[8:9]
	s_nop 0
	v_cvt_pk_bf16_f32 v10, v23, v23
	s_nop 0
	s_nop 0
	v_cvt_pk_bf16_f32 v9, v21, v21
	v_cvt_pk_bf16_f32 v8, v25, v25
	v_and_b32_e32 v9, 0xffff0000, v9
	v_and_b32_e32 v12, 0xffff0000, v12
	v_or_b32_sdwa v9, v9, v8 dst_sel:DWORD dst_unused:UNUSED_PAD src0_sel:DWORD src1_sel:WORD_1
	v_or_b32_sdwa v8, v12, v10 dst_sel:DWORD dst_unused:UNUSED_PAD src0_sel:DWORD src1_sel:WORD_1
	v_and_b32_sdwa v12, v15, v178 dst_sel:DWORD dst_unused:UNUSED_PAD src0_sel:WORD_1 src1_sel:DWORD
	v_add3_u32 v12, v15, v12, s81
	v_and_b32_sdwa v15, v11, v178 dst_sel:DWORD dst_unused:UNUSED_PAD src0_sel:WORD_1 src1_sel:DWORD
	v_cvt_pk_bf16_f32 v13, v13, v13
	v_add3_u32 v11, v11, v15, s81
	v_cvt_pk_bf16_f32 v10, v17, v17
	v_and_b32_e32 v13, 0xffff0000, v13
	v_and_b32_e32 v14, 0xffff0000, v11
	v_or_b32_sdwa v11, v13, v10 dst_sel:DWORD dst_unused:UNUSED_PAD src0_sel:DWORD src1_sel:WORD_1
	v_or_b32_sdwa v10, v14, v12 dst_sel:DWORD dst_unused:UNUSED_PAD src0_sel:DWORD src1_sel:WORD_1
	global_store_dwordx4 v[28:29], v[8:11], off
	s_barrier
	s_cbranch_scc1 .LBB0_911
	s_mov_b32 s51, 0x10000

; __device__ __forceinline__ int srccol(int perm, int n) {
;     ...
;   } else if (perm == 2) {
;     if (n < 2048) {
;       int part = n >> 10, hh = (n >> 8) & 3, cp = n & 255;
;       int grp = cp >> 5, t = (cp >> 4) & 1, i = cp & 15;
;       int pp = grp * 16 + i;
;       return part * 1024 + hh * 256 + t * 128 + pp;
;     }
;     return n;
; __device__ __forceinline__ void conv_family(const float* __restrict__ W, u16* __restrict__ Wt, int cnt, int K, int N, int perm,
;                             float* tile, const int tid, const float* __restrict__ kscale = nullptr) {
;     ...
;     int k0 = kt * 64, n0 = ntile * 256;
;     {
;       int n = tid & 255;
;       int sc = srccol(perm, n0 + n);
;       const float* wp = Ws + (size_t)(k0 + (tid >> 8)) * N + sc;
;       float v[32];
; #pragma unroll
;       for (int i = 0; i < 32; ++i) v[i] = wp[(size_t)(2 * i) * N];
;       if (kscale) {
;         const float* ks = kscale + (size_t)mi * K + k0 + (tid >> 8);
; #pragma unroll
;         for (int i = 0; i < 32; ++i) v[i] *= ks[2 * i];
;       }
; #pragma unroll
;       for (int i = 0; i < 32; ++i) tile[(2 * i + (tid >> 8)) * 257 + n] = v[i];
.LBB0_915:
	s_mul_hi_i32 s0, s4, 0x2aaaaaab
	s_lshr_b32 s1, s0, 31
	s_ashr_i32 s0, s0, 6
	s_add_i32 s0, s0, s1
	s_mul_i32 s1, s0, 0xfffffe80
	s_add_i32 s1, s4, s1
	s_mul_i32 s2, s1, 0x2aab
	s_lshr_b32 s3, s2, 31
	s_ashr_i32 s2, s2, 18
	s_add_i32 s5, s2, s3
	s_mul_i32 s2, s5, 24
	s_sub_i32 s1, s1, s2
	s_sext_i32_i16 s8, s1
	s_mul_hi_i32 s1, s0, 0x600000
	s_mul_i32 s0, s0, 0x600000
	s_lshl_b64 s[2:3], s[0:1], 2
	s_add_u32 s2, s22, s2
	s_addc_u32 s3, s23, s3
	s_lshl_b64 s[0:1], s[0:1], 1
	s_add_u32 s6, s54, s0
	s_addc_u32 s7, s55, s1
	s_lshl_b32 s0, s5, 6
	s_lshl_b32 s5, s8, 8
	v_lshlrev_b32_e32 v9, 3, v3
	v_mov_b32_e32 v10, 0xffffff0f
	v_or_b32_e32 v8, s5, v3
	s_movk_i32 s1, 0x800
	v_and_b32_e32 v9, 0x80, v9
	v_bitop3_b32 v10, s5, v10, v3 bitop3:0xc8
	v_cmp_gt_i32_e32 vcc, s1, v8
	v_or3_b32 v9, v10, v5, v9
	v_mov_b64_e32 v[10:11], s[2:3]
	v_cndmask_b32_e32 v8, v8, v9, vcc
	v_bfe_u32 v12, v3, 5, 2
	v_lshlrev_b32_e32 v12, 6, v12
	v_and_b32_e32 v13, 15, v3
	v_lshl_add_u32 v12, v13, 2, v12
	v_bfe_u32 v13, v3, 7, 1
	v_lshl_add_u32 v12, v13, 1, v12
	v_bfe_u32 v13, v3, 4, 1
	v_add3_u32 v12, v12, v13, s5
	v_cmp_lt_u32_e32 vcc, 0xfff, v8
	s_nop 1
	v_cndmask_b32_e32 v8, v8, v12, vcc
	v_add_u32_e32 v9, s0, v4
	v_mad_i64_i32 v[10:11], s[2:3], v9, s10, v[10:11]
	v_ashrrev_i32_e32 v9, 31, v8
	v_lshl_add_u64 v[8:9], v[8:9], 2, v[10:11]
	v_add_co_u32_e32 v10, vcc, s12, v8
	global_load_dword v12, v[8:9], off
	s_nop 0
	v_addc_co_u32_e32 v11, vcc, 0, v9, vcc
	global_load_dword v13, v[10:11], off
	v_add_co_u32_e32 v10, vcc, s11, v8
	s_mov_b32 s1, 0xc0000
	s_nop 0
	v_addc_co_u32_e32 v11, vcc, 0, v9, vcc
	global_load_dword v14, v[10:11], off
	v_add_co_u32_e32 v10, vcc, s30, v8
	s_nop 1
	v_addc_co_u32_e32 v11, vcc, 0, v9, vcc
	global_load_dword v15, v[10:11], off
	v_add_co_u32_e32 v10, vcc, s56, v8
	s_nop 1
	v_addc_co_u32_e32 v11, vcc, 0, v9, vcc
	global_load_dword v16, v[10:11], off
	v_add_co_u32_e32 v10, vcc, s15, v8
	s_nop 1
	v_addc_co_u32_e32 v11, vcc, 0, v9, vcc
	global_load_dword v17, v[10:11], off
	v_add_co_u32_e32 v10, vcc, s34, v8
	s_nop 1
	v_addc_co_u32_e32 v11, vcc, 0, v9, vcc
	global_load_dword v18, v[10:11], off
	v_add_co_u32_e32 v10, vcc, s16, v8
	s_nop 1
	v_addc_co_u32_e32 v11, vcc, 0, v9, vcc
	global_load_dword v19, v[10:11], off
	v_add_co_u32_e32 v10, vcc, s17, v8
	s_nop 1
	v_addc_co_u32_e32 v11, vcc, 0, v9, vcc
	global_load_dword v20, v[10:11], off
	v_add_co_u32_e32 v10, vcc, s97, v8
	s_nop 1
	v_addc_co_u32_e32 v11, vcc, 0, v9, vcc
	global_load_dword v21, v[10:11], off
	v_add_co_u32_e32 v10, vcc, s18, v8
	s_nop 1
	v_addc_co_u32_e32 v11, vcc, 0, v9, vcc
	global_load_dword v22, v[10:11], off
	v_add_co_u32_e32 v10, vcc, s13, v8
	s_nop 1
	v_addc_co_u32_e32 v11, vcc, 0, v9, vcc
	global_load_dword v23, v[10:11], off
	v_add_co_u32_e32 v10, vcc, s9, v8
	s_nop 1
	v_addc_co_u32_e32 v11, vcc, 0, v9, vcc
	global_load_dword v24, v[10:11], off
	v_add_co_u32_e32 v10, vcc, s19, v8
	s_nop 1
	v_addc_co_u32_e32 v11, vcc, 0, v9, vcc
	global_load_dword v25, v[10:11], off
	v_add_co_u32_e32 v10, vcc, s20, v8
	s_nop 1
	v_addc_co_u32_e32 v11, vcc, 0, v9, vcc
	global_load_dword v26, v[10:11], off
	v_add_co_u32_e32 v10, vcc, s21, v8
	s_nop 1
	v_addc_co_u32_e32 v11, vcc, 0, v9, vcc
	global_load_dword v27, v[10:11], off
	v_add_co_u32_e32 v10, vcc, s1, v8
	s_mov_b32 s1, 0xcc000
	s_nop 0
	v_addc_co_u32_e32 v11, vcc, 0, v9, vcc
	global_load_dword v30, v[10:11], off
	v_add_co_u32_e32 v10, vcc, s1, v8
	s_mov_b32 s1, 0xd8000
	s_nop 0
	v_addc_co_u32_e32 v11, vcc, 0, v9, vcc
	global_load_dword v31, v[10:11], off
	v_add_co_u32_e32 v10, vcc, s1, v8
	s_mov_b32 s1, 0xe4000
	s_nop 0
	v_addc_co_u32_e32 v11, vcc, 0, v9, vcc
	global_load_dword v32, v[10:11], off
	v_add_co_u32_e32 v10, vcc, s1, v8
	s_mov_b32 s1, 0xf0000
	s_nop 0
	v_addc_co_u32_e32 v11, vcc, 0, v9, vcc
	global_load_dword v33, v[10:11], off
	v_add_co_u32_e32 v10, vcc, s1, v8
	s_mov_b32 s1, 0xfc000
	s_nop 0
	v_addc_co_u32_e32 v11, vcc, 0, v9, vcc
	global_load_dword v34, v[10:11], off
	v_add_co_u32_e32 v10, vcc, s1, v8
	s_mov_b32 s1, 0x114000
	s_nop 0
	v_addc_co_u32_e32 v11, vcc, 0, v9, vcc
	global_load_dword v35, v[10:11], off
	v_add_co_u32_e32 v10, vcc, s14, v8
	s_nop 1
	v_addc_co_u32_e32 v11, vcc, 0, v9, vcc
	global_load_dword v36, v[10:11], off
	v_add_co_u32_e32 v10, vcc, s1, v8
	s_mov_b32 s1, 0x120000
	s_nop 0
	v_addc_co_u32_e32 v11, vcc, 0, v9, vcc
	global_load_dword v37, v[10:11], off
	v_add_co_u32_e32 v10, vcc, s1, v8
	s_mov_b32 s1, 0x12c000
	s_nop 0
	v_addc_co_u32_e32 v11, vcc, 0, v9, vcc
	global_load_dword v38, v[10:11], off
	v_add_co_u32_e32 v10, vcc, s1, v8
	s_mov_b32 s1, 0x138000
	s_nop 0
	v_addc_co_u32_e32 v11, vcc, 0, v9, vcc
	global_load_dword v39, v[10:11], off
	v_add_co_u32_e32 v10, vcc, s1, v8
	s_mov_b32 s1, 0x144000
	s_nop 0
	v_addc_co_u32_e32 v11, vcc, 0, v9, vcc
	global_load_dword v40, v[10:11], off
	v_add_co_u32_e32 v10, vcc, s1, v8
	s_mov_b32 s1, 0x150000
	s_nop 0
	v_addc_co_u32_e32 v11, vcc, 0, v9, vcc
	global_load_dword v41, v[10:11], off
	v_add_co_u32_e32 v10, vcc, s1, v8
	s_mov_b32 s1, 0x15c000
	s_nop 0
	v_addc_co_u32_e32 v11, vcc, 0, v9, vcc
	global_load_dword v42, v[10:11], off
	v_add_co_u32_e32 v10, vcc, s1, v8
	s_mov_b32 s1, 0x168000
	s_nop 0
	v_addc_co_u32_e32 v11, vcc, 0, v9, vcc
	global_load_dword v43, v[10:11], off
	v_add_co_u32_e32 v10, vcc, s1, v8
	s_mov_b32 s1, 0x174000
	s_nop 0
	v_addc_co_u32_e32 v11, vcc, 0, v9, vcc
	v_add_co_u32_e32 v8, vcc, s1, v8
	global_load_dword v10, v[10:11], off
	s_nop 0
	v_addc_co_u32_e32 v9, vcc, 0, v9, vcc
	global_load_dword v8, v[8:9], off
	s_waitcnt vmcnt(31)
	ds_write_b32 v29, v12
	s_waitcnt vmcnt(30)
	ds_write_b32 v29, v13 offset:2056
	s_waitcnt vmcnt(29)
; __device__ __forceinline__ void conv_family(const float* __restrict__ W, u16* __restrict__ Wt, int cnt, int K, int N, int perm,
;                             float* tile, const int tid, const float* __restrict__ kscale = nullptr) {
;     ...
;       for (int i = 0; i < 32; ++i) tile[(2 * i + (tid >> 8)) * 257 + n] = v[i];
;     }
;     __syncthreads();
	ds_write_b32 v29, v14 offset:4112
	s_waitcnt vmcnt(28)
	ds_write_b32 v29, v15 offset:6168
	s_waitcnt vmcnt(27)
	ds_write_b32 v29, v16 offset:8224
	s_waitcnt vmcnt(26)
	ds_write_b32 v29, v17 offset:10280
	s_waitcnt vmcnt(25)
	ds_write_b32 v29, v18 offset:12336
	s_waitcnt vmcnt(24)
	ds_write_b32 v29, v19 offset:14392
	s_waitcnt vmcnt(23)
	ds_write_b32 v29, v20 offset:16448
	s_waitcnt vmcnt(22)
	ds_write_b32 v29, v21 offset:18504
	s_waitcnt vmcnt(21)
	ds_write_b32 v29, v22 offset:20560
	s_waitcnt vmcnt(20)
	ds_write_b32 v29, v23 offset:22616
	s_waitcnt vmcnt(19)
	ds_write_b32 v29, v24 offset:24672
	s_waitcnt vmcnt(18)
	ds_write_b32 v29, v25 offset:26728
	s_waitcnt vmcnt(17)
	ds_write_b32 v29, v26 offset:28784
	s_waitcnt vmcnt(16)
	ds_write_b32 v29, v27 offset:30840
	s_waitcnt vmcnt(15)
	ds_write_b32 v29, v30 offset:32896
	s_waitcnt vmcnt(14)
	ds_write_b32 v29, v31 offset:34952
	s_waitcnt vmcnt(13)
	ds_write_b32 v29, v32 offset:37008
	s_waitcnt vmcnt(12)
	ds_write_b32 v29, v33 offset:39064
	s_waitcnt vmcnt(11)
	ds_write_b32 v29, v34 offset:41120
	s_waitcnt vmcnt(10)
	ds_write_b32 v29, v35 offset:43176
	s_waitcnt vmcnt(9)
	ds_write_b32 v29, v36 offset:45232
	s_waitcnt vmcnt(8)
	ds_write_b32 v29, v37 offset:47288
	s_waitcnt vmcnt(7)
	ds_write_b32 v29, v38 offset:49344
	s_waitcnt vmcnt(6)
	ds_write_b32 v29, v39 offset:51400
	s_waitcnt vmcnt(5)
	ds_write_b32 v29, v40 offset:53456
	s_waitcnt vmcnt(4)
	ds_write_b32 v29, v41 offset:55512
	s_waitcnt vmcnt(3)
	ds_write_b32 v29, v42 offset:57568
	s_waitcnt vmcnt(2)
	ds_write_b32 v29, v43 offset:59624
	s_waitcnt vmcnt(1)
	ds_write_b32 v29, v10 offset:61680
	s_waitcnt vmcnt(0)
	ds_write_b32 v29, v8 offset:63736
	v_add_u32_e32 v37, 8, v28
	s_waitcnt lgkmcnt(0)
	s_barrier
; __device__ __forceinline__ unsigned pack2(float a, float b) { return (unsigned)f2bf(a) | ((unsigned)f2bf(b) << 16); }
; __device__ __forceinline__ void conv_family(const float* __restrict__ W, u16* __restrict__ Wt, int cnt, int K, int N, int perm,
;                             float* tile, const int tid, const float* __restrict__ kscale = nullptr) {
;     ...
; #pragma unroll
;     for (int i = 0; i < 4; ++i) {
;       int n = i * 64 + (tid >> 3), ks = (tid & 7) * 8;
;       uint4 pk;
;       pk.x = pack2(tile[(ks + 0) * 257 + n], tile[(ks + 1) * 257 + n]);
;       pk.y = pack2(tile[(ks + 2) * 257 + n], tile[(ks + 3) * 257 + n]);
;       pk.z = pack2(tile[(ks + 4) * 257 + n], tile[(ks + 5) * 257 + n]);
;       pk.w = pack2(tile[(ks + 6) * 257 + n], tile[(ks + 7) * 257 + n]);
;       *(uint4*)(Wd + (size_t)(n0 + n) * K + k0 + ks) = pk;
;     }
;     __syncthreads();
;   }
	ds_read2st64_b32 v[16:17], v37 offset0:8 offset1:9
	v_add_u32_e32 v38, 12, v28
	ds_read2st64_b32 v[18:19], v38 offset0:12 offset1:13
	s_ashr_i32 s1, s0, 31
	ds_read2st64_b32 v[10:11], v28 offset1:1
	v_add_u32_e32 v36, 4, v28
	s_lshl_b64 s[0:1], s[0:1], 1
	ds_read2st64_b32 v[14:15], v36 offset0:4 offset1:5
	v_add_u32_e32 v40, 20, v28
	v_add_u32_e32 v12, s5, v7
	s_add_u32 s0, s6, s0
	v_add_u32_e32 v39, 16, v28
	ds_read2st64_b32 v[22:23], v40 offset0:20 offset1:21
	v_ashrrev_i32_e32 v13, 31, v12
	s_addc_u32 s1, s7, s1
	ds_read2st64_b32 v[20:21], v39 offset0:16 offset1:17
	v_add_u32_e32 v42, 28, v28
	v_lshlrev_b64 v[30:31], 11, v[12:13]
	s_waitcnt lgkmcnt(5)
	s_nop 0
	v_lshl_add_u64 v[8:9], s[0:1], 0, v[0:1]
	v_add_u32_e32 v41, 24, v28
	ds_read2st64_b32 v[26:27], v42 offset0:28 offset1:29
	v_cvt_pk_bf16_f32 v13, v16, v16
	s_waitcnt lgkmcnt(5)
	s_nop 0
	ds_read2st64_b32 v[24:25], v41 offset0:24 offset1:25
	v_lshl_add_u64 v[34:35], v[8:9], 0, v[30:31]
	s_waitcnt lgkmcnt(5)
	s_nop 0
	v_cvt_pk_bf16_f32 v16, v18, v18
	v_cvt_pk_bf16_f32 v10, v10, v10
	s_waitcnt lgkmcnt(4)
	v_and_b32_e32 v16, 0xffff0000, v16
	v_cvt_pk_bf16_f32 v14, v14, v14
	v_or_b32_sdwa v31, v16, v13 dst_sel:DWORD dst_unused:UNUSED_PAD src0_sel:DWORD src1_sel:WORD_1
	s_waitcnt lgkmcnt(3)
	v_and_b32_e32 v14, 0xffff0000, v14
	s_waitcnt lgkmcnt(2)
	v_cvt_pk_bf16_f32 v16, v22, v22
	v_or_b32_sdwa v30, v14, v10 dst_sel:DWORD dst_unused:UNUSED_PAD src0_sel:DWORD src1_sel:WORD_1
	v_cvt_pk_bf16_f32 v13, v20, v20
	s_waitcnt lgkmcnt(1)
	v_and_b32_e32 v16, 0xffff0000, v16
	s_waitcnt lgkmcnt(0)
	v_cvt_pk_bf16_f32 v14, v26, v26
	v_or_b32_sdwa v32, v16, v13 dst_sel:DWORD dst_unused:UNUSED_PAD src0_sel:DWORD src1_sel:WORD_1
	v_cvt_pk_bf16_f32 v10, v24, v24
	v_and_b32_e32 v14, 0xffff0000, v14
	v_cvt_pk_bf16_f32 v11, v11, v11
	v_or_b32_sdwa v33, v14, v10 dst_sel:DWORD dst_unused:UNUSED_PAD src0_sel:DWORD src1_sel:WORD_1
	v_cvt_pk_bf16_f32 v13, v19, v19
	v_cvt_pk_bf16_f32 v10, v17, v17
	v_cvt_pk_bf16_f32 v14, v15, v15
	v_and_b32_e32 v13, 0xffff0000, v13
	global_store_dwordx4 v[34:35], v[30:33], off
	v_and_b32_e32 v14, 0xffff0000, v14
	v_or_b32_sdwa v15, v13, v10 dst_sel:DWORD dst_unused:UNUSED_PAD src0_sel:DWORD src1_sel:WORD_1
	v_add_u32_e32 v30, 64, v12
	s_nop 0
	s_nop 0
	v_ashrrev_i32_e32 v31, 31, v30
	v_or_b32_sdwa v14, v14, v11 dst_sel:DWORD dst_unused:UNUSED_PAD src0_sel:DWORD src1_sel:WORD_1
	s_nop 0
	s_nop 0
	v_cvt_pk_bf16_f32 v13, v27, v27
	v_cvt_pk_bf16_f32 v16, v23, v23
	v_lshlrev_b64 v[30:31], 11, v[30:31]
	v_cvt_pk_bf16_f32 v11, v21, v21
	v_cvt_pk_bf16_f32 v10, v25, v25
	v_and_b32_e32 v13, 0xffff0000, v13
	v_and_b32_e32 v16, 0xffff0000, v16
	v_lshl_add_u64 v[30:31], v[8:9], 0, v[30:31]
	v_or_b32_sdwa v17, v13, v10 dst_sel:DWORD dst_unused:UNUSED_PAD src0_sel:DWORD src1_sel:WORD_1
	v_or_b32_sdwa v16, v16, v11 dst_sel:DWORD dst_unused:UNUSED_PAD src0_sel:DWORD src1_sel:WORD_1
	global_store_dwordx4 v[30:31], v[14:17], off
	ds_read2st64_b32 v[24:25], v28 offset0:2 offset1:3
	ds_read2st64_b32 v[20:21], v36 offset0:6 offset1:7
	ds_read2st64_b32 v[26:27], v37 offset0:10 offset1:11
	ds_read2st64_b32 v[22:23], v38 offset0:14 offset1:15
	ds_read2st64_b32 v[16:17], v39 offset0:18 offset1:19
	ds_read2st64_b32 v[10:11], v40 offset0:22 offset1:23
	ds_read2st64_b32 v[18:19], v41 offset0:26 offset1:27
	ds_read2st64_b32 v[14:15], v42 offset0:30 offset1:31
	v_add_u32_e32 v30, 0x80, v12
	s_waitcnt lgkmcnt(5)
	s_nop 0
	v_ashrrev_i32_e32 v31, 31, v30
	v_cvt_pk_bf16_f32 v13, v26, v26
	s_waitcnt lgkmcnt(4)
	v_and_b32_sdwa v26, v22, v178 dst_sel:DWORD dst_unused:UNUSED_PAD src0_sel:WORD_1 src1_sel:DWORD
	v_lshlrev_b64 v[30:31], 11, v[30:31]
	v_add3_u32 v22, v22, v26, s81
	v_lshl_add_u64 v[34:35], v[8:9], 0, v[30:31]
	v_and_b32_sdwa v30, v24, v178 dst_sel:DWORD dst_unused:UNUSED_PAD src0_sel:WORD_1 src1_sel:DWORD
	v_and_b32_e32 v22, 0xffff0000, v22
	v_add3_u32 v24, v24, v30, s81
	s_nop 0
	v_or_b32_sdwa v31, v22, v13 dst_sel:DWORD dst_unused:UNUSED_PAD src0_sel:DWORD src1_sel:WORD_1
	s_waitcnt lgkmcnt(1)
	v_cvt_pk_bf16_f32 v20, v20, v20
	v_cvt_pk_bf16_f32 v13, v18, v18
	s_waitcnt lgkmcnt(0)
	v_and_b32_sdwa v18, v14, v178 dst_sel:DWORD dst_unused:UNUSED_PAD src0_sel:WORD_1 src1_sel:DWORD
	v_and_b32_e32 v20, 0xffff0000, v20
	v_add3_u32 v14, v14, v18, s81
	v_or_b32_sdwa v30, v20, v24 dst_sel:DWORD dst_unused:UNUSED_PAD src0_sel:DWORD src1_sel:WORD_1
	v_and_b32_e32 v14, 0xffff0000, v14
	v_add_u32_e32 v12, 0xc0, v12
	v_cvt_pk_bf16_f32 v16, v16, v16
	v_and_b32_sdwa v20, v10, v178 dst_sel:DWORD dst_unused:UNUSED_PAD src0_sel:WORD_1 src1_sel:DWORD
	v_or_b32_sdwa v33, v14, v13 dst_sel:DWORD dst_unused:UNUSED_PAD src0_sel:DWORD src1_sel:WORD_1
	v_ashrrev_i32_e32 v13, 31, v12
	v_add3_u32 v10, v10, v20, s81
	v_lshlrev_b64 v[12:13], 11, v[12:13]
	v_and_b32_e32 v10, 0xffff0000, v10
	v_lshl_add_u64 v[12:13], v[8:9], 0, v[12:13]
	s_nop 0
	v_or_b32_sdwa v32, v10, v16 dst_sel:DWORD dst_unused:UNUSED_PAD src0_sel:DWORD src1_sel:WORD_1
	v_cvt_pk_bf16_f32 v10, v25, v25
	s_nop 0
	s_nop 0
	v_cvt_pk_bf16_f32 v9, v23, v23
	v_cvt_pk_bf16_f32 v14, v21, v21
	v_cvt_pk_bf16_f32 v8, v27, v27
	v_and_b32_e32 v9, 0xffff0000, v9
	v_and_b32_e32 v14, 0xffff0000, v14
	v_or_b32_sdwa v9, v9, v8 dst_sel:DWORD dst_unused:UNUSED_PAD src0_sel:DWORD src1_sel:WORD_1
	v_or_b32_sdwa v8, v14, v10 dst_sel:DWORD dst_unused:UNUSED_PAD src0_sel:DWORD src1_sel:WORD_1
	v_and_b32_sdwa v14, v17, v178 dst_sel:DWORD dst_unused:UNUSED_PAD src0_sel:WORD_1 src1_sel:DWORD
	v_add3_u32 v14, v17, v14, s81
	v_and_b32_sdwa v17, v11, v178 dst_sel:DWORD dst_unused:UNUSED_PAD src0_sel:WORD_1 src1_sel:DWORD
	v_cvt_pk_bf16_f32 v15, v15, v15
	v_add3_u32 v11, v11, v17, s81
	v_cvt_pk_bf16_f32 v10, v19, v19
	v_and_b32_e32 v15, 0xffff0000, v15
	v_and_b32_e32 v16, 0xffff0000, v11
	s_add_i32 s4, s4, s44
	v_or_b32_sdwa v11, v15, v10 dst_sel:DWORD dst_unused:UNUSED_PAD src0_sel:DWORD src1_sel:WORD_1
	v_or_b32_sdwa v10, v16, v14 dst_sel:DWORD dst_unused:UNUSED_PAD src0_sel:DWORD src1_sel:WORD_1
	s_cmpk_lt_i32 s4, 0x300
	global_store_dwordx4 v[34:35], v[30:33], off
	global_store_dwordx4 v[12:13], v[8:11], off
	s_barrier
	s_cbranch_scc1 .LBB0_915
	s_mov_b32 s38, 0x1e000
	s_mov_b32 s39, 0x2c000
	s_mov_b32 s40, 0x22000
	s_mov_b32 s41, 0x26000
	s_mov_b32 s43, 0x2a000
	s_mov_b32 s48, 0x2e000
	s_mov_b32 s54, 0x32000
	s_mov_b32 s55, 0x34000
	s_mov_b32 s57, 0x38000

; __device__ __forceinline__ void conv_family(const float* __restrict__ W, u16* __restrict__ Wt, int cnt, int K, int N, int perm,
;                             float* tile, const int tid, const float* __restrict__ kscale = nullptr) {
;     ...
;       for (int i = 0; i < 32; ++i) tile[(2 * i + (tid >> 8)) * 257 + n] = v[i];
;     }
;     __syncthreads();
.LBB0_919:
	s_lshl_b64 s[2:3], s[2:3], 21
	v_readlane_b32 s8, v252, 26
	s_lshl_b64 s[2:3], s[2:3], 1
	v_readlane_b32 s12, v252, 30
	v_readlane_b32 s13, v252, 31
	s_add_u32 s2, s12, s2
	ds_write_b32 v78, v70
	ds_write_b32 v78, v71 offset:2056
	ds_write_b32 v78, v68 offset:4112
	ds_write_b32 v78, v69 offset:6168
	ds_write_b32 v78, v66 offset:8224
	ds_write_b32 v78, v67 offset:10280
	ds_write_b32 v78, v64 offset:12336
	ds_write_b32 v78, v65 offset:14392
	ds_write_b32 v78, v62 offset:16448
	ds_write_b32 v78, v63 offset:18504
	ds_write_b32 v78, v60 offset:20560
	ds_write_b32 v78, v61 offset:22616
	ds_write_b32 v78, v58 offset:24672
	ds_write_b32 v78, v59 offset:26728
	ds_write_b32 v78, v56 offset:28784
	ds_write_b32 v78, v57 offset:30840
	ds_write_b32 v78, v54 offset:32896
	ds_write_b32 v78, v55 offset:34952
	ds_write_b32 v78, v52 offset:37008
	ds_write_b32 v78, v53 offset:39064
	ds_write_b32 v78, v50 offset:41120
	ds_write_b32 v78, v51 offset:43176
	ds_write_b32 v78, v48 offset:45232
	ds_write_b32 v78, v49 offset:47288
	ds_write_b32 v78, v46 offset:49344
	ds_write_b32 v78, v47 offset:51400
	ds_write_b32 v78, v44 offset:53456
	ds_write_b32 v78, v45 offset:55512
	ds_write_b32 v78, v42 offset:57568
	ds_write_b32 v78, v43 offset:59624
	ds_write_b32 v78, v40 offset:61680
	ds_write_b32 v78, v41 offset:63736
	s_waitcnt lgkmcnt(0)
	s_barrier
; __device__ __forceinline__ unsigned pack2(float a, float b) { return (unsigned)f2bf(a) | ((unsigned)f2bf(b) << 16); }
; __device__ __forceinline__ void conv_family(const float* __restrict__ W, u16* __restrict__ Wt, int cnt, int K, int N, int perm,
;                             float* tile, const int tid, const float* __restrict__ kscale = nullptr) {
;     ...
; #pragma unroll
;     for (int i = 0; i < 4; ++i) {
;       int n = i * 64 + (tid >> 3), ks = (tid & 7) * 8;
;       uint4 pk;
;       pk.x = pack2(tile[(ks + 0) * 257 + n], tile[(ks + 1) * 257 + n]);
;       pk.y = pack2(tile[(ks + 2) * 257 + n], tile[(ks + 3) * 257 + n]);
;       pk.z = pack2(tile[(ks + 4) * 257 + n], tile[(ks + 5) * 257 + n]);
;       pk.w = pack2(tile[(ks + 6) * 257 + n], tile[(ks + 7) * 257 + n]);
;       *(uint4*)(Wd + (size_t)(n0 + n) * K + k0 + ks) = pk;
;     }
;     __syncthreads();
;   }
	s_waitcnt vmcnt(30)
	ds_read2st64_b32 v[14:15], v77 offset1:1
	s_waitcnt vmcnt(4)
	ds_read2st64_b32 v[36:37], v77 offset0:2 offset1:3
	v_add_u32_e32 v10, 4, v77
	v_add_u32_e32 v38, 12, v77
	s_addc_u32 s3, s13, s3
	s_lshl_b64 s[0:1], s[0:1], 1
	ds_read2st64_b32 v[16:17], v10 offset0:4 offset1:5
	ds_read2st64_b32 v[40:41], v10 offset0:6 offset1:7
	v_add_u32_e32 v11, 8, v77
	ds_read2st64_b32 v[20:21], v38 offset0:12 offset1:13
	s_add_u32 s0, s2, s0
	ds_read2st64_b32 v[18:19], v11 offset0:8 offset1:9
	s_waitcnt vmcnt(2)
	ds_read2st64_b32 v[34:35], v11 offset0:10 offset1:11
	v_add_u32_e32 v30, s7, v7
	s_addc_u32 s1, s3, s1
	v_add_u32_e32 v44, 16, v77
	v_ashrrev_i32_e32 v31, 31, v30
	v_lshl_add_u64 v[12:13], s[0:1], 0, v[0:1]
	ds_read2st64_b32 v[22:23], v44 offset0:16 offset1:17
	v_add_u32_e32 v48, 20, v77
	v_add_u32_e32 v46, 28, v77
	v_lshlrev_b64 v[8:9], 12, v[30:31]
	ds_read2st64_b32 v[24:25], v48 offset0:20 offset1:21
	v_add_u32_e32 v42, 24, v77
	ds_read2st64_b32 v[28:29], v46 offset0:28 offset1:29
	s_waitcnt vmcnt(0)
	v_lshl_add_u64 v[32:33], v[12:13], 0, v[8:9]
	s_waitcnt lgkmcnt(9)
	s_nop 0
	ds_read2st64_b32 v[26:27], v42 offset0:24 offset1:25
	v_cvt_pk_bf16_f32 v11, v14, v14
	s_waitcnt lgkmcnt(6)
	s_waitcnt lgkmcnt(5)
	v_cvt_pk_bf16_f32 v9, v20, v20
	v_cvt_pk_bf16_f32 v10, v16, v16
	v_cvt_pk_bf16_f32 v8, v18, v18
	v_and_b32_e32 v9, 0xffff0000, v9
	v_and_b32_e32 v10, 0xffff0000, v10
	v_or_b32_sdwa v9, v9, v8 dst_sel:DWORD dst_unused:UNUSED_PAD src0_sel:DWORD src1_sel:WORD_1
	v_or_b32_sdwa v8, v10, v11 dst_sel:DWORD dst_unused:UNUSED_PAD src0_sel:DWORD src1_sel:WORD_1
	s_waitcnt lgkmcnt(3)
	v_cvt_pk_bf16_f32 v14, v22, v22
	s_waitcnt lgkmcnt(1)
	s_waitcnt lgkmcnt(0)
	v_cvt_pk_bf16_f32 v11, v28, v28
	v_cvt_pk_bf16_f32 v16, v24, v24
	v_cvt_pk_bf16_f32 v10, v26, v26
	v_and_b32_e32 v11, 0xffff0000, v11
	v_and_b32_e32 v16, 0xffff0000, v16
	v_or_b32_sdwa v11, v11, v10 dst_sel:DWORD dst_unused:UNUSED_PAD src0_sel:DWORD src1_sel:WORD_1
	v_or_b32_sdwa v10, v16, v14 dst_sel:DWORD dst_unused:UNUSED_PAD src0_sel:DWORD src1_sel:WORD_1
	global_store_dwordx4 v[32:33], v[8:11], off
	ds_read2st64_b32 v[38:39], v38 offset0:14 offset1:15
	ds_read2st64_b32 v[44:45], v44 offset0:18 offset1:19
	v_add_u32_e32 v8, 64, v30
	v_ashrrev_i32_e32 v9, 31, v8
	v_lshlrev_b64 v[8:9], 12, v[8:9]
	v_lshl_add_u64 v[32:33], v[12:13], 0, v[8:9]
	s_nop 0
	v_cvt_pk_bf16_f32 v10, v15, v15
	s_nop 0
	s_nop 0
	s_nop 0
	v_cvt_pk_bf16_f32 v9, v21, v21
	v_cvt_pk_bf16_f32 v11, v17, v17
	v_cvt_pk_bf16_f32 v8, v19, v19
	v_and_b32_e32 v9, 0xffff0000, v9
	v_and_b32_e32 v11, 0xffff0000, v11
	v_or_b32_sdwa v9, v9, v8 dst_sel:DWORD dst_unused:UNUSED_PAD src0_sel:DWORD src1_sel:WORD_1
	v_or_b32_sdwa v8, v11, v10 dst_sel:DWORD dst_unused:UNUSED_PAD src0_sel:DWORD src1_sel:WORD_1
	v_cvt_pk_bf16_f32 v14, v23, v23
	v_cvt_pk_bf16_f32 v11, v29, v29
	v_cvt_pk_bf16_f32 v15, v25, v25
	v_cvt_pk_bf16_f32 v10, v27, v27
	v_and_b32_e32 v11, 0xffff0000, v11
	v_and_b32_e32 v15, 0xffff0000, v15
	v_or_b32_sdwa v11, v11, v10 dst_sel:DWORD dst_unused:UNUSED_PAD src0_sel:DWORD src1_sel:WORD_1
	v_or_b32_sdwa v10, v15, v14 dst_sel:DWORD dst_unused:UNUSED_PAD src0_sel:DWORD src1_sel:WORD_1
	global_store_dwordx4 v[32:33], v[8:11], off
	ds_read2st64_b32 v[46:47], v46 offset0:30 offset1:31
	ds_read2st64_b32 v[48:49], v48 offset0:22 offset1:23
	v_add_u32_e32 v8, 0x80, v30
	v_ashrrev_i32_e32 v9, 31, v8
	v_lshlrev_b64 v[8:9], 12, v[8:9]
	v_lshl_add_u64 v[14:15], v[12:13], 0, v[8:9]
	s_nop 0
	ds_read2st64_b32 v[42:43], v42 offset0:26 offset1:27
	v_cvt_pk_bf16_f32 v10, v36, v36
	s_waitcnt lgkmcnt(4)
	s_nop 0
	v_cvt_pk_bf16_f32 v9, v38, v38
	v_cvt_pk_bf16_f32 v11, v40, v40
	v_cvt_pk_bf16_f32 v8, v34, v34
	v_and_b32_e32 v9, 0xffff0000, v9
	v_and_b32_e32 v11, 0xffff0000, v11
	v_or_b32_sdwa v9, v9, v8 dst_sel:DWORD dst_unused:UNUSED_PAD src0_sel:DWORD src1_sel:WORD_1
	v_or_b32_sdwa v8, v11, v10 dst_sel:DWORD dst_unused:UNUSED_PAD src0_sel:DWORD src1_sel:WORD_1
	s_waitcnt lgkmcnt(3)
	v_and_b32_sdwa v11, v44, v178 dst_sel:DWORD dst_unused:UNUSED_PAD src0_sel:WORD_1 src1_sel:DWORD
	v_add3_u32 v16, v44, v11, s81
	s_waitcnt lgkmcnt(2)
	s_waitcnt lgkmcnt(1)
	s_waitcnt lgkmcnt(0)
	v_cvt_pk_bf16_f32 v11, v46, v46
	v_cvt_pk_bf16_f32 v17, v48, v48
	v_cvt_pk_bf16_f32 v10, v42, v42
	v_and_b32_e32 v11, 0xffff0000, v11
	v_and_b32_e32 v17, 0xffff0000, v17
	v_or_b32_sdwa v11, v11, v10 dst_sel:DWORD dst_unused:UNUSED_PAD src0_sel:DWORD src1_sel:WORD_1
	v_or_b32_sdwa v10, v17, v16 dst_sel:DWORD dst_unused:UNUSED_PAD src0_sel:DWORD src1_sel:WORD_1
	global_store_dwordx4 v[14:15], v[8:11], off
	s_nop 0
	v_cvt_pk_bf16_f32 v15, v49, v49
	v_add_u32_e32 v8, 0xc0, v30
	v_ashrrev_i32_e32 v9, 31, v8
	v_lshlrev_b64 v[8:9], 12, v[8:9]
	v_lshl_add_u64 v[12:13], v[12:13], 0, v[8:9]
	s_nop 0
	v_cvt_pk_bf16_f32 v10, v37, v37
	s_nop 0
	s_nop 0
	s_nop 0
	v_cvt_pk_bf16_f32 v9, v39, v39
	v_cvt_pk_bf16_f32 v11, v41, v41
	v_cvt_pk_bf16_f32 v8, v35, v35
	v_and_b32_e32 v9, 0xffff0000, v9
	v_and_b32_e32 v11, 0xffff0000, v11
	v_or_b32_sdwa v9, v9, v8 dst_sel:DWORD dst_unused:UNUSED_PAD src0_sel:DWORD src1_sel:WORD_1
	v_or_b32_sdwa v8, v11, v10 dst_sel:DWORD dst_unused:UNUSED_PAD src0_sel:DWORD src1_sel:WORD_1
	v_and_b32_sdwa v11, v45, v178 dst_sel:DWORD dst_unused:UNUSED_PAD src0_sel:WORD_1 src1_sel:DWORD
	v_add3_u32 v14, v45, v11, s81
	v_cvt_pk_bf16_f32 v11, v47, v47
	v_cvt_pk_bf16_f32 v10, v43, v43
	v_and_b32_e32 v11, 0xffff0000, v11
	v_and_b32_e32 v15, 0xffff0000, v15
	s_add_i32 s6, s6, s44
	v_or_b32_sdwa v11, v11, v10 dst_sel:DWORD dst_unused:UNUSED_PAD src0_sel:DWORD src1_sel:WORD_1
	v_or_b32_sdwa v10, v15, v14 dst_sel:DWORD dst_unused:UNUSED_PAD src0_sel:DWORD src1_sel:WORD_1
	s_cmpk_lt_i32 s6, 0x100
	v_readlane_b32 s9, v252, 27
	v_readlane_b32 s10, v252, 28
	v_readlane_b32 s11, v252, 29
	v_readlane_b32 s14, v252, 32
	v_readlane_b32 s15, v252, 33
	v_readlane_b32 s16, v252, 34
	v_readlane_b32 s17, v252, 35
	v_readlane_b32 s18, v252, 36
	v_readlane_b32 s19, v252, 37
	v_readlane_b32 s20, v252, 38
	v_readlane_b32 s21, v252, 39
	v_readlane_b32 s22, v252, 40
	v_readlane_b32 s23, v252, 41
	global_store_dwordx4 v[12:13], v[8:11], off
	s_barrier
	s_cbranch_scc0 .LBB0_924

; __device__ __forceinline__ int srccol(int perm, int n) {
;     ...
;   } else if (perm == 3) {
;     if (n < 1024) return n;
;     int m = n - 1024;
;     int blk = m >> 5, t = (m >> 4) & 1, i = m & 15;
;     int j = blk * 16 + i;
;     return t ? 2048 + j : 1024 + j;
; __device__ __forceinline__ void conv_family(const float* __restrict__ W, u16* __restrict__ Wt, int cnt, int K, int N, int perm,
;                             float* tile, const int tid, const float* __restrict__ kscale = nullptr) {
;     ...
;     int k0 = kt * 64, n0 = ntile * 256;
;     {
;       int n = tid & 255;
;       int sc = srccol(perm, n0 + n);
;       const float* wp = Ws + (size_t)(k0 + (tid >> 8)) * N + sc;
;       float v[32];
; #pragma unroll
;       for (int i = 0; i < 32; ++i) v[i] = wp[(size_t)(2 * i) * N];
;       if (kscale) {
;         const float* ks = kscale + (size_t)mi * K + k0 + (tid >> 8);
; #pragma unroll
;         for (int i = 0; i < 32; ++i) v[i] *= ks[2 * i];
;       }
; #pragma unroll
;       for (int i = 0; i < 32; ++i) tile[(2 * i + (tid >> 8)) * 257 + n] = v[i];
.LBB0_926:
	s_mul_hi_i32 s1, s0, 0x2aaaaaab
	s_lshr_b32 s2, s1, 31
	s_ashr_i32 s1, s1, 5
	s_add_i32 s1, s1, s2
	s_mul_i32 s4, s1, 0xffffff40
	s_mul_hi_i32 s3, s1, 0x300000
	s_mul_i32 s2, s1, 0x300000
	s_add_i32 s1, s0, s4
	s_mul_i32 s6, s1, 0x2aab
	s_lshr_b32 s7, s6, 31
	s_ashr_i32 s6, s6, 17
	s_add_i32 s6, s6, s7
	s_mul_i32 s7, s6, 12
	s_lshl_b64 s[4:5], s[2:3], 2
	s_sub_i32 s1, s1, s7
	s_add_u32 s4, s12, s4
	s_addc_u32 s5, s13, s5
	s_lshl_b64 s[2:3], s[2:3], 1
	s_sext_i32_i16 s1, s1
	s_add_u32 s7, s58, s2
	s_addc_u32 s8, s59, s3
	s_lshl_b32 s1, s1, 8
	s_lshl_b32 s2, s6, 6
	v_or_b32_e32 v22, s1, v3
	v_mov_b64_e32 v[8:9], s[4:5]
	v_add_u32_e32 v11, s2, v4
	v_add_u32_e32 v10, s1, v7
	v_add_u32_e32 v13, 0xfffffc00, v22
	v_mad_i64_i32 v[16:17], s[4:5], v11, s15, v[8:9]
	v_add_u32_e32 v8, 64, v10
	v_lshrrev_b32_e32 v18, 1, v13
	v_ashrrev_i32_e32 v9, 31, v8
	v_and_b32_e32 v20, 0x7ffffff0, v18
	s_movk_i32 s1, 0x400
	v_lshlrev_b64 v[18:19], 11, v[8:9]
	v_add_u32_e32 v8, v5, v20
	v_cmp_gt_i32_e32 vcc, s1, v22
	s_ashr_i32 s3, s2, 31
	s_lshl_b64 s[2:3], s[2:3], 1
	v_cndmask_b32_e32 v22, v8, v22, vcc
	v_ashrrev_i32_e32 v23, 31, v22
	s_add_u32 s2, s7, s2
	v_lshl_add_u64 v[36:37], v[22:23], 2, v[16:17]
	v_ashrrev_i32_e32 v11, 31, v10
	s_addc_u32 s3, s8, s3
	v_add_co_u32_e32 v16, vcc, s10, v36
	v_add_u32_e32 v12, 0x80, v10
	v_add_u32_e32 v14, 0xc0, v10
	v_lshlrev_b64 v[10:11], 11, v[10:11]
	v_lshl_add_u64 v[20:21], s[2:3], 0, v[0:1]
	v_addc_co_u32_e32 v17, vcc, 0, v37, vcc
	v_ashrrev_i32_e32 v13, 31, v12
	v_ashrrev_i32_e32 v15, 31, v14
	v_lshl_add_u64 v[8:9], v[20:21], 0, v[10:11]
	v_lshl_add_u64 v[10:11], v[20:21], 0, v[18:19]
	v_add_co_u32_e32 v18, vcc, s16, v36
	v_lshlrev_b64 v[12:13], 11, v[12:13]
	v_lshlrev_b64 v[14:15], 11, v[14:15]
	v_addc_co_u32_e32 v19, vcc, 0, v37, vcc
	v_lshl_add_u64 v[12:13], v[20:21], 0, v[12:13]
	v_lshl_add_u64 v[14:15], v[20:21], 0, v[14:15]
	v_add_co_u32_e32 v20, vcc, s95, v36
	s_mov_b32 s1, 0x4e000
	s_nop 0
	v_addc_co_u32_e32 v21, vcc, 0, v37, vcc
	v_add_co_u32_e32 v22, vcc, s11, v36
	v_add_u32_e32 v52, 4, v50
	s_nop 0
	v_addc_co_u32_e32 v23, vcc, 0, v37, vcc
	v_add_co_u32_e32 v24, vcc, s14, v36
	v_add_u32_e32 v53, 8, v50
	s_nop 0
	v_addc_co_u32_e32 v25, vcc, 0, v37, vcc
	v_add_co_u32_e32 v26, vcc, s30, v36
	v_add_u32_e32 v54, 12, v50
	s_nop 0
	v_addc_co_u32_e32 v27, vcc, 0, v37, vcc
	v_add_co_u32_e32 v28, vcc, s19, v36
	v_add_u32_e32 v55, 16, v50
	s_waitcnt lgkmcnt(0)
	v_addc_co_u32_e32 v29, vcc, 0, v37, vcc
	v_add_co_u32_e32 v30, vcc, s20, v36
	v_add_u32_e32 v56, 20, v50
	s_nop 0
	v_addc_co_u32_e32 v31, vcc, 0, v37, vcc
	v_add_co_u32_e32 v32, vcc, s96, v36
	v_add_u32_e32 v57, 24, v50
	s_nop 0
	v_addc_co_u32_e32 v33, vcc, 0, v37, vcc
	v_add_co_u32_e32 v34, vcc, s21, v36
	v_add_u32_e32 v58, 28, v50
	s_nop 0
	v_addc_co_u32_e32 v35, vcc, 0, v37, vcc
	v_add_co_u32_e32 v38, vcc, s17, v36
	s_add_i32 s0, s0, s44
	s_nop 0
	v_addc_co_u32_e32 v39, vcc, 0, v37, vcc
	v_add_co_u32_e32 v40, vcc, s34, v36
	s_cmpk_lt_i32 s0, 0x180
	s_nop 0
	v_addc_co_u32_e32 v41, vcc, 0, v37, vcc
	v_add_co_u32_e32 v42, vcc, s1, v36
	s_mov_b32 s1, 0x66000
	s_nop 0
	v_addc_co_u32_e32 v43, vcc, 0, v37, vcc
	v_add_co_u32_e32 v44, vcc, s22, v36
	s_nop 1
	v_addc_co_u32_e32 v45, vcc, 0, v37, vcc
	v_add_co_u32_e32 v46, vcc, s83, v36
	s_nop 1
	v_addc_co_u32_e32 v47, vcc, 0, v37, vcc
	v_add_co_u32_e32 v48, vcc, s23, v36
	s_nop 1
	v_addc_co_u32_e32 v49, vcc, 0, v37, vcc
	v_add_co_u32_e32 v60, vcc, s1, v36
	s_mov_b32 s1, 0x72000
	s_nop 0
	v_addc_co_u32_e32 v61, vcc, 0, v37, vcc
	v_add_co_u32_e32 v62, vcc, s97, v36
	s_nop 1
	v_addc_co_u32_e32 v63, vcc, 0, v37, vcc
	v_add_co_u32_e32 v64, vcc, s1, v36
	s_mov_b32 s1, 0x8a000
	s_nop 0
	v_addc_co_u32_e32 v65, vcc, 0, v37, vcc
	v_add_co_u32_e32 v66, vcc, s24, v36
	s_nop 1
	v_addc_co_u32_e32 v67, vcc, 0, v37, vcc
	v_add_co_u32_e32 v68, vcc, s33, v36
	s_nop 1
	v_addc_co_u32_e32 v69, vcc, 0, v37, vcc
	v_add_co_u32_e32 v70, vcc, s18, v36
	s_nop 1
	v_addc_co_u32_e32 v71, vcc, 0, v37, vcc
	v_add_co_u32_e32 v76, vcc, s1, v36
	s_mov_b32 s1, 0x96000
	s_nop 0
	v_addc_co_u32_e32 v77, vcc, 0, v37, vcc
	v_add_co_u32_e32 v78, vcc, s9, v36
	s_nop 1
	v_addc_co_u32_e32 v79, vcc, 0, v37, vcc
	v_add_co_u32_e32 v80, vcc, s1, v36
	s_mov_b32 s1, 0xa2000
	s_nop 0
	v_addc_co_u32_e32 v81, vcc, 0, v37, vcc
	v_add_co_u32_e32 v82, vcc, s25, v36
	s_nop 1
	v_addc_co_u32_e32 v83, vcc, 0, v37, vcc
	v_add_co_u32_e32 v84, vcc, s1, v36
	s_mov_b32 s1, 0xae000
	s_nop 0
	v_addc_co_u32_e32 v85, vcc, 0, v37, vcc
	v_add_co_u32_e32 v86, vcc, s26, v36
	s_nop 1
	v_addc_co_u32_e32 v87, vcc, 0, v37, vcc
	v_add_co_u32_e32 v88, vcc, s1, v36
	s_mov_b32 s1, 0xba000
	s_nop 0
	v_addc_co_u32_e32 v89, vcc, 0, v37, vcc
	v_add_co_u32_e32 v90, vcc, s27, v36
	s_nop 1
	v_addc_co_u32_e32 v91, vcc, 0, v37, vcc
	v_add_co_u32_e32 v92, vcc, s1, v36
	s_nop 1
	v_addc_co_u32_e32 v93, vcc, 0, v37, vcc
	global_load_dword v36, v[36:37], off
	s_nop 0
	global_load_dword v16, v[16:17], off
	s_nop 0
	global_load_dword v17, v[18:19], off
	s_nop 0
	global_load_dword v18, v[20:21], off
	global_load_dword v19, v[22:23], off
	s_nop 0
	global_load_dword v20, v[24:25], off
	global_load_dword v21, v[26:27], off
	global_load_dword v22, v[28:29], off
	global_load_dword v23, v[30:31], off
	s_nop 0
	global_load_dword v24, v[32:33], off
	global_load_dword v25, v[34:35], off
	global_load_dword v26, v[38:39], off
	global_load_dword v27, v[40:41], off
	global_load_dword v28, v[42:43], off
	global_load_dword v29, v[44:45], off
	global_load_dword v30, v[46:47], off
	global_load_dword v31, v[48:49], off
	global_load_dword v32, v[60:61], off
	global_load_dword v33, v[62:63], off
	global_load_dword v34, v[64:65], off
	global_load_dword v35, v[66:67], off
	global_load_dword v37, v[68:69], off
	global_load_dword v38, v[70:71], off
	global_load_dword v39, v[76:77], off
	global_load_dword v40, v[78:79], off
	global_load_dword v41, v[80:81], off
	global_load_dword v42, v[82:83], off
	global_load_dword v43, v[84:85], off
	global_load_dword v44, v[86:87], off
	global_load_dword v45, v[88:89], off
	global_load_dword v46, v[90:91], off
	global_load_dword v47, v[92:93], off
	s_waitcnt vmcnt(31)
; __device__ __forceinline__ void conv_family(const float* __restrict__ W, u16* __restrict__ Wt, int cnt, int K, int N, int perm,
;                             float* tile, const int tid, const float* __restrict__ kscale = nullptr) {
;     ...
;       for (int i = 0; i < 32; ++i) tile[(2 * i + (tid >> 8)) * 257 + n] = v[i];
;     }
;     __syncthreads();
	ds_write_b32 v51, v36
	s_waitcnt vmcnt(30)
	ds_write_b32 v51, v16 offset:2056
	s_waitcnt vmcnt(29)
	ds_write_b32 v51, v17 offset:4112
	s_waitcnt vmcnt(28)
	ds_write_b32 v51, v18 offset:6168
	s_waitcnt vmcnt(27)
	ds_write_b32 v51, v19 offset:8224
	s_waitcnt vmcnt(26)
	ds_write_b32 v51, v20 offset:10280
	s_waitcnt vmcnt(25)
	ds_write_b32 v51, v21 offset:12336
	s_waitcnt vmcnt(24)
	ds_write_b32 v51, v22 offset:14392
	s_waitcnt vmcnt(23)
	ds_write_b32 v51, v23 offset:16448
	s_waitcnt vmcnt(22)
	ds_write_b32 v51, v24 offset:18504
	s_waitcnt vmcnt(21)
	ds_write_b32 v51, v25 offset:20560
	s_waitcnt vmcnt(20)
	ds_write_b32 v51, v26 offset:22616
	s_waitcnt vmcnt(19)
	ds_write_b32 v51, v27 offset:24672
	s_waitcnt vmcnt(18)
	ds_write_b32 v51, v28 offset:26728
	s_waitcnt vmcnt(17)
	ds_write_b32 v51, v29 offset:28784
	s_waitcnt vmcnt(16)
	ds_write_b32 v51, v30 offset:30840
	s_waitcnt vmcnt(15)
	ds_write_b32 v51, v31 offset:32896
	s_waitcnt vmcnt(14)
	ds_write_b32 v51, v32 offset:34952
	s_waitcnt vmcnt(13)
	ds_write_b32 v51, v33 offset:37008
	s_waitcnt vmcnt(12)
	ds_write_b32 v51, v34 offset:39064
	s_waitcnt vmcnt(11)
	ds_write_b32 v51, v35 offset:41120
	s_waitcnt vmcnt(10)
	ds_write_b32 v51, v37 offset:43176
	s_waitcnt vmcnt(9)
	ds_write_b32 v51, v38 offset:45232
	s_waitcnt vmcnt(8)
	ds_write_b32 v51, v39 offset:47288
	s_waitcnt vmcnt(7)
	ds_write_b32 v51, v40 offset:49344
	s_waitcnt vmcnt(6)
	ds_write_b32 v51, v41 offset:51400
	s_waitcnt vmcnt(5)
	ds_write_b32 v51, v42 offset:53456
	s_waitcnt vmcnt(4)
	ds_write_b32 v51, v43 offset:55512
	s_waitcnt vmcnt(3)
	ds_write_b32 v51, v44 offset:57568
	s_waitcnt vmcnt(2)
	ds_write_b32 v51, v45 offset:59624
	s_waitcnt vmcnt(1)
	ds_write_b32 v51, v46 offset:61680
	s_waitcnt vmcnt(0)
	ds_write_b32 v51, v47 offset:63736
	s_waitcnt lgkmcnt(0)
	s_barrier
; __device__ __forceinline__ unsigned pack2(float a, float b) { return (unsigned)f2bf(a) | ((unsigned)f2bf(b) << 16); }
; __device__ __forceinline__ void conv_family(const float* __restrict__ W, u16* __restrict__ Wt, int cnt, int K, int N, int perm,
;                             float* tile, const int tid, const float* __restrict__ kscale = nullptr) {
;     ...
; #pragma unroll
;     for (int i = 0; i < 4; ++i) {
;       int n = i * 64 + (tid >> 3), ks = (tid & 7) * 8;
;       uint4 pk;
;       pk.x = pack2(tile[(ks + 0) * 257 + n], tile[(ks + 1) * 257 + n]);
;       pk.y = pack2(tile[(ks + 2) * 257 + n], tile[(ks + 3) * 257 + n]);
;       pk.z = pack2(tile[(ks + 4) * 257 + n], tile[(ks + 5) * 257 + n]);
;       pk.w = pack2(tile[(ks + 6) * 257 + n], tile[(ks + 7) * 257 + n]);
;       *(uint4*)(Wd + (size_t)(n0 + n) * K + k0 + ks) = pk;
;     }
;     __syncthreads();
;   }
	ds_read2st64_b32 v[16:17], v50 offset1:1
	ds_read2st64_b32 v[18:19], v50 offset0:2 offset1:3
	ds_read2st64_b32 v[20:21], v52 offset0:4 offset1:5
	ds_read2st64_b32 v[22:23], v52 offset0:6 offset1:7
	ds_read2st64_b32 v[24:25], v53 offset0:8 offset1:9
	ds_read2st64_b32 v[26:27], v53 offset0:10 offset1:11
	ds_read2st64_b32 v[28:29], v54 offset0:12 offset1:13
	ds_read2st64_b32 v[30:31], v54 offset0:14 offset1:15
	ds_read2st64_b32 v[32:33], v55 offset0:16 offset1:17
	ds_read2st64_b32 v[34:35], v55 offset0:18 offset1:19
	ds_read2st64_b32 v[36:37], v56 offset0:20 offset1:21
	ds_read2st64_b32 v[38:39], v56 offset0:22 offset1:23
	ds_read2st64_b32 v[40:41], v57 offset0:24 offset1:25
	ds_read2st64_b32 v[42:43], v57 offset0:26 offset1:27
	ds_read2st64_b32 v[44:45], v58 offset0:28 offset1:29
	ds_read2st64_b32 v[46:47], v58 offset0:30 offset1:31
	s_waitcnt lgkmcnt(9)
	s_waitcnt lgkmcnt(5)
	v_and_b32_sdwa v57, v36, v178 dst_sel:DWORD dst_unused:UNUSED_PAD src0_sel:WORD_1 src1_sel:DWORD
	s_waitcnt lgkmcnt(1)
	v_and_b32_sdwa v54, v40, v178 dst_sel:DWORD dst_unused:UNUSED_PAD src0_sel:WORD_1 src1_sel:DWORD
	v_and_b32_sdwa v55, v32, v178 dst_sel:DWORD dst_unused:UNUSED_PAD src0_sel:WORD_1 src1_sel:DWORD
	v_and_b32_sdwa v59, v17, v178 dst_sel:DWORD dst_unused:UNUSED_PAD src0_sel:WORD_1 src1_sel:DWORD
	v_and_b32_sdwa v60, v29, v178 dst_sel:DWORD dst_unused:UNUSED_PAD src0_sel:WORD_1 src1_sel:DWORD
	v_and_b32_sdwa v61, v21, v178 dst_sel:DWORD dst_unused:UNUSED_PAD src0_sel:WORD_1 src1_sel:DWORD
	v_and_b32_sdwa v62, v41, v178 dst_sel:DWORD dst_unused:UNUSED_PAD src0_sel:WORD_1 src1_sel:DWORD
	v_and_b32_sdwa v63, v33, v178 dst_sel:DWORD dst_unused:UNUSED_PAD src0_sel:WORD_1 src1_sel:DWORD
	v_and_b32_sdwa v64, v45, v178 dst_sel:DWORD dst_unused:UNUSED_PAD src0_sel:WORD_1 src1_sel:DWORD
	v_and_b32_sdwa v65, v37, v178 dst_sel:DWORD dst_unused:UNUSED_PAD src0_sel:WORD_1 src1_sel:DWORD
	v_and_b32_sdwa v67, v18, v178 dst_sel:DWORD dst_unused:UNUSED_PAD src0_sel:WORD_1 src1_sel:DWORD
	v_and_b32_sdwa v68, v30, v178 dst_sel:DWORD dst_unused:UNUSED_PAD src0_sel:WORD_1 src1_sel:DWORD
	v_and_b32_sdwa v69, v22, v178 dst_sel:DWORD dst_unused:UNUSED_PAD src0_sel:WORD_1 src1_sel:DWORD
	v_and_b32_sdwa v70, v42, v178 dst_sel:DWORD dst_unused:UNUSED_PAD src0_sel:WORD_1 src1_sel:DWORD
	v_and_b32_sdwa v71, v34, v178 dst_sel:DWORD dst_unused:UNUSED_PAD src0_sel:WORD_1 src1_sel:DWORD
	s_waitcnt lgkmcnt(0)
	v_and_b32_sdwa v76, v46, v178 dst_sel:DWORD dst_unused:UNUSED_PAD src0_sel:WORD_1 src1_sel:DWORD
	v_and_b32_sdwa v77, v38, v178 dst_sel:DWORD dst_unused:UNUSED_PAD src0_sel:WORD_1 src1_sel:DWORD
	v_and_b32_sdwa v78, v27, v178 dst_sel:DWORD dst_unused:UNUSED_PAD src0_sel:WORD_1 src1_sel:DWORD
	v_and_b32_sdwa v79, v19, v178 dst_sel:DWORD dst_unused:UNUSED_PAD src0_sel:WORD_1 src1_sel:DWORD
	v_and_b32_sdwa v80, v31, v178 dst_sel:DWORD dst_unused:UNUSED_PAD src0_sel:WORD_1 src1_sel:DWORD
	v_and_b32_sdwa v81, v23, v178 dst_sel:DWORD dst_unused:UNUSED_PAD src0_sel:WORD_1 src1_sel:DWORD
	v_and_b32_sdwa v82, v43, v178 dst_sel:DWORD dst_unused:UNUSED_PAD src0_sel:WORD_1 src1_sel:DWORD
	v_and_b32_sdwa v84, v47, v178 dst_sel:DWORD dst_unused:UNUSED_PAD src0_sel:WORD_1 src1_sel:DWORD
	v_and_b32_sdwa v85, v39, v178 dst_sel:DWORD dst_unused:UNUSED_PAD src0_sel:WORD_1 src1_sel:DWORD
	v_cvt_pk_bf16_f32 v28, v28, v28
	v_cvt_pk_bf16_f32 v20, v20, v20
	v_cvt_pk_bf16_f32 v44, v44, v44
	v_add3_u32 v36, v36, v57, s81
	v_and_b32_sdwa v58, v25, v178 dst_sel:DWORD dst_unused:UNUSED_PAD src0_sel:WORD_1 src1_sel:DWORD
	v_and_b32_sdwa v66, v26, v178 dst_sel:DWORD dst_unused:UNUSED_PAD src0_sel:WORD_1 src1_sel:DWORD
	v_and_b32_sdwa v83, v35, v178 dst_sel:DWORD dst_unused:UNUSED_PAD src0_sel:WORD_1 src1_sel:DWORD
	v_cvt_pk_bf16_f32 v16, v16, v16
	v_cvt_pk_bf16_f32 v24, v24, v24
	v_add3_u32 v32, v32, v55, s81
	v_add3_u32 v40, v40, v54, s81
	v_add3_u32 v48, v17, v59, s81
	v_add3_u32 v17, v29, v60, s81
	v_add3_u32 v21, v21, v61, s81
	v_add3_u32 v29, v33, v63, s81
	v_add3_u32 v33, v41, v62, s81
	v_add3_u32 v41, v45, v64, s81
	v_add3_u32 v37, v37, v65, s81
	v_add3_u32 v45, v18, v67, s81
	v_add3_u32 v18, v30, v68, s81
	v_add3_u32 v22, v22, v69, s81
	v_add3_u32 v30, v34, v71, s81
	v_add3_u32 v34, v42, v70, s81
	v_add3_u32 v42, v46, v76, s81
	v_add3_u32 v38, v38, v77, s81
	v_add3_u32 v46, v19, v79, s81
	v_add3_u32 v49, v27, v78, s81
	v_add3_u32 v19, v31, v80, s81
	v_add3_u32 v23, v23, v81, s81
	v_add3_u32 v31, v43, v82, s81
	v_add3_u32 v27, v47, v84, s81
	v_add3_u32 v39, v39, v85, s81
	v_and_b32_e32 v28, 0xffff0000, v28
	v_and_b32_e32 v20, 0xffff0000, v20
	v_and_b32_e32 v43, 0xffff0000, v44
	v_and_b32_e32 v36, 0xffff0000, v36
	v_add3_u32 v25, v25, v58, s81
	v_add3_u32 v26, v26, v66, s81
	v_add3_u32 v35, v35, v83, s81
	v_and_b32_e32 v44, 0xffff0000, v17
	v_and_b32_e32 v47, 0xffff0000, v21
	v_and_b32_e32 v41, 0xffff0000, v41
	v_and_b32_e32 v37, 0xffff0000, v37
	v_and_b32_e32 v52, 0xffff0000, v18
	v_and_b32_e32 v53, 0xffff0000, v22
	v_and_b32_e32 v42, 0xffff0000, v42
	v_and_b32_e32 v38, 0xffff0000, v38
	v_and_b32_e32 v54, 0xffff0000, v19
	v_and_b32_e32 v55, 0xffff0000, v23
	v_and_b32_e32 v56, 0xffff0000, v27
	v_and_b32_e32 v39, 0xffff0000, v39
	v_or_b32_sdwa v17, v28, v24 dst_sel:DWORD dst_unused:UNUSED_PAD src0_sel:DWORD src1_sel:WORD_1
	v_or_b32_sdwa v16, v20, v16 dst_sel:DWORD dst_unused:UNUSED_PAD src0_sel:DWORD src1_sel:WORD_1
	v_or_b32_sdwa v19, v43, v40 dst_sel:DWORD dst_unused:UNUSED_PAD src0_sel:DWORD src1_sel:WORD_1
	v_or_b32_sdwa v18, v36, v32 dst_sel:DWORD dst_unused:UNUSED_PAD src0_sel:DWORD src1_sel:WORD_1
	v_or_b32_sdwa v21, v44, v25 dst_sel:DWORD dst_unused:UNUSED_PAD src0_sel:DWORD src1_sel:WORD_1
	v_or_b32_sdwa v20, v47, v48 dst_sel:DWORD dst_unused:UNUSED_PAD src0_sel:DWORD src1_sel:WORD_1
	v_or_b32_sdwa v23, v41, v33 dst_sel:DWORD dst_unused:UNUSED_PAD src0_sel:DWORD src1_sel:WORD_1
	v_or_b32_sdwa v22, v37, v29 dst_sel:DWORD dst_unused:UNUSED_PAD src0_sel:DWORD src1_sel:WORD_1
	v_or_b32_sdwa v25, v52, v26 dst_sel:DWORD dst_unused:UNUSED_PAD src0_sel:DWORD src1_sel:WORD_1
	v_or_b32_sdwa v24, v53, v45 dst_sel:DWORD dst_unused:UNUSED_PAD src0_sel:DWORD src1_sel:WORD_1
	v_or_b32_sdwa v27, v42, v34 dst_sel:DWORD dst_unused:UNUSED_PAD src0_sel:DWORD src1_sel:WORD_1
	v_or_b32_sdwa v26, v38, v30 dst_sel:DWORD dst_unused:UNUSED_PAD src0_sel:DWORD src1_sel:WORD_1
	v_or_b32_sdwa v29, v54, v49 dst_sel:DWORD dst_unused:UNUSED_PAD src0_sel:DWORD src1_sel:WORD_1
	v_or_b32_sdwa v28, v55, v46 dst_sel:DWORD dst_unused:UNUSED_PAD src0_sel:DWORD src1_sel:WORD_1
	v_or_b32_sdwa v31, v56, v31 dst_sel:DWORD dst_unused:UNUSED_PAD src0_sel:DWORD src1_sel:WORD_1
	v_or_b32_sdwa v30, v39, v35 dst_sel:DWORD dst_unused:UNUSED_PAD src0_sel:DWORD src1_sel:WORD_1
	global_store_dwordx4 v[8:9], v[16:19], off
	global_store_dwordx4 v[10:11], v[20:23], off
	global_store_dwordx4 v[12:13], v[24:27], off
	global_store_dwordx4 v[14:15], v[28:31], off
	s_barrier
	s_cbranch_scc1 .LBB0_926

; __device__ __forceinline__ int srccol(int perm, int n) {
;     ...
;   } else if (perm == 4) {
;     int grp = n >> 5, t = (n >> 4) & 1, i = n & 15;
;     return grp * 32 + 2 * i + t;
; __device__ __forceinline__ void conv_family(const float* __restrict__ W, u16* __restrict__ Wt, int cnt, int K, int N, int perm,
;                             float* tile, const int tid, const float* __restrict__ kscale = nullptr) {
;     ...
;     int k0 = kt * 64, n0 = ntile * 256;
;     {
;       int n = tid & 255;
;       int sc = srccol(perm, n0 + n);
;       const float* wp = Ws + (size_t)(k0 + (tid >> 8)) * N + sc;
;       float v[32];
; #pragma unroll
;       for (int i = 0; i < 32; ++i) v[i] = wp[(size_t)(2 * i) * N];
;       if (kscale) {
;         const float* ks = kscale + (size_t)mi * K + k0 + (tid >> 8);
; #pragma unroll
;         for (int i = 0; i < 32; ++i) v[i] *= ks[2 * i];
;       }
; #pragma unroll
;       for (int i = 0; i < 32; ++i) tile[(2 * i + (tid >> 8)) * 257 + n] = v[i];
.LBB0_929:
	s_ashr_i32 s0, s4, 31
	s_lshr_b32 s0, s0, 26
	s_add_i32 s0, s4, s0
	s_ashr_i32 s2, s0, 6
	s_and_b32 s0, s0, 0xffc0
	s_sub_i32 s5, s4, s0
	s_bfe_i32 s6, s5, 0x80000
	s_bfe_u32 s6, s6, 0x2000d
	s_add_i32 s6, s5, s6
	s_ashr_i32 s3, s2, 31
	s_sext_i32_i8 s7, s6
	s_and_b32 s6, s6, 0xfc
	s_lshl_b64 s[0:1], s[2:3], 22
	s_sub_i32 s5, s5, s6
	s_add_u32 s0, s16, s0
	s_addc_u32 s1, s17, s1
	s_lshl_b64 s[2:3], s[2:3], 21
	s_add_u32 s6, s60, s2
	s_addc_u32 s8, s61, s3
	s_lshl_b32 s2, s7, 4
	s_sext_i32_i8 s5, s5
	s_andn2_b32 s2, s2, 63
	v_lshlrev_b32_e32 v6, 1, v3
	s_lshl_b32 s3, s5, 8
	v_add_u32_e32 v14, s2, v4
	v_and_b32_e32 v6, 30, v6
	v_bitop3_b32 v11, s3, v99, v3 bitop3:0xc8
	v_ashrrev_i32_e32 v15, 31, v14
	v_or3_b32 v12, v11, v75, v6
	v_lshlrev_b64 v[14:15], 12, v[14:15]
	v_ashrrev_i32_e32 v13, 31, v12
	v_lshl_add_u64 v[14:15], s[0:1], 0, v[14:15]
	v_lshl_add_u64 v[12:13], v[12:13], 2, v[14:15]
	v_add_co_u32_e32 v22, vcc, s9, v12
	v_add_u32_e32 v10, s3, v7
	s_nop 0
	v_addc_co_u32_e32 v23, vcc, 0, v13, vcc
	v_add_co_u32_e32 v24, vcc, s13, v12
	s_ashr_i32 s3, s2, 31
	s_nop 0
	v_addc_co_u32_e32 v25, vcc, 0, v13, vcc
	v_add_co_u32_e32 v26, vcc, s14, v12
	s_lshl_b64 s[2:3], s[2:3], 1
	s_nop 0
	v_addc_co_u32_e32 v27, vcc, 0, v13, vcc
	v_add_co_u32_e32 v28, vcc, s84, v12
	v_add_u32_e32 v16, 64, v10
	s_waitcnt lgkmcnt(0)
	v_addc_co_u32_e32 v29, vcc, 0, v13, vcc
	v_add_co_u32_e32 v30, vcc, s19, v12
	v_add_u32_e32 v18, 0x80, v10
	s_nop 0
	v_addc_co_u32_e32 v31, vcc, 0, v13, vcc
	v_add_co_u32_e32 v32, vcc, s22, v12
	v_add_u32_e32 v20, 0xc0, v10
	s_nop 0
	v_addc_co_u32_e32 v33, vcc, 0, v13, vcc
	v_add_co_u32_e32 v34, vcc, s23, v12
	s_add_u32 s2, s6, s2
	s_nop 0
	v_addc_co_u32_e32 v35, vcc, 0, v13, vcc
	v_add_co_u32_e32 v36, vcc, s10, v12
	v_ashrrev_i32_e32 v11, 31, v10
	s_nop 0
	v_addc_co_u32_e32 v37, vcc, 0, v13, vcc
	v_add_co_u32_e32 v38, vcc, s95, v12
	v_ashrrev_i32_e32 v17, 31, v16
	s_nop 0
	v_addc_co_u32_e32 v39, vcc, 0, v13, vcc
	v_add_co_u32_e32 v40, vcc, s11, v12
	v_ashrrev_i32_e32 v19, 31, v18
	s_nop 0
	v_addc_co_u32_e32 v41, vcc, 0, v13, vcc
	v_add_co_u32_e32 v42, vcc, s12, v12
	v_ashrrev_i32_e32 v21, 31, v20
	s_nop 0
	v_addc_co_u32_e32 v43, vcc, 0, v13, vcc
	v_add_co_u32_e32 v44, vcc, s15, v12
	s_addc_u32 s3, s8, s3
	s_nop 0
	v_addc_co_u32_e32 v45, vcc, 0, v13, vcc
	v_add_co_u32_e32 v46, vcc, s18, v12
	v_lshlrev_b64 v[10:11], 11, v[10:11]
	s_nop 0
	v_addc_co_u32_e32 v47, vcc, 0, v13, vcc
	v_add_co_u32_e32 v48, vcc, s20, v12
	v_lshlrev_b64 v[16:17], 11, v[16:17]
	s_nop 0
	v_addc_co_u32_e32 v49, vcc, 0, v13, vcc
	v_add_co_u32_e32 v50, vcc, s21, v12
	v_lshlrev_b64 v[18:19], 11, v[18:19]
	s_nop 0
	v_addc_co_u32_e32 v51, vcc, 0, v13, vcc
	v_add_co_u32_e32 v52, vcc, s24, v12
	v_lshlrev_b64 v[20:21], 11, v[20:21]
	s_nop 0
	v_addc_co_u32_e32 v53, vcc, 0, v13, vcc
	v_add_co_u32_e32 v54, vcc, s27, v12
	v_lshl_add_u64 v[14:15], s[2:3], 0, v[0:1]
	s_nop 0
	v_addc_co_u32_e32 v55, vcc, 0, v13, vcc
	v_add_co_u32_e32 v56, vcc, s30, v12
	v_lshl_add_u64 v[86:87], v[14:15], 0, v[10:11]
	s_nop 0
	v_addc_co_u32_e32 v57, vcc, 0, v13, vcc
	v_add_co_u32_e32 v58, vcc, s36, v12
	v_lshl_add_u64 v[88:89], v[14:15], 0, v[16:17]
	s_nop 0
	v_addc_co_u32_e32 v59, vcc, 0, v13, vcc
	v_add_co_u32_e32 v60, vcc, s25, v12
	v_lshl_add_u64 v[90:91], v[14:15], 0, v[18:19]
	s_nop 0
	v_addc_co_u32_e32 v61, vcc, 0, v13, vcc
	v_add_co_u32_e32 v62, vcc, s37, v12
	v_lshl_add_u64 v[92:93], v[14:15], 0, v[20:21]
	s_nop 0
	v_addc_co_u32_e32 v63, vcc, 0, v13, vcc
	v_add_co_u32_e32 v64, vcc, s26, v12
	v_add_u32_e32 v9, 4, v5
	s_nop 0
	v_addc_co_u32_e32 v65, vcc, 0, v13, vcc
	v_add_co_u32_e32 v66, vcc, s38, v12
	v_add_u32_e32 v74, 8, v5
	s_nop 0
	v_addc_co_u32_e32 v67, vcc, 0, v13, vcc
	v_add_co_u32_e32 v68, vcc, s39, v12
	v_add_u32_e32 v94, 12, v5
	s_nop 0
	v_addc_co_u32_e32 v69, vcc, 0, v13, vcc
	v_add_co_u32_e32 v70, vcc, s40, v12
	v_add_u32_e32 v95, 16, v5
	s_nop 0
	v_addc_co_u32_e32 v71, vcc, 0, v13, vcc
	v_add_co_u32_e32 v72, vcc, s41, v12
	v_add_u32_e32 v96, 20, v5
	s_nop 0
	v_addc_co_u32_e32 v73, vcc, 0, v13, vcc
	v_add_co_u32_e32 v76, vcc, s96, v12
	v_add_u32_e32 v97, 24, v5
	s_nop 0
	v_addc_co_u32_e32 v77, vcc, 0, v13, vcc
	v_add_co_u32_e32 v78, vcc, s43, v12
	v_add_u32_e32 v98, 28, v5
	s_nop 0
	v_addc_co_u32_e32 v79, vcc, 0, v13, vcc
	v_add_co_u32_e32 v80, vcc, s48, v12
	s_add_i32 s4, s4, s44
	s_nop 0
	v_addc_co_u32_e32 v81, vcc, 0, v13, vcc
	v_add_co_u32_e32 v82, vcc, s50, v12
	s_cmpk_lt_i32 s4, 0x80
	s_nop 0
	v_addc_co_u32_e32 v83, vcc, 0, v13, vcc
	v_add_co_u32_e32 v84, vcc, s51, v12
	s_nop 1
	v_addc_co_u32_e32 v85, vcc, 0, v13, vcc
	global_load_dword v6, v[12:13], off
	global_load_dword v10, v[22:23], off
	global_load_dword v11, v[24:25], off
	s_nop 0
	global_load_dword v12, v[26:27], off
	global_load_dword v13, v[28:29], off
	global_load_dword v14, v[30:31], off
	global_load_dword v15, v[32:33], off
	global_load_dword v16, v[34:35], off
	global_load_dword v17, v[36:37], off
	global_load_dword v18, v[38:39], off
	global_load_dword v19, v[40:41], off
	global_load_dword v20, v[42:43], off
	global_load_dword v21, v[44:45], off
	global_load_dword v22, v[46:47], off
	global_load_dword v23, v[48:49], off
	global_load_dword v24, v[50:51], off
	global_load_dword v25, v[52:53], off
	global_load_dword v26, v[54:55], off
	global_load_dword v27, v[56:57], off
	global_load_dword v28, v[58:59], off
	global_load_dword v29, v[60:61], off
	global_load_dword v30, v[62:63], off
	global_load_dword v31, v[64:65], off
	global_load_dword v32, v[66:67], off
	global_load_dword v33, v[68:69], off
	global_load_dword v34, v[70:71], off
	global_load_dword v35, v[72:73], off
	global_load_dword v36, v[76:77], off
	global_load_dword v37, v[78:79], off
	global_load_dword v38, v[80:81], off
	global_load_dword v39, v[82:83], off
	global_load_dword v40, v[84:85], off
	s_waitcnt vmcnt(31)
; __device__ __forceinline__ void conv_family(const float* __restrict__ W, u16* __restrict__ Wt, int cnt, int K, int N, int perm,
;                             float* tile, const int tid, const float* __restrict__ kscale = nullptr) {
;     ...
;       for (int i = 0; i < 32; ++i) tile[(2 * i + (tid >> 8)) * 257 + n] = v[i];
;     }
;     __syncthreads();
	ds_write_b32 v8, v6
	s_waitcnt vmcnt(30)
	ds_write_b32 v8, v10 offset:2056
	s_waitcnt vmcnt(29)
	ds_write_b32 v8, v11 offset:4112
	s_waitcnt vmcnt(28)
	ds_write_b32 v8, v12 offset:6168
	s_waitcnt vmcnt(27)
	ds_write_b32 v8, v13 offset:8224
	s_waitcnt vmcnt(26)
	ds_write_b32 v8, v14 offset:10280
	s_waitcnt vmcnt(25)
	ds_write_b32 v8, v15 offset:12336
	s_waitcnt vmcnt(24)
	ds_write_b32 v8, v16 offset:14392
	s_waitcnt vmcnt(23)
	ds_write_b32 v8, v17 offset:16448
	s_waitcnt vmcnt(22)
	ds_write_b32 v8, v18 offset:18504
	s_waitcnt vmcnt(21)
	ds_write_b32 v8, v19 offset:20560
	s_waitcnt vmcnt(20)
	ds_write_b32 v8, v20 offset:22616
	s_waitcnt vmcnt(19)
	ds_write_b32 v8, v21 offset:24672
	s_waitcnt vmcnt(18)
	ds_write_b32 v8, v22 offset:26728
	s_waitcnt vmcnt(17)
	ds_write_b32 v8, v23 offset:28784
	s_waitcnt vmcnt(16)
	ds_write_b32 v8, v24 offset:30840
	s_waitcnt vmcnt(15)
	ds_write_b32 v8, v25 offset:32896
	s_waitcnt vmcnt(14)
	ds_write_b32 v8, v26 offset:34952
	s_waitcnt vmcnt(13)
	ds_write_b32 v8, v27 offset:37008
	s_waitcnt vmcnt(12)
	ds_write_b32 v8, v28 offset:39064
	s_waitcnt vmcnt(11)
	ds_write_b32 v8, v29 offset:41120
	s_waitcnt vmcnt(10)
	ds_write_b32 v8, v30 offset:43176
	s_waitcnt vmcnt(9)
	ds_write_b32 v8, v31 offset:45232
	s_waitcnt vmcnt(8)
	ds_write_b32 v8, v32 offset:47288
	s_waitcnt vmcnt(7)
	ds_write_b32 v8, v33 offset:49344
	s_waitcnt vmcnt(6)
	ds_write_b32 v8, v34 offset:51400
	s_waitcnt vmcnt(5)
	ds_write_b32 v8, v35 offset:53456
	s_waitcnt vmcnt(4)
	ds_write_b32 v8, v36 offset:55512
	s_waitcnt vmcnt(3)
	ds_write_b32 v8, v37 offset:57568
	s_waitcnt vmcnt(2)
	ds_write_b32 v8, v38 offset:59624
	s_waitcnt vmcnt(1)
	ds_write_b32 v8, v39 offset:61680
	s_waitcnt vmcnt(0)
	ds_write_b32 v8, v40 offset:63736
	s_waitcnt lgkmcnt(0)
	s_barrier
; __device__ __forceinline__ unsigned pack2(float a, float b) { return (unsigned)f2bf(a) | ((unsigned)f2bf(b) << 16); }
; __device__ __forceinline__ void conv_family(const float* __restrict__ W, u16* __restrict__ Wt, int cnt, int K, int N, int perm,
;                             float* tile, const int tid, const float* __restrict__ kscale = nullptr) {
;     ...
; #pragma unroll
;     for (int i = 0; i < 4; ++i) {
;       int n = i * 64 + (tid >> 3), ks = (tid & 7) * 8;
;       uint4 pk;
;       pk.x = pack2(tile[(ks + 0) * 257 + n], tile[(ks + 1) * 257 + n]);
;       pk.y = pack2(tile[(ks + 2) * 257 + n], tile[(ks + 3) * 257 + n]);
;       pk.z = pack2(tile[(ks + 4) * 257 + n], tile[(ks + 5) * 257 + n]);
;       pk.w = pack2(tile[(ks + 6) * 257 + n], tile[(ks + 7) * 257 + n]);
;       *(uint4*)(Wd + (size_t)(n0 + n) * K + k0 + ks) = pk;
;     }
;     __syncthreads();
;   }
	ds_read2st64_b32 v[10:11], v5 offset1:1
	ds_read2st64_b32 v[12:13], v5 offset0:2 offset1:3
	ds_read2st64_b32 v[14:15], v9 offset0:4 offset1:5
	ds_read2st64_b32 v[16:17], v9 offset0:6 offset1:7
	ds_read2st64_b32 v[18:19], v74 offset0:8 offset1:9
	ds_read2st64_b32 v[20:21], v74 offset0:10 offset1:11
	ds_read2st64_b32 v[22:23], v94 offset0:12 offset1:13
	ds_read2st64_b32 v[24:25], v94 offset0:14 offset1:15
	ds_read2st64_b32 v[26:27], v95 offset0:16 offset1:17
	ds_read2st64_b32 v[28:29], v95 offset0:18 offset1:19
	ds_read2st64_b32 v[30:31], v96 offset0:20 offset1:21
	ds_read2st64_b32 v[32:33], v96 offset0:22 offset1:23
	ds_read2st64_b32 v[34:35], v97 offset0:24 offset1:25
	ds_read2st64_b32 v[36:37], v97 offset0:26 offset1:27
	ds_read2st64_b32 v[38:39], v98 offset0:28 offset1:29
	ds_read2st64_b32 v[40:41], v98 offset0:30 offset1:31
	s_waitcnt lgkmcnt(11)
	v_and_b32_sdwa v6, v18, v178 dst_sel:DWORD dst_unused:UNUSED_PAD src0_sel:WORD_1 src1_sel:DWORD
	v_and_b32_sdwa v9, v10, v178 dst_sel:DWORD dst_unused:UNUSED_PAD src0_sel:WORD_1 src1_sel:DWORD
	s_waitcnt lgkmcnt(9)
	s_waitcnt lgkmcnt(7)
	s_waitcnt lgkmcnt(1)
	v_and_b32_sdwa v47, v30, v178 dst_sel:DWORD dst_unused:UNUSED_PAD src0_sel:WORD_1 src1_sel:DWORD
	v_and_b32_sdwa v49, v11, v178 dst_sel:DWORD dst_unused:UNUSED_PAD src0_sel:WORD_1 src1_sel:DWORD
	v_and_b32_sdwa v50, v23, v178 dst_sel:DWORD dst_unused:UNUSED_PAD src0_sel:WORD_1 src1_sel:DWORD
	v_and_b32_sdwa v51, v15, v178 dst_sel:DWORD dst_unused:UNUSED_PAD src0_sel:WORD_1 src1_sel:DWORD
	v_and_b32_sdwa v52, v35, v178 dst_sel:DWORD dst_unused:UNUSED_PAD src0_sel:WORD_1 src1_sel:DWORD
	v_and_b32_sdwa v53, v27, v178 dst_sel:DWORD dst_unused:UNUSED_PAD src0_sel:WORD_1 src1_sel:DWORD
	v_and_b32_sdwa v54, v39, v178 dst_sel:DWORD dst_unused:UNUSED_PAD src0_sel:WORD_1 src1_sel:DWORD
	v_and_b32_sdwa v55, v31, v178 dst_sel:DWORD dst_unused:UNUSED_PAD src0_sel:WORD_1 src1_sel:DWORD
	v_and_b32_sdwa v57, v12, v178 dst_sel:DWORD dst_unused:UNUSED_PAD src0_sel:WORD_1 src1_sel:DWORD
	v_and_b32_sdwa v58, v24, v178 dst_sel:DWORD dst_unused:UNUSED_PAD src0_sel:WORD_1 src1_sel:DWORD
	v_and_b32_sdwa v59, v16, v178 dst_sel:DWORD dst_unused:UNUSED_PAD src0_sel:WORD_1 src1_sel:DWORD
	v_and_b32_sdwa v60, v36, v178 dst_sel:DWORD dst_unused:UNUSED_PAD src0_sel:WORD_1 src1_sel:DWORD
	v_and_b32_sdwa v61, v28, v178 dst_sel:DWORD dst_unused:UNUSED_PAD src0_sel:WORD_1 src1_sel:DWORD
	s_waitcnt lgkmcnt(0)
	v_and_b32_sdwa v62, v40, v178 dst_sel:DWORD dst_unused:UNUSED_PAD src0_sel:WORD_1 src1_sel:DWORD
	v_and_b32_sdwa v63, v32, v178 dst_sel:DWORD dst_unused:UNUSED_PAD src0_sel:WORD_1 src1_sel:DWORD
	v_and_b32_sdwa v64, v21, v178 dst_sel:DWORD dst_unused:UNUSED_PAD src0_sel:WORD_1 src1_sel:DWORD
	v_and_b32_sdwa v65, v13, v178 dst_sel:DWORD dst_unused:UNUSED_PAD src0_sel:WORD_1 src1_sel:DWORD
	v_and_b32_sdwa v66, v25, v178 dst_sel:DWORD dst_unused:UNUSED_PAD src0_sel:WORD_1 src1_sel:DWORD
	v_and_b32_sdwa v67, v17, v178 dst_sel:DWORD dst_unused:UNUSED_PAD src0_sel:WORD_1 src1_sel:DWORD
	v_and_b32_sdwa v70, v41, v178 dst_sel:DWORD dst_unused:UNUSED_PAD src0_sel:WORD_1 src1_sel:DWORD
	v_and_b32_sdwa v71, v33, v178 dst_sel:DWORD dst_unused:UNUSED_PAD src0_sel:WORD_1 src1_sel:DWORD
	v_add3_u32 v9, v10, v9, s81
	v_add3_u32 v6, v18, v6, s81
	v_cvt_pk_bf16_f32 v10, v22, v22
	v_cvt_pk_bf16_f32 v14, v14, v14
	v_cvt_pk_bf16_f32 v18, v26, v26
	v_cvt_pk_bf16_f32 v26, v38, v38
	v_add3_u32 v30, v30, v47, s81
	v_and_b32_sdwa v48, v19, v178 dst_sel:DWORD dst_unused:UNUSED_PAD src0_sel:WORD_1 src1_sel:DWORD
	v_and_b32_sdwa v56, v20, v178 dst_sel:DWORD dst_unused:UNUSED_PAD src0_sel:WORD_1 src1_sel:DWORD
	v_and_b32_sdwa v68, v37, v178 dst_sel:DWORD dst_unused:UNUSED_PAD src0_sel:WORD_1 src1_sel:DWORD
	v_and_b32_sdwa v69, v29, v178 dst_sel:DWORD dst_unused:UNUSED_PAD src0_sel:WORD_1 src1_sel:DWORD
	v_cvt_pk_bf16_f32 v22, v34, v34
	v_add3_u32 v34, v11, v49, s81
	v_add3_u32 v11, v23, v50, s81
	v_add3_u32 v15, v15, v51, s81
	v_add3_u32 v23, v27, v53, s81
	v_add3_u32 v27, v35, v52, s81
	v_add3_u32 v35, v39, v54, s81
	v_add3_u32 v31, v31, v55, s81
	v_add3_u32 v38, v12, v57, s81
	v_add3_u32 v12, v24, v58, s81
	v_add3_u32 v16, v16, v59, s81
	v_add3_u32 v24, v28, v61, s81
	v_add3_u32 v28, v36, v60, s81
	v_add3_u32 v36, v40, v62, s81
	v_add3_u32 v32, v32, v63, s81
	v_add3_u32 v39, v13, v65, s81
	v_add3_u32 v40, v21, v64, s81
	v_add3_u32 v13, v25, v66, s81
	v_add3_u32 v17, v17, v67, s81
	v_add3_u32 v21, v41, v70, s81
	v_add3_u32 v33, v33, v71, s81
	v_and_b32_e32 v10, 0xffff0000, v10
	v_and_b32_e32 v14, 0xffff0000, v14
	v_and_b32_e32 v26, 0xffff0000, v26
	v_and_b32_e32 v30, 0xffff0000, v30
	v_add3_u32 v19, v19, v48, s81
	v_add3_u32 v20, v20, v56, s81
	v_add3_u32 v29, v29, v69, s81
	v_add3_u32 v25, v37, v68, s81
	v_and_b32_e32 v37, 0xffff0000, v11
	v_and_b32_e32 v41, 0xffff0000, v15
	v_and_b32_e32 v35, 0xffff0000, v35
	v_and_b32_e32 v31, 0xffff0000, v31
	v_and_b32_e32 v42, 0xffff0000, v12
	v_and_b32_e32 v43, 0xffff0000, v16
	v_and_b32_e32 v36, 0xffff0000, v36
	v_and_b32_e32 v32, 0xffff0000, v32
	v_and_b32_e32 v44, 0xffff0000, v13
	v_and_b32_e32 v45, 0xffff0000, v17
	v_and_b32_e32 v46, 0xffff0000, v21
	v_and_b32_e32 v33, 0xffff0000, v33
	v_or_b32_sdwa v11, v10, v6 dst_sel:DWORD dst_unused:UNUSED_PAD src0_sel:DWORD src1_sel:WORD_1
	v_or_b32_sdwa v10, v14, v9 dst_sel:DWORD dst_unused:UNUSED_PAD src0_sel:DWORD src1_sel:WORD_1
	v_or_b32_sdwa v13, v26, v22 dst_sel:DWORD dst_unused:UNUSED_PAD src0_sel:DWORD src1_sel:WORD_1
	v_or_b32_sdwa v12, v30, v18 dst_sel:DWORD dst_unused:UNUSED_PAD src0_sel:DWORD src1_sel:WORD_1
	v_or_b32_sdwa v15, v37, v19 dst_sel:DWORD dst_unused:UNUSED_PAD src0_sel:DWORD src1_sel:WORD_1
	v_or_b32_sdwa v14, v41, v34 dst_sel:DWORD dst_unused:UNUSED_PAD src0_sel:DWORD src1_sel:WORD_1
	v_or_b32_sdwa v17, v35, v27 dst_sel:DWORD dst_unused:UNUSED_PAD src0_sel:DWORD src1_sel:WORD_1
	v_or_b32_sdwa v16, v31, v23 dst_sel:DWORD dst_unused:UNUSED_PAD src0_sel:DWORD src1_sel:WORD_1
	v_or_b32_sdwa v19, v42, v20 dst_sel:DWORD dst_unused:UNUSED_PAD src0_sel:DWORD src1_sel:WORD_1
	v_or_b32_sdwa v18, v43, v38 dst_sel:DWORD dst_unused:UNUSED_PAD src0_sel:DWORD src1_sel:WORD_1
	v_or_b32_sdwa v21, v36, v28 dst_sel:DWORD dst_unused:UNUSED_PAD src0_sel:DWORD src1_sel:WORD_1
	v_or_b32_sdwa v20, v32, v24 dst_sel:DWORD dst_unused:UNUSED_PAD src0_sel:DWORD src1_sel:WORD_1
	v_or_b32_sdwa v23, v44, v40 dst_sel:DWORD dst_unused:UNUSED_PAD src0_sel:DWORD src1_sel:WORD_1
	v_or_b32_sdwa v22, v45, v39 dst_sel:DWORD dst_unused:UNUSED_PAD src0_sel:DWORD src1_sel:WORD_1
	v_or_b32_sdwa v25, v46, v25 dst_sel:DWORD dst_unused:UNUSED_PAD src0_sel:DWORD src1_sel:WORD_1
	v_or_b32_sdwa v24, v33, v29 dst_sel:DWORD dst_unused:UNUSED_PAD src0_sel:DWORD src1_sel:WORD_1
	global_store_dwordx4 v[86:87], v[10:13], off
	global_store_dwordx4 v[88:89], v[14:17], off
	global_store_dwordx4 v[90:91], v[18:21], off
	global_store_dwordx4 v[92:93], v[22:25], off
	s_barrier
	s_cbranch_scc1 .LBB0_929
	s_mov_b32 s51, 0x10000
